# GEMM mainloops: per-phase s_setprio flips replaced by one static priority raise for waves 0-3 before each K-loop (A/B: younger half 1352us, older half 1349us, none 1365us, flips 1356us)
# speedup vs baseline: 1.0670x; 1.0040x over previous
.LBB0_427:
	s_ashr_i32 s9, s8, 31
	s_lshl_b64 s[0:1], s[8:9], 11
	s_add_u32 s0, s62, s0
	s_addc_u32 s1, s63, s1
	v_add_u32_e32 v160, s31, v133
	v_lshlrev_b64 v[12:13], 1, v[130:131]
	v_lshl_add_u64 v[14:15], s[0:1], 0, v[12:13]
	v_readfirstlane_b32 s5, v160
	v_lshl_add_u64 v[14:15], v[14:15], 0, s[10:11]
	s_mov_b32 m0, s5
	v_mov_b32_e32 v135, v131
	s_ashr_i32 s27, s26, 31
	s_barrier
	global_load_lds_dwordx4 v[14:15], off
	v_lshlrev_b64 v[14:15], 1, v[134:135]
	v_add_u32_e32 v161, 0x2000, v160
	s_lshl_b64 s[38:39], s[26:27], 11
	v_lshl_add_u64 v[16:17], s[0:1], 0, v[14:15]
	v_readfirstlane_b32 s5, v161
	s_add_u32 s38, s60, s38
	v_lshl_add_u64 v[16:17], v[16:17], 0, s[10:11]
	s_mov_b32 m0, s5
	s_addc_u32 s39, s61, s39
	v_add_u32_e32 v162, s83, v133
	global_load_lds_dwordx4 v[16:17], off
	v_lshl_add_u64 v[16:17], s[38:39], 0, v[12:13]
	v_readfirstlane_b32 s5, v162
	s_or_b32 s92, s8, 0x80
	v_lshl_add_u64 v[16:17], v[16:17], 0, s[10:11]
	s_mov_b32 m0, s5
	s_ashr_i32 s93, s92, 31
	global_load_lds_dwordx4 v[16:17], off
	v_lshl_add_u64 v[16:17], s[38:39], 0, v[14:15]
	s_lshl_b64 s[38:39], s[92:93], 11
	v_add_u32_e32 v163, 0x2000, v162
	s_add_u32 s38, s62, s38
	v_readfirstlane_b32 s5, v163
	s_addc_u32 s39, s63, s39
	v_add_u32_e32 v164, s84, v133
	v_lshl_add_u64 v[16:17], v[16:17], 0, s[10:11]
	s_mov_b32 m0, s5
	v_lshl_add_u64 v[12:13], s[38:39], 0, v[12:13]
	v_readfirstlane_b32 s5, v164
	global_load_lds_dwordx4 v[16:17], off
	v_lshl_add_u64 v[12:13], v[12:13], 0, s[10:11]
	s_mov_b32 m0, s5
	v_add_u32_e32 v165, 0x2000, v164
	global_load_lds_dwordx4 v[12:13], off
	v_lshl_add_u64 v[12:13], s[38:39], 0, v[14:15]
	v_readfirstlane_b32 s5, v165
	v_lshl_add_u64 v[12:13], v[12:13], 0, s[10:11]
	s_mov_b32 m0, s5
	v_lshlrev_b32_e32 v2, 13, v2
	global_load_lds_dwordx4 v[12:13], off
	v_and_b32_e32 v2, 0xffffc000, v2
	v_lshl_add_u32 v2, v4, 10, v2
	v_lshlrev_b32_e32 v4, 13, v7
	v_and_b32_e32 v11, 15, v3
	v_and_b32_e32 v18, 48, v3
	v_lshlrev_b32_e32 v12, 2, v3
	v_lshlrev_b32_e32 v3, 6, v3
	v_and_b32_e32 v4, 0xffffc000, v4
	v_and_b32_e32 v12, 32, v12
	v_and_b32_e32 v3, 0x3c0, v3
	v_lshl_add_u32 v4, v8, 10, v4
	v_bitop3_b32 v3, v3, v12, v18 bitop3:0x36
	v_or_b32_e32 v2, v2, v5
	v_or_b32_e32 v4, v4, v9
	v_add_u32_e32 v167, 0, v3
	v_add_u32_e32 v168, s83, v3
	v_add_u32_e32 v169, s85, v3
	v_add_u32_sdwa v2, v2, sext(v6) dst_sel:DWORD dst_unused:UNUSED_PAD src0_sel:DWORD src1_sel:WORD_0
	v_mov_b32_e32 v3, v131
	v_add_u32_sdwa v4, v4, sext(v10) dst_sel:DWORD dst_unused:UNUSED_PAD src0_sel:DWORD src1_sel:WORD_0
	v_mov_b32_e32 v5, v131
	v_lshlrev_b64 v[2:3], 1, v[2:3]
	v_lshlrev_b64 v[4:5], 1, v[4:5]
	v_lshl_add_u64 v[136:137], s[0:1], 0, v[2:3]
	v_lshl_add_u64 v[138:139], s[0:1], 0, v[4:5]
	s_sub_i32 s0, s86, s82
	s_sub_i32 s0, s0, s29
	s_sext_i32_i16 s0, s0
	s_lshl_b32 s38, s28, 11
	s_lshl_b32 s0, s0, 8
	s_add_i32 s0, s38, s0
	s_lshl_b32 s5, s3, 6
	s_lshl_b32 s24, s24, 13
	s_ashr_i32 s1, s0, 31
	s_and_b32 s5, s5, 0x3000
	s_or_b32 s27, s24, 0x800
	s_or_b32 s39, s24, 0x1000
	s_or_b32 vcc_lo, s24, 0x1800
	s_lshl_b64 s[0:1], s[0:1], 11
	v_lshlrev_b32_e32 v11, 6, v11
	s_add_u32 s0, s60, s0
	s_waitcnt vmcnt(6)
	v_bitop3_b32 v11, v11, v12, v18 bitop3:0x36
	s_addc_u32 s1, s61, s1
	v_add_u32_e32 v166, 0, v11
	v_add_u32_e32 v13, s31, v11
	v_add_u32_e32 v14, s84, v11
	v_add_u32_e32 v12, s83, v11
	v_add_u32_e32 v11, s85, v11
	v_lshl_add_u64 v[140:141], s[0:1], 0, v[2:3]
	v_mov_b32_e32 v2, 0
	v_lshl_add_u64 v[142:143], s[0:1], 0, v[4:5]
	s_mov_b32 vcc_hi, -2
	s_mov_b64 s[0:1], 0
	v_add_u32_e32 v159, s5, v13
	v_add_u32_e32 v158, s24, v12
	v_add_u32_e32 v157, s5, v14
	v_add_u32_e32 v156, s24, v11
	v_mov_b32_e32 v3, v2
	v_mov_b32_e32 v4, v2
	v_mov_b32_e32 v5, v2
	v_mov_b32_e32 v6, v2
	v_mov_b32_e32 v7, v2
	v_mov_b32_e32 v8, v2
	v_mov_b32_e32 v9, v2
	v_mov_b32_e32 v10, v2
	v_mov_b32_e32 v11, v2
	v_mov_b32_e32 v12, v2
	v_mov_b32_e32 v13, v2
	v_mov_b32_e32 v14, v2
	v_mov_b32_e32 v15, v2
	v_mov_b32_e32 v16, v2
	v_mov_b32_e32 v17, v2
	v_mov_b32_e32 v18, v2
	v_mov_b32_e32 v19, v2
	v_mov_b32_e32 v20, v2
	v_mov_b32_e32 v21, v2
	v_mov_b32_e32 v22, v2
	v_mov_b32_e32 v23, v2
	v_mov_b32_e32 v24, v2
	v_mov_b32_e32 v25, v2
	v_mov_b32_e32 v26, v2
	v_mov_b32_e32 v27, v2
	v_mov_b32_e32 v28, v2
	v_mov_b32_e32 v29, v2
	v_mov_b32_e32 v30, v2
	v_mov_b32_e32 v31, v2
	v_mov_b32_e32 v32, v2
	v_mov_b32_e32 v33, v2
	v_mov_b32_e32 v34, v2
	v_mov_b32_e32 v35, v2
	v_mov_b32_e32 v36, v2
	v_mov_b32_e32 v37, v2
	v_mov_b32_e32 v38, v2
	v_mov_b32_e32 v39, v2
	v_mov_b32_e32 v40, v2
	v_mov_b32_e32 v41, v2
	v_mov_b32_e32 v42, v2
	v_mov_b32_e32 v43, v2
	v_mov_b32_e32 v44, v2
	v_mov_b32_e32 v45, v2
	s_waitcnt lgkmcnt(0)
	v_mov_b32_e32 v46, v2
	v_mov_b32_e32 v47, v2
	v_mov_b32_e32 v48, v2
	v_mov_b32_e32 v49, v2
	v_mov_b32_e32 v50, v2
	v_mov_b32_e32 v51, v2
	v_mov_b32_e32 v52, v2
	v_mov_b32_e32 v53, v2
	v_mov_b32_e32 v54, v2
	v_mov_b32_e32 v55, v2
	v_mov_b32_e32 v56, v2
	v_mov_b32_e32 v57, v2
	v_mov_b32_e32 v58, v2
	v_mov_b32_e32 v59, v2
	v_mov_b32_e32 v60, v2
	v_mov_b32_e32 v61, v2
	v_mov_b32_e32 v62, v2
	v_mov_b32_e32 v63, v2
	v_mov_b32_e32 v64, v2
	v_mov_b32_e32 v65, v2
	v_mov_b32_e32 v66, v2
	v_mov_b32_e32 v67, v2
	v_mov_b32_e32 v68, v2
	v_mov_b32_e32 v69, v2
	v_mov_b32_e32 v82, v2
	v_mov_b32_e32 v83, v2
	v_mov_b32_e32 v84, v2
	v_mov_b32_e32 v85, v2
	v_mov_b32_e32 v90, v2
	v_mov_b32_e32 v91, v2
	v_mov_b32_e32 v92, v2
	v_mov_b32_e32 v93, v2
	v_mov_b32_e32 v94, v2
	v_mov_b32_e32 v95, v2
	v_mov_b32_e32 v96, v2
	v_mov_b32_e32 v97, v2
	v_mov_b32_e32 v98, v2
	v_mov_b32_e32 v99, v2
	v_mov_b32_e32 v100, v2
	v_mov_b32_e32 v101, v2
	v_mov_b32_e32 v102, v2
	v_mov_b32_e32 v103, v2
	v_mov_b32_e32 v104, v2
	v_mov_b32_e32 v105, v2
	v_mov_b32_e32 v106, v2
	v_mov_b32_e32 v107, v2
	v_mov_b32_e32 v108, v2
	v_mov_b32_e32 v109, v2
	v_mov_b32_e32 v110, v2
	v_mov_b32_e32 v111, v2
	v_mov_b32_e32 v112, v2
	v_mov_b32_e32 v113, v2
	v_mov_b32_e32 v114, v2
	v_mov_b32_e32 v115, v2
	v_mov_b32_e32 v116, v2
	v_mov_b32_e32 v117, v2
	v_mov_b32_e32 v118, v2
	v_mov_b32_e32 v119, v2
	v_mov_b32_e32 v120, v2
	v_mov_b32_e32 v121, v2
	v_mov_b32_e32 v122, v2
	v_mov_b32_e32 v123, v2
	v_mov_b32_e32 v124, v2
	v_mov_b32_e32 v125, v2
	v_mov_b32_e32 v126, v2
	v_mov_b32_e32 v127, v2
	v_mov_b32_e32 v128, v2
	v_mov_b32_e32 v129, v2
	v_mov_b32_e32 v70, v2
	v_mov_b32_e32 v71, v2
	v_mov_b32_e32 v72, v2
	v_mov_b32_e32 v73, v2
	v_mov_b32_e32 v74, v2
	v_mov_b32_e32 v75, v2
	v_mov_b32_e32 v76, v2
	v_mov_b32_e32 v77, v2
	v_mov_b32_e32 v78, v2
	v_mov_b32_e32 v79, v2
	v_mov_b32_e32 v80, v2
	v_mov_b32_e32 v81, v2
	v_mov_b32_e32 v86, v2
	v_mov_b32_e32 v87, v2
	v_mov_b32_e32 v88, v2
	v_mov_b32_e32 v89, v2
	s_barrier
	v_readfirstlane_b32 s99, v0
	s_nop 3
	s_lshr_b32 s99, s99, 6
	s_cmp_lt_u32 s99, 4
	s_cbranch_scc0 .Lprio_k0
	s_setprio 1
.Lprio_k0:
.LBB0_428:
	v_add_u32_e32 v174, s5, v166
	ds_read_b128 v[178:181], v174 offset:32768
	ds_read_b128 v[182:185], v174 offset:33792
	ds_read_b128 v[186:189], v174 offset:34816
	ds_read_b128 v[190:193], v174 offset:35840
	v_add_u32_e32 v175, s85, v133
	v_lshl_add_u64 v[248:249], v[140:141], 0, s[0:1]
	v_readfirstlane_b32 s28, v175
	v_add_u32_e32 v170, s24, v166
	v_add_u32_e32 v171, s27, v167
	v_add_u32_e32 v172, s39, v167
	v_add_u32_e32 v173, vcc_lo, v167
	v_lshl_add_u64 v[176:177], v[248:249], 0, s[12:13]
	s_mov_b32 m0, s28
	ds_read_b128 v[194:197], v170
	ds_read_b128 v[198:201], v170 offset:1024
	ds_read_b128 v[202:205], v171
	ds_read_b128 v[206:209], v171 offset:1024
	ds_read_b128 v[210:213], v172
	ds_read_b128 v[214:217], v172 offset:1024
	ds_read_b128 v[218:221], v173
	ds_read_b128 v[222:225], v173 offset:1024
	global_load_lds_dwordx4 v[176:177], off
	v_add_u32_e32 v176, 0x2000, v175
	v_lshl_add_u64 v[250:251], v[142:143], 0, s[0:1]
	v_readfirstlane_b32 s28, v176
	v_lshl_add_u64 v[226:227], v[250:251], 0, s[12:13]
	s_mov_b32 m0, s28
	s_nop 0
	global_load_lds_dwordx4 v[226:227], off
	s_waitcnt lgkmcnt(8)
	s_barrier
	s_waitcnt lgkmcnt(0)
	s_waitcnt lgkmcnt(0)
	v_mfma_f32_16x16x32_bf16 v[126:129], v[194:197], v[178:181], v[126:129]
	v_mfma_f32_16x16x32_bf16 v[122:125], v[194:197], v[186:189], v[122:125]
	v_mfma_f32_16x16x32_bf16 v[118:121], v[202:205], v[178:181], v[118:121]
	v_mfma_f32_16x16x32_bf16 v[114:117], v[202:205], v[186:189], v[114:117]
	v_mfma_f32_16x16x32_bf16 v[110:113], v[210:213], v[178:181], v[110:113]
	v_mfma_f32_16x16x32_bf16 v[106:109], v[210:213], v[186:189], v[106:109]
	v_mfma_f32_16x16x32_bf16 v[102:105], v[218:221], v[178:181], v[102:105]
	v_mfma_f32_16x16x32_bf16 v[98:101], v[218:221], v[186:189], v[98:101]
	v_mfma_f32_16x16x32_bf16 v[126:129], v[198:201], v[182:185], v[126:129]
	v_mfma_f32_16x16x32_bf16 v[122:125], v[198:201], v[190:193], v[122:125]
	v_mfma_f32_16x16x32_bf16 v[118:121], v[206:209], v[182:185], v[118:121]
	v_mfma_f32_16x16x32_bf16 v[114:117], v[206:209], v[190:193], v[114:117]
	v_mfma_f32_16x16x32_bf16 v[110:113], v[214:217], v[182:185], v[110:113]
	v_mfma_f32_16x16x32_bf16 v[106:109], v[214:217], v[190:193], v[106:109]
	v_mfma_f32_16x16x32_bf16 v[102:105], v[222:225], v[182:185], v[102:105]
	v_mfma_f32_16x16x32_bf16 v[98:101], v[222:225], v[190:193], v[98:101]
	s_barrier
	v_lshl_add_u64 v[146:147], v[136:137], 0, s[0:1]
	v_readfirstlane_b32 s28, v149
	v_lshl_add_u64 v[242:243], v[146:147], 0, s[14:15]
	s_mov_b32 m0, s28
	v_lshl_add_u64 v[144:145], v[138:139], 0, s[0:1]
	v_readfirstlane_b32 s28, v150
	ds_read_b128 v[226:229], v174 offset:49152
	ds_read_b128 v[230:233], v174 offset:50176
	ds_read_b128 v[234:237], v174 offset:51200
	ds_read_b128 v[238:241], v174 offset:52224
	global_load_lds_dwordx4 v[242:243], off
	v_lshl_add_u64 v[242:243], v[144:145], 0, s[14:15]
	s_mov_b32 m0, s28
	s_nop 0
	global_load_lds_dwordx4 v[242:243], off
	s_barrier
	s_waitcnt lgkmcnt(0)
	s_waitcnt lgkmcnt(0)
	v_mfma_f32_16x16x32_bf16 v[94:97], v[194:197], v[226:229], v[94:97]
	v_mfma_f32_16x16x32_bf16 v[90:93], v[194:197], v[234:237], v[90:93]
	v_mfma_f32_16x16x32_bf16 v[82:85], v[202:205], v[226:229], v[82:85]
	v_mfma_f32_16x16x32_bf16 v[66:69], v[202:205], v[234:237], v[66:69]
	v_mfma_f32_16x16x32_bf16 v[62:65], v[210:213], v[226:229], v[62:65]
	v_mfma_f32_16x16x32_bf16 v[58:61], v[210:213], v[234:237], v[58:61]
	v_mfma_f32_16x16x32_bf16 v[54:57], v[218:221], v[226:229], v[54:57]
	v_mfma_f32_16x16x32_bf16 v[50:53], v[218:221], v[234:237], v[50:53]
	v_mfma_f32_16x16x32_bf16 v[94:97], v[198:201], v[230:233], v[94:97]
	v_mfma_f32_16x16x32_bf16 v[90:93], v[198:201], v[238:241], v[90:93]
	v_mfma_f32_16x16x32_bf16 v[82:85], v[206:209], v[230:233], v[82:85]
	v_mfma_f32_16x16x32_bf16 v[66:69], v[206:209], v[238:241], v[66:69]
	v_mfma_f32_16x16x32_bf16 v[62:65], v[214:217], v[230:233], v[62:65]
	v_mfma_f32_16x16x32_bf16 v[58:61], v[214:217], v[238:241], v[58:61]
	v_mfma_f32_16x16x32_bf16 v[54:57], v[222:225], v[230:233], v[54:57]
	v_mfma_f32_16x16x32_bf16 v[50:53], v[222:225], v[238:241], v[50:53]
	v_readfirstlane_b32 s28, v148
	v_lshl_add_u64 v[242:243], v[248:249], 0, s[14:15]
	s_mov_b32 m0, s28
	v_readfirstlane_b32 s28, v151
	s_barrier
	ds_read_b128 v[194:197], v170 offset:16384
	ds_read_b128 v[198:201], v170 offset:17408
	ds_read_b128 v[202:205], v171 offset:16384
	ds_read_b128 v[206:209], v171 offset:17408
	ds_read_b128 v[210:213], v172 offset:16384
	ds_read_b128 v[214:217], v172 offset:17408
	ds_read_b128 v[218:221], v173 offset:16384
	ds_read_b128 v[222:225], v173 offset:17408
	global_load_lds_dwordx4 v[242:243], off
	v_lshl_add_u64 v[242:243], v[250:251], 0, s[14:15]
	s_mov_b32 m0, s28
	s_nop 0
	global_load_lds_dwordx4 v[242:243], off
	s_barrier
	s_waitcnt lgkmcnt(0)
	s_waitcnt lgkmcnt(0)
	v_mfma_f32_16x16x32_bf16 v[46:49], v[194:197], v[178:181], v[46:49]
	v_mfma_f32_16x16x32_bf16 v[42:45], v[194:197], v[186:189], v[42:45]
	v_mfma_f32_16x16x32_bf16 v[38:41], v[202:205], v[178:181], v[38:41]
	v_mfma_f32_16x16x32_bf16 v[34:37], v[202:205], v[186:189], v[34:37]
	v_mfma_f32_16x16x32_bf16 v[30:33], v[210:213], v[178:181], v[30:33]
	v_mfma_f32_16x16x32_bf16 v[26:29], v[210:213], v[186:189], v[26:29]
	v_mfma_f32_16x16x32_bf16 v[22:25], v[218:221], v[178:181], v[22:25]
	v_mfma_f32_16x16x32_bf16 v[18:21], v[218:221], v[186:189], v[18:21]
	v_mfma_f32_16x16x32_bf16 v[46:49], v[198:201], v[182:185], v[46:49]
	v_mfma_f32_16x16x32_bf16 v[42:45], v[198:201], v[190:193], v[42:45]
	v_mfma_f32_16x16x32_bf16 v[38:41], v[206:209], v[182:185], v[38:41]
	v_mfma_f32_16x16x32_bf16 v[34:37], v[206:209], v[190:193], v[34:37]
	v_mfma_f32_16x16x32_bf16 v[30:33], v[214:217], v[182:185], v[30:33]
	v_mfma_f32_16x16x32_bf16 v[26:29], v[214:217], v[190:193], v[26:29]
	v_mfma_f32_16x16x32_bf16 v[22:25], v[222:225], v[182:185], v[22:25]
	v_mfma_f32_16x16x32_bf16 v[18:21], v[222:225], v[190:193], v[18:21]
	s_barrier
	v_readfirstlane_b32 s28, v152
	v_lshl_add_u64 v[178:179], v[146:147], 0, s[16:17]
	s_mov_b32 m0, s28
	v_readfirstlane_b32 s28, v153
	global_load_lds_dwordx4 v[178:179], off
	v_lshl_add_u64 v[178:179], v[144:145], 0, s[16:17]
	s_mov_b32 m0, s28
	s_nop 0
	global_load_lds_dwordx4 v[178:179], off
	s_waitcnt vmcnt(6)
	s_barrier
	v_mfma_f32_16x16x32_bf16 v[14:17], v[194:197], v[226:229], v[14:17]
	v_mfma_f32_16x16x32_bf16 v[10:13], v[194:197], v[234:237], v[10:13]
	v_mfma_f32_16x16x32_bf16 v[6:9], v[202:205], v[226:229], v[6:9]
	v_mfma_f32_16x16x32_bf16 v[2:5], v[202:205], v[234:237], v[2:5]
	v_mfma_f32_16x16x32_bf16 v[70:73], v[210:213], v[226:229], v[70:73]
	v_mfma_f32_16x16x32_bf16 v[74:77], v[210:213], v[234:237], v[74:77]
	v_mfma_f32_16x16x32_bf16 v[78:81], v[218:221], v[226:229], v[78:81]
	v_mfma_f32_16x16x32_bf16 v[86:89], v[218:221], v[234:237], v[86:89]
	v_mfma_f32_16x16x32_bf16 v[14:17], v[198:201], v[230:233], v[14:17]
	v_mfma_f32_16x16x32_bf16 v[10:13], v[198:201], v[238:241], v[10:13]
	v_mfma_f32_16x16x32_bf16 v[6:9], v[206:209], v[230:233], v[6:9]
	v_mfma_f32_16x16x32_bf16 v[2:5], v[206:209], v[238:241], v[2:5]
	v_mfma_f32_16x16x32_bf16 v[70:73], v[214:217], v[230:233], v[70:73]
	v_mfma_f32_16x16x32_bf16 v[74:77], v[214:217], v[238:241], v[74:77]
	v_mfma_f32_16x16x32_bf16 v[78:81], v[222:225], v[230:233], v[78:81]
	v_mfma_f32_16x16x32_bf16 v[86:89], v[222:225], v[238:241], v[86:89]
	s_barrier
	ds_read_b128 v[184:187], v159
	ds_read_b128 v[188:191], v159 offset:1024
	ds_read_b128 v[192:195], v159 offset:2048
	ds_read_b128 v[196:199], v159 offset:3072
	v_readfirstlane_b32 s28, v154
	v_add_u32_e32 v177, s27, v168
	v_add_u32_e32 v178, s39, v168
	v_add_u32_e32 v179, vcc_lo, v168
	v_lshl_add_u64 v[228:229], v[248:249], 0, s[16:17]
	s_mov_b32 m0, s28
	v_readfirstlane_b32 s28, v155
	ds_read_b128 v[180:183], v158
	ds_read_b128 v[200:203], v158 offset:1024
	ds_read_b128 v[204:207], v177
	ds_read_b128 v[208:211], v177 offset:1024
	ds_read_b128 v[212:215], v178
	ds_read_b128 v[216:219], v178 offset:1024
	ds_read_b128 v[220:223], v179
	ds_read_b128 v[224:227], v179 offset:1024
	global_load_lds_dwordx4 v[228:229], off
	v_lshl_add_u64 v[228:229], v[250:251], 0, s[16:17]
	s_mov_b32 m0, s28
	s_nop 0
	global_load_lds_dwordx4 v[228:229], off
	s_waitcnt lgkmcnt(8)
	s_barrier
	s_waitcnt lgkmcnt(0)
	s_waitcnt lgkmcnt(0)
	v_mfma_f32_16x16x32_bf16 v[126:129], v[180:183], v[184:187], v[126:129]
	v_mfma_f32_16x16x32_bf16 v[122:125], v[180:183], v[192:195], v[122:125]
	v_mfma_f32_16x16x32_bf16 v[118:121], v[204:207], v[184:187], v[118:121]
	v_mfma_f32_16x16x32_bf16 v[114:117], v[204:207], v[192:195], v[114:117]
	v_mfma_f32_16x16x32_bf16 v[110:113], v[212:215], v[184:187], v[110:113]
	v_mfma_f32_16x16x32_bf16 v[106:109], v[212:215], v[192:195], v[106:109]
	v_mfma_f32_16x16x32_bf16 v[102:105], v[220:223], v[184:187], v[102:105]
	v_mfma_f32_16x16x32_bf16 v[98:101], v[220:223], v[192:195], v[98:101]
	v_mfma_f32_16x16x32_bf16 v[126:129], v[200:203], v[188:191], v[126:129]
	v_mfma_f32_16x16x32_bf16 v[122:125], v[200:203], v[196:199], v[122:125]
	v_mfma_f32_16x16x32_bf16 v[118:121], v[208:211], v[188:191], v[118:121]
	v_mfma_f32_16x16x32_bf16 v[114:117], v[208:211], v[196:199], v[114:117]
	v_mfma_f32_16x16x32_bf16 v[110:113], v[216:219], v[188:191], v[110:113]
	v_mfma_f32_16x16x32_bf16 v[106:109], v[216:219], v[196:199], v[106:109]
	v_mfma_f32_16x16x32_bf16 v[102:105], v[224:227], v[188:191], v[102:105]
	v_mfma_f32_16x16x32_bf16 v[98:101], v[224:227], v[196:199], v[98:101]
	s_barrier
	v_readfirstlane_b32 s28, v160
	v_lshl_add_u64 v[244:245], v[146:147], 0, s[18:19]
	s_mov_b32 m0, s28
	v_readfirstlane_b32 s28, v161
	ds_read_b128 v[228:231], v157
	ds_read_b128 v[232:235], v157 offset:1024
	ds_read_b128 v[236:239], v157 offset:2048
	ds_read_b128 v[240:243], v157 offset:3072
	global_load_lds_dwordx4 v[244:245], off
	v_lshl_add_u64 v[244:245], v[144:145], 0, s[18:19]
	s_mov_b32 m0, s28
	s_nop 0
	global_load_lds_dwordx4 v[244:245], off
	s_barrier
	s_waitcnt lgkmcnt(0)
	s_waitcnt lgkmcnt(0)
	v_mfma_f32_16x16x32_bf16 v[94:97], v[180:183], v[228:231], v[94:97]
	v_mfma_f32_16x16x32_bf16 v[90:93], v[180:183], v[236:239], v[90:93]
	v_mfma_f32_16x16x32_bf16 v[82:85], v[204:207], v[228:231], v[82:85]
	v_mfma_f32_16x16x32_bf16 v[66:69], v[204:207], v[236:239], v[66:69]
	v_mfma_f32_16x16x32_bf16 v[62:65], v[212:215], v[228:231], v[62:65]
	v_mfma_f32_16x16x32_bf16 v[58:61], v[212:215], v[236:239], v[58:61]
	v_mfma_f32_16x16x32_bf16 v[54:57], v[220:223], v[228:231], v[54:57]
	v_mfma_f32_16x16x32_bf16 v[50:53], v[220:223], v[236:239], v[50:53]
	v_mfma_f32_16x16x32_bf16 v[94:97], v[200:203], v[232:235], v[94:97]
	v_mfma_f32_16x16x32_bf16 v[90:93], v[200:203], v[240:243], v[90:93]
	v_mfma_f32_16x16x32_bf16 v[82:85], v[208:211], v[232:235], v[82:85]
	v_mfma_f32_16x16x32_bf16 v[66:69], v[208:211], v[240:243], v[66:69]
	v_mfma_f32_16x16x32_bf16 v[62:65], v[216:219], v[232:235], v[62:65]
	v_mfma_f32_16x16x32_bf16 v[58:61], v[216:219], v[240:243], v[58:61]
	v_mfma_f32_16x16x32_bf16 v[54:57], v[224:227], v[232:235], v[54:57]
	v_mfma_f32_16x16x32_bf16 v[50:53], v[224:227], v[240:243], v[50:53]
	v_readfirstlane_b32 s28, v162
	v_add_u32_e32 v180, s27, v169
	v_add_u32_e32 v181, s39, v169
	v_add_u32_e32 v182, vcc_lo, v169
	v_lshl_add_u64 v[248:249], v[248:249], 0, s[18:19]
	s_mov_b32 m0, s28
	v_readfirstlane_b32 s28, v163
	s_barrier
	ds_read_b128 v[200:203], v156
	ds_read_b128 v[204:207], v156 offset:1024
	ds_read_b128 v[208:211], v180
	ds_read_b128 v[212:215], v180 offset:1024
	ds_read_b128 v[216:219], v181
	ds_read_b128 v[220:223], v181 offset:1024
	ds_read_b128 v[224:227], v182
	ds_read_b128 v[244:247], v182 offset:1024
	global_load_lds_dwordx4 v[248:249], off
	v_lshl_add_u64 v[248:249], v[250:251], 0, s[18:19]
	s_mov_b32 m0, s28
	s_nop 0
	global_load_lds_dwordx4 v[248:249], off
	s_barrier
	s_waitcnt lgkmcnt(0)
	s_waitcnt lgkmcnt(0)
	v_mfma_f32_16x16x32_bf16 v[46:49], v[200:203], v[184:187], v[46:49]
	v_mfma_f32_16x16x32_bf16 v[42:45], v[200:203], v[192:195], v[42:45]
	v_mfma_f32_16x16x32_bf16 v[38:41], v[208:211], v[184:187], v[38:41]
	v_mfma_f32_16x16x32_bf16 v[34:37], v[208:211], v[192:195], v[34:37]
	v_mfma_f32_16x16x32_bf16 v[30:33], v[216:219], v[184:187], v[30:33]
	v_mfma_f32_16x16x32_bf16 v[26:29], v[216:219], v[192:195], v[26:29]
	v_mfma_f32_16x16x32_bf16 v[22:25], v[224:227], v[184:187], v[22:25]
	v_mfma_f32_16x16x32_bf16 v[18:21], v[224:227], v[192:195], v[18:21]
	v_mfma_f32_16x16x32_bf16 v[46:49], v[204:207], v[188:191], v[46:49]
	v_mfma_f32_16x16x32_bf16 v[42:45], v[204:207], v[196:199], v[42:45]
	v_mfma_f32_16x16x32_bf16 v[38:41], v[212:215], v[188:191], v[38:41]
	v_mfma_f32_16x16x32_bf16 v[34:37], v[212:215], v[196:199], v[34:37]
	v_mfma_f32_16x16x32_bf16 v[30:33], v[220:223], v[188:191], v[30:33]
	v_mfma_f32_16x16x32_bf16 v[26:29], v[220:223], v[196:199], v[26:29]
	v_mfma_f32_16x16x32_bf16 v[22:25], v[244:247], v[188:191], v[22:25]
	v_mfma_f32_16x16x32_bf16 v[18:21], v[244:247], v[196:199], v[18:21]
	s_barrier
	v_readfirstlane_b32 s28, v164
	v_lshl_add_u64 v[146:147], v[146:147], 0, s[20:21]
	s_mov_b32 m0, s28
	v_readfirstlane_b32 s28, v165
	global_load_lds_dwordx4 v[146:147], off
	v_lshl_add_u64 v[144:145], v[144:145], 0, s[20:21]
	s_mov_b32 m0, s28
	s_nop 0
	global_load_lds_dwordx4 v[144:145], off
	s_waitcnt vmcnt(6)
	s_barrier
	v_mfma_f32_16x16x32_bf16 v[14:17], v[200:203], v[228:231], v[14:17]
	v_mfma_f32_16x16x32_bf16 v[10:13], v[200:203], v[236:239], v[10:13]
	v_mfma_f32_16x16x32_bf16 v[6:9], v[208:211], v[228:231], v[6:9]
	v_mfma_f32_16x16x32_bf16 v[2:5], v[208:211], v[236:239], v[2:5]
	v_mfma_f32_16x16x32_bf16 v[70:73], v[216:219], v[228:231], v[70:73]
	v_mfma_f32_16x16x32_bf16 v[74:77], v[216:219], v[236:239], v[74:77]
	v_mfma_f32_16x16x32_bf16 v[78:81], v[224:227], v[228:231], v[78:81]
	v_mfma_f32_16x16x32_bf16 v[86:89], v[224:227], v[236:239], v[86:89]
	v_mfma_f32_16x16x32_bf16 v[14:17], v[204:207], v[232:235], v[14:17]
	v_mfma_f32_16x16x32_bf16 v[10:13], v[204:207], v[240:243], v[10:13]
	v_mfma_f32_16x16x32_bf16 v[6:9], v[212:215], v[232:235], v[6:9]
	v_mfma_f32_16x16x32_bf16 v[2:5], v[212:215], v[240:243], v[2:5]
	v_mfma_f32_16x16x32_bf16 v[70:73], v[220:223], v[232:235], v[70:73]
	v_mfma_f32_16x16x32_bf16 v[74:77], v[220:223], v[240:243], v[74:77]
	v_mfma_f32_16x16x32_bf16 v[78:81], v[244:247], v[232:235], v[78:81]
	v_mfma_f32_16x16x32_bf16 v[86:89], v[244:247], v[240:243], v[86:89]
	s_add_i32 vcc_hi, vcc_hi, 2
	s_add_u32 s0, s0, 0x100
	s_addc_u32 s1, s1, 0
	s_cmp_lt_u32 vcc_hi, 12
	s_barrier
	s_cbranch_scc1 .LBB0_428
	s_bitset1_b32 s26, 7
	s_ashr_i32 s27, s26, 31
	s_lshl_b64 s[0:1], s[26:27], 11
	s_add_u32 s0, s60, s0
	s_addc_u32 s1, s61, s1
	v_lshl_add_u64 v[144:145], v[130:131], 1, s[0:1]
	v_readfirstlane_b32 s5, v175
	v_lshl_add_u64 v[144:145], v[144:145], 0, s[22:23]
	s_mov_b32 m0, s5
	v_lshl_add_u64 v[134:135], v[134:135], 1, s[0:1]
	v_readfirstlane_b32 s0, v176
	ds_read_b128 v[136:139], v174 offset:32768
	ds_read_b128 v[140:143], v174 offset:33792
	ds_read_b128 v[148:151], v174 offset:34816
	ds_read_b128 v[152:155], v174 offset:35840
	ds_read_b128 v[160:163], v170
	ds_read_b128 v[164:167], v170 offset:1024
	ds_read_b128 v[184:187], v171
	ds_read_b128 v[188:191], v171 offset:1024
	ds_read_b128 v[192:195], v172
	ds_read_b128 v[196:199], v172 offset:1024
	ds_read_b128 v[200:203], v173
	ds_read_b128 v[204:207], v173 offset:1024
	global_load_lds_dwordx4 v[144:145], off
	v_lshl_add_u64 v[134:135], v[134:135], 0, s[22:23]
	s_mov_b32 m0, s0
	s_nop 0
	global_load_lds_dwordx4 v[134:135], off
	s_barrier
	s_waitcnt lgkmcnt(0)
	s_waitcnt lgkmcnt(0)
	v_mfma_f32_16x16x32_bf16 v[126:129], v[160:163], v[136:139], v[126:129]
	v_mfma_f32_16x16x32_bf16 v[122:125], v[160:163], v[148:151], v[122:125]
	v_mfma_f32_16x16x32_bf16 v[118:121], v[184:187], v[136:139], v[118:121]
	v_mfma_f32_16x16x32_bf16 v[114:117], v[184:187], v[148:151], v[114:117]
	v_mfma_f32_16x16x32_bf16 v[110:113], v[192:195], v[136:139], v[110:113]
	v_mfma_f32_16x16x32_bf16 v[126:129], v[164:167], v[140:143], v[126:129]
	v_mfma_f32_16x16x32_bf16 v[122:125], v[164:167], v[152:155], v[122:125]
	v_mfma_f32_16x16x32_bf16 v[118:121], v[188:191], v[140:143], v[118:121]
	v_mfma_f32_16x16x32_bf16 v[114:117], v[188:191], v[152:155], v[114:117]
	v_mfma_f32_16x16x32_bf16 v[110:113], v[196:199], v[140:143], v[110:113]
	v_mfma_f32_16x16x32_bf16 v[106:109], v[192:195], v[148:151], v[106:109]
	v_mfma_f32_16x16x32_bf16 v[102:105], v[200:203], v[136:139], v[102:105]
	v_mfma_f32_16x16x32_bf16 v[98:101], v[200:203], v[148:151], v[98:101]
	v_mfma_f32_16x16x32_bf16 v[208:211], v[196:199], v[152:155], v[106:109]
	v_mfma_f32_16x16x32_bf16 v[212:215], v[204:207], v[140:143], v[102:105]
	v_mfma_f32_16x16x32_bf16 v[216:219], v[204:207], v[152:155], v[98:101]
	s_barrier
	s_nop 2
	ds_read_b128 v[98:101], v174 offset:49152
	ds_read_b128 v[102:105], v174 offset:50176
	ds_read_b128 v[106:109], v174 offset:51200
	ds_read_b128 v[220:223], v174 offset:52224
	s_barrier
	s_waitcnt lgkmcnt(0)
	s_waitcnt lgkmcnt(0)
	v_mfma_f32_16x16x32_bf16 v[94:97], v[160:163], v[98:101], v[94:97]
	v_mfma_f32_16x16x32_bf16 v[90:93], v[160:163], v[106:109], v[90:93]
	v_mfma_f32_16x16x32_bf16 v[82:85], v[184:187], v[98:101], v[82:85]
	v_mfma_f32_16x16x32_bf16 v[62:65], v[192:195], v[98:101], v[62:65]
	v_mfma_f32_16x16x32_bf16 v[58:61], v[192:195], v[106:109], v[58:61]
	v_mfma_f32_16x16x32_bf16 v[54:57], v[200:203], v[98:101], v[54:57]
	v_mfma_f32_16x16x32_bf16 v[50:53], v[200:203], v[106:109], v[50:53]
	v_mfma_f32_16x16x32_bf16 v[94:97], v[164:167], v[102:105], v[94:97]
	v_mfma_f32_16x16x32_bf16 v[90:93], v[164:167], v[220:223], v[90:93]
	v_mfma_f32_16x16x32_bf16 v[82:85], v[188:191], v[102:105], v[82:85]
	v_mfma_f32_16x16x32_bf16 v[66:69], v[184:187], v[106:109], v[66:69]
	v_mfma_f32_16x16x32_bf16 v[62:65], v[196:199], v[102:105], v[62:65]
	v_mfma_f32_16x16x32_bf16 v[58:61], v[196:199], v[220:223], v[58:61]
	v_mfma_f32_16x16x32_bf16 v[54:57], v[204:207], v[102:105], v[54:57]
	v_mfma_f32_16x16x32_bf16 v[50:53], v[204:207], v[220:223], v[50:53]
	v_mfma_f32_16x16x32_bf16 v[160:163], v[188:191], v[220:223], v[66:69]
	s_barrier
	s_nop 0
	ds_read_b128 v[66:69], v170 offset:16384
	ds_read_b128 v[164:167], v170 offset:17408
	ds_read_b128 v[184:187], v171 offset:16384
	ds_read_b128 v[168:171], v171 offset:17408
	ds_read_b128 v[188:191], v172 offset:16384
	ds_read_b128 v[192:195], v172 offset:17408
	ds_read_b128 v[196:199], v173 offset:16384
	ds_read_b128 v[172:175], v173 offset:17408
	s_waitcnt vmcnt(4)
	s_barrier
	s_waitcnt lgkmcnt(0)
	s_waitcnt lgkmcnt(0)
	v_mfma_f32_16x16x32_bf16 v[46:49], v[66:69], v[136:139], v[46:49]
	v_mfma_f32_16x16x32_bf16 v[42:45], v[66:69], v[148:151], v[42:45]
	v_mfma_f32_16x16x32_bf16 v[30:33], v[188:191], v[136:139], v[30:33]
	v_mfma_f32_16x16x32_bf16 v[26:29], v[188:191], v[148:151], v[26:29]
	v_mfma_f32_16x16x32_bf16 v[22:25], v[196:199], v[136:139], v[22:25]
	v_mfma_f32_16x16x32_bf16 v[18:21], v[196:199], v[148:151], v[18:21]
	v_mfma_f32_16x16x32_bf16 v[46:49], v[164:167], v[140:143], v[46:49]
	v_mfma_f32_16x16x32_bf16 v[42:45], v[164:167], v[152:155], v[42:45]
	v_mfma_f32_16x16x32_bf16 v[38:41], v[184:187], v[136:139], v[38:41]
	v_mfma_f32_16x16x32_bf16 v[34:37], v[184:187], v[148:151], v[34:37]
	v_mfma_f32_16x16x32_bf16 v[30:33], v[192:195], v[140:143], v[30:33]
	v_mfma_f32_16x16x32_bf16 v[26:29], v[192:195], v[152:155], v[26:29]
	v_mfma_f32_16x16x32_bf16 v[22:25], v[172:175], v[140:143], v[22:25]
	v_mfma_f32_16x16x32_bf16 v[18:21], v[172:175], v[152:155], v[18:21]
	v_mfma_f32_16x16x32_bf16 v[200:203], v[168:171], v[140:143], v[38:41]
	v_mfma_f32_16x16x32_bf16 v[204:207], v[168:171], v[152:155], v[34:37]
	v_mfma_f32_16x16x32_bf16 v[2:5], v[184:187], v[106:109], v[2:5]
	v_mfma_f32_16x16x32_bf16 v[138:141], v[168:171], v[220:223], v[2:5]
	v_mfma_f32_16x16x32_bf16 v[2:5], v[188:191], v[98:101], v[70:73]
	v_mfma_f32_16x16x32_bf16 v[148:151], v[192:195], v[102:105], v[2:5]
	v_mfma_f32_16x16x32_bf16 v[2:5], v[188:191], v[106:109], v[74:77]
	v_mfma_f32_16x16x32_bf16 v[14:17], v[66:69], v[98:101], v[14:17]
	v_mfma_f32_16x16x32_bf16 v[10:13], v[66:69], v[106:109], v[10:13]
	v_mfma_f32_16x16x32_bf16 v[152:155], v[192:195], v[220:223], v[2:5]
	v_mfma_f32_16x16x32_bf16 v[2:5], v[196:199], v[98:101], v[78:81]
	v_mfma_f32_16x16x32_bf16 v[14:17], v[164:167], v[102:105], v[14:17]
	v_mfma_f32_16x16x32_bf16 v[10:13], v[164:167], v[220:223], v[10:13]
	v_mfma_f32_16x16x32_bf16 v[6:9], v[184:187], v[98:101], v[6:9]
	v_mfma_f32_16x16x32_bf16 v[164:167], v[172:175], v[102:105], v[2:5]
	v_mfma_f32_16x16x32_bf16 v[2:5], v[196:199], v[106:109], v[86:89]
	v_mfma_f32_16x16x32_bf16 v[134:137], v[168:171], v[102:105], v[6:9]
	v_mfma_f32_16x16x32_bf16 v[168:171], v[172:175], v[220:223], v[2:5]
	s_barrier
	s_nop 3
	ds_read_b128 v[2:5], v159
	ds_read_b128 v[6:9], v159 offset:1024
	ds_read_b128 v[172:175], v159 offset:2048
	ds_read_b128 v[184:187], v159 offset:3072
	ds_read_b128 v[34:37], v158
	ds_read_b128 v[38:41], v158 offset:1024
	ds_read_b128 v[78:81], v177
	ds_read_b128 v[86:89], v177 offset:1024
	ds_read_b128 v[188:191], v178
	ds_read_b128 v[192:195], v178 offset:1024
	ds_read_b128 v[196:199], v179
	ds_read_b128 v[176:179], v179 offset:1024
	s_waitcnt vmcnt(2)
	s_barrier
	s_waitcnt lgkmcnt(0)
	s_waitcnt lgkmcnt(0)
	v_mfma_f32_16x16x32_bf16 v[66:69], v[34:37], v[2:5], v[126:129]
	v_mfma_f32_16x16x32_bf16 v[126:129], v[38:41], v[6:9], v[66:69]
	v_mfma_f32_16x16x32_bf16 v[66:69], v[34:37], v[172:175], v[122:125]
	v_mfma_f32_16x16x32_bf16 v[98:101], v[38:41], v[184:187], v[66:69]
	v_mfma_f32_16x16x32_bf16 v[66:69], v[78:81], v[2:5], v[118:121]
	v_mfma_f32_16x16x32_bf16 v[102:105], v[86:89], v[6:9], v[66:69]
	v_mfma_f32_16x16x32_bf16 v[66:69], v[78:81], v[172:175], v[114:117]
	v_mfma_f32_16x16x32_bf16 v[106:109], v[86:89], v[184:187], v[66:69]
	v_mfma_f32_16x16x32_bf16 v[66:69], v[188:191], v[2:5], v[110:113]
	v_mfma_f32_16x16x32_bf16 v[110:113], v[192:195], v[6:9], v[66:69]
	v_mfma_f32_16x16x32_bf16 v[66:69], v[188:191], v[172:175], v[208:211]
	v_mfma_f32_16x16x32_bf16 v[114:117], v[192:195], v[184:187], v[66:69]
	v_mfma_f32_16x16x32_bf16 v[66:69], v[196:199], v[2:5], v[212:215]
	v_mfma_f32_16x16x32_bf16 v[118:121], v[176:179], v[6:9], v[66:69]
	v_mfma_f32_16x16x32_bf16 v[66:69], v[196:199], v[172:175], v[216:219]
	v_mfma_f32_16x16x32_bf16 v[122:125], v[176:179], v[184:187], v[66:69]
	s_barrier
	ds_read_b128 v[208:211], v157
	ds_read_b128 v[212:215], v157 offset:1024
	ds_read_b128 v[216:219], v157 offset:2048
	ds_read_b128 v[220:223], v157 offset:3072
	s_waitcnt vmcnt(0)
	s_barrier
	s_waitcnt lgkmcnt(0)
	s_waitcnt lgkmcnt(0)
	v_mfma_f32_16x16x32_bf16 v[66:69], v[34:37], v[208:211], v[94:97]
	v_mfma_f32_16x16x32_bf16 v[34:37], v[34:37], v[216:219], v[90:93]
	v_mfma_f32_16x16x32_bf16 v[70:73], v[38:41], v[220:223], v[34:37]
	v_mfma_f32_16x16x32_bf16 v[34:37], v[78:81], v[208:211], v[82:85]
	v_mfma_f32_16x16x32_bf16 v[74:77], v[86:89], v[212:215], v[34:37]
	v_mfma_f32_16x16x32_bf16 v[34:37], v[78:81], v[216:219], v[160:163]
	v_mfma_f32_16x16x32_bf16 v[78:81], v[86:89], v[220:223], v[34:37]
	v_mfma_f32_16x16x32_bf16 v[34:37], v[188:191], v[208:211], v[62:65]
	v_mfma_f32_16x16x32_bf16 v[82:85], v[192:195], v[212:215], v[34:37]
	v_mfma_f32_16x16x32_bf16 v[34:37], v[188:191], v[216:219], v[58:61]
	v_mfma_f32_16x16x32_bf16 v[86:89], v[192:195], v[220:223], v[34:37]
	v_mfma_f32_16x16x32_bf16 v[34:37], v[196:199], v[208:211], v[54:57]
	v_mfma_f32_16x16x32_bf16 v[90:93], v[176:179], v[212:215], v[34:37]
	v_mfma_f32_16x16x32_bf16 v[34:37], v[196:199], v[216:219], v[50:53]
	v_mfma_f32_16x16x32_bf16 v[66:69], v[38:41], v[212:215], v[66:69]
	v_mfma_f32_16x16x32_bf16 v[94:97], v[176:179], v[220:223], v[34:37]
	s_barrier
	ds_read_b128 v[158:161], v156
	ds_read_b128 v[176:179], v156 offset:1024
	ds_read_b128 v[188:191], v180
	ds_read_b128 v[192:195], v180 offset:1024
	ds_read_b128 v[196:199], v181
	ds_read_b128 v[224:227], v181 offset:1024
	ds_read_b128 v[228:231], v182
	ds_read_b128 v[180:183], v182 offset:1024
	s_barrier
	s_waitcnt lgkmcnt(0)
	s_waitcnt lgkmcnt(0)
	v_mfma_f32_16x16x32_bf16 v[34:37], v[158:161], v[2:5], v[46:49]
	v_mfma_f32_16x16x32_bf16 v[38:41], v[158:161], v[172:175], v[42:45]
	v_mfma_f32_16x16x32_bf16 v[42:45], v[188:191], v[2:5], v[200:203]
	v_mfma_f32_16x16x32_bf16 v[30:33], v[196:199], v[2:5], v[30:33]
	v_mfma_f32_16x16x32_bf16 v[2:5], v[228:231], v[2:5], v[22:25]
	v_mfma_f32_16x16x32_bf16 v[46:49], v[188:191], v[172:175], v[204:207]
	v_mfma_f32_16x16x32_bf16 v[26:29], v[196:199], v[172:175], v[26:29]
	v_mfma_f32_16x16x32_bf16 v[58:61], v[180:183], v[6:9], v[2:5]
	v_mfma_f32_16x16x32_bf16 v[2:5], v[228:231], v[172:175], v[18:21]
	v_mfma_f32_16x16x32_bf16 v[34:37], v[176:179], v[6:9], v[34:37]
	v_mfma_f32_16x16x32_bf16 v[38:41], v[176:179], v[184:187], v[38:41]
	v_mfma_f32_16x16x32_bf16 v[42:45], v[192:195], v[6:9], v[42:45]
	v_mfma_f32_16x16x32_bf16 v[46:49], v[192:195], v[184:187], v[46:49]
	v_mfma_f32_16x16x32_bf16 v[50:53], v[224:227], v[6:9], v[30:33]
	v_mfma_f32_16x16x32_bf16 v[54:57], v[224:227], v[184:187], v[26:29]
	v_mfma_f32_16x16x32_bf16 v[62:65], v[180:183], v[184:187], v[2:5]
	v_mfma_f32_16x16x32_bf16 v[2:5], v[158:161], v[208:211], v[14:17]
	v_mfma_f32_16x16x32_bf16 v[6:9], v[158:161], v[216:219], v[10:13]
	v_mfma_f32_16x16x32_bf16 v[10:13], v[188:191], v[208:211], v[134:137]
	v_mfma_f32_16x16x32_bf16 v[14:17], v[188:191], v[216:219], v[138:141]
	v_mfma_f32_16x16x32_bf16 v[18:21], v[196:199], v[208:211], v[148:151]
	v_mfma_f32_16x16x32_bf16 v[22:25], v[196:199], v[216:219], v[152:155]
	v_mfma_f32_16x16x32_bf16 v[26:29], v[228:231], v[208:211], v[164:167]
	v_mfma_f32_16x16x32_bf16 v[30:33], v[228:231], v[216:219], v[168:171]
	v_mfma_f32_16x16x32_bf16 v[2:5], v[176:179], v[212:215], v[2:5]
	v_mfma_f32_16x16x32_bf16 v[6:9], v[176:179], v[220:223], v[6:9]
	v_mfma_f32_16x16x32_bf16 v[10:13], v[192:195], v[212:215], v[10:13]
	v_mfma_f32_16x16x32_bf16 v[14:17], v[192:195], v[220:223], v[14:17]
	v_mfma_f32_16x16x32_bf16 v[18:21], v[224:227], v[212:215], v[18:21]
	v_mfma_f32_16x16x32_bf16 v[22:25], v[224:227], v[220:223], v[22:25]
	v_mfma_f32_16x16x32_bf16 v[26:29], v[180:183], v[212:215], v[26:29]
	v_mfma_f32_16x16x32_bf16 v[30:33], v[180:183], v[220:223], v[30:33]
	s_setprio 0
	s_cmpk_gt_u32 s3, 0xff
	s_barrier
	s_cbranch_scc1 .LBB0_431
	s_barrier

.LBB0_780:
	s_movk_i32 s6, 0x7ff
	v_cmp_lt_i32_e32 vcc, s6, v66
	s_and_saveexec_b64 s[6:7], vcc
	s_xor_b64 s[6:7], exec, s[6:7]
	s_cbranch_execz .LBB0_782
	s_movk_i32 s11, 0x80
	v_add_u32_e32 v2, 0xfffff800, v66
	v_bfe_u32 v86, v66, 1, 2
	v_and_or_b32 v67, v77, s11, v1
	v_lshrrev_b32_e32 v87, 3, v2
	v_lshlrev_b32_e32 v2, 6, v67
	v_lshlrev_b32_e32 v3, 14, v86
	v_or3_b32 v89, v3, v2, v68
	v_lshlrev_b32_e32 v90, 4, v87
	v_lshl_or_b32 v88, v86, 13, v68
	v_add_u32_e32 v70, v89, v90
	v_lshlrev_b64 v[2:3], 9, v[70:71]
	v_add_u32_e32 v70, v88, v90
	v_lshlrev_b64 v[6:7], 9, v[70:71]
	v_lshl_add_u64 v[2:3], v[72:73], 0, v[2:3]
	v_lshl_add_u64 v[6:7], v[74:75], 0, v[6:7]
	s_mov_b64 vcc, 0x1000
	v_lshl_add_u64 v[100:101], v[2:3], 0, vcc
	s_mov_b64 vcc, 0x1000
	v_lshl_add_u64 v[102:103], v[6:7], 0, vcc
	s_mov_b64 vcc, 0x101000
	v_lshl_add_u64 v[104:105], v[6:7], 0, vcc
	s_mov_b64 vcc, 0x201000
	v_lshl_add_u64 v[106:107], v[6:7], 0, vcc
	s_mov_b64 vcc, 0x301000
	v_lshl_add_u64 v[108:109], v[6:7], 0, vcc
	global_load_dwordx4 v[112:115], v[100:101], off offset:-4096
	global_load_dwordx4 v[116:119], v[100:101], off offset:-3072
	global_load_dwordx4 v[144:147], v[102:103], off offset:-4096
	global_load_dwordx4 v[148:151], v[104:105], off offset:-4096
	global_load_dwordx4 v[152:155], v[106:107], off offset:-4096
	global_load_dwordx4 v[156:159], v[108:109], off offset:-4096
	global_load_dwordx4 v[120:123], v[100:101], off offset:-2048
	global_load_dwordx4 v[124:127], v[100:101], off offset:-1024
	global_load_dwordx4 v[128:131], v[100:101], off
	global_load_dwordx4 v[132:135], v[100:101], off offset:1024
	global_load_dwordx4 v[136:139], v[100:101], off offset:2048
	global_load_dwordx4 v[140:143], v[100:101], off offset:3072
	global_load_dwordx4 v[160:163], v[102:103], off offset:-3072
	global_load_dwordx4 v[164:167], v[104:105], off offset:-3072
	global_load_dwordx4 v[168:171], v[106:107], off offset:-3072
	global_load_dwordx4 v[172:175], v[108:109], off offset:-3072
	global_load_dwordx4 v[176:179], v[102:103], off offset:-2048
	global_load_dwordx4 v[180:183], v[104:105], off offset:-2048
	global_load_dwordx4 v[184:187], v[106:107], off offset:-2048
	global_load_dwordx4 v[188:191], v[108:109], off offset:-2048
	s_waitcnt vmcnt(17)
	v_mfma_f32_32x32x16_bf16 v[50:65], v[144:147], v[112:115], 0
	global_load_dwordx4 v[144:147], v[102:103], off offset:-1024
	s_waitcnt vmcnt(17)
	v_mfma_f32_32x32x16_bf16 v[34:49], v[148:151], v[112:115], 0
	global_load_dwordx4 v[148:151], v[104:105], off offset:-1024
	s_waitcnt vmcnt(17)
	v_mfma_f32_32x32x16_bf16 v[18:33], v[152:155], v[112:115], 0
	global_load_dwordx4 v[152:155], v[106:107], off offset:-1024
	s_waitcnt vmcnt(17)
	v_mfma_f32_32x32x16_bf16 v[2:17], v[156:159], v[112:115], 0
	global_load_dwordx4 v[156:159], v[108:109], off offset:-1024
	s_waitcnt vmcnt(11)
	v_mfma_f32_32x32x16_bf16 v[50:65], v[160:163], v[116:119], v[50:65]
	global_load_dwordx4 v[160:163], v[102:103], off
	s_waitcnt vmcnt(11)
	v_mfma_f32_32x32x16_bf16 v[34:49], v[164:167], v[116:119], v[34:49]
	global_load_dwordx4 v[164:167], v[104:105], off
	s_waitcnt vmcnt(11)
	v_mfma_f32_32x32x16_bf16 v[18:33], v[168:171], v[116:119], v[18:33]
	global_load_dwordx4 v[168:171], v[106:107], off
	s_waitcnt vmcnt(11)
	v_mfma_f32_32x32x16_bf16 v[2:17], v[172:175], v[116:119], v[2:17]
	global_load_dwordx4 v[172:175], v[108:109], off
	s_waitcnt vmcnt(11)
	v_mfma_f32_32x32x16_bf16 v[50:65], v[176:179], v[120:123], v[50:65]
	global_load_dwordx4 v[176:179], v[102:103], off offset:1024
	s_waitcnt vmcnt(11)
	v_mfma_f32_32x32x16_bf16 v[34:49], v[180:183], v[120:123], v[34:49]
	global_load_dwordx4 v[180:183], v[104:105], off offset:1024
	s_waitcnt vmcnt(11)
	v_mfma_f32_32x32x16_bf16 v[18:33], v[184:187], v[120:123], v[18:33]
	global_load_dwordx4 v[184:187], v[106:107], off offset:1024
	s_waitcnt vmcnt(11)
	v_mfma_f32_32x32x16_bf16 v[2:17], v[188:191], v[120:123], v[2:17]
	global_load_dwordx4 v[188:191], v[108:109], off offset:1024
	s_waitcnt vmcnt(11)
	v_mfma_f32_32x32x16_bf16 v[50:65], v[144:147], v[124:127], v[50:65]
	global_load_dwordx4 v[144:147], v[102:103], off offset:2048
	s_waitcnt vmcnt(11)
	v_mfma_f32_32x32x16_bf16 v[34:49], v[148:151], v[124:127], v[34:49]
	global_load_dwordx4 v[148:151], v[104:105], off offset:2048
	s_waitcnt vmcnt(11)
	v_mfma_f32_32x32x16_bf16 v[18:33], v[152:155], v[124:127], v[18:33]
	global_load_dwordx4 v[152:155], v[106:107], off offset:2048
	s_waitcnt vmcnt(11)
	v_mfma_f32_32x32x16_bf16 v[2:17], v[156:159], v[124:127], v[2:17]
	global_load_dwordx4 v[156:159], v[108:109], off offset:2048
	s_waitcnt vmcnt(11)
	v_mfma_f32_32x32x16_bf16 v[50:65], v[160:163], v[128:131], v[50:65]
	global_load_dwordx4 v[160:163], v[102:103], off offset:3072
	s_waitcnt vmcnt(11)
	v_mfma_f32_32x32x16_bf16 v[34:49], v[164:167], v[128:131], v[34:49]
	global_load_dwordx4 v[164:167], v[104:105], off offset:3072
	s_waitcnt vmcnt(11)
	v_mfma_f32_32x32x16_bf16 v[18:33], v[168:171], v[128:131], v[18:33]
	global_load_dwordx4 v[168:171], v[106:107], off offset:3072
	s_waitcnt vmcnt(11)
	v_mfma_f32_32x32x16_bf16 v[2:17], v[172:175], v[128:131], v[2:17]
	global_load_dwordx4 v[172:175], v[108:109], off offset:3072
	s_waitcnt vmcnt(11)
	v_mfma_f32_32x32x16_bf16 v[50:65], v[176:179], v[132:135], v[50:65]
	s_waitcnt vmcnt(10)
	v_mfma_f32_32x32x16_bf16 v[34:49], v[180:183], v[132:135], v[34:49]
	s_waitcnt vmcnt(9)
	v_mfma_f32_32x32x16_bf16 v[18:33], v[184:187], v[132:135], v[18:33]
	s_waitcnt vmcnt(8)
	v_mfma_f32_32x32x16_bf16 v[2:17], v[188:191], v[132:135], v[2:17]
	s_waitcnt vmcnt(7)
	v_mfma_f32_32x32x16_bf16 v[50:65], v[144:147], v[136:139], v[50:65]
	s_waitcnt vmcnt(6)
	v_mfma_f32_32x32x16_bf16 v[34:49], v[148:151], v[136:139], v[34:49]
	s_waitcnt vmcnt(5)
	v_mfma_f32_32x32x16_bf16 v[18:33], v[152:155], v[136:139], v[18:33]
	s_waitcnt vmcnt(4)
	v_mfma_f32_32x32x16_bf16 v[2:17], v[156:159], v[136:139], v[2:17]
	s_waitcnt vmcnt(3)
	v_mfma_f32_32x32x16_bf16 v[50:65], v[160:163], v[140:143], v[50:65]
	s_waitcnt vmcnt(2)
	v_mfma_f32_32x32x16_bf16 v[34:49], v[164:167], v[140:143], v[34:49]
	s_waitcnt vmcnt(1)
	v_mfma_f32_32x32x16_bf16 v[18:33], v[168:171], v[140:143], v[18:33]
	s_waitcnt vmcnt(0)
	v_mfma_f32_32x32x16_bf16 v[2:17], v[172:175], v[140:143], v[2:17]
	s_movk_i32 s11, 0x1000
	v_lshl_or_b32 v70, v87, 2, v86
	v_lshlrev_b64 v[86:87], 16, v[70:71]
	v_lshl_add_u64 v[86:87], s[68:69], 0, v[86:87]
	v_lshl_or_b32 v70, v67, 8, v85
	v_lshl_add_u64 v[192:193], v[86:87], 0, v[70:71]
	s_mov_b64 vcc, 0x1000
	v_lshl_add_u64 v[194:195], v[192:193], 0, vcc
	s_nop 7
	s_nop 7
	v_cvt_pk_bf16_f32 v196, v50, v51
	v_cvt_pk_bf16_f32 v197, v52, v53
	global_store_dwordx2 v[192:193], v[196:197], off
	v_cvt_pk_bf16_f32 v198, v54, v55
	v_cvt_pk_bf16_f32 v199, v56, v57
	global_store_dwordx2 v[192:193], v[198:199], off offset:512
	v_cvt_pk_bf16_f32 v200, v58, v59
	v_cvt_pk_bf16_f32 v201, v60, v61
	global_store_dwordx2 v[192:193], v[200:201], off offset:1024
	v_cvt_pk_bf16_f32 v202, v62, v63
	v_cvt_pk_bf16_f32 v203, v64, v65
	global_store_dwordx2 v[192:193], v[202:203], off offset:1536
	v_cvt_pk_bf16_f32 v196, v34, v35
	v_cvt_pk_bf16_f32 v197, v36, v37
	global_store_dwordx2 v[192:193], v[196:197], off offset:2048
	v_cvt_pk_bf16_f32 v198, v38, v39
	v_cvt_pk_bf16_f32 v199, v40, v41
	global_store_dwordx2 v[192:193], v[198:199], off offset:2560
	v_cvt_pk_bf16_f32 v200, v42, v43
	v_cvt_pk_bf16_f32 v201, v44, v45
	global_store_dwordx2 v[192:193], v[200:201], off offset:3072
	v_cvt_pk_bf16_f32 v202, v46, v47
	v_cvt_pk_bf16_f32 v203, v48, v49
	global_store_dwordx2 v[192:193], v[202:203], off offset:3584
	v_cvt_pk_bf16_f32 v196, v18, v19
	v_cvt_pk_bf16_f32 v197, v20, v21
	global_store_dwordx2 v[194:195], v[196:197], off
	v_cvt_pk_bf16_f32 v198, v22, v23
	v_cvt_pk_bf16_f32 v199, v24, v25
	global_store_dwordx2 v[194:195], v[198:199], off offset:512
	v_cvt_pk_bf16_f32 v200, v26, v27
	v_cvt_pk_bf16_f32 v201, v28, v29
	global_store_dwordx2 v[194:195], v[200:201], off offset:1024
	v_cvt_pk_bf16_f32 v202, v30, v31
	v_cvt_pk_bf16_f32 v203, v32, v33
	global_store_dwordx2 v[194:195], v[202:203], off offset:1536
	v_cvt_pk_bf16_f32 v196, v2, v3
	v_cvt_pk_bf16_f32 v197, v4, v5
	global_store_dwordx2 v[194:195], v[196:197], off offset:2048
	v_cvt_pk_bf16_f32 v198, v6, v7
	v_cvt_pk_bf16_f32 v199, v8, v9
	global_store_dwordx2 v[194:195], v[198:199], off offset:2560
	v_cvt_pk_bf16_f32 v200, v10, v11
	v_cvt_pk_bf16_f32 v201, v12, v13
	global_store_dwordx2 v[194:195], v[200:201], off offset:3072
	v_cvt_pk_bf16_f32 v202, v14, v15
	v_cvt_pk_bf16_f32 v203, v16, v17
	global_store_dwordx2 v[194:195], v[202:203], off offset:3584
	s_nop 0
	s_nop 0
	s_nop 0
	s_nop 0
	s_nop 0
	s_nop 0
	s_nop 0
	s_nop 0
.LBB0_782:
	s_andn2_saveexec_b64 s[6:7], s[6:7]
	s_cbranch_execz .LBB0_779
	v_and_b32_e32 v4, 15, v66
	v_lshlrev_b32_e32 v2, 10, v66
	v_and_b32_e32 v54, 0xffffff80, v84
	v_and_or_b32 v70, v2, s10, v69
	v_lshlrev_b32_e32 v2, 16, v4
	v_mov_b32_e32 v3, v71
	v_lshl_add_u64 v[34:35], s[2:3], 0, v[2:3]
	v_ashrrev_i32_e32 v2, 4, v54
	v_ashrrev_i32_e32 v3, 31, v2
	v_lshlrev_b64 v[30:31], 1, v[2:3]
	v_lshl_add_u64 v[2:3], v[30:31], 0, v[70:71]
	v_or_b32_e32 v36, v54, v76
	v_lshlrev_b64 v[2:3], 9, v[2:3]
	v_lshlrev_b32_e32 v46, 12, v4
	v_lshl_add_u64 v[2:3], v[78:79], 0, v[2:3]
	v_ashrrev_i32_e32 v37, 31, v36
	v_mov_b32_e32 v47, v71
	global_load_dwordx4 v[18:21], v[2:3], off
	v_lshl_add_u64 v[2:3], v[36:37], 2, v[34:35]
	v_or_b32_e32 v30, v30, v68
	v_or_b32_e32 v48, 0x800, v46
	v_mov_b32_e32 v49, v71
	global_load_dwordx4 v[22:25], v[2:3], off offset:16
	global_load_dwordx4 v[26:29], v[2:3], off
	v_lshl_add_u64 v[2:3], v[30:31], 0, v[46:47]
	v_lshl_add_u64 v[30:31], v[30:31], 0, v[48:49]
	v_lshlrev_b64 v[2:3], 9, v[2:3]
	v_lshlrev_b64 v[30:31], 9, v[30:31]
	v_lshl_add_u64 v[2:3], v[80:81], 0, v[2:3]
	v_lshl_add_u64 v[30:31], v[80:81], 0, v[30:31]
	global_load_dwordx4 v[2:5], v[2:3], off
	v_or_b32_e32 v37, 16, v54
	global_load_dwordx4 v[30:33], v[30:31], off
	v_ashrrev_i32_e32 v67, 31, v66
	s_waitcnt vmcnt(1)
	v_lshlrev_b32_e32 v6, 16, v2
	v_and_b32_e32 v7, 0xffff0000, v2
	s_waitcnt vmcnt(0)
	v_lshlrev_b32_e32 v38, 16, v30
	v_and_b32_e32 v39, 0xffff0000, v30
	v_pk_mul_f32 v[6:7], v[26:27], v[6:7]
	v_pk_mul_f32 v[26:27], v[26:27], v[38:39]
	v_ashrrev_i32_e32 v38, 4, v37
	v_ashrrev_i32_e32 v39, 31, v38
	v_lshlrev_b64 v[52:53], 1, v[38:39]
	v_lshl_add_u64 v[38:39], v[52:53], 0, v[70:71]
	v_or_b32_e32 v52, v52, v68
	v_lshl_add_u64 v[56:57], v[52:53], 0, v[46:47]
	v_lshlrev_b64 v[38:39], 9, v[38:39]
	v_ashrrev_i32_e32 v37, 31, v54
	v_lshlrev_b64 v[56:57], 9, v[56:57]
	v_lshl_add_u64 v[38:39], v[78:79], 0, v[38:39]
	v_lshl_add_u64 v[50:51], v[36:37], 2, v[34:35]
	v_lshl_add_u64 v[56:57], v[80:81], 0, v[56:57]
	global_load_dwordx4 v[38:41], v[38:39], off
	s_nop 0
	global_load_dwordx4 v[34:37], v[50:51], off offset:80
	global_load_dwordx4 v[42:45], v[50:51], off offset:64
	v_cvt_pk_bf16_f32 v2, v6, v7
	global_load_dwordx4 v[56:59], v[56:57], off
	v_lshlrev_b32_e32 v6, 16, v3
	v_and_b32_e32 v7, 0xffff0000, v3
	v_pk_mul_f32 v[6:7], v[28:29], v[6:7]
	v_lshl_add_u64 v[52:53], v[52:53], 0, v[48:49]
	v_cvt_pk_bf16_f32 v3, v6, v7
	v_lshlrev_b32_e32 v6, 16, v4
	v_and_b32_e32 v7, 0xffff0000, v4
	v_pk_mul_f32 v[6:7], v[22:23], v[6:7]
	v_lshlrev_b64 v[52:53], 9, v[52:53]
	v_cvt_pk_bf16_f32 v4, v6, v7
	v_lshlrev_b32_e32 v6, 16, v5
	v_and_b32_e32 v7, 0xffff0000, v5
	v_pk_mul_f32 v[6:7], v[24:25], v[6:7]
	v_lshl_add_u64 v[52:53], v[80:81], 0, v[52:53]
	v_cvt_pk_bf16_f32 v5, v6, v7
	v_lshlrev_b32_e32 v30, 16, v31
	v_and_b32_e32 v31, 0xffff0000, v31
	v_mfma_f32_32x32x16_bf16 v[2:17], v[18:21], v[2:5], 0
	v_mul_f32_e64 v28, v28, v30
	v_mul_f32_e64 v29, v29, v31
	v_cvt_pk_bf16_f32 v26, v26, v27
	v_cvt_pk_bf16_f32 v27, v28, v29
	v_lshlrev_b32_e32 v28, 16, v32
	v_and_b32_e32 v29, 0xffff0000, v32
	v_pk_mul_f32 v[22:23], v[22:23], v[28:29]
	s_waitcnt vmcnt(0)
	v_lshlrev_b32_e32 v60, 16, v56
	v_and_b32_e32 v61, 0xffff0000, v56
	v_pk_mul_f32 v[60:61], v[42:43], v[60:61]
	v_cvt_pk_bf16_f32 v28, v22, v23
	v_cvt_pk_bf16_f32 v56, v60, v61
	v_lshlrev_b32_e32 v60, 16, v57
	v_and_b32_e32 v61, 0xffff0000, v57
	v_pk_mul_f32 v[60:61], v[44:45], v[60:61]
	v_lshlrev_b32_e32 v22, 16, v33
	v_cvt_pk_bf16_f32 v57, v60, v61
	v_lshlrev_b32_e32 v60, 16, v58
	v_and_b32_e32 v61, 0xffff0000, v58
	v_pk_mul_f32 v[60:61], v[34:35], v[60:61]
	v_and_b32_e32 v23, 0xffff0000, v33
	v_cvt_pk_bf16_f32 v58, v60, v61
	v_lshlrev_b32_e32 v60, 16, v59
	v_and_b32_e32 v61, 0xffff0000, v59
	v_pk_mul_f32 v[60:61], v[36:37], v[60:61]
	v_pk_mul_f32 v[22:23], v[24:25], v[22:23]
	v_cvt_pk_bf16_f32 v59, v60, v61
	v_cvt_pk_bf16_f32 v29, v22, v23
	s_nop 0
	v_mfma_f32_32x32x16_bf16 v[2:17], v[38:41], v[56:59], v[2:17]
	global_load_dwordx4 v[56:59], v[52:53], off
	s_waitcnt vmcnt(0)
	v_lshlrev_b32_e32 v52, 16, v56
	v_and_b32_e32 v53, 0xffff0000, v56
	v_mul_f32_e64 v42, v42, v52
	v_mul_f32_e64 v43, v43, v53
	v_lshlrev_b32_e32 v52, 16, v57
	v_and_b32_e32 v53, 0xffff0000, v57
	v_pk_mul_f32 v[44:45], v[44:45], v[52:53]
	v_cvt_pk_bf16_f32 v42, v42, v43
	v_cvt_pk_bf16_f32 v43, v44, v45
	v_lshlrev_b32_e32 v44, 16, v58
	v_and_b32_e32 v45, 0xffff0000, v58
	v_pk_mul_f32 v[34:35], v[34:35], v[44:45]
	v_mfma_f32_32x32x16_bf16 v[18:33], v[18:21], v[26:29], 0
	v_cvt_pk_bf16_f32 v44, v34, v35
	v_lshlrev_b32_e32 v34, 16, v59
	v_and_b32_e32 v35, 0xffff0000, v59
	v_mul_f32_e64 v34, v36, v34
	v_mul_f32_e64 v35, v37, v35
	v_cvt_pk_bf16_f32 v45, v34, v35
	v_or_b32_e32 v34, 32, v54
	v_ashrrev_i32_e32 v34, 4, v34
	v_ashrrev_i32_e32 v35, 31, v34
	v_lshlrev_b64 v[52:53], 1, v[34:35]
	v_lshl_add_u64 v[34:35], v[52:53], 0, v[70:71]
	v_or_b32_e32 v52, v52, v68
	v_lshl_add_u64 v[56:57], v[52:53], 0, v[46:47]
	v_lshlrev_b64 v[34:35], 9, v[34:35]
	v_lshlrev_b64 v[56:57], 9, v[56:57]
	v_lshl_add_u64 v[34:35], v[78:79], 0, v[34:35]
	v_lshl_add_u64 v[56:57], v[80:81], 0, v[56:57]
	v_mfma_f32_32x32x16_bf16 v[18:33], v[38:41], v[42:45], v[18:33]
	global_load_dwordx4 v[34:37], v[34:35], off
	s_nop 0
	global_load_dwordx4 v[38:41], v[50:51], off offset:144
	global_load_dwordx4 v[42:45], v[50:51], off offset:128
	v_lshl_add_u64 v[52:53], v[52:53], 0, v[48:49]
	global_load_dwordx4 v[56:59], v[56:57], off
	v_lshlrev_b64 v[52:53], 9, v[52:53]
	v_lshl_add_u64 v[52:53], v[80:81], 0, v[52:53]
	s_waitcnt vmcnt(0)
	v_lshlrev_b32_e32 v60, 16, v56
	v_and_b32_e32 v61, 0xffff0000, v56
	v_pk_mul_f32 v[60:61], v[42:43], v[60:61]
	s_nop 0
	v_cvt_pk_bf16_f32 v56, v60, v61
	v_lshlrev_b32_e32 v60, 16, v57
	v_and_b32_e32 v61, 0xffff0000, v57
	v_pk_mul_f32 v[60:61], v[44:45], v[60:61]
	s_nop 0
	v_cvt_pk_bf16_f32 v57, v60, v61
	v_lshlrev_b32_e32 v60, 16, v58
	v_and_b32_e32 v61, 0xffff0000, v58
	v_pk_mul_f32 v[60:61], v[38:39], v[60:61]
	s_nop 0
	v_cvt_pk_bf16_f32 v58, v60, v61
	v_lshlrev_b32_e32 v60, 16, v59
	v_and_b32_e32 v61, 0xffff0000, v59
	v_pk_mul_f32 v[60:61], v[40:41], v[60:61]
	s_nop 0
	v_cvt_pk_bf16_f32 v59, v60, v61
	s_nop 1
	v_mfma_f32_32x32x16_bf16 v[2:17], v[34:37], v[56:59], v[2:17]
	global_load_dwordx4 v[56:59], v[52:53], off
	s_waitcnt vmcnt(0)
	v_lshlrev_b32_e32 v52, 16, v56
	v_and_b32_e32 v53, 0xffff0000, v56
	v_mul_f32_e64 v42, v42, v52
	v_mul_f32_e64 v43, v43, v53
	v_lshlrev_b32_e32 v52, 16, v57
	v_and_b32_e32 v53, 0xffff0000, v57
	v_pk_mul_f32 v[44:45], v[44:45], v[52:53]
	v_cvt_pk_bf16_f32 v42, v42, v43
	v_cvt_pk_bf16_f32 v43, v44, v45
	v_lshlrev_b32_e32 v44, 16, v58
	v_and_b32_e32 v45, 0xffff0000, v58
	v_pk_mul_f32 v[38:39], v[38:39], v[44:45]
	s_nop 0
	v_cvt_pk_bf16_f32 v44, v38, v39
	v_lshlrev_b32_e32 v38, 16, v59
	v_and_b32_e32 v39, 0xffff0000, v59
	v_pk_mul_f32 v[38:39], v[40:41], v[38:39]
	s_nop 0
	v_cvt_pk_bf16_f32 v45, v38, v39
	s_nop 1
	v_mfma_f32_32x32x16_bf16 v[18:33], v[34:37], v[42:45], v[18:33]
	v_or_b32_e32 v34, 48, v54
	v_ashrrev_i32_e32 v34, 4, v34
	v_ashrrev_i32_e32 v35, 31, v34
	v_lshlrev_b64 v[52:53], 1, v[34:35]
	v_lshl_add_u64 v[34:35], v[52:53], 0, v[70:71]
	v_or_b32_e32 v52, v52, v68
	v_lshl_add_u64 v[56:57], v[52:53], 0, v[46:47]
	v_lshlrev_b64 v[34:35], 9, v[34:35]
	v_lshlrev_b64 v[56:57], 9, v[56:57]
	v_lshl_add_u64 v[34:35], v[78:79], 0, v[34:35]
	v_lshl_add_u64 v[56:57], v[80:81], 0, v[56:57]
	global_load_dwordx4 v[34:37], v[34:35], off
	s_nop 0
	global_load_dwordx4 v[38:41], v[50:51], off offset:208
	global_load_dwordx4 v[42:45], v[50:51], off offset:192
	v_lshl_add_u64 v[52:53], v[52:53], 0, v[48:49]
	global_load_dwordx4 v[56:59], v[56:57], off
	v_lshlrev_b64 v[52:53], 9, v[52:53]
	v_lshl_add_u64 v[52:53], v[80:81], 0, v[52:53]
	s_waitcnt vmcnt(0)
	v_lshlrev_b32_e32 v60, 16, v56
	v_and_b32_e32 v61, 0xffff0000, v56
	v_pk_mul_f32 v[60:61], v[42:43], v[60:61]
	s_nop 0
	v_cvt_pk_bf16_f32 v56, v60, v61
	v_lshlrev_b32_e32 v60, 16, v57
	v_and_b32_e32 v61, 0xffff0000, v57
	v_pk_mul_f32 v[60:61], v[44:45], v[60:61]
	s_nop 0
	v_cvt_pk_bf16_f32 v57, v60, v61
	v_lshlrev_b32_e32 v60, 16, v58
	v_and_b32_e32 v61, 0xffff0000, v58
	v_pk_mul_f32 v[60:61], v[38:39], v[60:61]
	s_nop 0
	v_cvt_pk_bf16_f32 v58, v60, v61
	v_lshlrev_b32_e32 v60, 16, v59
	v_and_b32_e32 v61, 0xffff0000, v59
	v_pk_mul_f32 v[60:61], v[40:41], v[60:61]
	s_nop 0
	v_cvt_pk_bf16_f32 v59, v60, v61
	s_nop 1
	v_mfma_f32_32x32x16_bf16 v[2:17], v[34:37], v[56:59], v[2:17]
	global_load_dwordx4 v[56:59], v[52:53], off
	s_waitcnt vmcnt(0)
	v_lshlrev_b32_e32 v52, 16, v56
	v_and_b32_e32 v53, 0xffff0000, v56
	v_mul_f32_e64 v42, v42, v52
	v_mul_f32_e64 v43, v43, v53
	v_lshlrev_b32_e32 v52, 16, v57
	v_and_b32_e32 v53, 0xffff0000, v57
	v_pk_mul_f32 v[44:45], v[44:45], v[52:53]
	v_cvt_pk_bf16_f32 v42, v42, v43
	v_cvt_pk_bf16_f32 v43, v44, v45
	v_lshlrev_b32_e32 v44, 16, v58
	v_and_b32_e32 v45, 0xffff0000, v58
	v_pk_mul_f32 v[38:39], v[38:39], v[44:45]
	s_nop 0
	v_cvt_pk_bf16_f32 v44, v38, v39
	v_lshlrev_b32_e32 v38, 16, v59
	v_and_b32_e32 v39, 0xffff0000, v59
	v_pk_mul_f32 v[38:39], v[40:41], v[38:39]
	s_nop 0
	v_cvt_pk_bf16_f32 v45, v38, v39
	s_nop 1
	v_mfma_f32_32x32x16_bf16 v[18:33], v[34:37], v[42:45], v[18:33]
	v_or_b32_e32 v34, 64, v54
	v_ashrrev_i32_e32 v34, 4, v34
	v_ashrrev_i32_e32 v35, 31, v34
	v_lshlrev_b64 v[52:53], 1, v[34:35]
	v_lshl_add_u64 v[34:35], v[52:53], 0, v[70:71]
	v_or_b32_e32 v52, v52, v68
	v_lshl_add_u64 v[56:57], v[52:53], 0, v[46:47]
	v_lshlrev_b64 v[34:35], 9, v[34:35]
	v_lshlrev_b64 v[56:57], 9, v[56:57]
	v_lshl_add_u64 v[34:35], v[78:79], 0, v[34:35]
	v_lshl_add_u64 v[56:57], v[80:81], 0, v[56:57]
	global_load_dwordx4 v[34:37], v[34:35], off
	s_nop 0
	global_load_dwordx4 v[38:41], v[50:51], off offset:272
	global_load_dwordx4 v[42:45], v[50:51], off offset:256
	v_lshl_add_u64 v[52:53], v[52:53], 0, v[48:49]
	global_load_dwordx4 v[56:59], v[56:57], off
	v_lshlrev_b64 v[52:53], 9, v[52:53]
	v_lshl_add_u64 v[52:53], v[80:81], 0, v[52:53]
	s_waitcnt vmcnt(0)
	v_lshlrev_b32_e32 v60, 16, v56
	v_and_b32_e32 v61, 0xffff0000, v56
	v_pk_mul_f32 v[60:61], v[42:43], v[60:61]
	s_nop 0
	v_cvt_pk_bf16_f32 v56, v60, v61
	v_lshlrev_b32_e32 v60, 16, v57
	v_and_b32_e32 v61, 0xffff0000, v57
	v_pk_mul_f32 v[60:61], v[44:45], v[60:61]
	s_nop 0
	v_cvt_pk_bf16_f32 v57, v60, v61
	v_lshlrev_b32_e32 v60, 16, v58
	v_and_b32_e32 v61, 0xffff0000, v58
	v_pk_mul_f32 v[60:61], v[38:39], v[60:61]
	s_nop 0
	v_cvt_pk_bf16_f32 v58, v60, v61
	v_lshlrev_b32_e32 v60, 16, v59
	v_and_b32_e32 v61, 0xffff0000, v59
	v_pk_mul_f32 v[60:61], v[40:41], v[60:61]
	s_nop 0
	v_cvt_pk_bf16_f32 v59, v60, v61
	s_nop 1
	v_mfma_f32_32x32x16_bf16 v[2:17], v[34:37], v[56:59], v[2:17]
	global_load_dwordx4 v[56:59], v[52:53], off
	s_waitcnt vmcnt(0)
	v_lshlrev_b32_e32 v52, 16, v56
	v_and_b32_e32 v53, 0xffff0000, v56
	v_mul_f32_e64 v42, v42, v52
	v_mul_f32_e64 v43, v43, v53
	v_lshlrev_b32_e32 v52, 16, v57
	v_and_b32_e32 v53, 0xffff0000, v57
	v_pk_mul_f32 v[44:45], v[44:45], v[52:53]
	v_cvt_pk_bf16_f32 v42, v42, v43
	v_cvt_pk_bf16_f32 v43, v44, v45
	v_lshlrev_b32_e32 v44, 16, v58
	v_and_b32_e32 v45, 0xffff0000, v58
	v_pk_mul_f32 v[38:39], v[38:39], v[44:45]
	s_nop 0
	v_cvt_pk_bf16_f32 v44, v38, v39
	v_lshlrev_b32_e32 v38, 16, v59
	v_and_b32_e32 v39, 0xffff0000, v59
	v_pk_mul_f32 v[38:39], v[40:41], v[38:39]
	s_nop 0
	v_cvt_pk_bf16_f32 v45, v38, v39
	s_nop 1
	v_mfma_f32_32x32x16_bf16 v[18:33], v[34:37], v[42:45], v[18:33]
	v_or_b32_e32 v34, 0x50, v54
	v_ashrrev_i32_e32 v34, 4, v34
	v_ashrrev_i32_e32 v35, 31, v34
	v_lshlrev_b64 v[52:53], 1, v[34:35]
	v_lshl_add_u64 v[34:35], v[52:53], 0, v[70:71]
	v_or_b32_e32 v52, v52, v68
	v_lshl_add_u64 v[56:57], v[52:53], 0, v[46:47]
	v_lshlrev_b64 v[34:35], 9, v[34:35]
	v_lshlrev_b64 v[56:57], 9, v[56:57]
	v_lshl_add_u64 v[34:35], v[78:79], 0, v[34:35]
	v_lshl_add_u64 v[56:57], v[80:81], 0, v[56:57]
	global_load_dwordx4 v[34:37], v[34:35], off
	s_nop 0
	global_load_dwordx4 v[38:41], v[50:51], off offset:336
	global_load_dwordx4 v[42:45], v[50:51], off offset:320
	v_lshl_add_u64 v[52:53], v[52:53], 0, v[48:49]
	global_load_dwordx4 v[56:59], v[56:57], off
	v_lshlrev_b64 v[52:53], 9, v[52:53]
	v_lshl_add_u64 v[52:53], v[80:81], 0, v[52:53]
	s_waitcnt vmcnt(0)
	v_lshlrev_b32_e32 v60, 16, v56
	v_and_b32_e32 v61, 0xffff0000, v56
	v_pk_mul_f32 v[60:61], v[42:43], v[60:61]
	s_nop 0
	v_cvt_pk_bf16_f32 v56, v60, v61
	v_lshlrev_b32_e32 v60, 16, v57
	v_and_b32_e32 v61, 0xffff0000, v57
	v_pk_mul_f32 v[60:61], v[44:45], v[60:61]
	s_nop 0
	v_cvt_pk_bf16_f32 v57, v60, v61
	v_lshlrev_b32_e32 v60, 16, v58
	v_and_b32_e32 v61, 0xffff0000, v58
	v_pk_mul_f32 v[60:61], v[38:39], v[60:61]
	s_nop 0
	v_cvt_pk_bf16_f32 v58, v60, v61
	v_lshlrev_b32_e32 v60, 16, v59
	v_and_b32_e32 v61, 0xffff0000, v59
	v_pk_mul_f32 v[60:61], v[40:41], v[60:61]
	s_nop 0
	v_cvt_pk_bf16_f32 v59, v60, v61
	s_nop 1
	v_mfma_f32_32x32x16_bf16 v[2:17], v[34:37], v[56:59], v[2:17]
	global_load_dwordx4 v[56:59], v[52:53], off
	s_waitcnt vmcnt(0)
	v_lshlrev_b32_e32 v52, 16, v56
	v_and_b32_e32 v53, 0xffff0000, v56
	v_mul_f32_e64 v42, v42, v52
	v_mul_f32_e64 v43, v43, v53
	v_lshlrev_b32_e32 v52, 16, v57
	v_and_b32_e32 v53, 0xffff0000, v57
	v_pk_mul_f32 v[44:45], v[44:45], v[52:53]
	v_cvt_pk_bf16_f32 v42, v42, v43
	v_cvt_pk_bf16_f32 v43, v44, v45
	v_lshlrev_b32_e32 v44, 16, v58
	v_and_b32_e32 v45, 0xffff0000, v58
	v_pk_mul_f32 v[38:39], v[38:39], v[44:45]
	s_nop 0
	v_cvt_pk_bf16_f32 v44, v38, v39
	v_lshlrev_b32_e32 v38, 16, v59
	v_and_b32_e32 v39, 0xffff0000, v59
	v_pk_mul_f32 v[38:39], v[40:41], v[38:39]
	s_nop 0
	v_cvt_pk_bf16_f32 v45, v38, v39
	s_nop 1
	v_mfma_f32_32x32x16_bf16 v[18:33], v[34:37], v[42:45], v[18:33]
	v_or_b32_e32 v34, 0x60, v54
	v_ashrrev_i32_e32 v34, 4, v34
	v_ashrrev_i32_e32 v35, 31, v34
	v_lshlrev_b64 v[52:53], 1, v[34:35]
	v_lshl_add_u64 v[34:35], v[52:53], 0, v[70:71]
	v_or_b32_e32 v52, v52, v68
	v_lshl_add_u64 v[56:57], v[52:53], 0, v[46:47]
	v_lshlrev_b64 v[34:35], 9, v[34:35]
	v_lshlrev_b64 v[56:57], 9, v[56:57]
	v_lshl_add_u64 v[34:35], v[78:79], 0, v[34:35]
	v_lshl_add_u64 v[56:57], v[80:81], 0, v[56:57]
	global_load_dwordx4 v[34:37], v[34:35], off
	s_nop 0
	global_load_dwordx4 v[38:41], v[50:51], off offset:400
	global_load_dwordx4 v[42:45], v[50:51], off offset:384
	v_lshl_add_u64 v[52:53], v[52:53], 0, v[48:49]
	global_load_dwordx4 v[56:59], v[56:57], off
	v_lshlrev_b64 v[52:53], 9, v[52:53]
	v_lshl_add_u64 v[52:53], v[80:81], 0, v[52:53]
	s_waitcnt vmcnt(0)
	v_lshlrev_b32_e32 v60, 16, v56
	v_and_b32_e32 v61, 0xffff0000, v56
	v_pk_mul_f32 v[60:61], v[42:43], v[60:61]
	s_nop 0
	v_cvt_pk_bf16_f32 v56, v60, v61
	v_lshlrev_b32_e32 v60, 16, v57
	v_and_b32_e32 v61, 0xffff0000, v57
	v_pk_mul_f32 v[60:61], v[44:45], v[60:61]
	s_nop 0
	v_cvt_pk_bf16_f32 v57, v60, v61
	v_lshlrev_b32_e32 v60, 16, v58
	v_and_b32_e32 v61, 0xffff0000, v58
	v_pk_mul_f32 v[60:61], v[38:39], v[60:61]
	s_nop 0
	v_cvt_pk_bf16_f32 v58, v60, v61
	v_lshlrev_b32_e32 v60, 16, v59
	v_and_b32_e32 v61, 0xffff0000, v59
	v_pk_mul_f32 v[60:61], v[40:41], v[60:61]
	s_nop 0
	v_cvt_pk_bf16_f32 v59, v60, v61
	s_nop 1
	v_mfma_f32_32x32x16_bf16 v[2:17], v[34:37], v[56:59], v[2:17]
	global_load_dwordx4 v[56:59], v[52:53], off
	s_waitcnt vmcnt(0)
	v_lshlrev_b32_e32 v52, 16, v56
	v_and_b32_e32 v53, 0xffff0000, v56
	v_mul_f32_e64 v42, v42, v52
	v_mul_f32_e64 v43, v43, v53
	v_lshlrev_b32_e32 v52, 16, v57
	v_and_b32_e32 v53, 0xffff0000, v57
	v_pk_mul_f32 v[44:45], v[44:45], v[52:53]
	v_cvt_pk_bf16_f32 v42, v42, v43
	v_cvt_pk_bf16_f32 v43, v44, v45
	v_lshlrev_b32_e32 v44, 16, v58
	v_and_b32_e32 v45, 0xffff0000, v58
	v_pk_mul_f32 v[38:39], v[38:39], v[44:45]
	s_nop 0
	v_cvt_pk_bf16_f32 v44, v38, v39
	v_lshlrev_b32_e32 v38, 16, v59
	v_and_b32_e32 v39, 0xffff0000, v59
	v_pk_mul_f32 v[38:39], v[40:41], v[38:39]
	s_nop 0
	v_cvt_pk_bf16_f32 v45, v38, v39
	s_nop 1
	v_mfma_f32_32x32x16_bf16 v[18:33], v[34:37], v[42:45], v[18:33]
	v_or_b32_e32 v34, 0x70, v54
	v_ashrrev_i32_e32 v34, 4, v34
	v_ashrrev_i32_e32 v35, 31, v34
	v_lshlrev_b64 v[54:55], 1, v[34:35]
	v_lshl_add_u64 v[34:35], v[54:55], 0, v[70:71]
	v_or_b32_e32 v54, v54, v68
	v_lshl_add_u64 v[46:47], v[54:55], 0, v[46:47]
	v_lshlrev_b64 v[34:35], 9, v[34:35]
	v_lshlrev_b64 v[46:47], 9, v[46:47]
	v_lshl_add_u64 v[34:35], v[78:79], 0, v[34:35]
	v_lshl_add_u64 v[46:47], v[80:81], 0, v[46:47]
	global_load_dwordx4 v[34:37], v[34:35], off
	s_nop 0
	global_load_dwordx4 v[38:41], v[50:51], off offset:464
	global_load_dwordx4 v[42:45], v[50:51], off offset:448
	s_nop 0
	global_load_dwordx4 v[50:53], v[46:47], off
	s_waitcnt vmcnt(0)
	v_lshlrev_b32_e32 v46, 16, v50
	v_and_b32_e32 v47, 0xffff0000, v50
	v_pk_mul_f32 v[46:47], v[42:43], v[46:47]
	s_nop 0
	v_cvt_pk_bf16_f32 v50, v46, v47
	v_lshlrev_b32_e32 v46, 16, v51
	v_and_b32_e32 v47, 0xffff0000, v51
	v_pk_mul_f32 v[46:47], v[44:45], v[46:47]
	s_nop 0
	v_cvt_pk_bf16_f32 v51, v46, v47
	v_lshlrev_b32_e32 v46, 16, v52
	v_and_b32_e32 v47, 0xffff0000, v52
	v_pk_mul_f32 v[46:47], v[38:39], v[46:47]
	s_nop 0
	v_cvt_pk_bf16_f32 v52, v46, v47
	v_lshlrev_b32_e32 v46, 16, v53
	v_and_b32_e32 v47, 0xffff0000, v53
	v_pk_mul_f32 v[46:47], v[40:41], v[46:47]
	s_nop 0
	v_cvt_pk_bf16_f32 v53, v46, v47
	v_lshl_add_u64 v[46:47], v[54:55], 0, v[48:49]
	v_lshlrev_b64 v[46:47], 9, v[46:47]
	v_lshl_add_u64 v[46:47], v[80:81], 0, v[46:47]
	global_load_dwordx4 v[46:49], v[46:47], off
	v_mfma_f32_32x32x16_bf16 v[2:17], v[34:37], v[50:53], v[2:17]
	s_waitcnt vmcnt(0)
	v_lshlrev_b32_e32 v50, 16, v46
	v_and_b32_e32 v51, 0xffff0000, v46
	v_lshlrev_b32_e32 v46, 16, v47
	v_and_b32_e32 v47, 0xffff0000, v47
	v_pk_mul_f32 v[42:43], v[42:43], v[50:51]
	v_pk_mul_f32 v[44:45], v[44:45], v[46:47]
	v_cvt_pk_bf16_f32 v42, v42, v43
	v_cvt_pk_bf16_f32 v43, v44, v45
	v_lshlrev_b32_e32 v44, 16, v48
	v_and_b32_e32 v45, 0xffff0000, v48
	v_pk_mul_f32 v[38:39], v[38:39], v[44:45]
	v_cvt_pk_bf16_f32 v2, v2, v3
	v_cvt_pk_bf16_f32 v44, v38, v39
	v_lshlrev_b32_e32 v38, 16, v49
	v_and_b32_e32 v39, 0xffff0000, v49
	v_pk_mul_f32 v[38:39], v[40:41], v[38:39]
	v_cvt_pk_bf16_f32 v3, v4, v5
	v_cvt_pk_bf16_f32 v45, v38, v39
	s_nop 1
	v_mfma_f32_32x32x16_bf16 v[18:33], v[34:37], v[42:45], v[18:33]
	v_lshlrev_b64 v[34:35], 14, v[66:67]
	v_lshl_add_u64 v[4:5], v[82:83], 0, v[34:35]
	global_store_dwordx2 v[4:5], v[2:3], off
	v_cvt_pk_bf16_f32 v2, v6, v7
	v_cvt_pk_bf16_f32 v3, v8, v9
	global_store_dwordx2 v[4:5], v[2:3], off offset:512
	v_cvt_pk_bf16_f32 v2, v10, v11
	v_cvt_pk_bf16_f32 v3, v12, v13
	global_store_dwordx2 v[4:5], v[2:3], off offset:1024
	v_cvt_pk_bf16_f32 v2, v14, v15
	v_cvt_pk_bf16_f32 v3, v16, v17
	global_store_dwordx2 v[4:5], v[2:3], off offset:1536
	v_add_co_u32_e32 v4, vcc, s10, v4
	v_cvt_pk_bf16_f32 v2, v18, v19
	v_cvt_pk_bf16_f32 v3, v20, v21
	v_addc_co_u32_e32 v5, vcc, 0, v5, vcc
	global_store_dwordx2 v[4:5], v[2:3], off
	v_cvt_pk_bf16_f32 v2, v22, v23
	v_cvt_pk_bf16_f32 v3, v24, v25
	global_store_dwordx2 v[4:5], v[2:3], off offset:512
	v_cvt_pk_bf16_f32 v2, v26, v27
	v_cvt_pk_bf16_f32 v3, v28, v29
	global_store_dwordx2 v[4:5], v[2:3], off offset:1024
	v_cvt_pk_bf16_f32 v2, v30, v31
	v_cvt_pk_bf16_f32 v3, v32, v33
	global_store_dwordx2 v[4:5], v[2:3], off offset:1536
	s_branch .LBB0_779

.LBB0_1024:
	s_ashr_i32 s37, s36, 31
	s_lshl_b64 s[0:1], s[36:37], 12
	s_add_u32 s74, s31, s0
	v_mov_b32_e32 v3, v131
	s_addc_u32 s75, s33, s1
	v_add_u32_e32 v155, s76, v142
	v_lshlrev_b64 v[2:3], 1, v[2:3]
	v_lshl_add_u64 v[16:17], s[74:75], 0, v[2:3]
	v_readfirstlane_b32 s39, v155
	v_add_u32_e32 v156, 0x2000, v155
	v_lshl_add_u64 v[16:17], v[16:17], 0, s[4:5]
	s_mov_b32 m0, s39
	v_mov_b32_e32 v5, v131
	v_readfirstlane_b32 s39, v156
	s_barrier
	global_load_lds_dwordx4 v[16:17], off
	v_lshlrev_b64 v[4:5], 1, v[4:5]
	s_mov_b32 m0, s39
	s_ashr_i32 s39, s38, 31
	v_lshl_add_u64 v[16:17], s[74:75], 0, v[4:5]
	s_lshl_b64 s[74:75], s[38:39], 11
	s_add_u32 s74, s80, s74
	v_lshl_add_u64 v[16:17], v[16:17], 0, s[4:5]
	s_addc_u32 s75, s81, s75
	v_add_u32_e32 v157, s77, v142
	global_load_lds_dwordx4 v[16:17], off
	v_lshl_add_u64 v[16:17], v[130:131], 1, s[74:75]
	v_readfirstlane_b32 s39, v157
	v_lshl_add_u64 v[16:17], v[16:17], 0, s[4:5]
	s_mov_b32 m0, s39
	v_mov_b32_e32 v133, v131
	global_load_lds_dwordx4 v[16:17], off
	v_lshlrev_b64 v[16:17], 1, v[132:133]
	v_lshl_add_u64 v[18:19], s[74:75], 0, v[16:17]
	s_or_b32 s74, s36, 0x80
	s_ashr_i32 s75, s74, 31
	s_lshl_b64 s[74:75], s[74:75], 12
	v_add_u32_e32 v158, 0x2000, v157
	s_add_u32 s74, s31, s74
	v_readfirstlane_b32 s39, v158
	s_addc_u32 s75, s33, s75
	v_add_u32_e32 v159, s78, v142
	v_lshl_add_u64 v[18:19], v[18:19], 0, s[4:5]
	s_mov_b32 m0, s39
	v_lshl_add_u64 v[2:3], s[74:75], 0, v[2:3]
	v_readfirstlane_b32 s39, v159
	global_load_lds_dwordx4 v[18:19], off
	v_lshl_add_u64 v[2:3], v[2:3], 0, s[4:5]
	s_mov_b32 m0, s39
	v_add_u32_e32 v160, 0x2000, v159
	global_load_lds_dwordx4 v[2:3], off
	v_lshl_add_u64 v[2:3], s[74:75], 0, v[4:5]
	v_readfirstlane_b32 s39, v160
	v_lshl_add_u64 v[2:3], v[2:3], 0, s[4:5]
	s_mov_b32 m0, s39
	v_and_b32_e32 v15, 15, v10
	global_load_lds_dwordx4 v[2:3], off
	v_lshlrev_b32_e32 v3, 2, v10
	v_and_b32_e32 v20, 48, v10
	v_lshlrev_b32_e32 v2, 6, v15
	v_and_b32_e32 v3, 32, v3
	v_lshlrev_b32_e32 v10, 6, v10
	v_bitop3_b32 v2, v2, v3, v20 bitop3:0x36
	v_and_b32_e32 v10, 0x3c0, v10
	v_add_u32_e32 v161, 0, v2
	v_add_u32_e32 v4, s76, v2
	v_add_u32_e32 v5, s78, v2
	v_bitop3_b32 v3, v10, v3, v20 bitop3:0x36
	v_add_u32_e32 v10, s77, v2
	v_add_u32_e32 v15, s79, v2
	v_lshrrev_b32_e32 v9, 1, v9
	v_lshlrev_b32_e32 v2, 11, v6
	v_lshl_add_u32 v2, v9, 15, v2
	v_or_b32_e32 v2, v2, v7
	v_add_u32_e32 v162, 0, v3
	v_add_u32_e32 v163, s77, v3
	v_add_u32_e32 v164, s79, v3
	v_add_u32_e32 v2, v2, v8
	v_mov_b32_e32 v3, v131
	v_lshl_add_u64 v[134:135], v[2:3], 1, s[0:1]
	v_lshlrev_b32_e32 v2, 14, v11
	v_and_b32_e32 v2, 0xffff8000, v2
	v_lshl_add_u32 v2, v12, 11, v2
	v_or_b32_e32 v2, v2, v13
	v_add_u32_e32 v2, v2, v14
	v_lshl_add_u64 v[136:137], v[2:3], 1, s[0:1]
	s_sub_i32 s1, s87, s89
	s_lshl_b32 s87, s88, 5
	s_sub_i32 s1, s1, s87
	s_sext_i32_i8 s1, s1
	s_lshl_b32 s0, s88, 11
	s_lshl_b32 s1, s1, 8
	v_lshlrev_b32_e32 v2, 10, v6
	s_add_i32 s0, s0, s1
	v_lshl_add_u32 v2, v9, 14, v2
	s_ashr_i32 s1, s0, 31
	v_or_b32_e32 v2, v2, v7
	s_waitcnt vmcnt(6)
	s_lshl_b32 s39, s45, 6
	s_lshl_b64 s[0:1], s[0:1], 11
	v_add_u32_e32 v2, v2, v8
	s_and_b32 s39, s39, 0x3000
	s_lshl_b32 s71, s71, 13
	v_lshl_add_u64 v[138:139], v[2:3], 1, s[0:1]
	s_or_b32 s74, s71, 0x800
	s_or_b32 s75, s71, 0x1000
	s_or_b32 s86, s71, 0x1800
	v_lshl_add_u64 v[140:141], s[0:1], 0, v[16:17]
	s_mov_b32 s87, -2
	v_add_u32_e32 v154, s39, v4
	v_add_u32_e32 v153, s71, v10
	v_add_u32_e32 v152, s39, v5
	v_add_u32_e32 v151, s71, v15
	s_mov_b64 s[0:1], s[62:63]
	s_barrier
	v_mov_b32_e32 v2, v222
	v_mov_b32_e32 v3, v223
	v_mov_b32_e32 v4, v224
	v_mov_b32_e32 v5, v225
	v_mov_b32_e32 v6, v226
	v_mov_b32_e32 v7, v227
	v_mov_b32_e32 v8, v228
	v_mov_b32_e32 v9, v229
	v_mov_b32_e32 v10, v230
	v_mov_b32_e32 v11, v231
	v_mov_b32_e32 v12, v232
	v_mov_b32_e32 v13, v233
	v_mov_b32_e32 v14, v234
	v_mov_b32_e32 v15, v235
	v_mov_b32_e32 v16, v236
	v_mov_b32_e32 v17, v237
	v_mov_b32_e32 v18, v238
	v_mov_b32_e32 v19, v239
	v_mov_b32_e32 v20, v240
	v_mov_b32_e32 v21, v241
	v_mov_b32_e32 v22, v242
	v_mov_b32_e32 v23, v243
	v_mov_b32_e32 v24, v244
	v_mov_b32_e32 v25, v245
	v_readfirstlane_b32 s99, v0
	s_nop 3
	s_lshr_b32 s99, s99, 6
	s_cmp_lt_u32 s99, 4
	s_cbranch_scc0 .Lprio_k1
	s_setprio 1
.Lprio_k1:
.LBB0_1025:
	v_add_u32_e32 v169, s39, v161
	ds_read_b128 v[172:175], v169 offset:32768
	ds_read_b128 v[176:179], v169 offset:33792
	ds_read_b128 v[180:183], v169 offset:34816
	ds_read_b128 v[184:187], v169 offset:35840
	v_add_u32_e32 v170, s79, v142
	v_lshl_add_u64 v[246:247], s[0:1], 0, v[138:139]
	v_readfirstlane_b32 s88, v170
	v_add_u32_e32 v171, 0x2000, v170
	v_add_u32_e32 v165, s71, v161
	v_add_u32_e32 v166, s74, v162
	v_add_u32_e32 v167, s75, v162
	v_add_u32_e32 v168, s86, v162
	v_lshl_add_u64 v[220:221], v[246:247], 0, s[6:7]
	s_mov_b32 m0, s88
	v_lshl_add_u64 v[248:249], s[0:1], 0, v[140:141]
	v_readfirstlane_b32 s88, v171
	ds_read_b128 v[188:191], v165
	ds_read_b128 v[192:195], v165 offset:1024
	ds_read_b128 v[196:199], v166
	ds_read_b128 v[200:203], v166 offset:1024
	ds_read_b128 v[204:207], v167
	ds_read_b128 v[208:211], v167 offset:1024
	ds_read_b128 v[212:215], v168
	ds_read_b128 v[216:219], v168 offset:1024
	global_load_lds_dwordx4 v[220:221], off
	v_lshl_add_u64 v[220:221], v[248:249], 0, s[6:7]
	s_mov_b32 m0, s88
	s_nop 0
	global_load_lds_dwordx4 v[220:221], off
	s_waitcnt lgkmcnt(8)
	s_barrier
	s_waitcnt lgkmcnt(0)
	s_waitcnt lgkmcnt(0)
	v_mfma_f32_16x16x32_bf16 v[126:129], v[188:191], v[172:175], v[126:129]
	v_mfma_f32_16x16x32_bf16 v[122:125], v[188:191], v[180:183], v[122:125]
	v_mfma_f32_16x16x32_bf16 v[118:121], v[196:199], v[172:175], v[118:121]
	v_mfma_f32_16x16x32_bf16 v[114:117], v[196:199], v[180:183], v[114:117]
	v_mfma_f32_16x16x32_bf16 v[110:113], v[204:207], v[172:175], v[110:113]
	v_mfma_f32_16x16x32_bf16 v[106:109], v[204:207], v[180:183], v[106:109]
	v_mfma_f32_16x16x32_bf16 v[102:105], v[212:215], v[172:175], v[102:105]
	v_mfma_f32_16x16x32_bf16 v[98:101], v[212:215], v[180:183], v[98:101]
	v_mfma_f32_16x16x32_bf16 v[126:129], v[192:195], v[176:179], v[126:129]
	v_mfma_f32_16x16x32_bf16 v[122:125], v[192:195], v[184:187], v[122:125]
	v_mfma_f32_16x16x32_bf16 v[118:121], v[200:203], v[176:179], v[118:121]
	v_mfma_f32_16x16x32_bf16 v[114:117], v[200:203], v[184:187], v[114:117]
	v_mfma_f32_16x16x32_bf16 v[110:113], v[208:211], v[176:179], v[110:113]
	v_mfma_f32_16x16x32_bf16 v[106:109], v[208:211], v[184:187], v[106:109]
	v_mfma_f32_16x16x32_bf16 v[102:105], v[216:219], v[176:179], v[102:105]
	v_mfma_f32_16x16x32_bf16 v[98:101], v[216:219], v[184:187], v[98:101]
	s_barrier
	v_lshl_add_u64 v[250:251], s[0:1], 0, v[134:135]
	v_readfirstlane_b32 s88, v144
	v_lshl_add_u64 v[238:239], v[250:251], 0, s[8:9]
	s_mov_b32 m0, s88
	v_lshl_add_u64 v[224:225], s[0:1], 0, v[136:137]
	v_readfirstlane_b32 s88, v145
	ds_read_b128 v[220:223], v169 offset:49152
	ds_read_b128 v[226:229], v169 offset:50176
	ds_read_b128 v[230:233], v169 offset:51200
	ds_read_b128 v[234:237], v169 offset:52224
	global_load_lds_dwordx4 v[238:239], off
	v_lshl_add_u64 v[238:239], v[224:225], 0, s[8:9]
	s_mov_b32 m0, s88
	s_nop 0
	global_load_lds_dwordx4 v[238:239], off
	s_barrier
	s_waitcnt lgkmcnt(0)
	s_waitcnt lgkmcnt(0)
	v_mfma_f32_16x16x32_bf16 v[94:97], v[188:191], v[220:223], v[94:97]
	v_mfma_f32_16x16x32_bf16 v[90:93], v[188:191], v[230:233], v[90:93]
	v_mfma_f32_16x16x32_bf16 v[82:85], v[196:199], v[220:223], v[82:85]
	v_mfma_f32_16x16x32_bf16 v[66:69], v[196:199], v[230:233], v[66:69]
	v_mfma_f32_16x16x32_bf16 v[62:65], v[204:207], v[220:223], v[62:65]
	v_mfma_f32_16x16x32_bf16 v[58:61], v[204:207], v[230:233], v[58:61]
	v_mfma_f32_16x16x32_bf16 v[54:57], v[212:215], v[220:223], v[54:57]
	v_mfma_f32_16x16x32_bf16 v[50:53], v[212:215], v[230:233], v[50:53]
	v_mfma_f32_16x16x32_bf16 v[94:97], v[192:195], v[226:229], v[94:97]
	v_mfma_f32_16x16x32_bf16 v[90:93], v[192:195], v[234:237], v[90:93]
	v_mfma_f32_16x16x32_bf16 v[82:85], v[200:203], v[226:229], v[82:85]
	v_mfma_f32_16x16x32_bf16 v[66:69], v[200:203], v[234:237], v[66:69]
	v_mfma_f32_16x16x32_bf16 v[62:65], v[208:211], v[226:229], v[62:65]
	v_mfma_f32_16x16x32_bf16 v[58:61], v[208:211], v[234:237], v[58:61]
	v_mfma_f32_16x16x32_bf16 v[54:57], v[216:219], v[226:229], v[54:57]
	v_mfma_f32_16x16x32_bf16 v[50:53], v[216:219], v[234:237], v[50:53]
	v_readfirstlane_b32 s88, v143
	v_lshl_add_u64 v[238:239], v[246:247], 0, s[10:11]
	s_mov_b32 m0, s88
	v_readfirstlane_b32 s88, v146
	s_barrier
	ds_read_b128 v[188:191], v165 offset:16384
	ds_read_b128 v[192:195], v165 offset:17408
	ds_read_b128 v[196:199], v166 offset:16384
	ds_read_b128 v[200:203], v166 offset:17408
	ds_read_b128 v[204:207], v167 offset:16384
	ds_read_b128 v[208:211], v167 offset:17408
	ds_read_b128 v[212:215], v168 offset:16384
	ds_read_b128 v[216:219], v168 offset:17408
	global_load_lds_dwordx4 v[238:239], off
	v_lshl_add_u64 v[238:239], v[248:249], 0, s[10:11]
	s_mov_b32 m0, s88
	s_nop 0
	global_load_lds_dwordx4 v[238:239], off
	s_barrier
	s_waitcnt lgkmcnt(0)
	s_waitcnt lgkmcnt(0)
	v_mfma_f32_16x16x32_bf16 v[46:49], v[188:191], v[172:175], v[46:49]
	v_mfma_f32_16x16x32_bf16 v[42:45], v[188:191], v[180:183], v[42:45]
	v_mfma_f32_16x16x32_bf16 v[38:41], v[196:199], v[172:175], v[38:41]
	v_mfma_f32_16x16x32_bf16 v[34:37], v[196:199], v[180:183], v[34:37]
	v_mfma_f32_16x16x32_bf16 v[30:33], v[204:207], v[172:175], v[30:33]
	v_mfma_f32_16x16x32_bf16 v[26:29], v[204:207], v[180:183], v[26:29]
	v_mfma_f32_16x16x32_bf16 v[22:25], v[212:215], v[172:175], v[22:25]
	v_mfma_f32_16x16x32_bf16 v[18:21], v[212:215], v[180:183], v[18:21]
	v_mfma_f32_16x16x32_bf16 v[46:49], v[192:195], v[176:179], v[46:49]
	v_mfma_f32_16x16x32_bf16 v[42:45], v[192:195], v[184:187], v[42:45]
	v_mfma_f32_16x16x32_bf16 v[38:41], v[200:203], v[176:179], v[38:41]
	v_mfma_f32_16x16x32_bf16 v[34:37], v[200:203], v[184:187], v[34:37]
	v_mfma_f32_16x16x32_bf16 v[30:33], v[208:211], v[176:179], v[30:33]
	v_mfma_f32_16x16x32_bf16 v[26:29], v[208:211], v[184:187], v[26:29]
	v_mfma_f32_16x16x32_bf16 v[22:25], v[216:219], v[176:179], v[22:25]
	v_mfma_f32_16x16x32_bf16 v[18:21], v[216:219], v[184:187], v[18:21]
	s_barrier
	v_readfirstlane_b32 s88, v147
	v_lshl_add_u64 v[172:173], v[250:251], 0, s[12:13]
	s_mov_b32 m0, s88
	v_readfirstlane_b32 s88, v148
	global_load_lds_dwordx4 v[172:173], off
	v_lshl_add_u64 v[172:173], v[224:225], 0, s[12:13]
	s_mov_b32 m0, s88
	s_nop 0
	global_load_lds_dwordx4 v[172:173], off
	s_waitcnt vmcnt(6)
	s_barrier
	v_mfma_f32_16x16x32_bf16 v[14:17], v[188:191], v[220:223], v[14:17]
	v_mfma_f32_16x16x32_bf16 v[10:13], v[188:191], v[230:233], v[10:13]
	v_mfma_f32_16x16x32_bf16 v[6:9], v[196:199], v[220:223], v[6:9]
	v_mfma_f32_16x16x32_bf16 v[2:5], v[196:199], v[230:233], v[2:5]
	v_mfma_f32_16x16x32_bf16 v[70:73], v[204:207], v[220:223], v[70:73]
	v_mfma_f32_16x16x32_bf16 v[74:77], v[204:207], v[230:233], v[74:77]
	v_mfma_f32_16x16x32_bf16 v[78:81], v[212:215], v[220:223], v[78:81]
	v_mfma_f32_16x16x32_bf16 v[86:89], v[212:215], v[230:233], v[86:89]
	v_mfma_f32_16x16x32_bf16 v[14:17], v[192:195], v[226:229], v[14:17]
	v_mfma_f32_16x16x32_bf16 v[10:13], v[192:195], v[234:237], v[10:13]
	v_mfma_f32_16x16x32_bf16 v[6:9], v[200:203], v[226:229], v[6:9]
	v_mfma_f32_16x16x32_bf16 v[2:5], v[200:203], v[234:237], v[2:5]
	v_mfma_f32_16x16x32_bf16 v[70:73], v[208:211], v[226:229], v[70:73]
	v_mfma_f32_16x16x32_bf16 v[74:77], v[208:211], v[234:237], v[74:77]
	v_mfma_f32_16x16x32_bf16 v[78:81], v[216:219], v[226:229], v[78:81]
	v_mfma_f32_16x16x32_bf16 v[86:89], v[216:219], v[234:237], v[86:89]
	s_barrier
	ds_read_b128 v[178:181], v154
	ds_read_b128 v[182:185], v154 offset:1024
	ds_read_b128 v[186:189], v154 offset:2048
	ds_read_b128 v[190:193], v154 offset:3072
	v_readfirstlane_b32 s88, v149
	v_add_u32_e32 v172, s74, v163
	v_add_u32_e32 v173, s75, v163
	v_add_u32_e32 v174, s86, v163
	v_lshl_add_u64 v[176:177], v[246:247], 0, s[14:15]
	s_mov_b32 m0, s88
	v_readfirstlane_b32 s88, v150
	ds_read_b128 v[194:197], v153
	ds_read_b128 v[198:201], v153 offset:1024
	ds_read_b128 v[202:205], v172
	ds_read_b128 v[206:209], v172 offset:1024
	ds_read_b128 v[210:213], v173
	ds_read_b128 v[214:217], v173 offset:1024
	ds_read_b128 v[218:221], v174
	ds_read_b128 v[226:229], v174 offset:1024
	global_load_lds_dwordx4 v[176:177], off
	v_lshl_add_u64 v[176:177], v[248:249], 0, s[14:15]
	s_mov_b32 m0, s88
	s_nop 0
	global_load_lds_dwordx4 v[176:177], off
	s_waitcnt lgkmcnt(8)
	s_barrier
	s_waitcnt lgkmcnt(0)
	s_waitcnt lgkmcnt(0)
	v_mfma_f32_16x16x32_bf16 v[126:129], v[194:197], v[178:181], v[126:129]
	v_mfma_f32_16x16x32_bf16 v[122:125], v[194:197], v[186:189], v[122:125]
	v_mfma_f32_16x16x32_bf16 v[118:121], v[202:205], v[178:181], v[118:121]
	v_mfma_f32_16x16x32_bf16 v[114:117], v[202:205], v[186:189], v[114:117]
	v_mfma_f32_16x16x32_bf16 v[110:113], v[210:213], v[178:181], v[110:113]
	v_mfma_f32_16x16x32_bf16 v[106:109], v[210:213], v[186:189], v[106:109]
	v_mfma_f32_16x16x32_bf16 v[102:105], v[218:221], v[178:181], v[102:105]
	v_mfma_f32_16x16x32_bf16 v[98:101], v[218:221], v[186:189], v[98:101]
	v_mfma_f32_16x16x32_bf16 v[126:129], v[198:201], v[182:185], v[126:129]
	v_mfma_f32_16x16x32_bf16 v[122:125], v[198:201], v[190:193], v[122:125]
	v_mfma_f32_16x16x32_bf16 v[118:121], v[206:209], v[182:185], v[118:121]
	v_mfma_f32_16x16x32_bf16 v[114:117], v[206:209], v[190:193], v[114:117]
	v_mfma_f32_16x16x32_bf16 v[110:113], v[214:217], v[182:185], v[110:113]
	v_mfma_f32_16x16x32_bf16 v[106:109], v[214:217], v[190:193], v[106:109]
	v_mfma_f32_16x16x32_bf16 v[102:105], v[226:229], v[182:185], v[102:105]
	v_mfma_f32_16x16x32_bf16 v[98:101], v[226:229], v[190:193], v[98:101]
	s_barrier
	v_readfirstlane_b32 s88, v155
	v_lshl_add_u64 v[176:177], v[250:251], 0, s[16:17]
	s_mov_b32 m0, s88
	v_readfirstlane_b32 s88, v156
	ds_read_b128 v[230:233], v152
	ds_read_b128 v[234:237], v152 offset:1024
	ds_read_b128 v[238:241], v152 offset:2048
	ds_read_b128 v[242:245], v152 offset:3072
	global_load_lds_dwordx4 v[176:177], off
	v_lshl_add_u64 v[176:177], v[224:225], 0, s[16:17]
	s_mov_b32 m0, s88
	s_nop 0
	global_load_lds_dwordx4 v[176:177], off
	s_barrier
	s_waitcnt lgkmcnt(0)
	s_waitcnt lgkmcnt(0)
	v_mfma_f32_16x16x32_bf16 v[94:97], v[194:197], v[230:233], v[94:97]
	v_mfma_f32_16x16x32_bf16 v[90:93], v[194:197], v[238:241], v[90:93]
	v_mfma_f32_16x16x32_bf16 v[82:85], v[202:205], v[230:233], v[82:85]
	v_mfma_f32_16x16x32_bf16 v[66:69], v[202:205], v[238:241], v[66:69]
	v_mfma_f32_16x16x32_bf16 v[62:65], v[210:213], v[230:233], v[62:65]
	v_mfma_f32_16x16x32_bf16 v[58:61], v[210:213], v[238:241], v[58:61]
	v_mfma_f32_16x16x32_bf16 v[54:57], v[218:221], v[230:233], v[54:57]
	v_mfma_f32_16x16x32_bf16 v[50:53], v[218:221], v[238:241], v[50:53]
	v_mfma_f32_16x16x32_bf16 v[94:97], v[198:201], v[234:237], v[94:97]
	v_mfma_f32_16x16x32_bf16 v[90:93], v[198:201], v[242:245], v[90:93]
	v_mfma_f32_16x16x32_bf16 v[82:85], v[206:209], v[234:237], v[82:85]
	v_mfma_f32_16x16x32_bf16 v[66:69], v[206:209], v[242:245], v[66:69]
	v_mfma_f32_16x16x32_bf16 v[62:65], v[214:217], v[234:237], v[62:65]
	v_mfma_f32_16x16x32_bf16 v[58:61], v[214:217], v[242:245], v[58:61]
	v_mfma_f32_16x16x32_bf16 v[54:57], v[226:229], v[234:237], v[54:57]
	v_mfma_f32_16x16x32_bf16 v[50:53], v[226:229], v[242:245], v[50:53]
	v_readfirstlane_b32 s88, v157
	v_add_u32_e32 v175, s74, v164
	v_add_u32_e32 v176, s75, v164
	v_add_u32_e32 v177, s86, v164
	v_lshl_add_u64 v[222:223], v[246:247], 0, s[18:19]
	s_mov_b32 m0, s88
	v_readfirstlane_b32 s88, v158
	s_barrier
	ds_read_b128 v[194:197], v151
	ds_read_b128 v[198:201], v151 offset:1024
	ds_read_b128 v[202:205], v175
	ds_read_b128 v[206:209], v175 offset:1024
	ds_read_b128 v[210:213], v176
	ds_read_b128 v[214:217], v176 offset:1024
	ds_read_b128 v[218:221], v177
	ds_read_b128 v[226:229], v177 offset:1024
	global_load_lds_dwordx4 v[222:223], off
	v_lshl_add_u64 v[222:223], v[248:249], 0, s[18:19]
	s_mov_b32 m0, s88
	s_nop 0
	global_load_lds_dwordx4 v[222:223], off
	s_barrier
	s_waitcnt lgkmcnt(0)
	s_waitcnt lgkmcnt(0)
	v_mfma_f32_16x16x32_bf16 v[46:49], v[194:197], v[178:181], v[46:49]
	v_mfma_f32_16x16x32_bf16 v[42:45], v[194:197], v[186:189], v[42:45]
	v_mfma_f32_16x16x32_bf16 v[38:41], v[202:205], v[178:181], v[38:41]
	v_mfma_f32_16x16x32_bf16 v[34:37], v[202:205], v[186:189], v[34:37]
	v_mfma_f32_16x16x32_bf16 v[30:33], v[210:213], v[178:181], v[30:33]
	v_mfma_f32_16x16x32_bf16 v[26:29], v[210:213], v[186:189], v[26:29]
	v_mfma_f32_16x16x32_bf16 v[22:25], v[218:221], v[178:181], v[22:25]
	v_mfma_f32_16x16x32_bf16 v[18:21], v[218:221], v[186:189], v[18:21]
	v_mfma_f32_16x16x32_bf16 v[46:49], v[198:201], v[182:185], v[46:49]
	v_mfma_f32_16x16x32_bf16 v[42:45], v[198:201], v[190:193], v[42:45]
	v_mfma_f32_16x16x32_bf16 v[38:41], v[206:209], v[182:185], v[38:41]
	v_mfma_f32_16x16x32_bf16 v[34:37], v[206:209], v[190:193], v[34:37]
	v_mfma_f32_16x16x32_bf16 v[30:33], v[214:217], v[182:185], v[30:33]
	v_mfma_f32_16x16x32_bf16 v[26:29], v[214:217], v[190:193], v[26:29]
	v_mfma_f32_16x16x32_bf16 v[22:25], v[226:229], v[182:185], v[22:25]
	v_mfma_f32_16x16x32_bf16 v[18:21], v[226:229], v[190:193], v[18:21]
	s_barrier
	v_readfirstlane_b32 s88, v159
	v_lshl_add_u64 v[178:179], v[250:251], 0, s[20:21]
	s_mov_b32 m0, s88
	v_readfirstlane_b32 s88, v160
	global_load_lds_dwordx4 v[178:179], off
	v_lshl_add_u64 v[178:179], v[224:225], 0, s[20:21]
	s_mov_b32 m0, s88
	s_nop 0
	global_load_lds_dwordx4 v[178:179], off
	s_waitcnt vmcnt(6)
	s_barrier
	v_mfma_f32_16x16x32_bf16 v[14:17], v[194:197], v[230:233], v[14:17]
	v_mfma_f32_16x16x32_bf16 v[10:13], v[194:197], v[238:241], v[10:13]
	v_mfma_f32_16x16x32_bf16 v[6:9], v[202:205], v[230:233], v[6:9]
	v_mfma_f32_16x16x32_bf16 v[2:5], v[202:205], v[238:241], v[2:5]
	v_mfma_f32_16x16x32_bf16 v[70:73], v[210:213], v[230:233], v[70:73]
	v_mfma_f32_16x16x32_bf16 v[74:77], v[210:213], v[238:241], v[74:77]
	v_mfma_f32_16x16x32_bf16 v[78:81], v[218:221], v[230:233], v[78:81]
	v_mfma_f32_16x16x32_bf16 v[86:89], v[218:221], v[238:241], v[86:89]
	v_mfma_f32_16x16x32_bf16 v[14:17], v[198:201], v[234:237], v[14:17]
	v_mfma_f32_16x16x32_bf16 v[10:13], v[198:201], v[242:245], v[10:13]
	v_mfma_f32_16x16x32_bf16 v[6:9], v[206:209], v[234:237], v[6:9]
	v_mfma_f32_16x16x32_bf16 v[2:5], v[206:209], v[242:245], v[2:5]
	v_mfma_f32_16x16x32_bf16 v[70:73], v[214:217], v[234:237], v[70:73]
	v_mfma_f32_16x16x32_bf16 v[74:77], v[214:217], v[242:245], v[74:77]
	v_mfma_f32_16x16x32_bf16 v[78:81], v[226:229], v[234:237], v[78:81]
	v_mfma_f32_16x16x32_bf16 v[86:89], v[226:229], v[242:245], v[86:89]
	s_add_i32 s87, s87, 2
	s_add_u32 s0, s0, 0x100
	s_addc_u32 s1, s1, 0
	s_cmp_lt_u32 s87, 12
	s_barrier
	s_cbranch_scc1 .LBB0_1025
	s_or_b32 s0, s38, 0x80
	s_ashr_i32 s1, s0, 31
	s_lshl_b64 s[74:75], s[0:1], 11
	s_add_u32 s74, s80, s74
	s_addc_u32 s75, s81, s75
	v_lshl_add_u64 v[202:203], v[130:131], 1, s[74:75]
	v_readfirstlane_b32 s1, v170
	v_lshl_add_u64 v[202:203], v[202:203], 0, s[22:23]
	s_mov_b32 m0, s1
	v_lshl_add_u64 v[132:133], v[132:133], 1, s[74:75]
	v_readfirstlane_b32 s1, v171
	ds_read_b128 v[134:137], v169 offset:32768
	ds_read_b128 v[138:141], v169 offset:33792
	ds_read_b128 v[142:145], v169 offset:34816
	ds_read_b128 v[146:149], v169 offset:35840
	ds_read_b128 v[156:159], v165
	ds_read_b128 v[160:163], v165 offset:1024
	ds_read_b128 v[178:181], v166
	ds_read_b128 v[182:185], v166 offset:1024
	ds_read_b128 v[186:189], v167
	ds_read_b128 v[190:193], v167 offset:1024
	ds_read_b128 v[194:197], v168
	ds_read_b128 v[198:201], v168 offset:1024
	global_load_lds_dwordx4 v[202:203], off
	v_lshl_add_u64 v[132:133], v[132:133], 0, s[22:23]
	s_mov_b32 m0, s1
	s_nop 0
	global_load_lds_dwordx4 v[132:133], off
	s_barrier
	s_waitcnt lgkmcnt(0)
	s_waitcnt lgkmcnt(0)
	v_mfma_f32_16x16x32_bf16 v[126:129], v[156:159], v[134:137], v[126:129]
	v_mfma_f32_16x16x32_bf16 v[122:125], v[156:159], v[142:145], v[122:125]
	v_mfma_f32_16x16x32_bf16 v[118:121], v[178:181], v[134:137], v[118:121]
	v_mfma_f32_16x16x32_bf16 v[114:117], v[178:181], v[142:145], v[114:117]
	v_mfma_f32_16x16x32_bf16 v[110:113], v[186:189], v[134:137], v[110:113]
	v_mfma_f32_16x16x32_bf16 v[126:129], v[160:163], v[138:141], v[126:129]
	v_mfma_f32_16x16x32_bf16 v[122:125], v[160:163], v[146:149], v[122:125]
	v_mfma_f32_16x16x32_bf16 v[118:121], v[182:185], v[138:141], v[118:121]
	v_mfma_f32_16x16x32_bf16 v[114:117], v[182:185], v[146:149], v[114:117]
	v_mfma_f32_16x16x32_bf16 v[110:113], v[190:193], v[138:141], v[110:113]
	v_mfma_f32_16x16x32_bf16 v[106:109], v[186:189], v[142:145], v[106:109]
	v_mfma_f32_16x16x32_bf16 v[102:105], v[194:197], v[134:137], v[102:105]
	v_mfma_f32_16x16x32_bf16 v[98:101], v[194:197], v[142:145], v[98:101]
	v_mfma_f32_16x16x32_bf16 v[202:205], v[190:193], v[146:149], v[106:109]
	v_mfma_f32_16x16x32_bf16 v[206:209], v[198:201], v[138:141], v[102:105]
	v_mfma_f32_16x16x32_bf16 v[210:213], v[198:201], v[146:149], v[98:101]
	s_barrier
	s_nop 2
	ds_read_b128 v[98:101], v169 offset:49152
	ds_read_b128 v[102:105], v169 offset:50176
	ds_read_b128 v[106:109], v169 offset:51200
	ds_read_b128 v[214:217], v169 offset:52224
	s_barrier
	s_waitcnt lgkmcnt(0)
	s_waitcnt lgkmcnt(0)
	v_mfma_f32_16x16x32_bf16 v[94:97], v[156:159], v[98:101], v[94:97]
	v_mfma_f32_16x16x32_bf16 v[90:93], v[156:159], v[106:109], v[90:93]
	v_mfma_f32_16x16x32_bf16 v[82:85], v[178:181], v[98:101], v[82:85]
	v_mfma_f32_16x16x32_bf16 v[62:65], v[186:189], v[98:101], v[62:65]
	v_mfma_f32_16x16x32_bf16 v[58:61], v[186:189], v[106:109], v[58:61]
	v_mfma_f32_16x16x32_bf16 v[54:57], v[194:197], v[98:101], v[54:57]
	v_mfma_f32_16x16x32_bf16 v[50:53], v[194:197], v[106:109], v[50:53]
	v_mfma_f32_16x16x32_bf16 v[94:97], v[160:163], v[102:105], v[94:97]
	v_mfma_f32_16x16x32_bf16 v[90:93], v[160:163], v[214:217], v[90:93]
	v_mfma_f32_16x16x32_bf16 v[82:85], v[182:185], v[102:105], v[82:85]
	v_mfma_f32_16x16x32_bf16 v[66:69], v[178:181], v[106:109], v[66:69]
	v_mfma_f32_16x16x32_bf16 v[62:65], v[190:193], v[102:105], v[62:65]
	v_mfma_f32_16x16x32_bf16 v[58:61], v[190:193], v[214:217], v[58:61]
	v_mfma_f32_16x16x32_bf16 v[54:57], v[198:201], v[102:105], v[54:57]
	v_mfma_f32_16x16x32_bf16 v[50:53], v[198:201], v[214:217], v[50:53]
	v_mfma_f32_16x16x32_bf16 v[156:159], v[182:185], v[214:217], v[66:69]
	s_barrier
	s_nop 0
	ds_read_b128 v[66:69], v165 offset:16384
	ds_read_b128 v[160:163], v165 offset:17408
	ds_read_b128 v[178:181], v166 offset:16384
	ds_read_b128 v[182:185], v166 offset:17408
	ds_read_b128 v[186:189], v167 offset:16384
	ds_read_b128 v[164:167], v167 offset:17408
	ds_read_b128 v[190:193], v168 offset:16384
	ds_read_b128 v[168:171], v168 offset:17408
	s_waitcnt vmcnt(4)
	s_barrier
	s_waitcnt lgkmcnt(0)
	s_waitcnt lgkmcnt(0)
	v_mfma_f32_16x16x32_bf16 v[46:49], v[66:69], v[134:137], v[46:49]
	v_mfma_f32_16x16x32_bf16 v[42:45], v[66:69], v[142:145], v[42:45]
	v_mfma_f32_16x16x32_bf16 v[30:33], v[186:189], v[134:137], v[30:33]
	v_mfma_f32_16x16x32_bf16 v[26:29], v[186:189], v[142:145], v[26:29]
	v_mfma_f32_16x16x32_bf16 v[22:25], v[190:193], v[134:137], v[22:25]
	v_mfma_f32_16x16x32_bf16 v[18:21], v[190:193], v[142:145], v[18:21]
	v_mfma_f32_16x16x32_bf16 v[46:49], v[160:163], v[138:141], v[46:49]
	v_mfma_f32_16x16x32_bf16 v[42:45], v[160:163], v[146:149], v[42:45]
	v_mfma_f32_16x16x32_bf16 v[38:41], v[178:181], v[134:137], v[38:41]
	v_mfma_f32_16x16x32_bf16 v[34:37], v[178:181], v[142:145], v[34:37]
	v_mfma_f32_16x16x32_bf16 v[30:33], v[164:167], v[138:141], v[30:33]
	v_mfma_f32_16x16x32_bf16 v[26:29], v[164:167], v[146:149], v[26:29]
	v_mfma_f32_16x16x32_bf16 v[22:25], v[168:171], v[138:141], v[22:25]
	v_mfma_f32_16x16x32_bf16 v[18:21], v[168:171], v[146:149], v[18:21]
	v_mfma_f32_16x16x32_bf16 v[194:197], v[182:185], v[138:141], v[38:41]
	v_mfma_f32_16x16x32_bf16 v[198:201], v[182:185], v[146:149], v[34:37]
	v_mfma_f32_16x16x32_bf16 v[2:5], v[178:181], v[106:109], v[2:5]
	v_mfma_f32_16x16x32_bf16 v[136:139], v[182:185], v[214:217], v[2:5]
	v_mfma_f32_16x16x32_bf16 v[2:5], v[186:189], v[98:101], v[70:73]
	v_mfma_f32_16x16x32_bf16 v[140:143], v[164:167], v[102:105], v[2:5]
	v_mfma_f32_16x16x32_bf16 v[2:5], v[186:189], v[106:109], v[74:77]
	v_mfma_f32_16x16x32_bf16 v[14:17], v[66:69], v[98:101], v[14:17]
	v_mfma_f32_16x16x32_bf16 v[10:13], v[66:69], v[106:109], v[10:13]
	v_mfma_f32_16x16x32_bf16 v[144:147], v[164:167], v[214:217], v[2:5]
	v_mfma_f32_16x16x32_bf16 v[2:5], v[190:193], v[98:101], v[78:81]
	v_mfma_f32_16x16x32_bf16 v[14:17], v[160:163], v[102:105], v[14:17]
	v_mfma_f32_16x16x32_bf16 v[10:13], v[160:163], v[214:217], v[10:13]
	v_mfma_f32_16x16x32_bf16 v[6:9], v[178:181], v[98:101], v[6:9]
	v_mfma_f32_16x16x32_bf16 v[160:163], v[168:171], v[102:105], v[2:5]
	v_mfma_f32_16x16x32_bf16 v[2:5], v[190:193], v[106:109], v[86:89]
	v_mfma_f32_16x16x32_bf16 v[132:135], v[182:185], v[102:105], v[6:9]
	v_mfma_f32_16x16x32_bf16 v[164:167], v[168:171], v[214:217], v[2:5]
	s_barrier
	s_nop 3
	ds_read_b128 v[2:5], v154
	ds_read_b128 v[6:9], v154 offset:1024
	ds_read_b128 v[168:171], v154 offset:2048
	ds_read_b128 v[178:181], v154 offset:3072
	ds_read_b128 v[34:37], v153
	ds_read_b128 v[38:41], v153 offset:1024
	ds_read_b128 v[78:81], v172
	ds_read_b128 v[86:89], v172 offset:1024
	ds_read_b128 v[182:185], v173
	ds_read_b128 v[186:189], v173 offset:1024
	ds_read_b128 v[190:193], v174
	ds_read_b128 v[214:217], v174 offset:1024
	s_waitcnt vmcnt(2)
	s_barrier
	s_waitcnt lgkmcnt(0)
	s_waitcnt lgkmcnt(0)
	v_mfma_f32_16x16x32_bf16 v[66:69], v[34:37], v[2:5], v[126:129]
	v_mfma_f32_16x16x32_bf16 v[126:129], v[38:41], v[6:9], v[66:69]
	v_mfma_f32_16x16x32_bf16 v[66:69], v[34:37], v[168:171], v[122:125]
	v_mfma_f32_16x16x32_bf16 v[98:101], v[38:41], v[178:181], v[66:69]
	v_mfma_f32_16x16x32_bf16 v[66:69], v[78:81], v[2:5], v[118:121]
	v_mfma_f32_16x16x32_bf16 v[102:105], v[86:89], v[6:9], v[66:69]
	v_mfma_f32_16x16x32_bf16 v[66:69], v[78:81], v[168:171], v[114:117]
	v_mfma_f32_16x16x32_bf16 v[106:109], v[86:89], v[178:181], v[66:69]
	v_mfma_f32_16x16x32_bf16 v[66:69], v[182:185], v[2:5], v[110:113]
	v_mfma_f32_16x16x32_bf16 v[110:113], v[186:189], v[6:9], v[66:69]
	v_mfma_f32_16x16x32_bf16 v[66:69], v[182:185], v[168:171], v[202:205]
	v_mfma_f32_16x16x32_bf16 v[114:117], v[186:189], v[178:181], v[66:69]
	v_mfma_f32_16x16x32_bf16 v[66:69], v[190:193], v[2:5], v[206:209]
	v_mfma_f32_16x16x32_bf16 v[118:121], v[214:217], v[6:9], v[66:69]
	v_mfma_f32_16x16x32_bf16 v[66:69], v[190:193], v[168:171], v[210:213]
	v_mfma_f32_16x16x32_bf16 v[122:125], v[214:217], v[178:181], v[66:69]
	s_barrier
	ds_read_b128 v[202:205], v152
	ds_read_b128 v[206:209], v152 offset:1024
	ds_read_b128 v[210:213], v152 offset:2048
	ds_read_b128 v[152:155], v152 offset:3072
	s_waitcnt vmcnt(0)
	s_barrier
	s_waitcnt lgkmcnt(0)
	s_waitcnt lgkmcnt(0)
	v_mfma_f32_16x16x32_bf16 v[66:69], v[34:37], v[202:205], v[94:97]
	v_mfma_f32_16x16x32_bf16 v[34:37], v[34:37], v[210:213], v[90:93]
	v_mfma_f32_16x16x32_bf16 v[70:73], v[38:41], v[152:155], v[34:37]
	v_mfma_f32_16x16x32_bf16 v[34:37], v[78:81], v[202:205], v[82:85]
	v_mfma_f32_16x16x32_bf16 v[74:77], v[86:89], v[206:209], v[34:37]
	v_mfma_f32_16x16x32_bf16 v[34:37], v[78:81], v[210:213], v[156:159]
	v_mfma_f32_16x16x32_bf16 v[78:81], v[86:89], v[152:155], v[34:37]
	v_mfma_f32_16x16x32_bf16 v[34:37], v[182:185], v[202:205], v[62:65]
	v_mfma_f32_16x16x32_bf16 v[82:85], v[186:189], v[206:209], v[34:37]
	v_mfma_f32_16x16x32_bf16 v[34:37], v[182:185], v[210:213], v[58:61]
	v_mfma_f32_16x16x32_bf16 v[86:89], v[186:189], v[152:155], v[34:37]
	v_mfma_f32_16x16x32_bf16 v[34:37], v[190:193], v[202:205], v[54:57]
	v_mfma_f32_16x16x32_bf16 v[90:93], v[214:217], v[206:209], v[34:37]
	v_mfma_f32_16x16x32_bf16 v[34:37], v[190:193], v[210:213], v[50:53]
	v_mfma_f32_16x16x32_bf16 v[66:69], v[38:41], v[206:209], v[66:69]
	v_mfma_f32_16x16x32_bf16 v[94:97], v[214:217], v[152:155], v[34:37]
	s_barrier
	ds_read_b128 v[156:159], v151
	ds_read_b128 v[148:151], v151 offset:1024
	ds_read_b128 v[182:185], v175
	ds_read_b128 v[172:175], v175 offset:1024
	ds_read_b128 v[186:189], v176
	ds_read_b128 v[190:193], v176 offset:1024
	ds_read_b128 v[214:217], v177
	ds_read_b128 v[218:221], v177 offset:1024
	s_barrier
	s_waitcnt lgkmcnt(0)
	s_waitcnt lgkmcnt(0)
	v_mfma_f32_16x16x32_bf16 v[34:37], v[156:159], v[2:5], v[46:49]
	v_mfma_f32_16x16x32_bf16 v[38:41], v[156:159], v[168:171], v[42:45]
	v_mfma_f32_16x16x32_bf16 v[42:45], v[182:185], v[2:5], v[194:197]
	v_mfma_f32_16x16x32_bf16 v[30:33], v[186:189], v[2:5], v[30:33]
	v_mfma_f32_16x16x32_bf16 v[2:5], v[214:217], v[2:5], v[22:25]
	v_mfma_f32_16x16x32_bf16 v[46:49], v[182:185], v[168:171], v[198:201]
	v_mfma_f32_16x16x32_bf16 v[26:29], v[186:189], v[168:171], v[26:29]
	v_mfma_f32_16x16x32_bf16 v[58:61], v[218:221], v[6:9], v[2:5]
	v_mfma_f32_16x16x32_bf16 v[2:5], v[214:217], v[168:171], v[18:21]
	v_mfma_f32_16x16x32_bf16 v[34:37], v[148:151], v[6:9], v[34:37]
	v_mfma_f32_16x16x32_bf16 v[38:41], v[148:151], v[178:181], v[38:41]
	v_mfma_f32_16x16x32_bf16 v[42:45], v[172:175], v[6:9], v[42:45]
	v_mfma_f32_16x16x32_bf16 v[46:49], v[172:175], v[178:181], v[46:49]
	v_mfma_f32_16x16x32_bf16 v[50:53], v[190:193], v[6:9], v[30:33]
	v_mfma_f32_16x16x32_bf16 v[54:57], v[190:193], v[178:181], v[26:29]
	v_mfma_f32_16x16x32_bf16 v[62:65], v[218:221], v[178:181], v[2:5]
	v_mfma_f32_16x16x32_bf16 v[2:5], v[156:159], v[202:205], v[14:17]
	v_mfma_f32_16x16x32_bf16 v[6:9], v[156:159], v[210:213], v[10:13]
	v_mfma_f32_16x16x32_bf16 v[10:13], v[182:185], v[202:205], v[132:135]
	v_mfma_f32_16x16x32_bf16 v[14:17], v[182:185], v[210:213], v[136:139]
	v_mfma_f32_16x16x32_bf16 v[18:21], v[186:189], v[202:205], v[140:143]
	v_mfma_f32_16x16x32_bf16 v[22:25], v[186:189], v[210:213], v[144:147]
	v_mfma_f32_16x16x32_bf16 v[26:29], v[214:217], v[202:205], v[160:163]
	v_mfma_f32_16x16x32_bf16 v[30:33], v[214:217], v[210:213], v[164:167]
	v_mfma_f32_16x16x32_bf16 v[2:5], v[148:151], v[206:209], v[2:5]
	v_mfma_f32_16x16x32_bf16 v[6:9], v[148:151], v[152:155], v[6:9]
	v_mfma_f32_16x16x32_bf16 v[10:13], v[172:175], v[206:209], v[10:13]
	v_mfma_f32_16x16x32_bf16 v[14:17], v[172:175], v[152:155], v[14:17]
	v_mfma_f32_16x16x32_bf16 v[18:21], v[190:193], v[206:209], v[18:21]
	v_mfma_f32_16x16x32_bf16 v[22:25], v[190:193], v[152:155], v[22:25]
	v_mfma_f32_16x16x32_bf16 v[26:29], v[218:221], v[206:209], v[26:29]
	v_mfma_f32_16x16x32_bf16 v[30:33], v[218:221], v[152:155], v[30:33]
	s_setprio 0
	s_cmpk_gt_u32 s45, 0xff
	s_barrier
	s_cbranch_scc1 .LBB0_1028
	s_barrier

.LBB0_1042:
	s_ashr_i32 s37, s36, 31
	s_lshl_b64 s[70:71], s[36:37], 12
	s_add_u32 s0, s42, s70
	v_mov_b32_e32 v3, v139
	s_addc_u32 s1, s43, s71
	v_add_u32_e32 v156, s33, v142
	v_lshlrev_b64 v[2:3], 1, v[2:3]
	v_lshl_add_u64 v[16:17], s[0:1], 0, v[2:3]
	v_readfirstlane_b32 s35, v156
	v_mov_b32_e32 v5, v139
	v_lshl_add_u64 v[16:17], v[16:17], 0, s[2:3]
	s_mov_b32 m0, s35
	v_lshlrev_b64 v[4:5], 1, v[4:5]
	v_add_u32_e32 v157, 0x2000, v156
	s_barrier
	global_load_lds_dwordx4 v[16:17], off
	v_lshl_add_u64 v[16:17], s[0:1], 0, v[4:5]
	v_readfirstlane_b32 s0, v157
	s_ashr_i32 s35, s34, 31
	s_mov_b32 m0, s0
	s_lshl_b64 s[0:1], s[34:35], 11
	s_add_u32 s0, s94, s0
	v_lshl_add_u64 v[16:17], v[16:17], 0, s[2:3]
	s_addc_u32 s1, s95, s1
	v_add_u32_e32 v158, s72, v142
	global_load_lds_dwordx4 v[16:17], off
	v_lshl_add_u64 v[16:17], v[138:139], 1, s[0:1]
	v_readfirstlane_b32 s35, v158
	v_lshl_add_u64 v[16:17], v[16:17], 0, s[2:3]
	s_mov_b32 m0, s35
	v_mov_b32_e32 v131, v139
	global_load_lds_dwordx4 v[16:17], off
	v_lshlrev_b64 v[16:17], 1, v[130:131]
	v_add_u32_e32 v159, 0x2000, v158
	v_lshl_add_u64 v[18:19], s[0:1], 0, v[16:17]
	v_readfirstlane_b32 s0, v159
	s_mov_b32 m0, s0
	s_or_b32 s0, s36, 0x80
	s_ashr_i32 s1, s0, 31
	s_lshl_b64 s[78:79], s[0:1], 12
	s_add_u32 s78, s42, s78
	s_addc_u32 s79, s43, s79
	v_add_u32_e32 v160, s73, v142
	v_lshl_add_u64 v[18:19], v[18:19], 0, s[2:3]
	v_lshl_add_u64 v[2:3], s[78:79], 0, v[2:3]
	v_readfirstlane_b32 s35, v160
	global_load_lds_dwordx4 v[18:19], off
	v_lshl_add_u64 v[2:3], v[2:3], 0, s[2:3]
	s_mov_b32 m0, s35
	v_add_u32_e32 v161, 0x2000, v160
	global_load_lds_dwordx4 v[2:3], off
	v_lshl_add_u64 v[2:3], s[78:79], 0, v[4:5]
	v_readfirstlane_b32 s35, v161
	v_lshl_add_u64 v[2:3], v[2:3], 0, s[2:3]
	s_mov_b32 m0, s35
	v_and_b32_e32 v15, 15, v10
	global_load_lds_dwordx4 v[2:3], off
	v_lshlrev_b32_e32 v3, 2, v10
	v_and_b32_e32 v20, 48, v10
	v_lshlrev_b32_e32 v2, 6, v15
	v_and_b32_e32 v3, 32, v3
	v_lshlrev_b32_e32 v10, 6, v10
	v_bitop3_b32 v2, v2, v3, v20 bitop3:0x36
	v_and_b32_e32 v10, 0x3c0, v10
	v_add_u32_e32 v162, 0, v2
	v_add_u32_e32 v4, s33, v2
	v_add_u32_e32 v5, s73, v2
	v_bitop3_b32 v3, v10, v3, v20 bitop3:0x36
	v_add_u32_e32 v10, s72, v2
	v_add_u32_e32 v15, s74, v2
	v_lshrrev_b32_e32 v9, 1, v9
	v_lshlrev_b32_e32 v2, 11, v6
	v_lshl_add_u32 v2, v9, 15, v2
	v_or_b32_e32 v2, v2, v7
	v_add_u32_e32 v163, 0, v3
	v_add_u32_e32 v164, s72, v3
	v_add_u32_e32 v165, s74, v3
	v_add_u32_e32 v2, v2, v8
	v_mov_b32_e32 v3, v139
	v_lshl_add_u64 v[132:133], v[2:3], 1, s[70:71]
	v_lshlrev_b32_e32 v2, 14, v11
	v_and_b32_e32 v2, 0xffff8000, v2
	v_lshl_add_u32 v2, v12, 11, v2
	v_or_b32_e32 v2, v2, v13
	v_add_u32_e32 v2, v2, v14
	v_lshl_add_u64 v[134:135], v[2:3], 1, s[70:71]
	s_sub_i32 s71, s82, s84
	s_lshl_b32 s82, s83, 5
	s_sub_i32 s71, s71, s82
	s_sext_i32_i8 s71, s71
	s_lshl_b32 s70, s83, 11
	s_lshl_b32 s71, s71, 8
	v_lshlrev_b32_e32 v2, 10, v6
	s_add_i32 s70, s70, s71
	v_lshl_add_u32 v2, v9, 14, v2
	s_ashr_i32 s71, s70, 31
	v_or_b32_e32 v2, v2, v7
	s_waitcnt vmcnt(6)
	s_lshl_b32 s35, s39, 6
	s_lshl_b64 s[70:71], s[70:71], 11
	v_add_u32_e32 v2, v2, v8
	s_and_b32 s35, s35, 0x3000
	s_lshl_b32 s45, s45, 13
	v_lshl_add_u64 v[136:137], v[2:3], 1, s[70:71]
	v_mov_b32_e32 v2, 0
	s_or_b32 s77, s45, 0x800
	s_or_b32 s78, s45, 0x1000
	s_or_b32 s79, s45, 0x1800
	v_lshl_add_u64 v[140:141], s[70:71], 0, v[16:17]
	s_mov_b32 s82, -2
	v_add_u32_e32 v155, s35, v4
	v_add_u32_e32 v154, s45, v10
	v_add_u32_e32 v153, s35, v5
	v_add_u32_e32 v152, s45, v15
	s_mov_b64 s[70:71], s[62:63]
	v_mov_b32_e32 v3, v2
	v_mov_b32_e32 v4, v2
	v_mov_b32_e32 v5, v2
	v_mov_b32_e32 v6, v2
	v_mov_b32_e32 v7, v2
	v_mov_b32_e32 v8, v2
	v_mov_b32_e32 v9, v2
	v_mov_b32_e32 v10, v2
	v_mov_b32_e32 v11, v2
	v_mov_b32_e32 v12, v2
	v_mov_b32_e32 v13, v2
	v_mov_b32_e32 v14, v2
	v_mov_b32_e32 v15, v2
	v_mov_b32_e32 v16, v2
	v_mov_b32_e32 v17, v2
	v_mov_b32_e32 v18, v2
	v_mov_b32_e32 v19, v2
	v_mov_b32_e32 v20, v2
	v_mov_b32_e32 v21, v2
	v_mov_b32_e32 v22, v2
	v_mov_b32_e32 v23, v2
	v_mov_b32_e32 v24, v2
	v_mov_b32_e32 v25, v2
	v_mov_b32_e32 v26, v2
	v_mov_b32_e32 v27, v2
	v_mov_b32_e32 v28, v2
	v_mov_b32_e32 v29, v2
	v_mov_b32_e32 v30, v2
	v_mov_b32_e32 v31, v2
	v_mov_b32_e32 v32, v2
	v_mov_b32_e32 v33, v2
	v_mov_b32_e32 v34, v2
	v_mov_b32_e32 v35, v2
	v_mov_b32_e32 v36, v2
	v_mov_b32_e32 v37, v2
	v_mov_b32_e32 v38, v2
	v_mov_b32_e32 v39, v2
	v_mov_b32_e32 v40, v2
	v_mov_b32_e32 v41, v2
	v_mov_b32_e32 v42, v2
	v_mov_b32_e32 v43, v2
	v_mov_b32_e32 v44, v2
	v_mov_b32_e32 v45, v2
	v_mov_b32_e32 v46, v2
	v_mov_b32_e32 v47, v2
	v_mov_b32_e32 v48, v2
	v_mov_b32_e32 v49, v2
	v_mov_b32_e32 v50, v2
	v_mov_b32_e32 v51, v2
	v_mov_b32_e32 v52, v2
	v_mov_b32_e32 v53, v2
	v_mov_b32_e32 v54, v2
	v_mov_b32_e32 v55, v2
	v_mov_b32_e32 v56, v2
	v_mov_b32_e32 v57, v2
	v_mov_b32_e32 v58, v2
	v_mov_b32_e32 v59, v2
	v_mov_b32_e32 v60, v2
	v_mov_b32_e32 v61, v2
	v_mov_b32_e32 v62, v2
	v_mov_b32_e32 v63, v2
	v_mov_b32_e32 v64, v2
	v_mov_b32_e32 v65, v2
	v_mov_b32_e32 v66, v2
	v_mov_b32_e32 v67, v2
	v_mov_b32_e32 v68, v2
	v_mov_b32_e32 v69, v2
	v_mov_b32_e32 v82, v2
	v_mov_b32_e32 v83, v2
	v_mov_b32_e32 v84, v2
	v_mov_b32_e32 v85, v2
	v_mov_b32_e32 v90, v2
	v_mov_b32_e32 v91, v2
	v_mov_b32_e32 v92, v2
	v_mov_b32_e32 v93, v2
	v_mov_b32_e32 v94, v2
	v_mov_b32_e32 v95, v2
	v_mov_b32_e32 v96, v2
	v_mov_b32_e32 v97, v2
	v_mov_b32_e32 v98, v2
	v_mov_b32_e32 v99, v2
	v_mov_b32_e32 v100, v2
	v_mov_b32_e32 v101, v2
	v_mov_b32_e32 v102, v2
	v_mov_b32_e32 v103, v2
	v_mov_b32_e32 v104, v2
	v_mov_b32_e32 v105, v2
	v_mov_b32_e32 v106, v2
	v_mov_b32_e32 v107, v2
	v_mov_b32_e32 v108, v2
	v_mov_b32_e32 v109, v2
	v_mov_b32_e32 v110, v2
	v_mov_b32_e32 v111, v2
	v_mov_b32_e32 v112, v2
	v_mov_b32_e32 v113, v2
	v_mov_b32_e32 v114, v2
	v_mov_b32_e32 v115, v2
	v_mov_b32_e32 v116, v2
	v_mov_b32_e32 v117, v2
	v_mov_b32_e32 v118, v2
	v_mov_b32_e32 v119, v2
	v_mov_b32_e32 v120, v2
	v_mov_b32_e32 v121, v2
	v_mov_b32_e32 v122, v2
	v_mov_b32_e32 v123, v2
	v_mov_b32_e32 v124, v2
	v_mov_b32_e32 v125, v2
	v_mov_b32_e32 v126, v2
	v_mov_b32_e32 v127, v2
	v_mov_b32_e32 v128, v2
	v_mov_b32_e32 v129, v2
	v_mov_b32_e32 v70, v2
	v_mov_b32_e32 v71, v2
	v_mov_b32_e32 v72, v2
	v_mov_b32_e32 v73, v2
	v_mov_b32_e32 v74, v2
	v_mov_b32_e32 v75, v2
	v_mov_b32_e32 v76, v2
	v_mov_b32_e32 v77, v2
	v_mov_b32_e32 v78, v2
	v_mov_b32_e32 v79, v2
	v_mov_b32_e32 v80, v2
	v_mov_b32_e32 v81, v2
	v_mov_b32_e32 v86, v2
	v_mov_b32_e32 v87, v2
	v_mov_b32_e32 v88, v2
	v_mov_b32_e32 v89, v2
	s_barrier
	v_readfirstlane_b32 s99, v0
	s_nop 3
	s_lshr_b32 s99, s99, 6
	s_cmp_lt_u32 s99, 4
	s_cbranch_scc0 .Lprio_k2
	s_setprio 1
.Lprio_k2:
.LBB0_1043:
	v_add_u32_e32 v170, s35, v162
	ds_read_b128 v[174:177], v170 offset:32768
	ds_read_b128 v[178:181], v170 offset:33792
	ds_read_b128 v[182:185], v170 offset:34816
	ds_read_b128 v[186:189], v170 offset:35840
	v_add_u32_e32 v171, s74, v142
	v_lshl_add_u64 v[224:225], s[70:71], 0, v[136:137]
	v_readfirstlane_b32 s83, v171
	v_add_u32_e32 v166, s45, v162
	v_add_u32_e32 v167, s77, v163
	v_add_u32_e32 v168, s78, v163
	v_add_u32_e32 v169, s79, v163
	v_lshl_add_u64 v[172:173], v[224:225], 0, s[6:7]
	s_mov_b32 m0, s83
	ds_read_b128 v[190:193], v166
	ds_read_b128 v[194:197], v166 offset:1024
	ds_read_b128 v[198:201], v167
	ds_read_b128 v[202:205], v167 offset:1024
	ds_read_b128 v[206:209], v168
	ds_read_b128 v[210:213], v168 offset:1024
	ds_read_b128 v[214:217], v169
	ds_read_b128 v[218:221], v169 offset:1024
	global_load_lds_dwordx4 v[172:173], off
	v_add_u32_e32 v172, 0x2000, v171
	v_lshl_add_u64 v[246:247], s[70:71], 0, v[140:141]
	v_readfirstlane_b32 s83, v172
	v_lshl_add_u64 v[222:223], v[246:247], 0, s[6:7]
	s_mov_b32 m0, s83
	s_nop 0
	global_load_lds_dwordx4 v[222:223], off
	s_waitcnt lgkmcnt(8)
	s_barrier
	s_waitcnt lgkmcnt(0)
	s_waitcnt lgkmcnt(0)
	v_mfma_f32_16x16x32_bf16 v[126:129], v[190:193], v[174:177], v[126:129]
	v_mfma_f32_16x16x32_bf16 v[122:125], v[190:193], v[182:185], v[122:125]
	v_mfma_f32_16x16x32_bf16 v[118:121], v[198:201], v[174:177], v[118:121]
	v_mfma_f32_16x16x32_bf16 v[114:117], v[198:201], v[182:185], v[114:117]
	v_mfma_f32_16x16x32_bf16 v[110:113], v[206:209], v[174:177], v[110:113]
	v_mfma_f32_16x16x32_bf16 v[106:109], v[206:209], v[182:185], v[106:109]
	v_mfma_f32_16x16x32_bf16 v[102:105], v[214:217], v[174:177], v[102:105]
	v_mfma_f32_16x16x32_bf16 v[98:101], v[214:217], v[182:185], v[98:101]
	v_mfma_f32_16x16x32_bf16 v[126:129], v[194:197], v[178:181], v[126:129]
	v_mfma_f32_16x16x32_bf16 v[122:125], v[194:197], v[186:189], v[122:125]
	v_mfma_f32_16x16x32_bf16 v[118:121], v[202:205], v[178:181], v[118:121]
	v_mfma_f32_16x16x32_bf16 v[114:117], v[202:205], v[186:189], v[114:117]
	v_mfma_f32_16x16x32_bf16 v[110:113], v[210:213], v[178:181], v[110:113]
	v_mfma_f32_16x16x32_bf16 v[106:109], v[210:213], v[186:189], v[106:109]
	v_mfma_f32_16x16x32_bf16 v[102:105], v[218:221], v[178:181], v[102:105]
	v_mfma_f32_16x16x32_bf16 v[98:101], v[218:221], v[186:189], v[98:101]
	s_barrier
	v_lshl_add_u64 v[248:249], s[70:71], 0, v[132:133]
	v_readfirstlane_b32 s83, v144
	v_lshl_add_u64 v[222:223], v[248:249], 0, s[8:9]
	s_mov_b32 m0, s83
	v_lshl_add_u64 v[250:251], s[70:71], 0, v[134:135]
	v_readfirstlane_b32 s83, v145
	ds_read_b128 v[226:229], v170 offset:49152
	ds_read_b128 v[230:233], v170 offset:50176
	ds_read_b128 v[234:237], v170 offset:51200
	ds_read_b128 v[238:241], v170 offset:52224
	global_load_lds_dwordx4 v[222:223], off
	v_lshl_add_u64 v[222:223], v[250:251], 0, s[8:9]
	s_mov_b32 m0, s83
	s_nop 0
	global_load_lds_dwordx4 v[222:223], off
	s_barrier
	s_waitcnt lgkmcnt(0)
	s_waitcnt lgkmcnt(0)
	v_mfma_f32_16x16x32_bf16 v[94:97], v[190:193], v[226:229], v[94:97]
	v_mfma_f32_16x16x32_bf16 v[90:93], v[190:193], v[234:237], v[90:93]
	v_mfma_f32_16x16x32_bf16 v[82:85], v[198:201], v[226:229], v[82:85]
	v_mfma_f32_16x16x32_bf16 v[66:69], v[198:201], v[234:237], v[66:69]
	v_mfma_f32_16x16x32_bf16 v[62:65], v[206:209], v[226:229], v[62:65]
	v_mfma_f32_16x16x32_bf16 v[58:61], v[206:209], v[234:237], v[58:61]
	v_mfma_f32_16x16x32_bf16 v[54:57], v[214:217], v[226:229], v[54:57]
	v_mfma_f32_16x16x32_bf16 v[50:53], v[214:217], v[234:237], v[50:53]
	v_mfma_f32_16x16x32_bf16 v[94:97], v[194:197], v[230:233], v[94:97]
	v_mfma_f32_16x16x32_bf16 v[90:93], v[194:197], v[238:241], v[90:93]
	v_mfma_f32_16x16x32_bf16 v[82:85], v[202:205], v[230:233], v[82:85]
	v_mfma_f32_16x16x32_bf16 v[66:69], v[202:205], v[238:241], v[66:69]
	v_mfma_f32_16x16x32_bf16 v[62:65], v[210:213], v[230:233], v[62:65]
	v_mfma_f32_16x16x32_bf16 v[58:61], v[210:213], v[238:241], v[58:61]
	v_mfma_f32_16x16x32_bf16 v[54:57], v[218:221], v[230:233], v[54:57]
	v_mfma_f32_16x16x32_bf16 v[50:53], v[218:221], v[238:241], v[50:53]
	v_readfirstlane_b32 s83, v143
	v_lshl_add_u64 v[222:223], v[224:225], 0, s[10:11]
	s_mov_b32 m0, s83
	v_readfirstlane_b32 s83, v146
	s_barrier
	ds_read_b128 v[190:193], v166 offset:16384
	ds_read_b128 v[194:197], v166 offset:17408
	ds_read_b128 v[198:201], v167 offset:16384
	ds_read_b128 v[202:205], v167 offset:17408
	ds_read_b128 v[206:209], v168 offset:16384
	ds_read_b128 v[210:213], v168 offset:17408
	ds_read_b128 v[214:217], v169 offset:16384
	ds_read_b128 v[218:221], v169 offset:17408
	global_load_lds_dwordx4 v[222:223], off
	v_lshl_add_u64 v[222:223], v[246:247], 0, s[10:11]
	s_mov_b32 m0, s83
	s_nop 0
	global_load_lds_dwordx4 v[222:223], off
	s_barrier
	s_waitcnt lgkmcnt(0)
	s_waitcnt lgkmcnt(0)
	v_mfma_f32_16x16x32_bf16 v[46:49], v[190:193], v[174:177], v[46:49]
	v_mfma_f32_16x16x32_bf16 v[42:45], v[190:193], v[182:185], v[42:45]
	v_mfma_f32_16x16x32_bf16 v[38:41], v[198:201], v[174:177], v[38:41]
	v_mfma_f32_16x16x32_bf16 v[34:37], v[198:201], v[182:185], v[34:37]
	v_mfma_f32_16x16x32_bf16 v[30:33], v[206:209], v[174:177], v[30:33]
	v_mfma_f32_16x16x32_bf16 v[26:29], v[206:209], v[182:185], v[26:29]
	v_mfma_f32_16x16x32_bf16 v[22:25], v[214:217], v[174:177], v[22:25]
	v_mfma_f32_16x16x32_bf16 v[18:21], v[214:217], v[182:185], v[18:21]
	v_mfma_f32_16x16x32_bf16 v[46:49], v[194:197], v[178:181], v[46:49]
	v_mfma_f32_16x16x32_bf16 v[42:45], v[194:197], v[186:189], v[42:45]
	v_mfma_f32_16x16x32_bf16 v[38:41], v[202:205], v[178:181], v[38:41]
	v_mfma_f32_16x16x32_bf16 v[34:37], v[202:205], v[186:189], v[34:37]
	v_mfma_f32_16x16x32_bf16 v[30:33], v[210:213], v[178:181], v[30:33]
	v_mfma_f32_16x16x32_bf16 v[26:29], v[210:213], v[186:189], v[26:29]
	v_mfma_f32_16x16x32_bf16 v[22:25], v[218:221], v[178:181], v[22:25]
	v_mfma_f32_16x16x32_bf16 v[18:21], v[218:221], v[186:189], v[18:21]
	s_barrier
	v_readfirstlane_b32 s83, v147
	v_lshl_add_u64 v[174:175], v[248:249], 0, s[12:13]
	s_mov_b32 m0, s83
	v_readfirstlane_b32 s83, v148
	global_load_lds_dwordx4 v[174:175], off
	v_lshl_add_u64 v[174:175], v[250:251], 0, s[12:13]
	s_mov_b32 m0, s83
	s_nop 0
	global_load_lds_dwordx4 v[174:175], off
	s_waitcnt vmcnt(6)
	s_barrier
	v_mfma_f32_16x16x32_bf16 v[14:17], v[190:193], v[226:229], v[14:17]
	v_mfma_f32_16x16x32_bf16 v[10:13], v[190:193], v[234:237], v[10:13]
	v_mfma_f32_16x16x32_bf16 v[6:9], v[198:201], v[226:229], v[6:9]
	v_mfma_f32_16x16x32_bf16 v[2:5], v[198:201], v[234:237], v[2:5]
	v_mfma_f32_16x16x32_bf16 v[70:73], v[206:209], v[226:229], v[70:73]
	v_mfma_f32_16x16x32_bf16 v[74:77], v[206:209], v[234:237], v[74:77]
	v_mfma_f32_16x16x32_bf16 v[78:81], v[214:217], v[226:229], v[78:81]
	v_mfma_f32_16x16x32_bf16 v[86:89], v[214:217], v[234:237], v[86:89]
	v_mfma_f32_16x16x32_bf16 v[14:17], v[194:197], v[230:233], v[14:17]
	v_mfma_f32_16x16x32_bf16 v[10:13], v[194:197], v[238:241], v[10:13]
	v_mfma_f32_16x16x32_bf16 v[6:9], v[202:205], v[230:233], v[6:9]
	v_mfma_f32_16x16x32_bf16 v[2:5], v[202:205], v[238:241], v[2:5]
	v_mfma_f32_16x16x32_bf16 v[70:73], v[210:213], v[230:233], v[70:73]
	v_mfma_f32_16x16x32_bf16 v[74:77], v[210:213], v[238:241], v[74:77]
	v_mfma_f32_16x16x32_bf16 v[78:81], v[218:221], v[230:233], v[78:81]
	v_mfma_f32_16x16x32_bf16 v[86:89], v[218:221], v[238:241], v[86:89]
	s_barrier
	ds_read_b128 v[180:183], v155
	ds_read_b128 v[184:187], v155 offset:1024
	ds_read_b128 v[188:191], v155 offset:2048
	ds_read_b128 v[192:195], v155 offset:3072
	v_readfirstlane_b32 s83, v149
	v_add_u32_e32 v173, s77, v164
	v_add_u32_e32 v174, s78, v164
	v_add_u32_e32 v175, s79, v164
	v_lshl_add_u64 v[226:227], v[224:225], 0, s[14:15]
	s_mov_b32 m0, s83
	v_readfirstlane_b32 s83, v151
	ds_read_b128 v[176:179], v154
	ds_read_b128 v[196:199], v154 offset:1024
	ds_read_b128 v[200:203], v173
	ds_read_b128 v[204:207], v173 offset:1024
	ds_read_b128 v[208:211], v174
	ds_read_b128 v[212:215], v174 offset:1024
	ds_read_b128 v[216:219], v175
	ds_read_b128 v[220:223], v175 offset:1024
	global_load_lds_dwordx4 v[226:227], off
	v_lshl_add_u64 v[226:227], v[246:247], 0, s[14:15]
	s_mov_b32 m0, s83
	s_nop 0
	global_load_lds_dwordx4 v[226:227], off
	s_waitcnt lgkmcnt(8)
	s_barrier
	s_waitcnt lgkmcnt(0)
	s_waitcnt lgkmcnt(0)
	v_mfma_f32_16x16x32_bf16 v[126:129], v[176:179], v[180:183], v[126:129]
	v_mfma_f32_16x16x32_bf16 v[122:125], v[176:179], v[188:191], v[122:125]
	v_mfma_f32_16x16x32_bf16 v[118:121], v[200:203], v[180:183], v[118:121]
	v_mfma_f32_16x16x32_bf16 v[114:117], v[200:203], v[188:191], v[114:117]
	v_mfma_f32_16x16x32_bf16 v[110:113], v[208:211], v[180:183], v[110:113]
	v_mfma_f32_16x16x32_bf16 v[106:109], v[208:211], v[188:191], v[106:109]
	v_mfma_f32_16x16x32_bf16 v[102:105], v[216:219], v[180:183], v[102:105]
	v_mfma_f32_16x16x32_bf16 v[98:101], v[216:219], v[188:191], v[98:101]
	v_mfma_f32_16x16x32_bf16 v[126:129], v[196:199], v[184:187], v[126:129]
	v_mfma_f32_16x16x32_bf16 v[122:125], v[196:199], v[192:195], v[122:125]
	v_mfma_f32_16x16x32_bf16 v[118:121], v[204:207], v[184:187], v[118:121]
	v_mfma_f32_16x16x32_bf16 v[114:117], v[204:207], v[192:195], v[114:117]
	v_mfma_f32_16x16x32_bf16 v[110:113], v[212:215], v[184:187], v[110:113]
	v_mfma_f32_16x16x32_bf16 v[106:109], v[212:215], v[192:195], v[106:109]
	v_mfma_f32_16x16x32_bf16 v[102:105], v[220:223], v[184:187], v[102:105]
	v_mfma_f32_16x16x32_bf16 v[98:101], v[220:223], v[192:195], v[98:101]
	s_barrier
	v_readfirstlane_b32 s83, v156
	v_lshl_add_u64 v[242:243], v[248:249], 0, s[16:17]
	s_mov_b32 m0, s83
	v_readfirstlane_b32 s83, v157
	ds_read_b128 v[226:229], v153
	ds_read_b128 v[230:233], v153 offset:1024
	ds_read_b128 v[234:237], v153 offset:2048
	ds_read_b128 v[238:241], v153 offset:3072
	global_load_lds_dwordx4 v[242:243], off
	v_lshl_add_u64 v[242:243], v[250:251], 0, s[16:17]
	s_mov_b32 m0, s83
	s_nop 0
	global_load_lds_dwordx4 v[242:243], off
	s_barrier
	s_waitcnt lgkmcnt(0)
	s_waitcnt lgkmcnt(0)
	v_mfma_f32_16x16x32_bf16 v[94:97], v[176:179], v[226:229], v[94:97]
	v_mfma_f32_16x16x32_bf16 v[90:93], v[176:179], v[234:237], v[90:93]
	v_mfma_f32_16x16x32_bf16 v[82:85], v[200:203], v[226:229], v[82:85]
	v_mfma_f32_16x16x32_bf16 v[66:69], v[200:203], v[234:237], v[66:69]
	v_mfma_f32_16x16x32_bf16 v[62:65], v[208:211], v[226:229], v[62:65]
	v_mfma_f32_16x16x32_bf16 v[58:61], v[208:211], v[234:237], v[58:61]
	v_mfma_f32_16x16x32_bf16 v[54:57], v[216:219], v[226:229], v[54:57]
	v_mfma_f32_16x16x32_bf16 v[50:53], v[216:219], v[234:237], v[50:53]
	v_mfma_f32_16x16x32_bf16 v[94:97], v[196:199], v[230:233], v[94:97]
	v_mfma_f32_16x16x32_bf16 v[90:93], v[196:199], v[238:241], v[90:93]
	v_mfma_f32_16x16x32_bf16 v[82:85], v[204:207], v[230:233], v[82:85]
	v_mfma_f32_16x16x32_bf16 v[66:69], v[204:207], v[238:241], v[66:69]
	v_mfma_f32_16x16x32_bf16 v[62:65], v[212:215], v[230:233], v[62:65]
	v_mfma_f32_16x16x32_bf16 v[58:61], v[212:215], v[238:241], v[58:61]
	v_mfma_f32_16x16x32_bf16 v[54:57], v[220:223], v[230:233], v[54:57]
	v_mfma_f32_16x16x32_bf16 v[50:53], v[220:223], v[238:241], v[50:53]
	v_readfirstlane_b32 s83, v158
	v_add_u32_e32 v176, s77, v165
	v_add_u32_e32 v177, s78, v165
	v_add_u32_e32 v178, s79, v165
	v_lshl_add_u64 v[224:225], v[224:225], 0, s[18:19]
	s_mov_b32 m0, s83
	v_readfirstlane_b32 s83, v159
	s_barrier
	ds_read_b128 v[196:199], v152
	ds_read_b128 v[200:203], v152 offset:1024
	ds_read_b128 v[204:207], v176
	ds_read_b128 v[208:211], v176 offset:1024
	ds_read_b128 v[212:215], v177
	ds_read_b128 v[216:219], v177 offset:1024
	ds_read_b128 v[220:223], v178
	ds_read_b128 v[242:245], v178 offset:1024
	global_load_lds_dwordx4 v[224:225], off
	v_lshl_add_u64 v[224:225], v[246:247], 0, s[18:19]
	s_mov_b32 m0, s83
	s_nop 0
	global_load_lds_dwordx4 v[224:225], off
	s_barrier
	s_waitcnt lgkmcnt(0)
	s_waitcnt lgkmcnt(0)
	v_mfma_f32_16x16x32_bf16 v[46:49], v[196:199], v[180:183], v[46:49]
	v_mfma_f32_16x16x32_bf16 v[42:45], v[196:199], v[188:191], v[42:45]
	v_mfma_f32_16x16x32_bf16 v[38:41], v[204:207], v[180:183], v[38:41]
	v_mfma_f32_16x16x32_bf16 v[34:37], v[204:207], v[188:191], v[34:37]
	v_mfma_f32_16x16x32_bf16 v[30:33], v[212:215], v[180:183], v[30:33]
	v_mfma_f32_16x16x32_bf16 v[26:29], v[212:215], v[188:191], v[26:29]
	v_mfma_f32_16x16x32_bf16 v[22:25], v[220:223], v[180:183], v[22:25]
	v_mfma_f32_16x16x32_bf16 v[18:21], v[220:223], v[188:191], v[18:21]
	v_mfma_f32_16x16x32_bf16 v[46:49], v[200:203], v[184:187], v[46:49]
	v_mfma_f32_16x16x32_bf16 v[42:45], v[200:203], v[192:195], v[42:45]
	v_mfma_f32_16x16x32_bf16 v[38:41], v[208:211], v[184:187], v[38:41]
	v_mfma_f32_16x16x32_bf16 v[34:37], v[208:211], v[192:195], v[34:37]
	v_mfma_f32_16x16x32_bf16 v[30:33], v[216:219], v[184:187], v[30:33]
	v_mfma_f32_16x16x32_bf16 v[26:29], v[216:219], v[192:195], v[26:29]
	v_mfma_f32_16x16x32_bf16 v[22:25], v[242:245], v[184:187], v[22:25]
	v_mfma_f32_16x16x32_bf16 v[18:21], v[242:245], v[192:195], v[18:21]
	s_barrier
	v_readfirstlane_b32 s83, v160
	v_lshl_add_u64 v[180:181], v[248:249], 0, s[20:21]
	s_mov_b32 m0, s83
	v_readfirstlane_b32 s83, v161
	global_load_lds_dwordx4 v[180:181], off
	v_lshl_add_u64 v[180:181], v[250:251], 0, s[20:21]
	s_mov_b32 m0, s83
	s_nop 0
	global_load_lds_dwordx4 v[180:181], off
	s_waitcnt vmcnt(6)
	s_barrier
	v_mfma_f32_16x16x32_bf16 v[14:17], v[196:199], v[226:229], v[14:17]
	v_mfma_f32_16x16x32_bf16 v[10:13], v[196:199], v[234:237], v[10:13]
	v_mfma_f32_16x16x32_bf16 v[6:9], v[204:207], v[226:229], v[6:9]
	v_mfma_f32_16x16x32_bf16 v[2:5], v[204:207], v[234:237], v[2:5]
	v_mfma_f32_16x16x32_bf16 v[70:73], v[212:215], v[226:229], v[70:73]
	v_mfma_f32_16x16x32_bf16 v[74:77], v[212:215], v[234:237], v[74:77]
	v_mfma_f32_16x16x32_bf16 v[78:81], v[220:223], v[226:229], v[78:81]
	v_mfma_f32_16x16x32_bf16 v[86:89], v[220:223], v[234:237], v[86:89]
	v_mfma_f32_16x16x32_bf16 v[14:17], v[200:203], v[230:233], v[14:17]
	v_mfma_f32_16x16x32_bf16 v[10:13], v[200:203], v[238:241], v[10:13]
	v_mfma_f32_16x16x32_bf16 v[6:9], v[208:211], v[230:233], v[6:9]
	v_mfma_f32_16x16x32_bf16 v[2:5], v[208:211], v[238:241], v[2:5]
	v_mfma_f32_16x16x32_bf16 v[70:73], v[216:219], v[230:233], v[70:73]
	v_mfma_f32_16x16x32_bf16 v[74:77], v[216:219], v[238:241], v[74:77]
	v_mfma_f32_16x16x32_bf16 v[78:81], v[242:245], v[230:233], v[78:81]
	v_mfma_f32_16x16x32_bf16 v[86:89], v[242:245], v[238:241], v[86:89]
	s_add_i32 s82, s82, 2
	s_add_u32 s70, s70, 0x100
	s_addc_u32 s71, s71, 0
	s_cmp_lt_u32 s82, 12
	s_barrier
	s_cbranch_scc1 .LBB0_1043
	s_or_b32 s70, s34, 0x80
	s_ashr_i32 s71, s70, 31
	s_lshl_b64 s[78:79], s[70:71], 11
	s_add_u32 s78, s94, s78
	s_addc_u32 s79, s95, s79
	v_lshl_add_u64 v[136:137], v[138:139], 1, s[78:79]
	v_readfirstlane_b32 s35, v171
	v_lshl_add_u64 v[136:137], v[136:137], 0, s[22:23]
	s_mov_b32 m0, s35
	v_lshl_add_u64 v[130:131], v[130:131], 1, s[78:79]
	v_readfirstlane_b32 s35, v172
	ds_read_b128 v[132:135], v170 offset:32768
	ds_read_b128 v[140:143], v170 offset:33792
	ds_read_b128 v[144:147], v170 offset:34816
	ds_read_b128 v[156:159], v170 offset:35840
	ds_read_b128 v[160:163], v166
	ds_read_b128 v[180:183], v166 offset:1024
	ds_read_b128 v[184:187], v167
	ds_read_b128 v[188:191], v167 offset:1024
	ds_read_b128 v[192:195], v168
	ds_read_b128 v[196:199], v168 offset:1024
	ds_read_b128 v[200:203], v169
	ds_read_b128 v[204:207], v169 offset:1024
	global_load_lds_dwordx4 v[136:137], off
	v_lshl_add_u64 v[130:131], v[130:131], 0, s[22:23]
	s_mov_b32 m0, s35
	s_nop 0
	global_load_lds_dwordx4 v[130:131], off
	s_barrier
	s_waitcnt lgkmcnt(0)
	s_waitcnt lgkmcnt(0)
	v_mfma_f32_16x16x32_bf16 v[126:129], v[160:163], v[132:135], v[126:129]
	v_mfma_f32_16x16x32_bf16 v[122:125], v[160:163], v[144:147], v[122:125]
	v_mfma_f32_16x16x32_bf16 v[118:121], v[184:187], v[132:135], v[118:121]
	v_mfma_f32_16x16x32_bf16 v[114:117], v[184:187], v[144:147], v[114:117]
	v_mfma_f32_16x16x32_bf16 v[110:113], v[192:195], v[132:135], v[110:113]
	v_mfma_f32_16x16x32_bf16 v[126:129], v[180:183], v[140:143], v[126:129]
	v_mfma_f32_16x16x32_bf16 v[122:125], v[180:183], v[156:159], v[122:125]
	v_mfma_f32_16x16x32_bf16 v[118:121], v[188:191], v[140:143], v[118:121]
	v_mfma_f32_16x16x32_bf16 v[114:117], v[188:191], v[156:159], v[114:117]
	v_mfma_f32_16x16x32_bf16 v[110:113], v[196:199], v[140:143], v[110:113]
	v_mfma_f32_16x16x32_bf16 v[106:109], v[192:195], v[144:147], v[106:109]
	v_mfma_f32_16x16x32_bf16 v[102:105], v[200:203], v[132:135], v[102:105]
	v_mfma_f32_16x16x32_bf16 v[98:101], v[200:203], v[144:147], v[98:101]
	v_mfma_f32_16x16x32_bf16 v[208:211], v[196:199], v[156:159], v[106:109]
	v_mfma_f32_16x16x32_bf16 v[212:215], v[204:207], v[140:143], v[102:105]
	v_mfma_f32_16x16x32_bf16 v[216:219], v[204:207], v[156:159], v[98:101]
	s_barrier
	s_nop 2
	ds_read_b128 v[98:101], v170 offset:49152
	ds_read_b128 v[102:105], v170 offset:50176
	ds_read_b128 v[106:109], v170 offset:51200
	ds_read_b128 v[220:223], v170 offset:52224
	s_barrier
	s_waitcnt lgkmcnt(0)
	s_waitcnt lgkmcnt(0)
	v_mfma_f32_16x16x32_bf16 v[94:97], v[160:163], v[98:101], v[94:97]
	v_mfma_f32_16x16x32_bf16 v[90:93], v[160:163], v[106:109], v[90:93]
	v_mfma_f32_16x16x32_bf16 v[82:85], v[184:187], v[98:101], v[82:85]
	v_mfma_f32_16x16x32_bf16 v[62:65], v[192:195], v[98:101], v[62:65]
	v_mfma_f32_16x16x32_bf16 v[58:61], v[192:195], v[106:109], v[58:61]
	v_mfma_f32_16x16x32_bf16 v[54:57], v[200:203], v[98:101], v[54:57]
	v_mfma_f32_16x16x32_bf16 v[50:53], v[200:203], v[106:109], v[50:53]
	v_mfma_f32_16x16x32_bf16 v[94:97], v[180:183], v[102:105], v[94:97]
	v_mfma_f32_16x16x32_bf16 v[90:93], v[180:183], v[220:223], v[90:93]
	v_mfma_f32_16x16x32_bf16 v[82:85], v[188:191], v[102:105], v[82:85]
	v_mfma_f32_16x16x32_bf16 v[66:69], v[184:187], v[106:109], v[66:69]
	v_mfma_f32_16x16x32_bf16 v[62:65], v[196:199], v[102:105], v[62:65]
	v_mfma_f32_16x16x32_bf16 v[58:61], v[196:199], v[220:223], v[58:61]
	v_mfma_f32_16x16x32_bf16 v[54:57], v[204:207], v[102:105], v[54:57]
	v_mfma_f32_16x16x32_bf16 v[50:53], v[204:207], v[220:223], v[50:53]
	v_mfma_f32_16x16x32_bf16 v[160:163], v[188:191], v[220:223], v[66:69]
	s_barrier
	s_nop 0
	ds_read_b128 v[66:69], v166 offset:16384
	ds_read_b128 v[180:183], v166 offset:17408
	ds_read_b128 v[184:187], v167 offset:16384
	ds_read_b128 v[164:167], v167 offset:17408
	ds_read_b128 v[188:191], v168 offset:16384
	ds_read_b128 v[192:195], v168 offset:17408
	ds_read_b128 v[196:199], v169 offset:16384
	ds_read_b128 v[168:171], v169 offset:17408
	s_waitcnt vmcnt(4)
	s_barrier
	s_waitcnt lgkmcnt(0)
	s_waitcnt lgkmcnt(0)
	v_mfma_f32_16x16x32_bf16 v[46:49], v[66:69], v[132:135], v[46:49]
	v_mfma_f32_16x16x32_bf16 v[42:45], v[66:69], v[144:147], v[42:45]
	v_mfma_f32_16x16x32_bf16 v[30:33], v[188:191], v[132:135], v[30:33]
	v_mfma_f32_16x16x32_bf16 v[26:29], v[188:191], v[144:147], v[26:29]
	v_mfma_f32_16x16x32_bf16 v[22:25], v[196:199], v[132:135], v[22:25]
	v_mfma_f32_16x16x32_bf16 v[18:21], v[196:199], v[144:147], v[18:21]
	v_mfma_f32_16x16x32_bf16 v[46:49], v[180:183], v[140:143], v[46:49]
	v_mfma_f32_16x16x32_bf16 v[42:45], v[180:183], v[156:159], v[42:45]
	v_mfma_f32_16x16x32_bf16 v[38:41], v[184:187], v[132:135], v[38:41]
	v_mfma_f32_16x16x32_bf16 v[34:37], v[184:187], v[144:147], v[34:37]
	v_mfma_f32_16x16x32_bf16 v[30:33], v[192:195], v[140:143], v[30:33]
	v_mfma_f32_16x16x32_bf16 v[26:29], v[192:195], v[156:159], v[26:29]
	v_mfma_f32_16x16x32_bf16 v[22:25], v[168:171], v[140:143], v[22:25]
	v_mfma_f32_16x16x32_bf16 v[18:21], v[168:171], v[156:159], v[18:21]
	v_mfma_f32_16x16x32_bf16 v[200:203], v[164:167], v[140:143], v[38:41]
	v_mfma_f32_16x16x32_bf16 v[204:207], v[164:167], v[156:159], v[34:37]
	v_mfma_f32_16x16x32_bf16 v[2:5], v[184:187], v[106:109], v[2:5]
	v_mfma_f32_16x16x32_bf16 v[134:137], v[164:167], v[220:223], v[2:5]
	v_mfma_f32_16x16x32_bf16 v[2:5], v[188:191], v[98:101], v[70:73]
	v_mfma_f32_16x16x32_bf16 v[140:143], v[192:195], v[102:105], v[2:5]
	v_mfma_f32_16x16x32_bf16 v[2:5], v[188:191], v[106:109], v[74:77]
	v_mfma_f32_16x16x32_bf16 v[14:17], v[66:69], v[98:101], v[14:17]
	v_mfma_f32_16x16x32_bf16 v[10:13], v[66:69], v[106:109], v[10:13]
	v_mfma_f32_16x16x32_bf16 v[144:147], v[192:195], v[220:223], v[2:5]
	v_mfma_f32_16x16x32_bf16 v[2:5], v[196:199], v[98:101], v[78:81]
	v_mfma_f32_16x16x32_bf16 v[14:17], v[180:183], v[102:105], v[14:17]
	v_mfma_f32_16x16x32_bf16 v[10:13], v[180:183], v[220:223], v[10:13]
	v_mfma_f32_16x16x32_bf16 v[6:9], v[184:187], v[98:101], v[6:9]
	v_mfma_f32_16x16x32_bf16 v[156:159], v[168:171], v[102:105], v[2:5]
	v_mfma_f32_16x16x32_bf16 v[2:5], v[196:199], v[106:109], v[86:89]
	v_mfma_f32_16x16x32_bf16 v[130:133], v[164:167], v[102:105], v[6:9]
	v_mfma_f32_16x16x32_bf16 v[164:167], v[168:171], v[220:223], v[2:5]
	s_barrier
	s_nop 3
	ds_read_b128 v[2:5], v155
	ds_read_b128 v[6:9], v155 offset:1024
	ds_read_b128 v[168:171], v155 offset:2048
	ds_read_b128 v[180:183], v155 offset:3072
	ds_read_b128 v[34:37], v154
	ds_read_b128 v[38:41], v154 offset:1024
	ds_read_b128 v[78:81], v173
	ds_read_b128 v[86:89], v173 offset:1024
	ds_read_b128 v[184:187], v174
	ds_read_b128 v[188:191], v174 offset:1024
	ds_read_b128 v[192:195], v175
	ds_read_b128 v[172:175], v175 offset:1024
	s_waitcnt vmcnt(2)
	s_barrier
	s_waitcnt lgkmcnt(0)
	s_waitcnt lgkmcnt(0)
	v_mfma_f32_16x16x32_bf16 v[66:69], v[34:37], v[2:5], v[126:129]
	v_mfma_f32_16x16x32_bf16 v[126:129], v[38:41], v[6:9], v[66:69]
	v_mfma_f32_16x16x32_bf16 v[66:69], v[34:37], v[168:171], v[122:125]
	v_mfma_f32_16x16x32_bf16 v[98:101], v[38:41], v[180:183], v[66:69]
	v_mfma_f32_16x16x32_bf16 v[66:69], v[78:81], v[2:5], v[118:121]
	v_mfma_f32_16x16x32_bf16 v[102:105], v[86:89], v[6:9], v[66:69]
	v_mfma_f32_16x16x32_bf16 v[66:69], v[78:81], v[168:171], v[114:117]
	v_mfma_f32_16x16x32_bf16 v[106:109], v[86:89], v[180:183], v[66:69]
	v_mfma_f32_16x16x32_bf16 v[66:69], v[184:187], v[2:5], v[110:113]
	v_mfma_f32_16x16x32_bf16 v[110:113], v[188:191], v[6:9], v[66:69]
	v_mfma_f32_16x16x32_bf16 v[66:69], v[184:187], v[168:171], v[208:211]
	v_mfma_f32_16x16x32_bf16 v[114:117], v[188:191], v[180:183], v[66:69]
	v_mfma_f32_16x16x32_bf16 v[66:69], v[192:195], v[2:5], v[212:215]
	v_mfma_f32_16x16x32_bf16 v[118:121], v[172:175], v[6:9], v[66:69]
	v_mfma_f32_16x16x32_bf16 v[66:69], v[192:195], v[168:171], v[216:219]
	v_mfma_f32_16x16x32_bf16 v[122:125], v[172:175], v[180:183], v[66:69]
	s_barrier
	ds_read_b128 v[196:199], v153
	ds_read_b128 v[208:211], v153 offset:1024
	ds_read_b128 v[212:215], v153 offset:2048
	ds_read_b128 v[216:219], v153 offset:3072
	s_waitcnt vmcnt(0)
	s_barrier
	s_waitcnt lgkmcnt(0)
	s_waitcnt lgkmcnt(0)
	v_mfma_f32_16x16x32_bf16 v[66:69], v[34:37], v[196:199], v[94:97]
	v_mfma_f32_16x16x32_bf16 v[34:37], v[34:37], v[212:215], v[90:93]
	v_mfma_f32_16x16x32_bf16 v[70:73], v[38:41], v[216:219], v[34:37]
	v_mfma_f32_16x16x32_bf16 v[34:37], v[78:81], v[196:199], v[82:85]
	v_mfma_f32_16x16x32_bf16 v[74:77], v[86:89], v[208:211], v[34:37]
	v_mfma_f32_16x16x32_bf16 v[34:37], v[78:81], v[212:215], v[160:163]
	v_mfma_f32_16x16x32_bf16 v[78:81], v[86:89], v[216:219], v[34:37]
	v_mfma_f32_16x16x32_bf16 v[34:37], v[184:187], v[196:199], v[62:65]
	v_mfma_f32_16x16x32_bf16 v[82:85], v[188:191], v[208:211], v[34:37]
	v_mfma_f32_16x16x32_bf16 v[34:37], v[184:187], v[212:215], v[58:61]
	v_mfma_f32_16x16x32_bf16 v[86:89], v[188:191], v[216:219], v[34:37]
	v_mfma_f32_16x16x32_bf16 v[34:37], v[192:195], v[196:199], v[54:57]
	v_mfma_f32_16x16x32_bf16 v[90:93], v[172:175], v[208:211], v[34:37]
	v_mfma_f32_16x16x32_bf16 v[34:37], v[192:195], v[212:215], v[50:53]
	v_mfma_f32_16x16x32_bf16 v[66:69], v[38:41], v[208:211], v[66:69]
	v_mfma_f32_16x16x32_bf16 v[94:97], v[172:175], v[216:219], v[34:37]
	s_barrier
	ds_read_b128 v[160:163], v152
	ds_read_b128 v[152:155], v152 offset:1024
	ds_read_b128 v[172:175], v176
	ds_read_b128 v[184:187], v176 offset:1024
	ds_read_b128 v[188:191], v177
	ds_read_b128 v[192:195], v177 offset:1024
	ds_read_b128 v[220:223], v178
	ds_read_b128 v[176:179], v178 offset:1024
	s_barrier
	s_waitcnt lgkmcnt(0)
	s_waitcnt lgkmcnt(0)
	v_mfma_f32_16x16x32_bf16 v[34:37], v[160:163], v[2:5], v[46:49]
	v_mfma_f32_16x16x32_bf16 v[38:41], v[160:163], v[168:171], v[42:45]
	v_mfma_f32_16x16x32_bf16 v[42:45], v[172:175], v[2:5], v[200:203]
	v_mfma_f32_16x16x32_bf16 v[30:33], v[188:191], v[2:5], v[30:33]
	v_mfma_f32_16x16x32_bf16 v[2:5], v[220:223], v[2:5], v[22:25]
	v_mfma_f32_16x16x32_bf16 v[46:49], v[172:175], v[168:171], v[204:207]
	v_mfma_f32_16x16x32_bf16 v[26:29], v[188:191], v[168:171], v[26:29]
	v_mfma_f32_16x16x32_bf16 v[58:61], v[176:179], v[6:9], v[2:5]
	v_mfma_f32_16x16x32_bf16 v[2:5], v[220:223], v[168:171], v[18:21]
	v_mfma_f32_16x16x32_bf16 v[34:37], v[152:155], v[6:9], v[34:37]
	v_mfma_f32_16x16x32_bf16 v[38:41], v[152:155], v[180:183], v[38:41]
	v_mfma_f32_16x16x32_bf16 v[42:45], v[184:187], v[6:9], v[42:45]
	v_mfma_f32_16x16x32_bf16 v[46:49], v[184:187], v[180:183], v[46:49]
	v_mfma_f32_16x16x32_bf16 v[50:53], v[192:195], v[6:9], v[30:33]
	v_mfma_f32_16x16x32_bf16 v[54:57], v[192:195], v[180:183], v[26:29]
	v_mfma_f32_16x16x32_bf16 v[62:65], v[176:179], v[180:183], v[2:5]
	v_mfma_f32_16x16x32_bf16 v[2:5], v[160:163], v[196:199], v[14:17]
	v_mfma_f32_16x16x32_bf16 v[6:9], v[160:163], v[212:215], v[10:13]
	v_mfma_f32_16x16x32_bf16 v[10:13], v[172:175], v[196:199], v[130:133]
	v_mfma_f32_16x16x32_bf16 v[14:17], v[172:175], v[212:215], v[134:137]
	v_mfma_f32_16x16x32_bf16 v[18:21], v[188:191], v[196:199], v[140:143]
	v_mfma_f32_16x16x32_bf16 v[22:25], v[188:191], v[212:215], v[144:147]
	v_mfma_f32_16x16x32_bf16 v[26:29], v[220:223], v[196:199], v[156:159]
	v_mfma_f32_16x16x32_bf16 v[30:33], v[220:223], v[212:215], v[164:167]
	v_mfma_f32_16x16x32_bf16 v[2:5], v[152:155], v[208:211], v[2:5]
	v_mfma_f32_16x16x32_bf16 v[6:9], v[152:155], v[216:219], v[6:9]
	v_mfma_f32_16x16x32_bf16 v[10:13], v[184:187], v[208:211], v[10:13]
	v_mfma_f32_16x16x32_bf16 v[14:17], v[184:187], v[216:219], v[14:17]
	v_mfma_f32_16x16x32_bf16 v[18:21], v[192:195], v[208:211], v[18:21]
	v_mfma_f32_16x16x32_bf16 v[22:25], v[192:195], v[216:219], v[22:25]
	v_mfma_f32_16x16x32_bf16 v[26:29], v[176:179], v[208:211], v[26:29]
	v_mfma_f32_16x16x32_bf16 v[30:33], v[176:179], v[216:219], v[30:33]
	s_setprio 0
	s_cmpk_gt_u32 s39, 0xff
	s_barrier
	s_cbranch_scc1 .LBB0_1046
	s_barrier

.LBB0_1174:
	s_ashr_i32 s37, s36, 31
	s_lshl_b64 s[0:1], s[36:37], 11
	s_add_u32 s46, s40, s0
	s_addc_u32 s47, s41, s1
	v_add_u32_e32 v155, s33, v142
	v_lshlrev_b64 v[12:13], 1, v[130:131]
	v_lshl_add_u64 v[14:15], s[46:47], 0, v[12:13]
	v_readfirstlane_b32 s35, v155
	v_add_u32_e32 v156, 0x2000, v155
	v_lshl_add_u64 v[14:15], v[14:15], 0, s[2:3]
	s_mov_b32 m0, s35
	v_mov_b32_e32 v133, v131
	v_readfirstlane_b32 s35, v156
	s_barrier
	global_load_lds_dwordx4 v[14:15], off
	v_lshlrev_b64 v[14:15], 1, v[132:133]
	s_mov_b32 m0, s35
	s_ashr_i32 s35, s34, 31
	v_lshl_add_u64 v[16:17], s[46:47], 0, v[14:15]
	s_lshl_b64 s[46:47], s[34:35], 11
	s_add_u32 s46, s60, s46
	v_lshl_add_u64 v[16:17], v[16:17], 0, s[2:3]
	s_addc_u32 s47, s61, s47
	v_add_u32_e32 v157, s64, v142
	global_load_lds_dwordx4 v[16:17], off
	v_lshl_add_u64 v[16:17], s[46:47], 0, v[12:13]
	v_readfirstlane_b32 s35, v157
	s_bitset1_b32 s36, 7
	v_lshl_add_u64 v[16:17], v[16:17], 0, s[2:3]
	s_mov_b32 m0, s35
	s_ashr_i32 s37, s36, 31
	global_load_lds_dwordx4 v[16:17], off
	v_lshl_add_u64 v[16:17], s[46:47], 0, v[14:15]
	s_lshl_b64 s[46:47], s[36:37], 11
	v_add_u32_e32 v158, 0x2000, v157
	s_add_u32 s46, s40, s46
	v_readfirstlane_b32 s35, v158
	s_addc_u32 s47, s41, s47
	v_add_u32_e32 v159, s65, v142
	v_lshl_add_u64 v[16:17], v[16:17], 0, s[2:3]
	s_mov_b32 m0, s35
	v_lshl_add_u64 v[12:13], s[46:47], 0, v[12:13]
	v_readfirstlane_b32 s35, v159
	global_load_lds_dwordx4 v[16:17], off
	v_lshl_add_u64 v[12:13], v[12:13], 0, s[2:3]
	s_mov_b32 m0, s35
	v_add_u32_e32 v160, 0x2000, v159
	global_load_lds_dwordx4 v[12:13], off
	v_lshl_add_u64 v[12:13], s[46:47], 0, v[14:15]
	v_readfirstlane_b32 s35, v160
	v_lshl_add_u64 v[12:13], v[12:13], 0, s[2:3]
	s_mov_b32 m0, s35
	v_lshlrev_b32_e32 v2, 13, v2
	global_load_lds_dwordx4 v[12:13], off
	v_and_b32_e32 v2, 0xffffc000, v2
	v_lshl_add_u32 v2, v4, 10, v2
	v_lshlrev_b32_e32 v4, 13, v6
	v_and_b32_e32 v11, 15, v3
	v_and_b32_e32 v18, 48, v3
	v_lshlrev_b32_e32 v12, 2, v3
	v_lshlrev_b32_e32 v3, 6, v3
	v_and_b32_e32 v4, 0xffffc000, v4
	v_and_b32_e32 v12, 32, v12
	s_lshl_b32 s35, s39, 6
	s_lshl_b32 s37, s43, 13
	v_and_b32_e32 v3, 0x3c0, v3
	v_lshl_add_u32 v4, v8, 10, v4
	s_and_b32 s35, s35, 0x3000
	v_bitop3_b32 v3, v3, v12, v18 bitop3:0x36
	s_or_b32 s43, s37, 0x800
	s_or_b32 s46, s37, 0x1000
	s_or_b32 s47, s37, 0x1800
	v_or_b32_e32 v2, v2, v5
	v_or_b32_e32 v4, v4, v9
	v_add_u32_e32 v162, 0, v3
	v_add_u32_e32 v163, s64, v3
	v_add_u32_e32 v164, s70, v3
	v_add_u32_sdwa v2, v2, sext(v7) dst_sel:DWORD dst_unused:UNUSED_PAD src0_sel:DWORD src1_sel:WORD_0
	v_mov_b32_e32 v3, v131
	s_add_u32 s0, s62, s0
	v_add_u32_sdwa v4, v4, sext(v10) dst_sel:DWORD dst_unused:UNUSED_PAD src0_sel:DWORD src1_sel:WORD_0
	v_mov_b32_e32 v5, v131
	v_lshlrev_b64 v[2:3], 1, v[2:3]
	s_addc_u32 s1, s63, s1
	v_lshlrev_b64 v[4:5], 1, v[4:5]
	v_lshl_add_u64 v[134:135], s[0:1], 0, v[2:3]
	v_lshl_add_u64 v[136:137], s[0:1], 0, v[4:5]
	s_sub_i32 s1, s74, s77
	s_sub_i32 s1, s1, s76
	s_sext_i32_i16 s1, s1
	s_lshl_b32 s0, s75, 11
	s_lshl_b32 s1, s1, 8
	s_add_i32 s0, s0, s1
	s_ashr_i32 s1, s0, 31
	s_lshl_b64 s[0:1], s[0:1], 11
	v_lshlrev_b32_e32 v11, 6, v11
	s_add_u32 s0, s60, s0
	s_waitcnt vmcnt(6)
	v_bitop3_b32 v11, v11, v12, v18 bitop3:0x36
	s_addc_u32 s1, s61, s1
	v_add_u32_e32 v161, 0, v11
	v_add_u32_e32 v13, s33, v11
	v_add_u32_e32 v14, s65, v11
	v_add_u32_e32 v12, s64, v11
	v_add_u32_e32 v11, s70, v11
	v_lshl_add_u64 v[138:139], s[0:1], 0, v[2:3]
	v_mov_b32_e32 v2, 0
	v_lshl_add_u64 v[140:141], s[0:1], 0, v[4:5]
	s_mov_b32 s74, -2
	s_mov_b64 s[0:1], 0
	v_add_u32_e32 v154, s35, v13
	v_add_u32_e32 v153, s37, v12
	v_add_u32_e32 v152, s35, v14
	v_add_u32_e32 v151, s37, v11
	v_mov_b32_e32 v3, v2
	v_mov_b32_e32 v4, v2
	v_mov_b32_e32 v5, v2
	v_mov_b32_e32 v6, v2
	v_mov_b32_e32 v7, v2
	v_mov_b32_e32 v8, v2
	v_mov_b32_e32 v9, v2
	v_mov_b32_e32 v10, v2
	v_mov_b32_e32 v11, v2
	v_mov_b32_e32 v12, v2
	v_mov_b32_e32 v13, v2
	v_mov_b32_e32 v14, v2
	v_mov_b32_e32 v15, v2
	v_mov_b32_e32 v16, v2
	v_mov_b32_e32 v17, v2
	v_mov_b32_e32 v18, v2
	v_mov_b32_e32 v19, v2
	v_mov_b32_e32 v20, v2
	v_mov_b32_e32 v21, v2
	v_mov_b32_e32 v22, v2
	v_mov_b32_e32 v23, v2
	v_mov_b32_e32 v24, v2
	v_mov_b32_e32 v25, v2
	v_mov_b32_e32 v26, v2
	v_mov_b32_e32 v27, v2
	v_mov_b32_e32 v28, v2
	v_mov_b32_e32 v29, v2
	v_mov_b32_e32 v30, v2
	v_mov_b32_e32 v31, v2
	v_mov_b32_e32 v32, v2
	v_mov_b32_e32 v33, v2
	v_mov_b32_e32 v34, v2
	v_mov_b32_e32 v35, v2
	v_mov_b32_e32 v36, v2
	v_mov_b32_e32 v37, v2
	v_mov_b32_e32 v38, v2
	v_mov_b32_e32 v39, v2
	v_mov_b32_e32 v40, v2
	v_mov_b32_e32 v41, v2
	v_mov_b32_e32 v42, v2
	v_mov_b32_e32 v43, v2
	v_mov_b32_e32 v44, v2
	v_mov_b32_e32 v45, v2
	v_mov_b32_e32 v46, v2
	v_mov_b32_e32 v47, v2
	v_mov_b32_e32 v48, v2
	v_mov_b32_e32 v49, v2
	v_mov_b32_e32 v50, v2
	v_mov_b32_e32 v51, v2
	v_mov_b32_e32 v52, v2
	v_mov_b32_e32 v53, v2
	v_mov_b32_e32 v54, v2
	v_mov_b32_e32 v55, v2
	v_mov_b32_e32 v56, v2
	v_mov_b32_e32 v57, v2
	v_mov_b32_e32 v58, v2
	v_mov_b32_e32 v59, v2
	v_mov_b32_e32 v60, v2
	v_mov_b32_e32 v61, v2
	v_mov_b32_e32 v62, v2
	v_mov_b32_e32 v63, v2
	v_mov_b32_e32 v64, v2
	v_mov_b32_e32 v65, v2
	v_mov_b32_e32 v66, v2
	v_mov_b32_e32 v67, v2
	v_mov_b32_e32 v68, v2
	v_mov_b32_e32 v69, v2
	v_mov_b32_e32 v82, v2
	v_mov_b32_e32 v83, v2
	v_mov_b32_e32 v84, v2
	v_mov_b32_e32 v85, v2
	v_mov_b32_e32 v90, v2
	v_mov_b32_e32 v91, v2
	v_mov_b32_e32 v92, v2
	v_mov_b32_e32 v93, v2
	v_mov_b32_e32 v94, v2
	v_mov_b32_e32 v95, v2
	v_mov_b32_e32 v96, v2
	v_mov_b32_e32 v97, v2
	v_mov_b32_e32 v98, v2
	v_mov_b32_e32 v99, v2
	v_mov_b32_e32 v100, v2
	v_mov_b32_e32 v101, v2
	v_mov_b32_e32 v102, v2
	v_mov_b32_e32 v103, v2
	v_mov_b32_e32 v104, v2
	v_mov_b32_e32 v105, v2
	v_mov_b32_e32 v106, v2
	v_mov_b32_e32 v107, v2
	v_mov_b32_e32 v108, v2
	v_mov_b32_e32 v109, v2
	v_mov_b32_e32 v110, v2
	v_mov_b32_e32 v111, v2
	v_mov_b32_e32 v112, v2
	v_mov_b32_e32 v113, v2
	v_mov_b32_e32 v114, v2
	v_mov_b32_e32 v115, v2
	v_mov_b32_e32 v116, v2
	v_mov_b32_e32 v117, v2
	v_mov_b32_e32 v118, v2
	v_mov_b32_e32 v119, v2
	v_mov_b32_e32 v120, v2
	v_mov_b32_e32 v121, v2
	v_mov_b32_e32 v122, v2
	v_mov_b32_e32 v123, v2
	v_mov_b32_e32 v124, v2
	v_mov_b32_e32 v125, v2
	v_mov_b32_e32 v126, v2
	v_mov_b32_e32 v127, v2
	v_mov_b32_e32 v128, v2
	v_mov_b32_e32 v129, v2
	v_mov_b32_e32 v70, v2
	v_mov_b32_e32 v71, v2
	v_mov_b32_e32 v72, v2
	v_mov_b32_e32 v73, v2
	v_mov_b32_e32 v74, v2
	v_mov_b32_e32 v75, v2
	v_mov_b32_e32 v76, v2
	v_mov_b32_e32 v77, v2
	v_mov_b32_e32 v78, v2
	v_mov_b32_e32 v79, v2
	v_mov_b32_e32 v80, v2
	v_mov_b32_e32 v81, v2
	v_mov_b32_e32 v86, v2
	v_mov_b32_e32 v87, v2
	v_mov_b32_e32 v88, v2
	v_mov_b32_e32 v89, v2
	s_barrier
	v_readfirstlane_b32 s99, v0
	s_nop 3
	s_lshr_b32 s99, s99, 6
	s_cmp_lt_u32 s99, 4
	s_cbranch_scc0 .Lprio_k3
	s_setprio 1
.Lprio_k3:
.LBB0_1175:
	v_add_u32_e32 v169, s35, v161
	ds_read_b128 v[172:175], v169 offset:32768
	ds_read_b128 v[176:179], v169 offset:33792
	ds_read_b128 v[180:183], v169 offset:34816
	ds_read_b128 v[184:187], v169 offset:35840
	v_add_u32_e32 v170, s70, v142
	v_lshl_add_u64 v[224:225], v[138:139], 0, s[0:1]
	v_readfirstlane_b32 s75, v170
	v_add_u32_e32 v171, 0x2000, v170
	v_add_u32_e32 v165, s37, v161
	v_add_u32_e32 v166, s43, v162
	v_add_u32_e32 v167, s46, v162
	v_add_u32_e32 v168, s47, v162
	v_lshl_add_u64 v[220:221], v[224:225], 0, s[8:9]
	s_mov_b32 m0, s75
	v_lshl_add_u64 v[246:247], v[140:141], 0, s[0:1]
	v_readfirstlane_b32 s75, v171
	ds_read_b128 v[188:191], v165
	ds_read_b128 v[192:195], v165 offset:1024
	ds_read_b128 v[196:199], v166
	ds_read_b128 v[200:203], v166 offset:1024
	ds_read_b128 v[204:207], v167
	ds_read_b128 v[208:211], v167 offset:1024
	ds_read_b128 v[212:215], v168
	ds_read_b128 v[216:219], v168 offset:1024
	global_load_lds_dwordx4 v[220:221], off
	v_lshl_add_u64 v[220:221], v[246:247], 0, s[8:9]
	s_mov_b32 m0, s75
	s_nop 0
	global_load_lds_dwordx4 v[220:221], off
	s_waitcnt lgkmcnt(8)
	s_barrier
	s_waitcnt lgkmcnt(0)
	s_waitcnt lgkmcnt(0)
	v_mfma_f32_16x16x32_bf16 v[126:129], v[172:175], v[188:191], v[126:129]
	v_mfma_f32_16x16x32_bf16 v[122:125], v[180:183], v[188:191], v[122:125]
	v_mfma_f32_16x16x32_bf16 v[118:121], v[172:175], v[196:199], v[118:121]
	v_mfma_f32_16x16x32_bf16 v[114:117], v[180:183], v[196:199], v[114:117]
	v_mfma_f32_16x16x32_bf16 v[110:113], v[172:175], v[204:207], v[110:113]
	v_mfma_f32_16x16x32_bf16 v[106:109], v[180:183], v[204:207], v[106:109]
	v_mfma_f32_16x16x32_bf16 v[102:105], v[172:175], v[212:215], v[102:105]
	v_mfma_f32_16x16x32_bf16 v[98:101], v[180:183], v[212:215], v[98:101]
	v_mfma_f32_16x16x32_bf16 v[126:129], v[176:179], v[192:195], v[126:129]
	v_mfma_f32_16x16x32_bf16 v[122:125], v[184:187], v[192:195], v[122:125]
	v_mfma_f32_16x16x32_bf16 v[118:121], v[176:179], v[200:203], v[118:121]
	v_mfma_f32_16x16x32_bf16 v[114:117], v[184:187], v[200:203], v[114:117]
	v_mfma_f32_16x16x32_bf16 v[110:113], v[176:179], v[208:211], v[110:113]
	v_mfma_f32_16x16x32_bf16 v[106:109], v[184:187], v[208:211], v[106:109]
	v_mfma_f32_16x16x32_bf16 v[102:105], v[176:179], v[216:219], v[102:105]
	v_mfma_f32_16x16x32_bf16 v[98:101], v[184:187], v[216:219], v[98:101]
	s_barrier
	v_lshl_add_u64 v[248:249], v[134:135], 0, s[0:1]
	v_readfirstlane_b32 s75, v144
	v_lshl_add_u64 v[238:239], v[248:249], 0, s[10:11]
	s_mov_b32 m0, s75
	v_lshl_add_u64 v[250:251], v[136:137], 0, s[0:1]
	v_readfirstlane_b32 s75, v145
	ds_read_b128 v[220:223], v169 offset:49152
	ds_read_b128 v[226:229], v169 offset:50176
	ds_read_b128 v[230:233], v169 offset:51200
	ds_read_b128 v[234:237], v169 offset:52224
	global_load_lds_dwordx4 v[238:239], off
	v_lshl_add_u64 v[238:239], v[250:251], 0, s[10:11]
	s_mov_b32 m0, s75
	s_nop 0
	global_load_lds_dwordx4 v[238:239], off
	s_barrier
	s_waitcnt lgkmcnt(0)
	s_waitcnt lgkmcnt(0)
	v_mfma_f32_16x16x32_bf16 v[94:97], v[220:223], v[188:191], v[94:97]
	v_mfma_f32_16x16x32_bf16 v[90:93], v[230:233], v[188:191], v[90:93]
	v_mfma_f32_16x16x32_bf16 v[82:85], v[220:223], v[196:199], v[82:85]
	v_mfma_f32_16x16x32_bf16 v[66:69], v[230:233], v[196:199], v[66:69]
	v_mfma_f32_16x16x32_bf16 v[62:65], v[220:223], v[204:207], v[62:65]
	v_mfma_f32_16x16x32_bf16 v[58:61], v[230:233], v[204:207], v[58:61]
	v_mfma_f32_16x16x32_bf16 v[54:57], v[220:223], v[212:215], v[54:57]
	v_mfma_f32_16x16x32_bf16 v[50:53], v[230:233], v[212:215], v[50:53]
	v_mfma_f32_16x16x32_bf16 v[94:97], v[226:229], v[192:195], v[94:97]
	v_mfma_f32_16x16x32_bf16 v[90:93], v[234:237], v[192:195], v[90:93]
	v_mfma_f32_16x16x32_bf16 v[82:85], v[226:229], v[200:203], v[82:85]
	v_mfma_f32_16x16x32_bf16 v[66:69], v[234:237], v[200:203], v[66:69]
	v_mfma_f32_16x16x32_bf16 v[62:65], v[226:229], v[208:211], v[62:65]
	v_mfma_f32_16x16x32_bf16 v[58:61], v[234:237], v[208:211], v[58:61]
	v_mfma_f32_16x16x32_bf16 v[54:57], v[226:229], v[216:219], v[54:57]
	v_mfma_f32_16x16x32_bf16 v[50:53], v[234:237], v[216:219], v[50:53]
	v_readfirstlane_b32 s75, v143
	v_lshl_add_u64 v[238:239], v[224:225], 0, s[12:13]
	s_mov_b32 m0, s75
	v_readfirstlane_b32 s75, v146
	s_barrier
	ds_read_b128 v[188:191], v165 offset:16384
	ds_read_b128 v[192:195], v165 offset:17408
	ds_read_b128 v[196:199], v166 offset:16384
	ds_read_b128 v[200:203], v166 offset:17408
	ds_read_b128 v[204:207], v167 offset:16384
	ds_read_b128 v[208:211], v167 offset:17408
	ds_read_b128 v[212:215], v168 offset:16384
	ds_read_b128 v[216:219], v168 offset:17408
	global_load_lds_dwordx4 v[238:239], off
	v_lshl_add_u64 v[238:239], v[246:247], 0, s[12:13]
	s_mov_b32 m0, s75
	s_nop 0
	global_load_lds_dwordx4 v[238:239], off
	s_barrier
	s_waitcnt lgkmcnt(0)
	s_waitcnt lgkmcnt(0)
	v_mfma_f32_16x16x32_bf16 v[46:49], v[172:175], v[188:191], v[46:49]
	v_mfma_f32_16x16x32_bf16 v[42:45], v[180:183], v[188:191], v[42:45]
	v_mfma_f32_16x16x32_bf16 v[38:41], v[172:175], v[196:199], v[38:41]
	v_mfma_f32_16x16x32_bf16 v[34:37], v[180:183], v[196:199], v[34:37]
	v_mfma_f32_16x16x32_bf16 v[30:33], v[172:175], v[204:207], v[30:33]
	v_mfma_f32_16x16x32_bf16 v[26:29], v[180:183], v[204:207], v[26:29]
	v_mfma_f32_16x16x32_bf16 v[22:25], v[172:175], v[212:215], v[22:25]
	v_mfma_f32_16x16x32_bf16 v[18:21], v[180:183], v[212:215], v[18:21]
	v_mfma_f32_16x16x32_bf16 v[46:49], v[176:179], v[192:195], v[46:49]
	v_mfma_f32_16x16x32_bf16 v[42:45], v[184:187], v[192:195], v[42:45]
	v_mfma_f32_16x16x32_bf16 v[38:41], v[176:179], v[200:203], v[38:41]
	v_mfma_f32_16x16x32_bf16 v[34:37], v[184:187], v[200:203], v[34:37]
	v_mfma_f32_16x16x32_bf16 v[30:33], v[176:179], v[208:211], v[30:33]
	v_mfma_f32_16x16x32_bf16 v[26:29], v[184:187], v[208:211], v[26:29]
	v_mfma_f32_16x16x32_bf16 v[22:25], v[176:179], v[216:219], v[22:25]
	v_mfma_f32_16x16x32_bf16 v[18:21], v[184:187], v[216:219], v[18:21]
	s_barrier
	v_readfirstlane_b32 s75, v147
	v_lshl_add_u64 v[172:173], v[248:249], 0, s[16:17]
	s_mov_b32 m0, s75
	v_readfirstlane_b32 s75, v148
	global_load_lds_dwordx4 v[172:173], off
	v_lshl_add_u64 v[172:173], v[250:251], 0, s[16:17]
	s_mov_b32 m0, s75
	s_nop 0
	global_load_lds_dwordx4 v[172:173], off
	s_waitcnt vmcnt(6)
	s_barrier
	v_mfma_f32_16x16x32_bf16 v[14:17], v[220:223], v[188:191], v[14:17]
	v_mfma_f32_16x16x32_bf16 v[10:13], v[230:233], v[188:191], v[10:13]
	v_mfma_f32_16x16x32_bf16 v[6:9], v[220:223], v[196:199], v[6:9]
	v_mfma_f32_16x16x32_bf16 v[2:5], v[230:233], v[196:199], v[2:5]
	v_mfma_f32_16x16x32_bf16 v[70:73], v[220:223], v[204:207], v[70:73]
	v_mfma_f32_16x16x32_bf16 v[74:77], v[230:233], v[204:207], v[74:77]
	v_mfma_f32_16x16x32_bf16 v[78:81], v[220:223], v[212:215], v[78:81]
	v_mfma_f32_16x16x32_bf16 v[86:89], v[230:233], v[212:215], v[86:89]
	v_mfma_f32_16x16x32_bf16 v[14:17], v[226:229], v[192:195], v[14:17]
	v_mfma_f32_16x16x32_bf16 v[10:13], v[234:237], v[192:195], v[10:13]
	v_mfma_f32_16x16x32_bf16 v[6:9], v[226:229], v[200:203], v[6:9]
	v_mfma_f32_16x16x32_bf16 v[2:5], v[234:237], v[200:203], v[2:5]
	v_mfma_f32_16x16x32_bf16 v[70:73], v[226:229], v[208:211], v[70:73]
	v_mfma_f32_16x16x32_bf16 v[74:77], v[234:237], v[208:211], v[74:77]
	v_mfma_f32_16x16x32_bf16 v[78:81], v[226:229], v[216:219], v[78:81]
	v_mfma_f32_16x16x32_bf16 v[86:89], v[234:237], v[216:219], v[86:89]
	s_barrier
	ds_read_b128 v[178:181], v154
	ds_read_b128 v[182:185], v154 offset:1024
	ds_read_b128 v[186:189], v154 offset:2048
	ds_read_b128 v[190:193], v154 offset:3072
	v_readfirstlane_b32 s75, v149
	v_add_u32_e32 v172, s43, v163
	v_add_u32_e32 v173, s46, v163
	v_add_u32_e32 v174, s47, v163
	v_lshl_add_u64 v[176:177], v[224:225], 0, s[20:21]
	s_mov_b32 m0, s75
	v_readfirstlane_b32 s75, v150
	ds_read_b128 v[194:197], v153
	ds_read_b128 v[198:201], v153 offset:1024
	ds_read_b128 v[202:205], v172
	ds_read_b128 v[206:209], v172 offset:1024
	ds_read_b128 v[210:213], v173
	ds_read_b128 v[214:217], v173 offset:1024
	ds_read_b128 v[218:221], v174
	ds_read_b128 v[226:229], v174 offset:1024
	global_load_lds_dwordx4 v[176:177], off
	v_lshl_add_u64 v[176:177], v[246:247], 0, s[20:21]
	s_mov_b32 m0, s75
	s_nop 0
	global_load_lds_dwordx4 v[176:177], off
	s_waitcnt lgkmcnt(8)
	s_barrier
	s_waitcnt lgkmcnt(0)
	s_waitcnt lgkmcnt(0)
	v_mfma_f32_16x16x32_bf16 v[126:129], v[178:181], v[194:197], v[126:129]
	v_mfma_f32_16x16x32_bf16 v[122:125], v[186:189], v[194:197], v[122:125]
	v_mfma_f32_16x16x32_bf16 v[118:121], v[178:181], v[202:205], v[118:121]
	v_mfma_f32_16x16x32_bf16 v[114:117], v[186:189], v[202:205], v[114:117]
	v_mfma_f32_16x16x32_bf16 v[110:113], v[178:181], v[210:213], v[110:113]
	v_mfma_f32_16x16x32_bf16 v[106:109], v[186:189], v[210:213], v[106:109]
	v_mfma_f32_16x16x32_bf16 v[102:105], v[178:181], v[218:221], v[102:105]
	v_mfma_f32_16x16x32_bf16 v[98:101], v[186:189], v[218:221], v[98:101]
	v_mfma_f32_16x16x32_bf16 v[126:129], v[182:185], v[198:201], v[126:129]
	v_mfma_f32_16x16x32_bf16 v[122:125], v[190:193], v[198:201], v[122:125]
	v_mfma_f32_16x16x32_bf16 v[118:121], v[182:185], v[206:209], v[118:121]
	v_mfma_f32_16x16x32_bf16 v[114:117], v[190:193], v[206:209], v[114:117]
	v_mfma_f32_16x16x32_bf16 v[110:113], v[182:185], v[214:217], v[110:113]
	v_mfma_f32_16x16x32_bf16 v[106:109], v[190:193], v[214:217], v[106:109]
	v_mfma_f32_16x16x32_bf16 v[102:105], v[182:185], v[226:229], v[102:105]
	v_mfma_f32_16x16x32_bf16 v[98:101], v[190:193], v[226:229], v[98:101]
	s_barrier
	v_readfirstlane_b32 s75, v155
	v_lshl_add_u64 v[176:177], v[248:249], 0, s[22:23]
	s_mov_b32 m0, s75
	v_readfirstlane_b32 s75, v156
	ds_read_b128 v[230:233], v152
	ds_read_b128 v[234:237], v152 offset:1024
	ds_read_b128 v[238:241], v152 offset:2048
	ds_read_b128 v[242:245], v152 offset:3072
	global_load_lds_dwordx4 v[176:177], off
	v_lshl_add_u64 v[176:177], v[250:251], 0, s[22:23]
	s_mov_b32 m0, s75
	s_nop 0
	global_load_lds_dwordx4 v[176:177], off
	s_barrier
	s_waitcnt lgkmcnt(0)
	s_waitcnt lgkmcnt(0)
	v_mfma_f32_16x16x32_bf16 v[94:97], v[230:233], v[194:197], v[94:97]
	v_mfma_f32_16x16x32_bf16 v[90:93], v[238:241], v[194:197], v[90:93]
	v_mfma_f32_16x16x32_bf16 v[82:85], v[230:233], v[202:205], v[82:85]
	v_mfma_f32_16x16x32_bf16 v[66:69], v[238:241], v[202:205], v[66:69]
	v_mfma_f32_16x16x32_bf16 v[62:65], v[230:233], v[210:213], v[62:65]
	v_mfma_f32_16x16x32_bf16 v[58:61], v[238:241], v[210:213], v[58:61]
	v_mfma_f32_16x16x32_bf16 v[54:57], v[230:233], v[218:221], v[54:57]
	v_mfma_f32_16x16x32_bf16 v[50:53], v[238:241], v[218:221], v[50:53]
	v_mfma_f32_16x16x32_bf16 v[94:97], v[234:237], v[198:201], v[94:97]
	v_mfma_f32_16x16x32_bf16 v[90:93], v[242:245], v[198:201], v[90:93]
	v_mfma_f32_16x16x32_bf16 v[82:85], v[234:237], v[206:209], v[82:85]
	v_mfma_f32_16x16x32_bf16 v[66:69], v[242:245], v[206:209], v[66:69]
	v_mfma_f32_16x16x32_bf16 v[62:65], v[234:237], v[214:217], v[62:65]
	v_mfma_f32_16x16x32_bf16 v[58:61], v[242:245], v[214:217], v[58:61]
	v_mfma_f32_16x16x32_bf16 v[54:57], v[234:237], v[226:229], v[54:57]
	v_mfma_f32_16x16x32_bf16 v[50:53], v[242:245], v[226:229], v[50:53]
	v_readfirstlane_b32 s75, v157
	v_add_u32_e32 v175, s43, v164
	v_add_u32_e32 v176, s46, v164
	v_add_u32_e32 v177, s47, v164
	v_lshl_add_u64 v[222:223], v[224:225], 0, s[24:25]
	s_mov_b32 m0, s75
	v_readfirstlane_b32 s75, v158
	s_barrier
	ds_read_b128 v[194:197], v151
	ds_read_b128 v[198:201], v151 offset:1024
	ds_read_b128 v[202:205], v175
	ds_read_b128 v[206:209], v175 offset:1024
	ds_read_b128 v[210:213], v176
	ds_read_b128 v[214:217], v176 offset:1024
	ds_read_b128 v[218:221], v177
	ds_read_b128 v[226:229], v177 offset:1024
	global_load_lds_dwordx4 v[222:223], off
	v_lshl_add_u64 v[222:223], v[246:247], 0, s[24:25]
	s_mov_b32 m0, s75
	s_nop 0
	global_load_lds_dwordx4 v[222:223], off
	s_barrier
	s_waitcnt lgkmcnt(0)
	s_waitcnt lgkmcnt(0)
	v_mfma_f32_16x16x32_bf16 v[46:49], v[178:181], v[194:197], v[46:49]
	v_mfma_f32_16x16x32_bf16 v[42:45], v[186:189], v[194:197], v[42:45]
	v_mfma_f32_16x16x32_bf16 v[38:41], v[178:181], v[202:205], v[38:41]
	v_mfma_f32_16x16x32_bf16 v[34:37], v[186:189], v[202:205], v[34:37]
	v_mfma_f32_16x16x32_bf16 v[30:33], v[178:181], v[210:213], v[30:33]
	v_mfma_f32_16x16x32_bf16 v[26:29], v[186:189], v[210:213], v[26:29]
	v_mfma_f32_16x16x32_bf16 v[22:25], v[178:181], v[218:221], v[22:25]
	v_mfma_f32_16x16x32_bf16 v[18:21], v[186:189], v[218:221], v[18:21]
	v_mfma_f32_16x16x32_bf16 v[46:49], v[182:185], v[198:201], v[46:49]
	v_mfma_f32_16x16x32_bf16 v[42:45], v[190:193], v[198:201], v[42:45]
	v_mfma_f32_16x16x32_bf16 v[38:41], v[182:185], v[206:209], v[38:41]
	v_mfma_f32_16x16x32_bf16 v[34:37], v[190:193], v[206:209], v[34:37]
	v_mfma_f32_16x16x32_bf16 v[30:33], v[182:185], v[214:217], v[30:33]
	v_mfma_f32_16x16x32_bf16 v[26:29], v[190:193], v[214:217], v[26:29]
	v_mfma_f32_16x16x32_bf16 v[22:25], v[182:185], v[226:229], v[22:25]
	v_mfma_f32_16x16x32_bf16 v[18:21], v[190:193], v[226:229], v[18:21]
	s_barrier
	v_readfirstlane_b32 s75, v159
	v_lshl_add_u64 v[178:179], v[248:249], 0, s[26:27]
	s_mov_b32 m0, s75
	v_readfirstlane_b32 s75, v160
	global_load_lds_dwordx4 v[178:179], off
	v_lshl_add_u64 v[178:179], v[250:251], 0, s[26:27]
	s_mov_b32 m0, s75
	s_nop 0
	global_load_lds_dwordx4 v[178:179], off
	s_waitcnt vmcnt(6)
	s_barrier
	v_mfma_f32_16x16x32_bf16 v[14:17], v[230:233], v[194:197], v[14:17]
	v_mfma_f32_16x16x32_bf16 v[10:13], v[238:241], v[194:197], v[10:13]
	v_mfma_f32_16x16x32_bf16 v[6:9], v[230:233], v[202:205], v[6:9]
	v_mfma_f32_16x16x32_bf16 v[2:5], v[238:241], v[202:205], v[2:5]
	v_mfma_f32_16x16x32_bf16 v[70:73], v[230:233], v[210:213], v[70:73]
	v_mfma_f32_16x16x32_bf16 v[74:77], v[238:241], v[210:213], v[74:77]
	v_mfma_f32_16x16x32_bf16 v[78:81], v[230:233], v[218:221], v[78:81]
	v_mfma_f32_16x16x32_bf16 v[86:89], v[238:241], v[218:221], v[86:89]
	v_mfma_f32_16x16x32_bf16 v[14:17], v[234:237], v[198:201], v[14:17]
	v_mfma_f32_16x16x32_bf16 v[10:13], v[242:245], v[198:201], v[10:13]
	v_mfma_f32_16x16x32_bf16 v[6:9], v[234:237], v[206:209], v[6:9]
	v_mfma_f32_16x16x32_bf16 v[2:5], v[242:245], v[206:209], v[2:5]
	v_mfma_f32_16x16x32_bf16 v[70:73], v[234:237], v[214:217], v[70:73]
	v_mfma_f32_16x16x32_bf16 v[74:77], v[242:245], v[214:217], v[74:77]
	v_mfma_f32_16x16x32_bf16 v[78:81], v[234:237], v[226:229], v[78:81]
	v_mfma_f32_16x16x32_bf16 v[86:89], v[242:245], v[226:229], v[86:89]
	s_add_i32 s74, s74, 2
	s_add_u32 s0, s0, 0x100
	s_addc_u32 s1, s1, 0
	s_cmp_lt_u32 s74, 12
	s_barrier
	s_cbranch_scc1 .LBB0_1175
	s_or_b32 s0, s34, 0x80
	s_ashr_i32 s1, s0, 31
	s_lshl_b64 s[46:47], s[0:1], 11
	s_add_u32 s46, s60, s46
	s_addc_u32 s47, s61, s47
	v_lshl_add_u64 v[202:203], v[130:131], 1, s[46:47]
	v_readfirstlane_b32 s1, v170
	v_lshl_add_u64 v[202:203], v[202:203], 0, s[28:29]
	s_mov_b32 m0, s1
	v_lshl_add_u64 v[132:133], v[132:133], 1, s[46:47]
	v_readfirstlane_b32 s1, v171
	ds_read_b128 v[134:137], v169 offset:32768
	ds_read_b128 v[138:141], v169 offset:33792
	ds_read_b128 v[142:145], v169 offset:34816
	ds_read_b128 v[146:149], v169 offset:35840
	ds_read_b128 v[156:159], v165
	ds_read_b128 v[160:163], v165 offset:1024
	ds_read_b128 v[178:181], v166
	ds_read_b128 v[182:185], v166 offset:1024
	ds_read_b128 v[186:189], v167
	ds_read_b128 v[190:193], v167 offset:1024
	ds_read_b128 v[194:197], v168
	ds_read_b128 v[198:201], v168 offset:1024
	global_load_lds_dwordx4 v[202:203], off
	v_lshl_add_u64 v[132:133], v[132:133], 0, s[28:29]
	s_mov_b32 m0, s1
	s_nop 0
	global_load_lds_dwordx4 v[132:133], off
	s_barrier
	s_waitcnt lgkmcnt(0)
	s_waitcnt lgkmcnt(0)
	v_mfma_f32_16x16x32_bf16 v[126:129], v[134:137], v[156:159], v[126:129]
	v_mfma_f32_16x16x32_bf16 v[122:125], v[142:145], v[156:159], v[122:125]
	v_mfma_f32_16x16x32_bf16 v[118:121], v[134:137], v[178:181], v[118:121]
	v_mfma_f32_16x16x32_bf16 v[114:117], v[142:145], v[178:181], v[114:117]
	v_mfma_f32_16x16x32_bf16 v[110:113], v[134:137], v[186:189], v[110:113]
	v_mfma_f32_16x16x32_bf16 v[126:129], v[138:141], v[160:163], v[126:129]
	v_mfma_f32_16x16x32_bf16 v[122:125], v[146:149], v[160:163], v[122:125]
	v_mfma_f32_16x16x32_bf16 v[118:121], v[138:141], v[182:185], v[118:121]
	v_mfma_f32_16x16x32_bf16 v[114:117], v[146:149], v[182:185], v[114:117]
	v_mfma_f32_16x16x32_bf16 v[110:113], v[138:141], v[190:193], v[110:113]
	v_mfma_f32_16x16x32_bf16 v[106:109], v[142:145], v[186:189], v[106:109]
	v_mfma_f32_16x16x32_bf16 v[102:105], v[134:137], v[194:197], v[102:105]
	v_mfma_f32_16x16x32_bf16 v[98:101], v[142:145], v[194:197], v[98:101]
	v_mfma_f32_16x16x32_bf16 v[202:205], v[146:149], v[190:193], v[106:109]
	v_mfma_f32_16x16x32_bf16 v[206:209], v[138:141], v[198:201], v[102:105]
	v_mfma_f32_16x16x32_bf16 v[210:213], v[146:149], v[198:201], v[98:101]
	s_barrier
	s_nop 2
	ds_read_b128 v[98:101], v169 offset:49152
	ds_read_b128 v[102:105], v169 offset:50176
	ds_read_b128 v[106:109], v169 offset:51200
	ds_read_b128 v[214:217], v169 offset:52224
	s_barrier
	s_waitcnt lgkmcnt(0)
	s_waitcnt lgkmcnt(0)
	v_mfma_f32_16x16x32_bf16 v[94:97], v[98:101], v[156:159], v[94:97]
	v_mfma_f32_16x16x32_bf16 v[90:93], v[106:109], v[156:159], v[90:93]
	v_mfma_f32_16x16x32_bf16 v[82:85], v[98:101], v[178:181], v[82:85]
	v_mfma_f32_16x16x32_bf16 v[62:65], v[98:101], v[186:189], v[62:65]
	v_mfma_f32_16x16x32_bf16 v[58:61], v[106:109], v[186:189], v[58:61]
	v_mfma_f32_16x16x32_bf16 v[54:57], v[98:101], v[194:197], v[54:57]
	v_mfma_f32_16x16x32_bf16 v[50:53], v[106:109], v[194:197], v[50:53]
	v_mfma_f32_16x16x32_bf16 v[94:97], v[102:105], v[160:163], v[94:97]
	v_mfma_f32_16x16x32_bf16 v[90:93], v[214:217], v[160:163], v[90:93]
	v_mfma_f32_16x16x32_bf16 v[82:85], v[102:105], v[182:185], v[82:85]
	v_mfma_f32_16x16x32_bf16 v[66:69], v[106:109], v[178:181], v[66:69]
	v_mfma_f32_16x16x32_bf16 v[62:65], v[102:105], v[190:193], v[62:65]
	v_mfma_f32_16x16x32_bf16 v[58:61], v[214:217], v[190:193], v[58:61]
	v_mfma_f32_16x16x32_bf16 v[54:57], v[102:105], v[198:201], v[54:57]
	v_mfma_f32_16x16x32_bf16 v[50:53], v[214:217], v[198:201], v[50:53]
	v_mfma_f32_16x16x32_bf16 v[156:159], v[214:217], v[182:185], v[66:69]
	s_barrier
	s_nop 0
	ds_read_b128 v[66:69], v165 offset:16384
	ds_read_b128 v[160:163], v165 offset:17408
	ds_read_b128 v[178:181], v166 offset:16384
	ds_read_b128 v[182:185], v166 offset:17408
	ds_read_b128 v[186:189], v167 offset:16384
	ds_read_b128 v[164:167], v167 offset:17408
	ds_read_b128 v[190:193], v168 offset:16384
	ds_read_b128 v[168:171], v168 offset:17408
	s_waitcnt vmcnt(4)
	s_barrier
	s_waitcnt lgkmcnt(0)
	s_waitcnt lgkmcnt(0)
	v_mfma_f32_16x16x32_bf16 v[46:49], v[134:137], v[66:69], v[46:49]
	v_mfma_f32_16x16x32_bf16 v[42:45], v[142:145], v[66:69], v[42:45]
	v_mfma_f32_16x16x32_bf16 v[30:33], v[134:137], v[186:189], v[30:33]
	v_mfma_f32_16x16x32_bf16 v[26:29], v[142:145], v[186:189], v[26:29]
	v_mfma_f32_16x16x32_bf16 v[22:25], v[134:137], v[190:193], v[22:25]
	v_mfma_f32_16x16x32_bf16 v[18:21], v[142:145], v[190:193], v[18:21]
	v_mfma_f32_16x16x32_bf16 v[46:49], v[138:141], v[160:163], v[46:49]
	v_mfma_f32_16x16x32_bf16 v[42:45], v[146:149], v[160:163], v[42:45]
	v_mfma_f32_16x16x32_bf16 v[38:41], v[134:137], v[178:181], v[38:41]
	v_mfma_f32_16x16x32_bf16 v[34:37], v[142:145], v[178:181], v[34:37]
	v_mfma_f32_16x16x32_bf16 v[30:33], v[138:141], v[164:167], v[30:33]
	v_mfma_f32_16x16x32_bf16 v[26:29], v[146:149], v[164:167], v[26:29]
	v_mfma_f32_16x16x32_bf16 v[22:25], v[138:141], v[168:171], v[22:25]
	v_mfma_f32_16x16x32_bf16 v[18:21], v[146:149], v[168:171], v[18:21]
	v_mfma_f32_16x16x32_bf16 v[194:197], v[138:141], v[182:185], v[38:41]
	v_mfma_f32_16x16x32_bf16 v[198:201], v[146:149], v[182:185], v[34:37]
	v_mfma_f32_16x16x32_bf16 v[2:5], v[106:109], v[178:181], v[2:5]
	v_mfma_f32_16x16x32_bf16 v[136:139], v[214:217], v[182:185], v[2:5]
	v_mfma_f32_16x16x32_bf16 v[2:5], v[98:101], v[186:189], v[70:73]
	v_mfma_f32_16x16x32_bf16 v[140:143], v[102:105], v[164:167], v[2:5]
	v_mfma_f32_16x16x32_bf16 v[2:5], v[106:109], v[186:189], v[74:77]
	v_mfma_f32_16x16x32_bf16 v[14:17], v[98:101], v[66:69], v[14:17]
	v_mfma_f32_16x16x32_bf16 v[10:13], v[106:109], v[66:69], v[10:13]
	v_mfma_f32_16x16x32_bf16 v[144:147], v[214:217], v[164:167], v[2:5]
	v_mfma_f32_16x16x32_bf16 v[2:5], v[98:101], v[190:193], v[78:81]
	v_mfma_f32_16x16x32_bf16 v[14:17], v[102:105], v[160:163], v[14:17]
	v_mfma_f32_16x16x32_bf16 v[10:13], v[214:217], v[160:163], v[10:13]
	v_mfma_f32_16x16x32_bf16 v[6:9], v[98:101], v[178:181], v[6:9]
	v_mfma_f32_16x16x32_bf16 v[160:163], v[102:105], v[168:171], v[2:5]
	v_mfma_f32_16x16x32_bf16 v[2:5], v[106:109], v[190:193], v[86:89]
	v_mfma_f32_16x16x32_bf16 v[132:135], v[102:105], v[182:185], v[6:9]
	v_mfma_f32_16x16x32_bf16 v[164:167], v[214:217], v[168:171], v[2:5]
	s_barrier
	s_nop 3
	ds_read_b128 v[2:5], v154
	ds_read_b128 v[6:9], v154 offset:1024
	ds_read_b128 v[168:171], v154 offset:2048
	ds_read_b128 v[178:181], v154 offset:3072
	ds_read_b128 v[34:37], v153
	ds_read_b128 v[38:41], v153 offset:1024
	ds_read_b128 v[78:81], v172
	ds_read_b128 v[86:89], v172 offset:1024
	ds_read_b128 v[182:185], v173
	ds_read_b128 v[186:189], v173 offset:1024
	ds_read_b128 v[190:193], v174
	ds_read_b128 v[214:217], v174 offset:1024
	s_waitcnt vmcnt(2)
	s_barrier
	s_waitcnt lgkmcnt(0)
	s_waitcnt lgkmcnt(0)
	v_mfma_f32_16x16x32_bf16 v[66:69], v[2:5], v[34:37], v[126:129]
	v_mfma_f32_16x16x32_bf16 v[126:129], v[6:9], v[38:41], v[66:69]
	v_mfma_f32_16x16x32_bf16 v[66:69], v[168:171], v[34:37], v[122:125]
	v_mfma_f32_16x16x32_bf16 v[98:101], v[178:181], v[38:41], v[66:69]
	v_mfma_f32_16x16x32_bf16 v[66:69], v[2:5], v[78:81], v[118:121]
	v_mfma_f32_16x16x32_bf16 v[102:105], v[6:9], v[86:89], v[66:69]
	v_mfma_f32_16x16x32_bf16 v[66:69], v[168:171], v[78:81], v[114:117]
	v_mfma_f32_16x16x32_bf16 v[106:109], v[178:181], v[86:89], v[66:69]
	v_mfma_f32_16x16x32_bf16 v[66:69], v[2:5], v[182:185], v[110:113]
	v_mfma_f32_16x16x32_bf16 v[110:113], v[6:9], v[186:189], v[66:69]
	v_mfma_f32_16x16x32_bf16 v[66:69], v[168:171], v[182:185], v[202:205]
	v_mfma_f32_16x16x32_bf16 v[114:117], v[178:181], v[186:189], v[66:69]
	v_mfma_f32_16x16x32_bf16 v[66:69], v[2:5], v[190:193], v[206:209]
	v_mfma_f32_16x16x32_bf16 v[118:121], v[6:9], v[214:217], v[66:69]
	v_mfma_f32_16x16x32_bf16 v[66:69], v[168:171], v[190:193], v[210:213]
	v_mfma_f32_16x16x32_bf16 v[122:125], v[178:181], v[214:217], v[66:69]
	s_barrier
	ds_read_b128 v[202:205], v152
	ds_read_b128 v[206:209], v152 offset:1024
	ds_read_b128 v[210:213], v152 offset:2048
	ds_read_b128 v[152:155], v152 offset:3072
	s_waitcnt vmcnt(0)
	s_barrier
	s_waitcnt lgkmcnt(0)
	s_waitcnt lgkmcnt(0)
	v_mfma_f32_16x16x32_bf16 v[66:69], v[202:205], v[34:37], v[94:97]
	v_mfma_f32_16x16x32_bf16 v[34:37], v[210:213], v[34:37], v[90:93]
	v_mfma_f32_16x16x32_bf16 v[70:73], v[152:155], v[38:41], v[34:37]
	v_mfma_f32_16x16x32_bf16 v[34:37], v[202:205], v[78:81], v[82:85]
	v_mfma_f32_16x16x32_bf16 v[74:77], v[206:209], v[86:89], v[34:37]
	v_mfma_f32_16x16x32_bf16 v[34:37], v[210:213], v[78:81], v[156:159]
	v_mfma_f32_16x16x32_bf16 v[78:81], v[152:155], v[86:89], v[34:37]
	v_mfma_f32_16x16x32_bf16 v[34:37], v[202:205], v[182:185], v[62:65]
	v_mfma_f32_16x16x32_bf16 v[82:85], v[206:209], v[186:189], v[34:37]
	v_mfma_f32_16x16x32_bf16 v[34:37], v[210:213], v[182:185], v[58:61]
	v_mfma_f32_16x16x32_bf16 v[86:89], v[152:155], v[186:189], v[34:37]
	v_mfma_f32_16x16x32_bf16 v[34:37], v[202:205], v[190:193], v[54:57]
	v_mfma_f32_16x16x32_bf16 v[90:93], v[206:209], v[214:217], v[34:37]
	v_mfma_f32_16x16x32_bf16 v[34:37], v[210:213], v[190:193], v[50:53]
	v_mfma_f32_16x16x32_bf16 v[66:69], v[206:209], v[38:41], v[66:69]
	v_mfma_f32_16x16x32_bf16 v[94:97], v[152:155], v[214:217], v[34:37]
	s_barrier
	ds_read_b128 v[156:159], v151
	ds_read_b128 v[148:151], v151 offset:1024
	ds_read_b128 v[182:185], v175
	ds_read_b128 v[172:175], v175 offset:1024
	ds_read_b128 v[186:189], v176
	ds_read_b128 v[190:193], v176 offset:1024
	ds_read_b128 v[214:217], v177
	ds_read_b128 v[218:221], v177 offset:1024
	s_barrier
	s_waitcnt lgkmcnt(0)
	s_waitcnt lgkmcnt(0)
	v_mfma_f32_16x16x32_bf16 v[34:37], v[2:5], v[156:159], v[46:49]
	v_mfma_f32_16x16x32_bf16 v[38:41], v[168:171], v[156:159], v[42:45]
	v_mfma_f32_16x16x32_bf16 v[42:45], v[2:5], v[182:185], v[194:197]
	v_mfma_f32_16x16x32_bf16 v[30:33], v[2:5], v[186:189], v[30:33]
	v_mfma_f32_16x16x32_bf16 v[2:5], v[2:5], v[214:217], v[22:25]
	v_mfma_f32_16x16x32_bf16 v[46:49], v[168:171], v[182:185], v[198:201]
	v_mfma_f32_16x16x32_bf16 v[26:29], v[168:171], v[186:189], v[26:29]
	v_mfma_f32_16x16x32_bf16 v[58:61], v[6:9], v[218:221], v[2:5]
	v_mfma_f32_16x16x32_bf16 v[2:5], v[168:171], v[214:217], v[18:21]
	v_mfma_f32_16x16x32_bf16 v[34:37], v[6:9], v[148:151], v[34:37]
	v_mfma_f32_16x16x32_bf16 v[38:41], v[178:181], v[148:151], v[38:41]
	v_mfma_f32_16x16x32_bf16 v[42:45], v[6:9], v[172:175], v[42:45]
	v_mfma_f32_16x16x32_bf16 v[46:49], v[178:181], v[172:175], v[46:49]
	v_mfma_f32_16x16x32_bf16 v[50:53], v[6:9], v[190:193], v[30:33]
	v_mfma_f32_16x16x32_bf16 v[54:57], v[178:181], v[190:193], v[26:29]
	v_mfma_f32_16x16x32_bf16 v[62:65], v[178:181], v[218:221], v[2:5]
	v_mfma_f32_16x16x32_bf16 v[2:5], v[202:205], v[156:159], v[14:17]
	v_mfma_f32_16x16x32_bf16 v[6:9], v[210:213], v[156:159], v[10:13]
	v_mfma_f32_16x16x32_bf16 v[10:13], v[202:205], v[182:185], v[132:135]
	v_mfma_f32_16x16x32_bf16 v[14:17], v[210:213], v[182:185], v[136:139]
	v_mfma_f32_16x16x32_bf16 v[18:21], v[202:205], v[186:189], v[140:143]
	v_mfma_f32_16x16x32_bf16 v[22:25], v[210:213], v[186:189], v[144:147]
	v_mfma_f32_16x16x32_bf16 v[26:29], v[202:205], v[214:217], v[160:163]
	v_mfma_f32_16x16x32_bf16 v[30:33], v[210:213], v[214:217], v[164:167]
	v_mfma_f32_16x16x32_bf16 v[2:5], v[206:209], v[148:151], v[2:5]
	v_mfma_f32_16x16x32_bf16 v[6:9], v[152:155], v[148:151], v[6:9]
	v_mfma_f32_16x16x32_bf16 v[10:13], v[206:209], v[172:175], v[10:13]
	v_mfma_f32_16x16x32_bf16 v[14:17], v[152:155], v[172:175], v[14:17]
	v_mfma_f32_16x16x32_bf16 v[18:21], v[206:209], v[190:193], v[18:21]
	v_mfma_f32_16x16x32_bf16 v[22:25], v[152:155], v[190:193], v[22:25]
	v_mfma_f32_16x16x32_bf16 v[26:29], v[206:209], v[218:221], v[26:29]
	v_mfma_f32_16x16x32_bf16 v[30:33], v[152:155], v[218:221], v[30:33]
	s_setprio 0
	s_cmpk_gt_u32 s39, 0xff
	s_barrier
	s_cbranch_scc1 .LBB0_1178
	s_barrier

.LBB0_1467:
	s_lshl_b32 s46, s76, 8
	s_ashr_i32 s47, s46, 31
	s_mul_i32 s76, s76, 0x160000
	v_readlane_b32 s84, v253, 48
	s_mul_hi_i32 s1, s46, 0x1600
	v_readlane_b32 s85, v253, 49
	s_add_u32 s0, s84, s76
	s_addc_u32 s1, s85, s1
	v_add_u32_e32 v156, s43, v143
	v_lshlrev_b64 v[12:13], 1, v[130:131]
	v_lshl_add_u64 v[14:15], s[0:1], 0, v[12:13]
	v_readfirstlane_b32 s76, v156
	v_lshl_add_u64 v[14:15], v[14:15], 0, s[2:3]
	s_mov_b32 m0, s76
	v_mov_b32_e32 v133, v131
	s_barrier
	global_load_lds_dwordx4 v[14:15], off
	v_lshlrev_b64 v[14:15], 1, v[132:133]
	v_add_u32_e32 v157, 0x2000, v156
	v_lshl_add_u64 v[16:17], s[0:1], 0, v[14:15]
	v_readfirstlane_b32 s0, v157
	s_mov_b32 m0, s0
	s_add_u32 s0, s94, s78
	v_lshl_add_u64 v[16:17], v[16:17], 0, s[2:3]
	s_addc_u32 s1, s95, s77
	v_add_u32_e32 v158, s64, v143
	global_load_lds_dwordx4 v[16:17], off
	v_lshl_add_u64 v[16:17], s[0:1], 0, v[12:13]
	v_readfirstlane_b32 s76, v158
	v_lshl_add_u64 v[16:17], v[16:17], 0, s[2:3]
	s_mov_b32 m0, s76
	v_add_u32_e32 v159, 0x2000, v158
	global_load_lds_dwordx4 v[16:17], off
	v_lshl_add_u64 v[16:17], s[0:1], 0, v[14:15]
	v_readfirstlane_b32 s0, v159
	s_mov_b32 m0, s0
	s_or_b32 s0, s46, 0x80
	s_ashr_i32 s1, s0, 31
	s_mul_i32 s76, s0, 0x1600
	s_mul_hi_i32 s77, s0, 0x1600
	s_add_u32 s76, s84, s76
	s_addc_u32 s77, s85, s77
	v_add_u32_e32 v160, s65, v143
	v_lshl_add_u64 v[16:17], v[16:17], 0, s[2:3]
	v_lshl_add_u64 v[12:13], s[76:77], 0, v[12:13]
	v_readfirstlane_b32 s78, v160
	global_load_lds_dwordx4 v[16:17], off
	v_lshl_add_u64 v[12:13], v[12:13], 0, s[2:3]
	s_mov_b32 m0, s78
	v_add_u32_e32 v161, 0x2000, v160
	global_load_lds_dwordx4 v[12:13], off
	v_lshl_add_u64 v[12:13], s[76:77], 0, v[14:15]
	v_readfirstlane_b32 s76, v161
	v_lshl_add_u64 v[12:13], v[12:13], 0, s[2:3]
	s_mov_b32 m0, s76
	v_and_b32_e32 v11, 15, v3
	global_load_lds_dwordx4 v[12:13], off
	v_and_b32_e32 v18, 48, v3
	v_lshlrev_b32_e32 v12, 2, v3
	v_lshlrev_b32_e32 v3, 6, v3
	v_and_b32_e32 v12, 32, v12
	v_and_b32_e32 v3, 0x3c0, v3
	v_bitop3_b32 v3, v3, v12, v18 bitop3:0x36
	v_add_u32_e32 v163, 0, v3
	v_add_u32_e32 v164, s64, v3
	v_add_u32_e32 v165, s70, v3
	v_lshrrev_b32_e32 v3, 1, v2
	v_mul_lo_u32 v2, v4, s33
	v_mad_u64_u32 v[2:3], s[84:85], v3, s71, v[2:3]
	v_or_b32_e32 v2, v2, v5
	v_lshrrev_b32_e32 v5, 1, v7
	v_mul_lo_u32 v4, v8, s33
	v_mad_u64_u32 v[4:5], s[84:85], v5, s71, v[4:5]
	v_or_b32_e32 v4, v4, v9
	v_add_u32_sdwa v2, v2, sext(v6) dst_sel:DWORD dst_unused:UNUSED_PAD src0_sel:DWORD src1_sel:WORD_0
	v_mov_b32_e32 v3, v131
	v_add_u32_sdwa v4, v4, sext(v10) dst_sel:DWORD dst_unused:UNUSED_PAD src0_sel:DWORD src1_sel:WORD_0
	v_mov_b32_e32 v5, v131
	v_lshlrev_b64 v[2:3], 1, v[2:3]
	v_lshlrev_b64 v[4:5], 1, v[4:5]
	v_mad_i64_i32 v[134:135], s[84:85], s46, v1, v[2:3]
	v_mad_i64_i32 v[136:137], s[84:85], s46, v1, v[4:5]
	s_lshl_b32 s84, s55, 11
	s_sub_i32 s54, s54, s83
	s_lshl_b32 s55, s55, 5
	s_sub_i32 s54, s54, s55
	s_sext_i32_i8 s54, s54
	v_lshlrev_b32_e32 v11, 6, v11
	s_lshl_b32 s54, s54, 8
	s_waitcnt vmcnt(6)
	v_bitop3_b32 v11, v11, v12, v18 bitop3:0x36
	s_lshl_b32 s76, s75, 6
	s_add_i32 s84, s84, s54
	v_add_u32_e32 v162, 0, v11
	v_add_u32_e32 v13, s43, v11
	v_add_u32_e32 v14, s65, v11
	s_and_b32 s76, s76, 0x3000
	s_lshl_b32 s77, s79, 13
	v_add_u32_e32 v12, s64, v11
	v_add_u32_e32 v11, s70, v11
	v_mad_i64_i32 v[138:139], s[54:55], s84, v1, v[2:3]
	v_mad_i64_i32 v[140:141], s[54:55], s84, v1, v[4:5]
	v_mov_b32_e32 v2, 0
	s_or_b32 s78, s77, 0x800
	s_or_b32 s79, s77, 0x1000
	s_or_b32 s82, s77, 0x1800
	s_mov_b32 s83, -2
	v_add_u32_e32 v155, s76, v13
	v_add_u32_e32 v154, s77, v12
	v_add_u32_e32 v153, s76, v14
	v_add_u32_e32 v152, s77, v11
	s_mov_b64 s[54:55], s[62:63]
	v_mov_b32_e32 v3, v2
	v_mov_b32_e32 v4, v2
	v_mov_b32_e32 v5, v2
	v_mov_b32_e32 v6, v2
	v_mov_b32_e32 v7, v2
	v_mov_b32_e32 v8, v2
	v_mov_b32_e32 v9, v2
	v_mov_b32_e32 v10, v2
	v_mov_b32_e32 v11, v2
	v_mov_b32_e32 v12, v2
	v_mov_b32_e32 v13, v2
	v_mov_b32_e32 v14, v2
	v_mov_b32_e32 v15, v2
	v_mov_b32_e32 v16, v2
	v_mov_b32_e32 v17, v2
	v_mov_b32_e32 v18, v2
	v_mov_b32_e32 v19, v2
	v_mov_b32_e32 v20, v2
	v_mov_b32_e32 v21, v2
	v_mov_b32_e32 v22, v2
	v_mov_b32_e32 v23, v2
	v_mov_b32_e32 v24, v2
	v_mov_b32_e32 v25, v2
	v_mov_b32_e32 v26, v2
	v_mov_b32_e32 v27, v2
	v_mov_b32_e32 v28, v2
	v_mov_b32_e32 v29, v2
	v_mov_b32_e32 v30, v2
	v_mov_b32_e32 v31, v2
	v_mov_b32_e32 v32, v2
	v_mov_b32_e32 v33, v2
	v_mov_b32_e32 v34, v2
	v_mov_b32_e32 v35, v2
	v_mov_b32_e32 v36, v2
	v_mov_b32_e32 v37, v2
	v_mov_b32_e32 v38, v2
	v_mov_b32_e32 v39, v2
	v_mov_b32_e32 v40, v2
	v_mov_b32_e32 v41, v2
	v_mov_b32_e32 v42, v2
	v_mov_b32_e32 v43, v2
	v_mov_b32_e32 v44, v2
	v_mov_b32_e32 v45, v2
	v_mov_b32_e32 v46, v2
	v_mov_b32_e32 v47, v2
	v_mov_b32_e32 v48, v2
	v_mov_b32_e32 v49, v2
	v_mov_b32_e32 v50, v2
	v_mov_b32_e32 v51, v2
	v_mov_b32_e32 v52, v2
	v_mov_b32_e32 v53, v2
	v_mov_b32_e32 v54, v2
	v_mov_b32_e32 v55, v2
	v_mov_b32_e32 v56, v2
	v_mov_b32_e32 v57, v2
	v_mov_b32_e32 v58, v2
	v_mov_b32_e32 v59, v2
	v_mov_b32_e32 v60, v2
	v_mov_b32_e32 v61, v2
	v_mov_b32_e32 v62, v2
	v_mov_b32_e32 v63, v2
	v_mov_b32_e32 v64, v2
	v_mov_b32_e32 v65, v2
	v_mov_b32_e32 v66, v2
	v_mov_b32_e32 v67, v2
	v_mov_b32_e32 v68, v2
	v_mov_b32_e32 v69, v2
	v_mov_b32_e32 v82, v2
	v_mov_b32_e32 v83, v2
	v_mov_b32_e32 v84, v2
	v_mov_b32_e32 v85, v2
	v_mov_b32_e32 v90, v2
	v_mov_b32_e32 v91, v2
	v_mov_b32_e32 v92, v2
	v_mov_b32_e32 v93, v2
	v_mov_b32_e32 v94, v2
	v_mov_b32_e32 v95, v2
	v_mov_b32_e32 v96, v2
	v_mov_b32_e32 v97, v2
	v_mov_b32_e32 v98, v2
	v_mov_b32_e32 v99, v2
	v_mov_b32_e32 v100, v2
	v_mov_b32_e32 v101, v2
	v_mov_b32_e32 v102, v2
	v_mov_b32_e32 v103, v2
	v_mov_b32_e32 v104, v2
	v_mov_b32_e32 v105, v2
	v_mov_b32_e32 v106, v2
	v_mov_b32_e32 v107, v2
	v_mov_b32_e32 v108, v2
	v_mov_b32_e32 v109, v2
	v_mov_b32_e32 v110, v2
	v_mov_b32_e32 v111, v2
	v_mov_b32_e32 v112, v2
	v_mov_b32_e32 v113, v2
	v_mov_b32_e32 v114, v2
	v_mov_b32_e32 v115, v2
	v_mov_b32_e32 v116, v2
	v_mov_b32_e32 v117, v2
	v_mov_b32_e32 v118, v2
	v_mov_b32_e32 v119, v2
	v_mov_b32_e32 v120, v2
	v_mov_b32_e32 v121, v2
	v_mov_b32_e32 v122, v2
	v_mov_b32_e32 v123, v2
	v_mov_b32_e32 v124, v2
	v_mov_b32_e32 v125, v2
	v_mov_b32_e32 v126, v2
	v_mov_b32_e32 v127, v2
	v_mov_b32_e32 v128, v2
	v_mov_b32_e32 v129, v2
	v_mov_b32_e32 v70, v2
	v_mov_b32_e32 v71, v2
	v_mov_b32_e32 v72, v2
	v_mov_b32_e32 v73, v2
	v_mov_b32_e32 v74, v2
	v_mov_b32_e32 v75, v2
	v_mov_b32_e32 v76, v2
	v_mov_b32_e32 v77, v2
	v_mov_b32_e32 v78, v2
	v_mov_b32_e32 v79, v2
	v_mov_b32_e32 v80, v2
	v_mov_b32_e32 v81, v2
	v_mov_b32_e32 v86, v2
	v_mov_b32_e32 v87, v2
	v_mov_b32_e32 v88, v2
	v_mov_b32_e32 v89, v2
	s_barrier
	v_readfirstlane_b32 s99, v0
	s_nop 3
	s_lshr_b32 s99, s99, 6
	s_cmp_lt_u32 s99, 4
	s_cbranch_scc0 .Lprio_k4
	s_setprio 1
.Lprio_k4:
.LBB0_1468:
	v_add_u32_e32 v170, s76, v162
	ds_read_b128 v[174:177], v170 offset:32768
	ds_read_b128 v[178:181], v170 offset:33792
	ds_read_b128 v[182:185], v170 offset:34816
	ds_read_b128 v[186:189], v170 offset:35840
	v_add_u32_e32 v171, s70, v143
	v_lshl_add_u64 v[224:225], s[54:55], 0, v[138:139]
	v_readfirstlane_b32 s84, v171
	v_add_u32_e32 v166, s77, v162
	v_add_u32_e32 v167, s78, v163
	v_add_u32_e32 v168, s79, v163
	v_add_u32_e32 v169, s82, v163
	v_lshl_add_u64 v[172:173], v[224:225], 0, s[8:9]
	s_mov_b32 m0, s84
	ds_read_b128 v[190:193], v166
	ds_read_b128 v[194:197], v166 offset:1024
	ds_read_b128 v[198:201], v167
	ds_read_b128 v[202:205], v167 offset:1024
	ds_read_b128 v[206:209], v168
	ds_read_b128 v[210:213], v168 offset:1024
	ds_read_b128 v[214:217], v169
	ds_read_b128 v[218:221], v169 offset:1024
	global_load_lds_dwordx4 v[172:173], off
	v_add_u32_e32 v172, 0x2000, v171
	v_lshl_add_u64 v[246:247], s[54:55], 0, v[140:141]
	v_readfirstlane_b32 s84, v172
	v_lshl_add_u64 v[222:223], v[246:247], 0, s[8:9]
	s_mov_b32 m0, s84
	s_nop 0
	global_load_lds_dwordx4 v[222:223], off
	s_waitcnt lgkmcnt(8)
	s_barrier
	s_waitcnt lgkmcnt(0)
	s_waitcnt lgkmcnt(0)
	v_mfma_f32_16x16x32_bf16 v[126:129], v[190:193], v[174:177], v[126:129]
	v_mfma_f32_16x16x32_bf16 v[122:125], v[190:193], v[182:185], v[122:125]
	v_mfma_f32_16x16x32_bf16 v[118:121], v[198:201], v[174:177], v[118:121]
	v_mfma_f32_16x16x32_bf16 v[114:117], v[198:201], v[182:185], v[114:117]
	v_mfma_f32_16x16x32_bf16 v[110:113], v[206:209], v[174:177], v[110:113]
	v_mfma_f32_16x16x32_bf16 v[106:109], v[206:209], v[182:185], v[106:109]
	v_mfma_f32_16x16x32_bf16 v[102:105], v[214:217], v[174:177], v[102:105]
	v_mfma_f32_16x16x32_bf16 v[98:101], v[214:217], v[182:185], v[98:101]
	v_mfma_f32_16x16x32_bf16 v[126:129], v[194:197], v[178:181], v[126:129]
	v_mfma_f32_16x16x32_bf16 v[122:125], v[194:197], v[186:189], v[122:125]
	v_mfma_f32_16x16x32_bf16 v[118:121], v[202:205], v[178:181], v[118:121]
	v_mfma_f32_16x16x32_bf16 v[114:117], v[202:205], v[186:189], v[114:117]
	v_mfma_f32_16x16x32_bf16 v[110:113], v[210:213], v[178:181], v[110:113]
	v_mfma_f32_16x16x32_bf16 v[106:109], v[210:213], v[186:189], v[106:109]
	v_mfma_f32_16x16x32_bf16 v[102:105], v[218:221], v[178:181], v[102:105]
	v_mfma_f32_16x16x32_bf16 v[98:101], v[218:221], v[186:189], v[98:101]
	s_barrier
	v_lshl_add_u64 v[248:249], s[54:55], 0, v[134:135]
	v_readfirstlane_b32 s84, v145
	v_lshl_add_u64 v[222:223], v[248:249], 0, s[10:11]
	s_mov_b32 m0, s84
	v_lshl_add_u64 v[250:251], s[54:55], 0, v[136:137]
	v_readfirstlane_b32 s84, v146
	ds_read_b128 v[226:229], v170 offset:49152
	ds_read_b128 v[230:233], v170 offset:50176
	ds_read_b128 v[234:237], v170 offset:51200
	ds_read_b128 v[238:241], v170 offset:52224
	global_load_lds_dwordx4 v[222:223], off
	v_lshl_add_u64 v[222:223], v[250:251], 0, s[10:11]
	s_mov_b32 m0, s84
	s_nop 0
	global_load_lds_dwordx4 v[222:223], off
	s_barrier
	s_waitcnt lgkmcnt(0)
	s_waitcnt lgkmcnt(0)
	v_mfma_f32_16x16x32_bf16 v[94:97], v[190:193], v[226:229], v[94:97]
	v_mfma_f32_16x16x32_bf16 v[90:93], v[190:193], v[234:237], v[90:93]
	v_mfma_f32_16x16x32_bf16 v[82:85], v[198:201], v[226:229], v[82:85]
	v_mfma_f32_16x16x32_bf16 v[66:69], v[198:201], v[234:237], v[66:69]
	v_mfma_f32_16x16x32_bf16 v[62:65], v[206:209], v[226:229], v[62:65]
	v_mfma_f32_16x16x32_bf16 v[58:61], v[206:209], v[234:237], v[58:61]
	v_mfma_f32_16x16x32_bf16 v[54:57], v[214:217], v[226:229], v[54:57]
	v_mfma_f32_16x16x32_bf16 v[50:53], v[214:217], v[234:237], v[50:53]
	v_mfma_f32_16x16x32_bf16 v[94:97], v[194:197], v[230:233], v[94:97]
	v_mfma_f32_16x16x32_bf16 v[90:93], v[194:197], v[238:241], v[90:93]
	v_mfma_f32_16x16x32_bf16 v[82:85], v[202:205], v[230:233], v[82:85]
	v_mfma_f32_16x16x32_bf16 v[66:69], v[202:205], v[238:241], v[66:69]
	v_mfma_f32_16x16x32_bf16 v[62:65], v[210:213], v[230:233], v[62:65]
	v_mfma_f32_16x16x32_bf16 v[58:61], v[210:213], v[238:241], v[58:61]
	v_mfma_f32_16x16x32_bf16 v[54:57], v[218:221], v[230:233], v[54:57]
	v_mfma_f32_16x16x32_bf16 v[50:53], v[218:221], v[238:241], v[50:53]
	v_readfirstlane_b32 s84, v144
	v_lshl_add_u64 v[222:223], v[224:225], 0, s[12:13]
	s_mov_b32 m0, s84
	v_readfirstlane_b32 s84, v147
	s_barrier
	ds_read_b128 v[190:193], v166 offset:16384
	ds_read_b128 v[194:197], v166 offset:17408
	ds_read_b128 v[198:201], v167 offset:16384
	ds_read_b128 v[202:205], v167 offset:17408
	ds_read_b128 v[206:209], v168 offset:16384
	ds_read_b128 v[210:213], v168 offset:17408
	ds_read_b128 v[214:217], v169 offset:16384
	ds_read_b128 v[218:221], v169 offset:17408
	global_load_lds_dwordx4 v[222:223], off
	v_lshl_add_u64 v[222:223], v[246:247], 0, s[12:13]
	s_mov_b32 m0, s84
	s_nop 0
	global_load_lds_dwordx4 v[222:223], off
	s_barrier
	s_waitcnt lgkmcnt(0)
	s_waitcnt lgkmcnt(0)
	v_mfma_f32_16x16x32_bf16 v[46:49], v[190:193], v[174:177], v[46:49]
	v_mfma_f32_16x16x32_bf16 v[42:45], v[190:193], v[182:185], v[42:45]
	v_mfma_f32_16x16x32_bf16 v[38:41], v[198:201], v[174:177], v[38:41]
	v_mfma_f32_16x16x32_bf16 v[34:37], v[198:201], v[182:185], v[34:37]
	v_mfma_f32_16x16x32_bf16 v[30:33], v[206:209], v[174:177], v[30:33]
	v_mfma_f32_16x16x32_bf16 v[26:29], v[206:209], v[182:185], v[26:29]
	v_mfma_f32_16x16x32_bf16 v[22:25], v[214:217], v[174:177], v[22:25]
	v_mfma_f32_16x16x32_bf16 v[18:21], v[214:217], v[182:185], v[18:21]
	v_mfma_f32_16x16x32_bf16 v[46:49], v[194:197], v[178:181], v[46:49]
	v_mfma_f32_16x16x32_bf16 v[42:45], v[194:197], v[186:189], v[42:45]
	v_mfma_f32_16x16x32_bf16 v[38:41], v[202:205], v[178:181], v[38:41]
	v_mfma_f32_16x16x32_bf16 v[34:37], v[202:205], v[186:189], v[34:37]
	v_mfma_f32_16x16x32_bf16 v[30:33], v[210:213], v[178:181], v[30:33]
	v_mfma_f32_16x16x32_bf16 v[26:29], v[210:213], v[186:189], v[26:29]
	v_mfma_f32_16x16x32_bf16 v[22:25], v[218:221], v[178:181], v[22:25]
	v_mfma_f32_16x16x32_bf16 v[18:21], v[218:221], v[186:189], v[18:21]
	s_barrier
	v_readfirstlane_b32 s84, v148
	v_lshl_add_u64 v[174:175], v[248:249], 0, s[24:25]
	s_mov_b32 m0, s84
	v_readfirstlane_b32 s84, v149
	global_load_lds_dwordx4 v[174:175], off
	v_lshl_add_u64 v[174:175], v[250:251], 0, s[24:25]
	s_mov_b32 m0, s84
	s_nop 0
	global_load_lds_dwordx4 v[174:175], off
	s_waitcnt vmcnt(6)
	s_barrier
	v_mfma_f32_16x16x32_bf16 v[14:17], v[190:193], v[226:229], v[14:17]
	v_mfma_f32_16x16x32_bf16 v[10:13], v[190:193], v[234:237], v[10:13]
	v_mfma_f32_16x16x32_bf16 v[6:9], v[198:201], v[226:229], v[6:9]
	v_mfma_f32_16x16x32_bf16 v[2:5], v[198:201], v[234:237], v[2:5]
	v_mfma_f32_16x16x32_bf16 v[70:73], v[206:209], v[226:229], v[70:73]
	v_mfma_f32_16x16x32_bf16 v[74:77], v[206:209], v[234:237], v[74:77]
	v_mfma_f32_16x16x32_bf16 v[78:81], v[214:217], v[226:229], v[78:81]
	v_mfma_f32_16x16x32_bf16 v[86:89], v[214:217], v[234:237], v[86:89]
	v_mfma_f32_16x16x32_bf16 v[14:17], v[194:197], v[230:233], v[14:17]
	v_mfma_f32_16x16x32_bf16 v[10:13], v[194:197], v[238:241], v[10:13]
	v_mfma_f32_16x16x32_bf16 v[6:9], v[202:205], v[230:233], v[6:9]
	v_mfma_f32_16x16x32_bf16 v[2:5], v[202:205], v[238:241], v[2:5]
	v_mfma_f32_16x16x32_bf16 v[70:73], v[210:213], v[230:233], v[70:73]
	v_mfma_f32_16x16x32_bf16 v[74:77], v[210:213], v[238:241], v[74:77]
	v_mfma_f32_16x16x32_bf16 v[78:81], v[218:221], v[230:233], v[78:81]
	v_mfma_f32_16x16x32_bf16 v[86:89], v[218:221], v[238:241], v[86:89]
	s_barrier
	ds_read_b128 v[180:183], v155
	ds_read_b128 v[184:187], v155 offset:1024
	ds_read_b128 v[188:191], v155 offset:2048
	ds_read_b128 v[192:195], v155 offset:3072
	v_readfirstlane_b32 s84, v150
	v_add_u32_e32 v173, s78, v164
	v_add_u32_e32 v174, s79, v164
	v_add_u32_e32 v175, s82, v164
	v_lshl_add_u64 v[226:227], v[224:225], 0, s[26:27]
	s_mov_b32 m0, s84
	v_readfirstlane_b32 s84, v151
	ds_read_b128 v[176:179], v154
	ds_read_b128 v[196:199], v154 offset:1024
	ds_read_b128 v[200:203], v173
	ds_read_b128 v[204:207], v173 offset:1024
	ds_read_b128 v[208:211], v174
	ds_read_b128 v[212:215], v174 offset:1024
	ds_read_b128 v[216:219], v175
	ds_read_b128 v[220:223], v175 offset:1024
	global_load_lds_dwordx4 v[226:227], off
	v_lshl_add_u64 v[226:227], v[246:247], 0, s[26:27]
	s_mov_b32 m0, s84
	s_nop 0
	global_load_lds_dwordx4 v[226:227], off
	s_waitcnt lgkmcnt(8)
	s_barrier
	s_waitcnt lgkmcnt(0)
	s_waitcnt lgkmcnt(0)
	v_mfma_f32_16x16x32_bf16 v[126:129], v[176:179], v[180:183], v[126:129]
	v_mfma_f32_16x16x32_bf16 v[122:125], v[176:179], v[188:191], v[122:125]
	v_mfma_f32_16x16x32_bf16 v[118:121], v[200:203], v[180:183], v[118:121]
	v_mfma_f32_16x16x32_bf16 v[114:117], v[200:203], v[188:191], v[114:117]
	v_mfma_f32_16x16x32_bf16 v[110:113], v[208:211], v[180:183], v[110:113]
	v_mfma_f32_16x16x32_bf16 v[106:109], v[208:211], v[188:191], v[106:109]
	v_mfma_f32_16x16x32_bf16 v[102:105], v[216:219], v[180:183], v[102:105]
	v_mfma_f32_16x16x32_bf16 v[98:101], v[216:219], v[188:191], v[98:101]
	v_mfma_f32_16x16x32_bf16 v[126:129], v[196:199], v[184:187], v[126:129]
	v_mfma_f32_16x16x32_bf16 v[122:125], v[196:199], v[192:195], v[122:125]
	v_mfma_f32_16x16x32_bf16 v[118:121], v[204:207], v[184:187], v[118:121]
	v_mfma_f32_16x16x32_bf16 v[114:117], v[204:207], v[192:195], v[114:117]
	v_mfma_f32_16x16x32_bf16 v[110:113], v[212:215], v[184:187], v[110:113]
	v_mfma_f32_16x16x32_bf16 v[106:109], v[212:215], v[192:195], v[106:109]
	v_mfma_f32_16x16x32_bf16 v[102:105], v[220:223], v[184:187], v[102:105]
	v_mfma_f32_16x16x32_bf16 v[98:101], v[220:223], v[192:195], v[98:101]
	s_barrier
	v_readfirstlane_b32 s84, v156
	v_lshl_add_u64 v[242:243], v[248:249], 0, s[28:29]
	s_mov_b32 m0, s84
	v_readfirstlane_b32 s84, v157
	ds_read_b128 v[226:229], v153
	ds_read_b128 v[230:233], v153 offset:1024
	ds_read_b128 v[234:237], v153 offset:2048
	ds_read_b128 v[238:241], v153 offset:3072
	global_load_lds_dwordx4 v[242:243], off
	v_lshl_add_u64 v[242:243], v[250:251], 0, s[28:29]
	s_mov_b32 m0, s84
	s_nop 0
	global_load_lds_dwordx4 v[242:243], off
	s_barrier
	s_waitcnt lgkmcnt(0)
	s_waitcnt lgkmcnt(0)
	v_mfma_f32_16x16x32_bf16 v[94:97], v[176:179], v[226:229], v[94:97]
	v_mfma_f32_16x16x32_bf16 v[90:93], v[176:179], v[234:237], v[90:93]
	v_mfma_f32_16x16x32_bf16 v[82:85], v[200:203], v[226:229], v[82:85]
	v_mfma_f32_16x16x32_bf16 v[66:69], v[200:203], v[234:237], v[66:69]
	v_mfma_f32_16x16x32_bf16 v[62:65], v[208:211], v[226:229], v[62:65]
	v_mfma_f32_16x16x32_bf16 v[58:61], v[208:211], v[234:237], v[58:61]
	v_mfma_f32_16x16x32_bf16 v[54:57], v[216:219], v[226:229], v[54:57]
	v_mfma_f32_16x16x32_bf16 v[50:53], v[216:219], v[234:237], v[50:53]
	v_mfma_f32_16x16x32_bf16 v[94:97], v[196:199], v[230:233], v[94:97]
	v_mfma_f32_16x16x32_bf16 v[90:93], v[196:199], v[238:241], v[90:93]
	v_mfma_f32_16x16x32_bf16 v[82:85], v[204:207], v[230:233], v[82:85]
	v_mfma_f32_16x16x32_bf16 v[66:69], v[204:207], v[238:241], v[66:69]
	v_mfma_f32_16x16x32_bf16 v[62:65], v[212:215], v[230:233], v[62:65]
	v_mfma_f32_16x16x32_bf16 v[58:61], v[212:215], v[238:241], v[58:61]
	v_mfma_f32_16x16x32_bf16 v[54:57], v[220:223], v[230:233], v[54:57]
	v_mfma_f32_16x16x32_bf16 v[50:53], v[220:223], v[238:241], v[50:53]
	v_readfirstlane_b32 s84, v158
	v_add_u32_e32 v176, s78, v165
	v_add_u32_e32 v177, s79, v165
	v_add_u32_e32 v178, s82, v165
	v_lshl_add_u64 v[224:225], v[224:225], 0, s[30:31]
	s_mov_b32 m0, s84
	v_readfirstlane_b32 s84, v159
	s_barrier
	ds_read_b128 v[196:199], v152
	ds_read_b128 v[200:203], v152 offset:1024
	ds_read_b128 v[204:207], v176
	ds_read_b128 v[208:211], v176 offset:1024
	ds_read_b128 v[212:215], v177
	ds_read_b128 v[216:219], v177 offset:1024
	ds_read_b128 v[220:223], v178
	ds_read_b128 v[242:245], v178 offset:1024
	global_load_lds_dwordx4 v[224:225], off
	v_lshl_add_u64 v[224:225], v[246:247], 0, s[30:31]
	s_mov_b32 m0, s84
	s_nop 0
	global_load_lds_dwordx4 v[224:225], off
	s_barrier
	s_waitcnt lgkmcnt(0)
	s_waitcnt lgkmcnt(0)
	v_mfma_f32_16x16x32_bf16 v[46:49], v[196:199], v[180:183], v[46:49]
	v_mfma_f32_16x16x32_bf16 v[42:45], v[196:199], v[188:191], v[42:45]
	v_mfma_f32_16x16x32_bf16 v[38:41], v[204:207], v[180:183], v[38:41]
	v_mfma_f32_16x16x32_bf16 v[34:37], v[204:207], v[188:191], v[34:37]
	v_mfma_f32_16x16x32_bf16 v[30:33], v[212:215], v[180:183], v[30:33]
	v_mfma_f32_16x16x32_bf16 v[26:29], v[212:215], v[188:191], v[26:29]
	v_mfma_f32_16x16x32_bf16 v[22:25], v[220:223], v[180:183], v[22:25]
	v_mfma_f32_16x16x32_bf16 v[18:21], v[220:223], v[188:191], v[18:21]
	v_mfma_f32_16x16x32_bf16 v[46:49], v[200:203], v[184:187], v[46:49]
	v_mfma_f32_16x16x32_bf16 v[42:45], v[200:203], v[192:195], v[42:45]
	v_mfma_f32_16x16x32_bf16 v[38:41], v[208:211], v[184:187], v[38:41]
	v_mfma_f32_16x16x32_bf16 v[34:37], v[208:211], v[192:195], v[34:37]
	v_mfma_f32_16x16x32_bf16 v[30:33], v[216:219], v[184:187], v[30:33]
	v_mfma_f32_16x16x32_bf16 v[26:29], v[216:219], v[192:195], v[26:29]
	v_mfma_f32_16x16x32_bf16 v[22:25], v[242:245], v[184:187], v[22:25]
	v_mfma_f32_16x16x32_bf16 v[18:21], v[242:245], v[192:195], v[18:21]
	s_barrier
	v_readfirstlane_b32 s84, v160
	v_lshl_add_u64 v[180:181], v[248:249], 0, s[34:35]
	s_mov_b32 m0, s84
	v_readfirstlane_b32 s84, v161
	global_load_lds_dwordx4 v[180:181], off
	v_lshl_add_u64 v[180:181], v[250:251], 0, s[34:35]
	s_mov_b32 m0, s84
	s_nop 0
	global_load_lds_dwordx4 v[180:181], off
	s_waitcnt vmcnt(6)
	s_barrier
	v_mfma_f32_16x16x32_bf16 v[14:17], v[196:199], v[226:229], v[14:17]
	v_mfma_f32_16x16x32_bf16 v[10:13], v[196:199], v[234:237], v[10:13]
	v_mfma_f32_16x16x32_bf16 v[6:9], v[204:207], v[226:229], v[6:9]
	v_mfma_f32_16x16x32_bf16 v[2:5], v[204:207], v[234:237], v[2:5]
	v_mfma_f32_16x16x32_bf16 v[70:73], v[212:215], v[226:229], v[70:73]
	v_mfma_f32_16x16x32_bf16 v[74:77], v[212:215], v[234:237], v[74:77]
	v_mfma_f32_16x16x32_bf16 v[78:81], v[220:223], v[226:229], v[78:81]
	v_mfma_f32_16x16x32_bf16 v[86:89], v[220:223], v[234:237], v[86:89]
	v_mfma_f32_16x16x32_bf16 v[14:17], v[200:203], v[230:233], v[14:17]
	v_mfma_f32_16x16x32_bf16 v[10:13], v[200:203], v[238:241], v[10:13]
	v_mfma_f32_16x16x32_bf16 v[6:9], v[208:211], v[230:233], v[6:9]
	v_mfma_f32_16x16x32_bf16 v[2:5], v[208:211], v[238:241], v[2:5]
	v_mfma_f32_16x16x32_bf16 v[70:73], v[216:219], v[230:233], v[70:73]
	v_mfma_f32_16x16x32_bf16 v[74:77], v[216:219], v[238:241], v[74:77]
	v_mfma_f32_16x16x32_bf16 v[78:81], v[242:245], v[230:233], v[78:81]
	v_mfma_f32_16x16x32_bf16 v[86:89], v[242:245], v[238:241], v[86:89]
	s_add_i32 s83, s83, 2
	s_add_u32 s54, s54, 0x100
	s_addc_u32 s55, s55, 0
	s_cmp_lt_u32 s83, 40
	s_barrier
	s_cbranch_scc1 .LBB0_1468
	s_or_b32 s54, s73, 0x80
	s_mul_i32 s76, s54, 0x1600
	s_mul_hi_i32 s55, s54, 0x1600
	s_add_u32 s76, s94, s76
	s_addc_u32 s55, s95, s55
	s_add_u32 s76, s76, 0x1580
	s_addc_u32 s77, s55, 0
	v_readfirstlane_b32 s55, v171
	v_lshl_add_u64 v[164:165], v[130:131], 1, s[76:77]
	s_mov_b32 m0, s55
	v_readfirstlane_b32 s55, v172
	ds_read_b128 v[134:137], v170 offset:32768
	ds_read_b128 v[138:141], v170 offset:33792
	ds_read_b128 v[144:147], v170 offset:34816
	ds_read_b128 v[148:151], v170 offset:35840
	ds_read_b128 v[156:159], v166
	ds_read_b128 v[160:163], v166 offset:1024
	ds_read_b128 v[180:183], v167
	ds_read_b128 v[184:187], v167 offset:1024
	ds_read_b128 v[188:191], v168
	ds_read_b128 v[192:195], v168 offset:1024
	ds_read_b128 v[196:199], v169
	ds_read_b128 v[200:203], v169 offset:1024
	global_load_lds_dwordx4 v[164:165], off
	v_lshl_add_u64 v[132:133], v[132:133], 1, s[76:77]
	s_mov_b32 m0, s55
	s_nop 0
	global_load_lds_dwordx4 v[132:133], off
	s_barrier
	s_waitcnt lgkmcnt(0)
	s_waitcnt lgkmcnt(0)
	v_mfma_f32_16x16x32_bf16 v[126:129], v[156:159], v[134:137], v[126:129]
	v_mfma_f32_16x16x32_bf16 v[122:125], v[156:159], v[144:147], v[122:125]
	v_mfma_f32_16x16x32_bf16 v[118:121], v[180:183], v[134:137], v[118:121]
	v_mfma_f32_16x16x32_bf16 v[114:117], v[180:183], v[144:147], v[114:117]
	v_mfma_f32_16x16x32_bf16 v[110:113], v[188:191], v[134:137], v[110:113]
	v_mfma_f32_16x16x32_bf16 v[126:129], v[160:163], v[138:141], v[126:129]
	v_mfma_f32_16x16x32_bf16 v[122:125], v[160:163], v[148:151], v[122:125]
	v_mfma_f32_16x16x32_bf16 v[118:121], v[184:187], v[138:141], v[118:121]
	v_mfma_f32_16x16x32_bf16 v[114:117], v[184:187], v[148:151], v[114:117]
	v_mfma_f32_16x16x32_bf16 v[110:113], v[192:195], v[138:141], v[110:113]
	v_mfma_f32_16x16x32_bf16 v[106:109], v[188:191], v[144:147], v[106:109]
	v_mfma_f32_16x16x32_bf16 v[102:105], v[196:199], v[134:137], v[102:105]
	v_mfma_f32_16x16x32_bf16 v[98:101], v[196:199], v[144:147], v[98:101]
	v_mfma_f32_16x16x32_bf16 v[204:207], v[192:195], v[148:151], v[106:109]
	v_mfma_f32_16x16x32_bf16 v[208:211], v[200:203], v[138:141], v[102:105]
	v_mfma_f32_16x16x32_bf16 v[212:215], v[200:203], v[148:151], v[98:101]
	s_barrier
	s_nop 2
	ds_read_b128 v[98:101], v170 offset:49152
	ds_read_b128 v[102:105], v170 offset:50176
	ds_read_b128 v[106:109], v170 offset:51200
	ds_read_b128 v[216:219], v170 offset:52224
	s_barrier
	s_waitcnt lgkmcnt(0)
	s_waitcnt lgkmcnt(0)
	v_mfma_f32_16x16x32_bf16 v[94:97], v[156:159], v[98:101], v[94:97]
	v_mfma_f32_16x16x32_bf16 v[90:93], v[156:159], v[106:109], v[90:93]
	v_mfma_f32_16x16x32_bf16 v[82:85], v[180:183], v[98:101], v[82:85]
	v_mfma_f32_16x16x32_bf16 v[62:65], v[188:191], v[98:101], v[62:65]
	v_mfma_f32_16x16x32_bf16 v[58:61], v[188:191], v[106:109], v[58:61]
	v_mfma_f32_16x16x32_bf16 v[54:57], v[196:199], v[98:101], v[54:57]
	v_mfma_f32_16x16x32_bf16 v[50:53], v[196:199], v[106:109], v[50:53]
	v_mfma_f32_16x16x32_bf16 v[94:97], v[160:163], v[102:105], v[94:97]
	v_mfma_f32_16x16x32_bf16 v[90:93], v[160:163], v[216:219], v[90:93]
	v_mfma_f32_16x16x32_bf16 v[82:85], v[184:187], v[102:105], v[82:85]
	v_mfma_f32_16x16x32_bf16 v[66:69], v[180:183], v[106:109], v[66:69]
	v_mfma_f32_16x16x32_bf16 v[62:65], v[192:195], v[102:105], v[62:65]
	v_mfma_f32_16x16x32_bf16 v[58:61], v[192:195], v[216:219], v[58:61]
	v_mfma_f32_16x16x32_bf16 v[54:57], v[200:203], v[102:105], v[54:57]
	v_mfma_f32_16x16x32_bf16 v[50:53], v[200:203], v[216:219], v[50:53]
	v_mfma_f32_16x16x32_bf16 v[156:159], v[184:187], v[216:219], v[66:69]
	s_barrier
	s_nop 0
	ds_read_b128 v[66:69], v166 offset:16384
	ds_read_b128 v[160:163], v166 offset:17408
	ds_read_b128 v[180:183], v167 offset:16384
	ds_read_b128 v[164:167], v167 offset:17408
	ds_read_b128 v[184:187], v168 offset:16384
	ds_read_b128 v[188:191], v168 offset:17408
	ds_read_b128 v[192:195], v169 offset:16384
	ds_read_b128 v[168:171], v169 offset:17408
	s_waitcnt vmcnt(4)
	s_barrier
	s_waitcnt lgkmcnt(0)
	s_waitcnt lgkmcnt(0)
	v_mfma_f32_16x16x32_bf16 v[46:49], v[66:69], v[134:137], v[46:49]
	v_mfma_f32_16x16x32_bf16 v[42:45], v[66:69], v[144:147], v[42:45]
	v_mfma_f32_16x16x32_bf16 v[30:33], v[184:187], v[134:137], v[30:33]
	v_mfma_f32_16x16x32_bf16 v[26:29], v[184:187], v[144:147], v[26:29]
	v_mfma_f32_16x16x32_bf16 v[22:25], v[192:195], v[134:137], v[22:25]
	v_mfma_f32_16x16x32_bf16 v[18:21], v[192:195], v[144:147], v[18:21]
	v_mfma_f32_16x16x32_bf16 v[46:49], v[160:163], v[138:141], v[46:49]
	v_mfma_f32_16x16x32_bf16 v[42:45], v[160:163], v[148:151], v[42:45]
	v_mfma_f32_16x16x32_bf16 v[38:41], v[180:183], v[134:137], v[38:41]
	v_mfma_f32_16x16x32_bf16 v[34:37], v[180:183], v[144:147], v[34:37]
	v_mfma_f32_16x16x32_bf16 v[30:33], v[188:191], v[138:141], v[30:33]
	v_mfma_f32_16x16x32_bf16 v[26:29], v[188:191], v[148:151], v[26:29]
	v_mfma_f32_16x16x32_bf16 v[22:25], v[168:171], v[138:141], v[22:25]
	v_mfma_f32_16x16x32_bf16 v[18:21], v[168:171], v[148:151], v[18:21]
	v_mfma_f32_16x16x32_bf16 v[196:199], v[164:167], v[138:141], v[38:41]
	v_mfma_f32_16x16x32_bf16 v[200:203], v[164:167], v[148:151], v[34:37]
	v_mfma_f32_16x16x32_bf16 v[2:5], v[180:183], v[106:109], v[2:5]
	v_mfma_f32_16x16x32_bf16 v[136:139], v[164:167], v[216:219], v[2:5]
	v_mfma_f32_16x16x32_bf16 v[2:5], v[184:187], v[98:101], v[70:73]
	v_mfma_f32_16x16x32_bf16 v[144:147], v[188:191], v[102:105], v[2:5]
	v_mfma_f32_16x16x32_bf16 v[2:5], v[184:187], v[106:109], v[74:77]
	v_mfma_f32_16x16x32_bf16 v[14:17], v[66:69], v[98:101], v[14:17]
	v_mfma_f32_16x16x32_bf16 v[10:13], v[66:69], v[106:109], v[10:13]
	v_mfma_f32_16x16x32_bf16 v[148:151], v[188:191], v[216:219], v[2:5]
	v_mfma_f32_16x16x32_bf16 v[2:5], v[192:195], v[98:101], v[78:81]
	v_mfma_f32_16x16x32_bf16 v[14:17], v[160:163], v[102:105], v[14:17]
	v_mfma_f32_16x16x32_bf16 v[10:13], v[160:163], v[216:219], v[10:13]
	v_mfma_f32_16x16x32_bf16 v[6:9], v[180:183], v[98:101], v[6:9]
	v_mfma_f32_16x16x32_bf16 v[160:163], v[168:171], v[102:105], v[2:5]
	v_mfma_f32_16x16x32_bf16 v[2:5], v[192:195], v[106:109], v[86:89]
	v_mfma_f32_16x16x32_bf16 v[132:135], v[164:167], v[102:105], v[6:9]
	v_mfma_f32_16x16x32_bf16 v[164:167], v[168:171], v[216:219], v[2:5]
	s_barrier
	s_nop 3
	ds_read_b128 v[2:5], v155
	ds_read_b128 v[6:9], v155 offset:1024
	ds_read_b128 v[168:171], v155 offset:2048
	ds_read_b128 v[180:183], v155 offset:3072
	ds_read_b128 v[34:37], v154
	ds_read_b128 v[38:41], v154 offset:1024
	ds_read_b128 v[78:81], v173
	ds_read_b128 v[86:89], v173 offset:1024
	ds_read_b128 v[184:187], v174
	ds_read_b128 v[188:191], v174 offset:1024
	ds_read_b128 v[192:195], v175
	ds_read_b128 v[172:175], v175 offset:1024
	s_waitcnt vmcnt(2)
	s_barrier
	s_waitcnt lgkmcnt(0)
	s_waitcnt lgkmcnt(0)
	v_mfma_f32_16x16x32_bf16 v[66:69], v[34:37], v[2:5], v[126:129]
	v_mfma_f32_16x16x32_bf16 v[126:129], v[38:41], v[6:9], v[66:69]
	v_mfma_f32_16x16x32_bf16 v[66:69], v[34:37], v[168:171], v[122:125]
	v_mfma_f32_16x16x32_bf16 v[98:101], v[38:41], v[180:183], v[66:69]
	v_mfma_f32_16x16x32_bf16 v[66:69], v[78:81], v[2:5], v[118:121]
	v_mfma_f32_16x16x32_bf16 v[102:105], v[86:89], v[6:9], v[66:69]
	v_mfma_f32_16x16x32_bf16 v[66:69], v[78:81], v[168:171], v[114:117]
	v_mfma_f32_16x16x32_bf16 v[106:109], v[86:89], v[180:183], v[66:69]
	v_mfma_f32_16x16x32_bf16 v[66:69], v[184:187], v[2:5], v[110:113]
	v_mfma_f32_16x16x32_bf16 v[110:113], v[188:191], v[6:9], v[66:69]
	v_mfma_f32_16x16x32_bf16 v[66:69], v[184:187], v[168:171], v[204:207]
	v_mfma_f32_16x16x32_bf16 v[114:117], v[188:191], v[180:183], v[66:69]
	v_mfma_f32_16x16x32_bf16 v[66:69], v[192:195], v[2:5], v[208:211]
	v_mfma_f32_16x16x32_bf16 v[118:121], v[172:175], v[6:9], v[66:69]
	v_mfma_f32_16x16x32_bf16 v[66:69], v[192:195], v[168:171], v[212:215]
	v_mfma_f32_16x16x32_bf16 v[122:125], v[172:175], v[180:183], v[66:69]
	s_barrier
	ds_read_b128 v[204:207], v153
	ds_read_b128 v[208:211], v153 offset:1024
	ds_read_b128 v[212:215], v153 offset:2048
	ds_read_b128 v[216:219], v153 offset:3072
	s_waitcnt vmcnt(0)
	s_barrier
	s_waitcnt lgkmcnt(0)
	s_waitcnt lgkmcnt(0)
	v_mfma_f32_16x16x32_bf16 v[66:69], v[34:37], v[204:207], v[94:97]
	v_mfma_f32_16x16x32_bf16 v[34:37], v[34:37], v[212:215], v[90:93]
	v_mfma_f32_16x16x32_bf16 v[70:73], v[38:41], v[216:219], v[34:37]
	v_mfma_f32_16x16x32_bf16 v[34:37], v[78:81], v[204:207], v[82:85]
	v_mfma_f32_16x16x32_bf16 v[74:77], v[86:89], v[208:211], v[34:37]
	v_mfma_f32_16x16x32_bf16 v[34:37], v[78:81], v[212:215], v[156:159]
	v_mfma_f32_16x16x32_bf16 v[78:81], v[86:89], v[216:219], v[34:37]
	v_mfma_f32_16x16x32_bf16 v[34:37], v[184:187], v[204:207], v[62:65]
	v_mfma_f32_16x16x32_bf16 v[82:85], v[188:191], v[208:211], v[34:37]
	v_mfma_f32_16x16x32_bf16 v[34:37], v[184:187], v[212:215], v[58:61]
	v_mfma_f32_16x16x32_bf16 v[86:89], v[188:191], v[216:219], v[34:37]
	v_mfma_f32_16x16x32_bf16 v[34:37], v[192:195], v[204:207], v[54:57]
	v_mfma_f32_16x16x32_bf16 v[90:93], v[172:175], v[208:211], v[34:37]
	v_mfma_f32_16x16x32_bf16 v[34:37], v[192:195], v[212:215], v[50:53]
	v_mfma_f32_16x16x32_bf16 v[66:69], v[38:41], v[208:211], v[66:69]
	v_mfma_f32_16x16x32_bf16 v[94:97], v[172:175], v[216:219], v[34:37]
	s_barrier
	ds_read_b128 v[154:157], v152
	ds_read_b128 v[172:175], v152 offset:1024
	ds_read_b128 v[184:187], v176
	ds_read_b128 v[188:191], v176 offset:1024
	ds_read_b128 v[192:195], v177
	ds_read_b128 v[220:223], v177 offset:1024
	ds_read_b128 v[226:229], v178
	ds_read_b128 v[176:179], v178 offset:1024
	s_barrier
	s_waitcnt lgkmcnt(0)
	s_waitcnt lgkmcnt(0)
	v_mfma_f32_16x16x32_bf16 v[34:37], v[154:157], v[2:5], v[46:49]
	v_mfma_f32_16x16x32_bf16 v[38:41], v[154:157], v[168:171], v[42:45]
	v_mfma_f32_16x16x32_bf16 v[42:45], v[184:187], v[2:5], v[196:199]
	v_mfma_f32_16x16x32_bf16 v[30:33], v[192:195], v[2:5], v[30:33]
	v_mfma_f32_16x16x32_bf16 v[2:5], v[226:229], v[2:5], v[22:25]
	v_mfma_f32_16x16x32_bf16 v[46:49], v[184:187], v[168:171], v[200:203]
	v_mfma_f32_16x16x32_bf16 v[26:29], v[192:195], v[168:171], v[26:29]
	v_mfma_f32_16x16x32_bf16 v[58:61], v[176:179], v[6:9], v[2:5]
	v_mfma_f32_16x16x32_bf16 v[2:5], v[226:229], v[168:171], v[18:21]
	v_mfma_f32_16x16x32_bf16 v[34:37], v[172:175], v[6:9], v[34:37]
	v_mfma_f32_16x16x32_bf16 v[38:41], v[172:175], v[180:183], v[38:41]
	v_mfma_f32_16x16x32_bf16 v[42:45], v[188:191], v[6:9], v[42:45]
	v_mfma_f32_16x16x32_bf16 v[46:49], v[188:191], v[180:183], v[46:49]
	v_mfma_f32_16x16x32_bf16 v[50:53], v[220:223], v[6:9], v[30:33]
	v_mfma_f32_16x16x32_bf16 v[54:57], v[220:223], v[180:183], v[26:29]
	v_mfma_f32_16x16x32_bf16 v[62:65], v[176:179], v[180:183], v[2:5]
	v_mfma_f32_16x16x32_bf16 v[2:5], v[154:157], v[204:207], v[14:17]
	v_mfma_f32_16x16x32_bf16 v[6:9], v[154:157], v[212:215], v[10:13]
	v_mfma_f32_16x16x32_bf16 v[10:13], v[184:187], v[204:207], v[132:135]
	v_mfma_f32_16x16x32_bf16 v[14:17], v[184:187], v[212:215], v[136:139]
	v_mfma_f32_16x16x32_bf16 v[18:21], v[192:195], v[204:207], v[144:147]
	v_mfma_f32_16x16x32_bf16 v[22:25], v[192:195], v[212:215], v[148:151]
	v_mfma_f32_16x16x32_bf16 v[26:29], v[226:229], v[204:207], v[160:163]
	v_mfma_f32_16x16x32_bf16 v[30:33], v[226:229], v[212:215], v[164:167]
	v_mfma_f32_16x16x32_bf16 v[2:5], v[172:175], v[208:211], v[2:5]
	v_mfma_f32_16x16x32_bf16 v[6:9], v[172:175], v[216:219], v[6:9]
	v_mfma_f32_16x16x32_bf16 v[10:13], v[188:191], v[208:211], v[10:13]
	v_mfma_f32_16x16x32_bf16 v[14:17], v[188:191], v[216:219], v[14:17]
	v_mfma_f32_16x16x32_bf16 v[18:21], v[220:223], v[208:211], v[18:21]
	v_mfma_f32_16x16x32_bf16 v[22:25], v[220:223], v[216:219], v[22:25]
	v_mfma_f32_16x16x32_bf16 v[26:29], v[176:179], v[208:211], v[26:29]
	v_mfma_f32_16x16x32_bf16 v[30:33], v[176:179], v[216:219], v[30:33]
	s_setprio 0
	s_cmpk_gt_u32 s75, 0xff
	s_barrier
	s_cbranch_scc1 .LBB0_1471
	s_barrier

.LBB0_1595:
	v_add_u32_e32 v2, s1, v168
	v_ashrrev_i32_e32 v3, 31, v2
	v_add_u32_e32 v4, 16, v2
	v_lshlrev_b64 v[2:3], 11, v[2:3]
	v_ashrrev_i32_e32 v5, 31, v4
	v_lshl_add_u64 v[2:3], v[156:157], 0, v[2:3]
	v_lshlrev_b64 v[6:7], 11, v[4:5]
	global_load_dwordx4 v[2:5], v[2:3], off
	v_lshl_add_u64 v[6:7], v[156:157], 0, v[6:7]
	global_load_dwordx4 v[114:117], v[6:7], off
	s_add_i32 s1, s1, 32
	s_cmpk_eq_i32 s1, 0x80
	s_waitcnt vmcnt(1)
	v_mfma_f32_32x32x16_bf16 v[176:191], v[2:5], v[130:133], 0
	v_mfma_f32_32x32x16_bf16 v[192:207], v[2:5], v[134:137], 0
	v_mfma_f32_32x32x16_bf16 v[208:223], v[2:5], v[138:141], 0
	v_mfma_f32_32x32x16_bf16 v[224:239], v[2:5], v[142:145], 0
	s_waitcnt vmcnt(0)
	v_mfma_f32_32x32x16_bf16 v[50:65], v[114:117], v[130:133], 0
	v_mfma_f32_32x32x16_bf16 v[66:81], v[114:117], v[134:137], 0
	v_mfma_f32_32x32x16_bf16 v[82:97], v[114:117], v[138:141], 0
	v_mfma_f32_32x32x16_bf16 v[98:113], v[114:117], v[142:145], 0
	s_nop 7
	v_fma_f32 v244, -v153, v35, v176
	v_fma_f32 v245, v153, v34, v192
	v_fma_f32 v246, -v155, v119, v208
	v_fma_f32 v247, v155, v118, v224
	v_fma_f32 v240, v152, v34, v244
	v_fma_f32 v241, v152, v35, v245
	v_fma_f32 v242, v154, v118, v246
	v_fma_f32 v243, v154, v119, v247
	v_fma_f32 v244, -v153, v241, v177
	v_fma_f32 v245, v153, v240, v193
	v_fma_f32 v246, -v155, v243, v209
	v_fma_f32 v247, v155, v242, v225
	v_fma_f32 v34, v152, v240, v244
	v_fma_f32 v35, v152, v241, v245
	v_fma_f32 v118, v154, v242, v246
	v_fma_f32 v119, v154, v243, v247
	v_fma_f32 v244, -v153, v35, v178
	v_fma_f32 v245, v153, v34, v194
	v_fma_f32 v246, -v155, v119, v210
	v_fma_f32 v247, v155, v118, v226
	v_fma_f32 v240, v152, v34, v244
	v_fma_f32 v241, v152, v35, v245
	v_fma_f32 v242, v154, v118, v246
	v_fma_f32 v243, v154, v119, v247
	v_fma_f32 v244, -v153, v241, v179
	v_fma_f32 v245, v153, v240, v195
	v_fma_f32 v246, -v155, v243, v211
	v_fma_f32 v247, v155, v242, v227
	v_fma_f32 v34, v152, v240, v244
	v_fma_f32 v35, v152, v241, v245
	v_fma_f32 v118, v154, v242, v246
	v_fma_f32 v119, v154, v243, v247
	v_fma_f32 v244, -v153, v35, v180
	v_fma_f32 v245, v153, v34, v196
	v_fma_f32 v246, -v155, v119, v212
	v_fma_f32 v247, v155, v118, v228
	v_fma_f32 v240, v152, v34, v244
	v_fma_f32 v241, v152, v35, v245
	v_fma_f32 v242, v154, v118, v246
	v_fma_f32 v243, v154, v119, v247
	v_fma_f32 v244, -v153, v241, v181
	v_fma_f32 v245, v153, v240, v197
	v_fma_f32 v246, -v155, v243, v213
	v_fma_f32 v247, v155, v242, v229
	v_fma_f32 v34, v152, v240, v244
	v_fma_f32 v35, v152, v241, v245
	v_fma_f32 v118, v154, v242, v246
	v_fma_f32 v119, v154, v243, v247
	v_fma_f32 v244, -v153, v35, v182
	v_fma_f32 v245, v153, v34, v198
	v_fma_f32 v246, -v155, v119, v214
	v_fma_f32 v247, v155, v118, v230
	v_fma_f32 v240, v152, v34, v244
	v_fma_f32 v241, v152, v35, v245
	v_fma_f32 v242, v154, v118, v246
	v_fma_f32 v243, v154, v119, v247
	v_fma_f32 v244, -v153, v241, v183
	v_fma_f32 v245, v153, v240, v199
	v_fma_f32 v246, -v155, v243, v215
	v_fma_f32 v247, v155, v242, v231
	v_fma_f32 v34, v152, v240, v244
	v_fma_f32 v35, v152, v241, v245
	v_fma_f32 v118, v154, v242, v246
	v_fma_f32 v119, v154, v243, v247
	v_fma_f32 v244, -v153, v35, v184
	v_fma_f32 v245, v153, v34, v200
	v_fma_f32 v246, -v155, v119, v216
	v_fma_f32 v247, v155, v118, v232
	v_fma_f32 v240, v152, v34, v244
	v_fma_f32 v241, v152, v35, v245
	v_fma_f32 v242, v154, v118, v246
	v_fma_f32 v243, v154, v119, v247
	v_fma_f32 v244, -v153, v241, v185
	v_fma_f32 v245, v153, v240, v201
	v_fma_f32 v246, -v155, v243, v217
	v_fma_f32 v247, v155, v242, v233
	v_fma_f32 v34, v152, v240, v244
	v_fma_f32 v35, v152, v241, v245
	v_fma_f32 v118, v154, v242, v246
	v_fma_f32 v119, v154, v243, v247
	v_fma_f32 v244, -v153, v35, v186
	v_fma_f32 v245, v153, v34, v202
	v_fma_f32 v246, -v155, v119, v218
	v_fma_f32 v247, v155, v118, v234
	v_fma_f32 v240, v152, v34, v244
	v_fma_f32 v241, v152, v35, v245
	v_fma_f32 v242, v154, v118, v246
	v_fma_f32 v243, v154, v119, v247
	v_fma_f32 v244, -v153, v241, v187
	v_fma_f32 v245, v153, v240, v203
	v_fma_f32 v246, -v155, v243, v219
	v_fma_f32 v247, v155, v242, v235
	v_fma_f32 v34, v152, v240, v244
	v_fma_f32 v35, v152, v241, v245
	v_fma_f32 v118, v154, v242, v246
	v_fma_f32 v119, v154, v243, v247
	v_fma_f32 v244, -v153, v35, v188
	v_fma_f32 v245, v153, v34, v204
	v_fma_f32 v246, -v155, v119, v220
	v_fma_f32 v247, v155, v118, v236
	v_fma_f32 v240, v152, v34, v244
	v_fma_f32 v241, v152, v35, v245
	v_fma_f32 v242, v154, v118, v246
	v_fma_f32 v243, v154, v119, v247
	v_fma_f32 v244, -v153, v241, v189
	v_fma_f32 v245, v153, v240, v205
	v_fma_f32 v246, -v155, v243, v221
	v_fma_f32 v247, v155, v242, v237
	v_fma_f32 v34, v152, v240, v244
	v_fma_f32 v35, v152, v241, v245
	v_fma_f32 v118, v154, v242, v246
	v_fma_f32 v119, v154, v243, v247
	v_fma_f32 v244, -v153, v35, v190
	v_fma_f32 v245, v153, v34, v206
	v_fma_f32 v246, -v155, v119, v222
	v_fma_f32 v247, v155, v118, v238
	v_fma_f32 v240, v152, v34, v244
	v_fma_f32 v241, v152, v35, v245
	v_fma_f32 v242, v154, v118, v246
	v_fma_f32 v243, v154, v119, v247
	v_fma_f32 v244, -v153, v241, v191
	v_fma_f32 v245, v153, v240, v207
	v_fma_f32 v246, -v155, v243, v223
	v_fma_f32 v247, v155, v242, v239
	v_fma_f32 v34, v152, v240, v244
	v_fma_f32 v35, v152, v241, v245
	v_fma_f32 v118, v154, v242, v246
	v_fma_f32 v119, v154, v243, v247
	v_fma_f32 v244, -v153, v35, v50
	v_fma_f32 v245, v153, v34, v66
	v_fma_f32 v246, -v155, v119, v82
	v_fma_f32 v247, v155, v118, v98
	v_fma_f32 v240, v152, v34, v244
	v_fma_f32 v241, v152, v35, v245
	v_fma_f32 v242, v154, v118, v246
	v_fma_f32 v243, v154, v119, v247
	v_fma_f32 v244, -v153, v241, v51
	v_fma_f32 v245, v153, v240, v67
	v_fma_f32 v246, -v155, v243, v83
	v_fma_f32 v247, v155, v242, v99
	v_fma_f32 v34, v152, v240, v244
	v_fma_f32 v35, v152, v241, v245
	v_fma_f32 v118, v154, v242, v246
	v_fma_f32 v119, v154, v243, v247
	v_fma_f32 v244, -v153, v35, v52
	v_fma_f32 v245, v153, v34, v68
	v_fma_f32 v246, -v155, v119, v84
	v_fma_f32 v247, v155, v118, v100
	v_fma_f32 v240, v152, v34, v244
	v_fma_f32 v241, v152, v35, v245
	v_fma_f32 v242, v154, v118, v246
	v_fma_f32 v243, v154, v119, v247
	v_fma_f32 v244, -v153, v241, v53
	v_fma_f32 v245, v153, v240, v69
	v_fma_f32 v246, -v155, v243, v85
	v_fma_f32 v247, v155, v242, v101
	v_fma_f32 v34, v152, v240, v244
	v_fma_f32 v35, v152, v241, v245
	v_fma_f32 v118, v154, v242, v246
	v_fma_f32 v119, v154, v243, v247
	v_fma_f32 v244, -v153, v35, v54
	v_fma_f32 v245, v153, v34, v70
	v_fma_f32 v246, -v155, v119, v86
	v_fma_f32 v247, v155, v118, v102
	v_fma_f32 v240, v152, v34, v244
	v_fma_f32 v241, v152, v35, v245
	v_fma_f32 v242, v154, v118, v246
	v_fma_f32 v243, v154, v119, v247
	v_fma_f32 v244, -v153, v241, v55
	v_fma_f32 v245, v153, v240, v71
	v_fma_f32 v246, -v155, v243, v87
	v_fma_f32 v247, v155, v242, v103
	v_fma_f32 v34, v152, v240, v244
	v_fma_f32 v35, v152, v241, v245
	v_fma_f32 v118, v154, v242, v246
	v_fma_f32 v119, v154, v243, v247
	v_fma_f32 v244, -v153, v35, v56
	v_fma_f32 v245, v153, v34, v72
	v_fma_f32 v246, -v155, v119, v88
	v_fma_f32 v247, v155, v118, v104
	v_fma_f32 v240, v152, v34, v244
	v_fma_f32 v241, v152, v35, v245
	v_fma_f32 v242, v154, v118, v246
	v_fma_f32 v243, v154, v119, v247
	v_fma_f32 v244, -v153, v241, v57
	v_fma_f32 v245, v153, v240, v73
	v_fma_f32 v246, -v155, v243, v89
	v_fma_f32 v247, v155, v242, v105
	v_fma_f32 v34, v152, v240, v244
	v_fma_f32 v35, v152, v241, v245
	v_fma_f32 v118, v154, v242, v246
	v_fma_f32 v119, v154, v243, v247
	v_fma_f32 v244, -v153, v35, v58
	v_fma_f32 v245, v153, v34, v74
	v_fma_f32 v246, -v155, v119, v90
	v_fma_f32 v247, v155, v118, v106
	v_fma_f32 v240, v152, v34, v244
	v_fma_f32 v241, v152, v35, v245
	v_fma_f32 v242, v154, v118, v246
	v_fma_f32 v243, v154, v119, v247
	v_fma_f32 v244, -v153, v241, v59
	v_fma_f32 v245, v153, v240, v75
	v_fma_f32 v246, -v155, v243, v91
	v_fma_f32 v247, v155, v242, v107
	v_fma_f32 v34, v152, v240, v244
	v_fma_f32 v35, v152, v241, v245
	v_fma_f32 v118, v154, v242, v246
	v_fma_f32 v119, v154, v243, v247
	v_fma_f32 v244, -v153, v35, v60
	v_fma_f32 v245, v153, v34, v76
	v_fma_f32 v246, -v155, v119, v92
	v_fma_f32 v247, v155, v118, v108
	v_fma_f32 v240, v152, v34, v244
	v_fma_f32 v241, v152, v35, v245
	v_fma_f32 v242, v154, v118, v246
	v_fma_f32 v243, v154, v119, v247
	v_fma_f32 v244, -v153, v241, v61
	v_fma_f32 v245, v153, v240, v77
	v_fma_f32 v246, -v155, v243, v93
	v_fma_f32 v247, v155, v242, v109
	v_fma_f32 v34, v152, v240, v244
	v_fma_f32 v35, v152, v241, v245
	v_fma_f32 v118, v154, v242, v246
	v_fma_f32 v119, v154, v243, v247
	v_fma_f32 v244, -v153, v35, v62
	v_fma_f32 v245, v153, v34, v78
	v_fma_f32 v246, -v155, v119, v94
	v_fma_f32 v247, v155, v118, v110
	v_fma_f32 v240, v152, v34, v244
	v_fma_f32 v241, v152, v35, v245
	v_fma_f32 v242, v154, v118, v246
	v_fma_f32 v243, v154, v119, v247
	v_fma_f32 v244, -v153, v241, v63
	v_fma_f32 v245, v153, v240, v79
	v_fma_f32 v246, -v155, v243, v95
	v_fma_f32 v247, v155, v242, v111
	v_fma_f32 v34, v152, v240, v244
	v_fma_f32 v35, v152, v241, v245
	v_fma_f32 v118, v154, v242, v246
	v_fma_f32 v119, v154, v243, v247
	v_fma_f32 v244, -v153, v35, v64
	v_fma_f32 v245, v153, v34, v80
	v_fma_f32 v246, -v155, v119, v96
	v_fma_f32 v247, v155, v118, v112
	v_fma_f32 v240, v152, v34, v244
	v_fma_f32 v241, v152, v35, v245
	v_fma_f32 v242, v154, v118, v246
	v_fma_f32 v243, v154, v119, v247
	v_fma_f32 v244, -v153, v241, v65
	v_fma_f32 v245, v153, v240, v81
	v_fma_f32 v246, -v155, v243, v97
	v_fma_f32 v247, v155, v242, v113
	v_fma_f32 v34, v152, v240, v244
	v_fma_f32 v35, v152, v241, v245
	v_fma_f32 v118, v154, v242, v246
	v_fma_f32 v119, v154, v243, v247
	s_cbranch_scc0 .LBB0_1595
	s_nop 0
	s_nop 0
	s_nop 0
	s_nop 0
	s_nop 0
	s_nop 0
	s_nop 0
	s_nop 0
	s_nop 0
	s_nop 0
	s_nop 0
	s_nop 0
	v_lshlrev_b32_e32 v2, 7, v167
	v_or3_b32 v2, v2, v163, v166
	v_ashrrev_i32_e32 v3, 31, v2
	v_lshlrev_b64 v[2:3], 9, v[2:3]
	s_add_i32 s0, s0, s96
	v_lshl_add_u64 v[2:3], v[150:151], 0, v[2:3]
	s_cmpk_gt_i32 s0, 0x1ff
	global_store_dwordx2 v[2:3], v[34:35], off
	global_store_dwordx2 v[2:3], v[118:119], off offset:256
	s_cbranch_scc0 .LBB0_1594

.LBB0_1779:
	s_ashr_i32 s65, s64, 31
	s_lshl_b64 s[82:83], s[64:65], 11
	s_add_u32 s0, s22, s82
	s_addc_u32 s1, s23, s83
	v_add_u32_e32 v155, s33, v142
	v_lshlrev_b64 v[12:13], 1, v[138:139]
	v_lshl_add_u64 v[14:15], s[0:1], 0, v[12:13]
	v_readfirstlane_b32 s47, v155
	v_lshl_add_u64 v[14:15], v[14:15], 0, s[2:3]
	s_mov_b32 m0, s47
	v_mov_b32_e32 v131, v139
	s_barrier
	global_load_lds_dwordx4 v[14:15], off
	v_lshlrev_b64 v[14:15], 1, v[130:131]
	v_add_u32_e32 v156, 0x2000, v155
	v_lshl_add_u64 v[16:17], s[0:1], 0, v[14:15]
	v_readfirstlane_b32 s0, v156
	s_ashr_i32 s47, s46, 31
	s_mov_b32 m0, s0
	s_lshl_b64 s[0:1], s[46:47], 11
	s_add_u32 s0, s68, s0
	v_lshl_add_u64 v[16:17], v[16:17], 0, s[2:3]
	s_addc_u32 s1, s69, s1
	v_add_u32_e32 v157, s43, v142
	global_load_lds_dwordx4 v[16:17], off
	v_lshl_add_u64 v[16:17], s[0:1], 0, v[12:13]
	v_readfirstlane_b32 s47, v157
	v_lshl_add_u64 v[16:17], v[16:17], 0, s[2:3]
	s_mov_b32 m0, s47
	v_add_u32_e32 v158, 0x2000, v157
	global_load_lds_dwordx4 v[16:17], off
	v_lshl_add_u64 v[16:17], s[0:1], 0, v[14:15]
	v_readfirstlane_b32 s0, v158
	s_mov_b32 m0, s0
	s_or_b32 s0, s64, 0x80
	s_ashr_i32 s1, s0, 31
	s_lshl_b64 s[64:65], s[0:1], 11
	s_add_u32 s64, s22, s64
	s_addc_u32 s65, s23, s65
	v_add_u32_e32 v159, s72, v142
	v_lshl_add_u64 v[16:17], v[16:17], 0, s[2:3]
	v_lshl_add_u64 v[12:13], s[64:65], 0, v[12:13]
	v_readfirstlane_b32 s1, v159
	global_load_lds_dwordx4 v[16:17], off
	v_lshl_add_u64 v[12:13], v[12:13], 0, s[2:3]
	s_mov_b32 m0, s1
	v_add_u32_e32 v160, 0x2000, v159
	global_load_lds_dwordx4 v[12:13], off
	v_lshl_add_u64 v[12:13], s[64:65], 0, v[14:15]
	v_readfirstlane_b32 s1, v160
	v_lshl_add_u64 v[12:13], v[12:13], 0, s[2:3]
	s_mov_b32 m0, s1
	v_lshlrev_b32_e32 v2, 13, v2
	global_load_lds_dwordx4 v[12:13], off
	v_and_b32_e32 v2, 0xffffc000, v2
	v_lshl_add_u32 v2, v4, 10, v2
	v_lshlrev_b32_e32 v4, 13, v6
	v_and_b32_e32 v11, 15, v3
	v_and_b32_e32 v18, 48, v3
	v_lshlrev_b32_e32 v12, 2, v3
	v_lshlrev_b32_e32 v3, 6, v3
	v_and_b32_e32 v4, 0xffffc000, v4
	v_and_b32_e32 v12, 32, v12
	s_lshl_b32 s1, s51, 6
	s_lshl_b32 s47, s53, 13
	v_and_b32_e32 v3, 0x3c0, v3
	v_lshl_add_u32 v4, v8, 10, v4
	s_and_b32 s1, s1, 0x3000
	v_bitop3_b32 v3, v3, v12, v18 bitop3:0x36
	s_or_b32 s53, s47, 0x800
	s_or_b32 s70, s47, 0x1000
	s_or_b32 s71, s47, 0x1800
	v_or_b32_e32 v2, v2, v5
	v_or_b32_e32 v4, v4, v9
	v_add_u32_e32 v162, 0, v3
	v_add_u32_e32 v163, s43, v3
	v_add_u32_e32 v164, s73, v3
	v_add_u32_sdwa v2, v2, sext(v7) dst_sel:DWORD dst_unused:UNUSED_PAD src0_sel:DWORD src1_sel:WORD_0
	v_mov_b32_e32 v3, v139
	s_add_u32 s64, s62, s82
	v_add_u32_sdwa v4, v4, sext(v10) dst_sel:DWORD dst_unused:UNUSED_PAD src0_sel:DWORD src1_sel:WORD_0
	v_mov_b32_e32 v5, v139
	v_lshlrev_b64 v[2:3], 1, v[2:3]
	s_addc_u32 s65, s63, s83
	v_lshlrev_b64 v[4:5], 1, v[4:5]
	v_lshl_add_u64 v[132:133], s[64:65], 0, v[2:3]
	v_lshl_add_u64 v[134:135], s[64:65], 0, v[4:5]
	s_sub_i32 s65, s76, s78
	s_lshl_b32 s76, s77, 6
	s_sub_i32 s65, s65, s76
	s_sext_i32_i8 s65, s65
	s_lshl_b32 s64, s77, 11
	s_lshl_b32 s65, s65, 8
	s_add_i32 s64, s64, s65
	s_ashr_i32 s65, s64, 31
	s_lshl_b64 s[64:65], s[64:65], 11
	v_lshlrev_b32_e32 v11, 6, v11
	s_add_u32 s64, s60, s64
	s_waitcnt vmcnt(6)
	v_bitop3_b32 v11, v11, v12, v18 bitop3:0x36
	s_addc_u32 s65, s61, s65
	v_add_u32_e32 v161, 0, v11
	v_add_u32_e32 v13, s33, v11
	v_add_u32_e32 v14, s72, v11
	v_add_u32_e32 v12, s43, v11
	v_add_u32_e32 v11, s73, v11
	v_lshl_add_u64 v[136:137], s[64:65], 0, v[2:3]
	v_mov_b32_e32 v2, 0
	v_lshl_add_u64 v[140:141], s[64:65], 0, v[4:5]
	s_mov_b32 s76, -2
	s_mov_b64 s[64:65], 0
	v_add_u32_e32 v154, s1, v13
	v_add_u32_e32 v153, s47, v12
	v_add_u32_e32 v152, s1, v14
	v_add_u32_e32 v151, s47, v11
	v_mov_b32_e32 v3, v2
	v_mov_b32_e32 v4, v2
	v_mov_b32_e32 v5, v2
	v_mov_b32_e32 v6, v2
	v_mov_b32_e32 v7, v2
	v_mov_b32_e32 v8, v2
	v_mov_b32_e32 v9, v2
	v_mov_b32_e32 v10, v2
	v_mov_b32_e32 v11, v2
	v_mov_b32_e32 v12, v2
	v_mov_b32_e32 v13, v2
	v_mov_b32_e32 v14, v2
	v_mov_b32_e32 v15, v2
	v_mov_b32_e32 v16, v2
	v_mov_b32_e32 v17, v2
	v_mov_b32_e32 v18, v2
	v_mov_b32_e32 v19, v2
	v_mov_b32_e32 v20, v2
	v_mov_b32_e32 v21, v2
	v_mov_b32_e32 v22, v2
	v_mov_b32_e32 v23, v2
	v_mov_b32_e32 v24, v2
	v_mov_b32_e32 v25, v2
	v_mov_b32_e32 v26, v2
	v_mov_b32_e32 v27, v2
	v_mov_b32_e32 v28, v2
	v_mov_b32_e32 v29, v2
	v_mov_b32_e32 v30, v2
	v_mov_b32_e32 v31, v2
	v_mov_b32_e32 v32, v2
	v_mov_b32_e32 v33, v2
	v_mov_b32_e32 v34, v2
	v_mov_b32_e32 v35, v2
	v_mov_b32_e32 v36, v2
	v_mov_b32_e32 v37, v2
	v_mov_b32_e32 v38, v2
	v_mov_b32_e32 v39, v2
	v_mov_b32_e32 v40, v2
	v_mov_b32_e32 v41, v2
	v_mov_b32_e32 v42, v2
	v_mov_b32_e32 v43, v2
	v_mov_b32_e32 v44, v2
	v_mov_b32_e32 v45, v2
	v_mov_b32_e32 v46, v2
	v_mov_b32_e32 v47, v2
	v_mov_b32_e32 v48, v2
	v_mov_b32_e32 v49, v2
	v_mov_b32_e32 v50, v2
	v_mov_b32_e32 v51, v2
	v_mov_b32_e32 v52, v2
	v_mov_b32_e32 v53, v2
	v_mov_b32_e32 v54, v2
	v_mov_b32_e32 v55, v2
	v_mov_b32_e32 v56, v2
	v_mov_b32_e32 v57, v2
	v_mov_b32_e32 v58, v2
	v_mov_b32_e32 v59, v2
	v_mov_b32_e32 v60, v2
	v_mov_b32_e32 v61, v2
	v_mov_b32_e32 v62, v2
	v_mov_b32_e32 v63, v2
	v_mov_b32_e32 v64, v2
	v_mov_b32_e32 v65, v2
	v_mov_b32_e32 v66, v2
	v_mov_b32_e32 v67, v2
	v_mov_b32_e32 v68, v2
	v_mov_b32_e32 v69, v2
	v_mov_b32_e32 v82, v2
	v_mov_b32_e32 v83, v2
	v_mov_b32_e32 v84, v2
	v_mov_b32_e32 v85, v2
	v_mov_b32_e32 v90, v2
	v_mov_b32_e32 v91, v2
	v_mov_b32_e32 v92, v2
	v_mov_b32_e32 v93, v2
	v_mov_b32_e32 v94, v2
	v_mov_b32_e32 v95, v2
	v_mov_b32_e32 v96, v2
	v_mov_b32_e32 v97, v2
	v_mov_b32_e32 v98, v2
	v_mov_b32_e32 v99, v2
	v_mov_b32_e32 v100, v2
	v_mov_b32_e32 v101, v2
	v_mov_b32_e32 v102, v2
	v_mov_b32_e32 v103, v2
	v_mov_b32_e32 v104, v2
	v_mov_b32_e32 v105, v2
	v_mov_b32_e32 v106, v2
	v_mov_b32_e32 v107, v2
	v_mov_b32_e32 v108, v2
	v_mov_b32_e32 v109, v2
	v_mov_b32_e32 v110, v2
	v_mov_b32_e32 v111, v2
	v_mov_b32_e32 v112, v2
	v_mov_b32_e32 v113, v2
	v_mov_b32_e32 v114, v2
	v_mov_b32_e32 v115, v2
	v_mov_b32_e32 v116, v2
	v_mov_b32_e32 v117, v2
	v_mov_b32_e32 v118, v2
	v_mov_b32_e32 v119, v2
	v_mov_b32_e32 v120, v2
	v_mov_b32_e32 v121, v2
	v_mov_b32_e32 v122, v2
	v_mov_b32_e32 v123, v2
	v_mov_b32_e32 v124, v2
	v_mov_b32_e32 v125, v2
	v_mov_b32_e32 v126, v2
	v_mov_b32_e32 v127, v2
	v_mov_b32_e32 v128, v2
	v_mov_b32_e32 v129, v2
	v_mov_b32_e32 v70, v2
	v_mov_b32_e32 v71, v2
	v_mov_b32_e32 v72, v2
	v_mov_b32_e32 v73, v2
	v_mov_b32_e32 v74, v2
	v_mov_b32_e32 v75, v2
	v_mov_b32_e32 v76, v2
	v_mov_b32_e32 v77, v2
	v_mov_b32_e32 v78, v2
	v_mov_b32_e32 v79, v2
	v_mov_b32_e32 v80, v2
	v_mov_b32_e32 v81, v2
	v_mov_b32_e32 v86, v2
	v_mov_b32_e32 v87, v2
	v_mov_b32_e32 v88, v2
	v_mov_b32_e32 v89, v2
	s_barrier
	v_readfirstlane_b32 s99, v0
	s_nop 3
	s_lshr_b32 s99, s99, 6
	s_cmp_lt_u32 s99, 4
	s_cbranch_scc0 .Lprio_k5
	s_setprio 1
.Lprio_k5:
.LBB0_1780:
	v_add_u32_e32 v169, s1, v161
	ds_read_b128 v[172:175], v169 offset:32768
	ds_read_b128 v[176:179], v169 offset:33792
	ds_read_b128 v[180:183], v169 offset:34816
	ds_read_b128 v[184:187], v169 offset:35840
	v_add_u32_e32 v170, s73, v142
	v_lshl_add_u64 v[224:225], v[136:137], 0, s[64:65]
	v_readfirstlane_b32 s77, v170
	v_add_u32_e32 v171, 0x2000, v170
	v_add_u32_e32 v165, s47, v161
	v_add_u32_e32 v166, s53, v162
	v_add_u32_e32 v167, s70, v162
	v_add_u32_e32 v168, s71, v162
	v_lshl_add_u64 v[220:221], v[224:225], 0, s[10:11]
	s_mov_b32 m0, s77
	v_lshl_add_u64 v[246:247], v[140:141], 0, s[64:65]
	v_readfirstlane_b32 s77, v171
	ds_read_b128 v[188:191], v165
	ds_read_b128 v[192:195], v165 offset:1024
	ds_read_b128 v[196:199], v166
	ds_read_b128 v[200:203], v166 offset:1024
	ds_read_b128 v[204:207], v167
	ds_read_b128 v[208:211], v167 offset:1024
	ds_read_b128 v[212:215], v168
	ds_read_b128 v[216:219], v168 offset:1024
	global_load_lds_dwordx4 v[220:221], off
	v_lshl_add_u64 v[220:221], v[246:247], 0, s[10:11]
	s_mov_b32 m0, s77
	s_nop 0
	global_load_lds_dwordx4 v[220:221], off
	s_waitcnt lgkmcnt(8)
	s_barrier
	s_waitcnt lgkmcnt(0)
	s_waitcnt lgkmcnt(0)
	v_mfma_f32_16x16x32_bf16 v[126:129], v[188:191], v[172:175], v[126:129]
	v_mfma_f32_16x16x32_bf16 v[122:125], v[188:191], v[180:183], v[122:125]
	v_mfma_f32_16x16x32_bf16 v[118:121], v[196:199], v[172:175], v[118:121]
	v_mfma_f32_16x16x32_bf16 v[114:117], v[196:199], v[180:183], v[114:117]
	v_mfma_f32_16x16x32_bf16 v[110:113], v[204:207], v[172:175], v[110:113]
	v_mfma_f32_16x16x32_bf16 v[106:109], v[204:207], v[180:183], v[106:109]
	v_mfma_f32_16x16x32_bf16 v[102:105], v[212:215], v[172:175], v[102:105]
	v_mfma_f32_16x16x32_bf16 v[98:101], v[212:215], v[180:183], v[98:101]
	v_mfma_f32_16x16x32_bf16 v[126:129], v[192:195], v[176:179], v[126:129]
	v_mfma_f32_16x16x32_bf16 v[122:125], v[192:195], v[184:187], v[122:125]
	v_mfma_f32_16x16x32_bf16 v[118:121], v[200:203], v[176:179], v[118:121]
	v_mfma_f32_16x16x32_bf16 v[114:117], v[200:203], v[184:187], v[114:117]
	v_mfma_f32_16x16x32_bf16 v[110:113], v[208:211], v[176:179], v[110:113]
	v_mfma_f32_16x16x32_bf16 v[106:109], v[208:211], v[184:187], v[106:109]
	v_mfma_f32_16x16x32_bf16 v[102:105], v[216:219], v[176:179], v[102:105]
	v_mfma_f32_16x16x32_bf16 v[98:101], v[216:219], v[184:187], v[98:101]
	s_barrier
	v_lshl_add_u64 v[248:249], v[132:133], 0, s[64:65]
	v_readfirstlane_b32 s77, v144
	v_lshl_add_u64 v[238:239], v[248:249], 0, s[12:13]
	s_mov_b32 m0, s77
	v_lshl_add_u64 v[250:251], v[134:135], 0, s[64:65]
	v_readfirstlane_b32 s77, v145
	ds_read_b128 v[220:223], v169 offset:49152
	ds_read_b128 v[226:229], v169 offset:50176
	ds_read_b128 v[230:233], v169 offset:51200
	ds_read_b128 v[234:237], v169 offset:52224
	global_load_lds_dwordx4 v[238:239], off
	v_lshl_add_u64 v[238:239], v[250:251], 0, s[12:13]
	s_mov_b32 m0, s77
	s_nop 0
	global_load_lds_dwordx4 v[238:239], off
	s_barrier
	s_waitcnt lgkmcnt(0)
	s_waitcnt lgkmcnt(0)
	v_mfma_f32_16x16x32_bf16 v[94:97], v[188:191], v[220:223], v[94:97]
	v_mfma_f32_16x16x32_bf16 v[90:93], v[188:191], v[230:233], v[90:93]
	v_mfma_f32_16x16x32_bf16 v[82:85], v[196:199], v[220:223], v[82:85]
	v_mfma_f32_16x16x32_bf16 v[66:69], v[196:199], v[230:233], v[66:69]
	v_mfma_f32_16x16x32_bf16 v[62:65], v[204:207], v[220:223], v[62:65]
	v_mfma_f32_16x16x32_bf16 v[58:61], v[204:207], v[230:233], v[58:61]
	v_mfma_f32_16x16x32_bf16 v[54:57], v[212:215], v[220:223], v[54:57]
	v_mfma_f32_16x16x32_bf16 v[50:53], v[212:215], v[230:233], v[50:53]
	v_mfma_f32_16x16x32_bf16 v[94:97], v[192:195], v[226:229], v[94:97]
	v_mfma_f32_16x16x32_bf16 v[90:93], v[192:195], v[234:237], v[90:93]
	v_mfma_f32_16x16x32_bf16 v[82:85], v[200:203], v[226:229], v[82:85]
	v_mfma_f32_16x16x32_bf16 v[66:69], v[200:203], v[234:237], v[66:69]
	v_mfma_f32_16x16x32_bf16 v[62:65], v[208:211], v[226:229], v[62:65]
	v_mfma_f32_16x16x32_bf16 v[58:61], v[208:211], v[234:237], v[58:61]
	v_mfma_f32_16x16x32_bf16 v[54:57], v[216:219], v[226:229], v[54:57]
	v_mfma_f32_16x16x32_bf16 v[50:53], v[216:219], v[234:237], v[50:53]
	v_readfirstlane_b32 s77, v143
	v_lshl_add_u64 v[238:239], v[224:225], 0, s[24:25]
	s_mov_b32 m0, s77
	v_readfirstlane_b32 s77, v146
	s_barrier
	ds_read_b128 v[188:191], v165 offset:16384
	ds_read_b128 v[192:195], v165 offset:17408
	ds_read_b128 v[196:199], v166 offset:16384
	ds_read_b128 v[200:203], v166 offset:17408
	ds_read_b128 v[204:207], v167 offset:16384
	ds_read_b128 v[208:211], v167 offset:17408
	ds_read_b128 v[212:215], v168 offset:16384
	ds_read_b128 v[216:219], v168 offset:17408
	global_load_lds_dwordx4 v[238:239], off
	v_lshl_add_u64 v[238:239], v[246:247], 0, s[24:25]
	s_mov_b32 m0, s77
	s_nop 0
	global_load_lds_dwordx4 v[238:239], off
	s_barrier
	s_waitcnt lgkmcnt(0)
	s_waitcnt lgkmcnt(0)
	v_mfma_f32_16x16x32_bf16 v[46:49], v[188:191], v[172:175], v[46:49]
	v_mfma_f32_16x16x32_bf16 v[42:45], v[188:191], v[180:183], v[42:45]
	v_mfma_f32_16x16x32_bf16 v[38:41], v[196:199], v[172:175], v[38:41]
	v_mfma_f32_16x16x32_bf16 v[34:37], v[196:199], v[180:183], v[34:37]
	v_mfma_f32_16x16x32_bf16 v[30:33], v[204:207], v[172:175], v[30:33]
	v_mfma_f32_16x16x32_bf16 v[26:29], v[204:207], v[180:183], v[26:29]
	v_mfma_f32_16x16x32_bf16 v[22:25], v[212:215], v[172:175], v[22:25]
	v_mfma_f32_16x16x32_bf16 v[18:21], v[212:215], v[180:183], v[18:21]
	v_mfma_f32_16x16x32_bf16 v[46:49], v[192:195], v[176:179], v[46:49]
	v_mfma_f32_16x16x32_bf16 v[42:45], v[192:195], v[184:187], v[42:45]
	v_mfma_f32_16x16x32_bf16 v[38:41], v[200:203], v[176:179], v[38:41]
	v_mfma_f32_16x16x32_bf16 v[34:37], v[200:203], v[184:187], v[34:37]
	v_mfma_f32_16x16x32_bf16 v[30:33], v[208:211], v[176:179], v[30:33]
	v_mfma_f32_16x16x32_bf16 v[26:29], v[208:211], v[184:187], v[26:29]
	v_mfma_f32_16x16x32_bf16 v[22:25], v[216:219], v[176:179], v[22:25]
	v_mfma_f32_16x16x32_bf16 v[18:21], v[216:219], v[184:187], v[18:21]
	s_barrier
	v_readfirstlane_b32 s77, v147
	v_lshl_add_u64 v[172:173], v[248:249], 0, s[26:27]
	s_mov_b32 m0, s77
	v_readfirstlane_b32 s77, v148
	global_load_lds_dwordx4 v[172:173], off
	v_lshl_add_u64 v[172:173], v[250:251], 0, s[26:27]
	s_mov_b32 m0, s77
	s_nop 0
	global_load_lds_dwordx4 v[172:173], off
	s_waitcnt vmcnt(6)
	s_barrier
	v_mfma_f32_16x16x32_bf16 v[14:17], v[188:191], v[220:223], v[14:17]
	v_mfma_f32_16x16x32_bf16 v[10:13], v[188:191], v[230:233], v[10:13]
	v_mfma_f32_16x16x32_bf16 v[6:9], v[196:199], v[220:223], v[6:9]
	v_mfma_f32_16x16x32_bf16 v[2:5], v[196:199], v[230:233], v[2:5]
	v_mfma_f32_16x16x32_bf16 v[70:73], v[204:207], v[220:223], v[70:73]
	v_mfma_f32_16x16x32_bf16 v[74:77], v[204:207], v[230:233], v[74:77]
	v_mfma_f32_16x16x32_bf16 v[78:81], v[212:215], v[220:223], v[78:81]
	v_mfma_f32_16x16x32_bf16 v[86:89], v[212:215], v[230:233], v[86:89]
	v_mfma_f32_16x16x32_bf16 v[14:17], v[192:195], v[226:229], v[14:17]
	v_mfma_f32_16x16x32_bf16 v[10:13], v[192:195], v[234:237], v[10:13]
	v_mfma_f32_16x16x32_bf16 v[6:9], v[200:203], v[226:229], v[6:9]
	v_mfma_f32_16x16x32_bf16 v[2:5], v[200:203], v[234:237], v[2:5]
	v_mfma_f32_16x16x32_bf16 v[70:73], v[208:211], v[226:229], v[70:73]
	v_mfma_f32_16x16x32_bf16 v[74:77], v[208:211], v[234:237], v[74:77]
	v_mfma_f32_16x16x32_bf16 v[78:81], v[216:219], v[226:229], v[78:81]
	v_mfma_f32_16x16x32_bf16 v[86:89], v[216:219], v[234:237], v[86:89]
	s_barrier
	ds_read_b128 v[178:181], v154
	ds_read_b128 v[182:185], v154 offset:1024
	ds_read_b128 v[186:189], v154 offset:2048
	ds_read_b128 v[190:193], v154 offset:3072
	v_readfirstlane_b32 s77, v149
	v_add_u32_e32 v172, s53, v163
	v_add_u32_e32 v173, s70, v163
	v_add_u32_e32 v174, s71, v163
	v_lshl_add_u64 v[176:177], v[224:225], 0, s[28:29]
	s_mov_b32 m0, s77
	v_readfirstlane_b32 s77, v150
	ds_read_b128 v[194:197], v153
	ds_read_b128 v[198:201], v153 offset:1024
	ds_read_b128 v[202:205], v172
	ds_read_b128 v[206:209], v172 offset:1024
	ds_read_b128 v[210:213], v173
	ds_read_b128 v[214:217], v173 offset:1024
	ds_read_b128 v[218:221], v174
	ds_read_b128 v[226:229], v174 offset:1024
	global_load_lds_dwordx4 v[176:177], off
	v_lshl_add_u64 v[176:177], v[246:247], 0, s[28:29]
	s_mov_b32 m0, s77
	s_nop 0
	global_load_lds_dwordx4 v[176:177], off
	s_waitcnt lgkmcnt(8)
	s_barrier
	s_waitcnt lgkmcnt(0)
	s_waitcnt lgkmcnt(0)
	v_mfma_f32_16x16x32_bf16 v[126:129], v[194:197], v[178:181], v[126:129]
	v_mfma_f32_16x16x32_bf16 v[122:125], v[194:197], v[186:189], v[122:125]
	v_mfma_f32_16x16x32_bf16 v[118:121], v[202:205], v[178:181], v[118:121]
	v_mfma_f32_16x16x32_bf16 v[114:117], v[202:205], v[186:189], v[114:117]
	v_mfma_f32_16x16x32_bf16 v[110:113], v[210:213], v[178:181], v[110:113]
	v_mfma_f32_16x16x32_bf16 v[106:109], v[210:213], v[186:189], v[106:109]
	v_mfma_f32_16x16x32_bf16 v[102:105], v[218:221], v[178:181], v[102:105]
	v_mfma_f32_16x16x32_bf16 v[98:101], v[218:221], v[186:189], v[98:101]
	v_mfma_f32_16x16x32_bf16 v[126:129], v[198:201], v[182:185], v[126:129]
	v_mfma_f32_16x16x32_bf16 v[122:125], v[198:201], v[190:193], v[122:125]
	v_mfma_f32_16x16x32_bf16 v[118:121], v[206:209], v[182:185], v[118:121]
	v_mfma_f32_16x16x32_bf16 v[114:117], v[206:209], v[190:193], v[114:117]
	v_mfma_f32_16x16x32_bf16 v[110:113], v[214:217], v[182:185], v[110:113]
	v_mfma_f32_16x16x32_bf16 v[106:109], v[214:217], v[190:193], v[106:109]
	v_mfma_f32_16x16x32_bf16 v[102:105], v[226:229], v[182:185], v[102:105]
	v_mfma_f32_16x16x32_bf16 v[98:101], v[226:229], v[190:193], v[98:101]
	s_barrier
	v_readfirstlane_b32 s77, v155
	v_lshl_add_u64 v[176:177], v[248:249], 0, s[30:31]
	s_mov_b32 m0, s77
	v_readfirstlane_b32 s77, v156
	ds_read_b128 v[230:233], v152
	ds_read_b128 v[234:237], v152 offset:1024
	ds_read_b128 v[238:241], v152 offset:2048
	ds_read_b128 v[242:245], v152 offset:3072
	global_load_lds_dwordx4 v[176:177], off
	v_lshl_add_u64 v[176:177], v[250:251], 0, s[30:31]
	s_mov_b32 m0, s77
	s_nop 0
	global_load_lds_dwordx4 v[176:177], off
	s_barrier
	s_waitcnt lgkmcnt(0)
	s_waitcnt lgkmcnt(0)
	v_mfma_f32_16x16x32_bf16 v[94:97], v[194:197], v[230:233], v[94:97]
	v_mfma_f32_16x16x32_bf16 v[90:93], v[194:197], v[238:241], v[90:93]
	v_mfma_f32_16x16x32_bf16 v[82:85], v[202:205], v[230:233], v[82:85]
	v_mfma_f32_16x16x32_bf16 v[66:69], v[202:205], v[238:241], v[66:69]
	v_mfma_f32_16x16x32_bf16 v[62:65], v[210:213], v[230:233], v[62:65]
	v_mfma_f32_16x16x32_bf16 v[58:61], v[210:213], v[238:241], v[58:61]
	v_mfma_f32_16x16x32_bf16 v[54:57], v[218:221], v[230:233], v[54:57]
	v_mfma_f32_16x16x32_bf16 v[50:53], v[218:221], v[238:241], v[50:53]
	v_mfma_f32_16x16x32_bf16 v[94:97], v[198:201], v[234:237], v[94:97]
	v_mfma_f32_16x16x32_bf16 v[90:93], v[198:201], v[242:245], v[90:93]
	v_mfma_f32_16x16x32_bf16 v[82:85], v[206:209], v[234:237], v[82:85]
	v_mfma_f32_16x16x32_bf16 v[66:69], v[206:209], v[242:245], v[66:69]
	v_mfma_f32_16x16x32_bf16 v[62:65], v[214:217], v[234:237], v[62:65]
	v_mfma_f32_16x16x32_bf16 v[58:61], v[214:217], v[242:245], v[58:61]
	v_mfma_f32_16x16x32_bf16 v[54:57], v[226:229], v[234:237], v[54:57]
	v_mfma_f32_16x16x32_bf16 v[50:53], v[226:229], v[242:245], v[50:53]
	v_readfirstlane_b32 s77, v157
	v_add_u32_e32 v175, s53, v164
	v_add_u32_e32 v176, s70, v164
	v_add_u32_e32 v177, s71, v164
	v_lshl_add_u64 v[222:223], v[224:225], 0, s[34:35]
	s_mov_b32 m0, s77
	v_readfirstlane_b32 s77, v158
	s_barrier
	ds_read_b128 v[194:197], v151
	ds_read_b128 v[198:201], v151 offset:1024
	ds_read_b128 v[202:205], v175
	ds_read_b128 v[206:209], v175 offset:1024
	ds_read_b128 v[210:213], v176
	ds_read_b128 v[214:217], v176 offset:1024
	ds_read_b128 v[218:221], v177
	ds_read_b128 v[226:229], v177 offset:1024
	global_load_lds_dwordx4 v[222:223], off
	v_lshl_add_u64 v[222:223], v[246:247], 0, s[34:35]
	s_mov_b32 m0, s77
	s_nop 0
	global_load_lds_dwordx4 v[222:223], off
	s_barrier
	s_waitcnt lgkmcnt(0)
	s_waitcnt lgkmcnt(0)
	v_mfma_f32_16x16x32_bf16 v[46:49], v[194:197], v[178:181], v[46:49]
	v_mfma_f32_16x16x32_bf16 v[42:45], v[194:197], v[186:189], v[42:45]
	v_mfma_f32_16x16x32_bf16 v[38:41], v[202:205], v[178:181], v[38:41]
	v_mfma_f32_16x16x32_bf16 v[34:37], v[202:205], v[186:189], v[34:37]
	v_mfma_f32_16x16x32_bf16 v[30:33], v[210:213], v[178:181], v[30:33]
	v_mfma_f32_16x16x32_bf16 v[26:29], v[210:213], v[186:189], v[26:29]
	v_mfma_f32_16x16x32_bf16 v[22:25], v[218:221], v[178:181], v[22:25]
	v_mfma_f32_16x16x32_bf16 v[18:21], v[218:221], v[186:189], v[18:21]
	v_mfma_f32_16x16x32_bf16 v[46:49], v[198:201], v[182:185], v[46:49]
	v_mfma_f32_16x16x32_bf16 v[42:45], v[198:201], v[190:193], v[42:45]
	v_mfma_f32_16x16x32_bf16 v[38:41], v[206:209], v[182:185], v[38:41]
	v_mfma_f32_16x16x32_bf16 v[34:37], v[206:209], v[190:193], v[34:37]
	v_mfma_f32_16x16x32_bf16 v[30:33], v[214:217], v[182:185], v[30:33]
	v_mfma_f32_16x16x32_bf16 v[26:29], v[214:217], v[190:193], v[26:29]
	v_mfma_f32_16x16x32_bf16 v[22:25], v[226:229], v[182:185], v[22:25]
	v_mfma_f32_16x16x32_bf16 v[18:21], v[226:229], v[190:193], v[18:21]
	s_barrier
	v_readfirstlane_b32 s77, v159
	v_lshl_add_u64 v[178:179], v[248:249], 0, s[36:37]
	s_mov_b32 m0, s77
	v_readfirstlane_b32 s77, v160
	global_load_lds_dwordx4 v[178:179], off
	v_lshl_add_u64 v[178:179], v[250:251], 0, s[36:37]
	s_mov_b32 m0, s77
	s_nop 0
	global_load_lds_dwordx4 v[178:179], off
	s_waitcnt vmcnt(6)
	s_barrier
	v_mfma_f32_16x16x32_bf16 v[14:17], v[194:197], v[230:233], v[14:17]
	v_mfma_f32_16x16x32_bf16 v[10:13], v[194:197], v[238:241], v[10:13]
	v_mfma_f32_16x16x32_bf16 v[6:9], v[202:205], v[230:233], v[6:9]
	v_mfma_f32_16x16x32_bf16 v[2:5], v[202:205], v[238:241], v[2:5]
	v_mfma_f32_16x16x32_bf16 v[70:73], v[210:213], v[230:233], v[70:73]
	v_mfma_f32_16x16x32_bf16 v[74:77], v[210:213], v[238:241], v[74:77]
	v_mfma_f32_16x16x32_bf16 v[78:81], v[218:221], v[230:233], v[78:81]
	v_mfma_f32_16x16x32_bf16 v[86:89], v[218:221], v[238:241], v[86:89]
	v_mfma_f32_16x16x32_bf16 v[14:17], v[198:201], v[234:237], v[14:17]
	v_mfma_f32_16x16x32_bf16 v[10:13], v[198:201], v[242:245], v[10:13]
	v_mfma_f32_16x16x32_bf16 v[6:9], v[206:209], v[234:237], v[6:9]
	v_mfma_f32_16x16x32_bf16 v[2:5], v[206:209], v[242:245], v[2:5]
	v_mfma_f32_16x16x32_bf16 v[70:73], v[214:217], v[234:237], v[70:73]
	v_mfma_f32_16x16x32_bf16 v[74:77], v[214:217], v[242:245], v[74:77]
	v_mfma_f32_16x16x32_bf16 v[78:81], v[226:229], v[234:237], v[78:81]
	v_mfma_f32_16x16x32_bf16 v[86:89], v[226:229], v[242:245], v[86:89]
	s_add_i32 s76, s76, 2
	s_add_u32 s64, s64, 0x100
	s_addc_u32 s65, s65, 0
	s_cmp_lt_u32 s76, 12
	s_barrier
	s_cbranch_scc1 .LBB0_1780
	s_or_b32 s64, s46, 0x80
	s_ashr_i32 s65, s64, 31
	s_lshl_b64 s[70:71], s[64:65], 11
	s_add_u32 s70, s68, s70
	s_addc_u32 s71, s69, s71
	v_lshl_add_u64 v[136:137], v[138:139], 1, s[70:71]
	v_readfirstlane_b32 s1, v170
	v_lshl_add_u64 v[136:137], v[136:137], 0, s[38:39]
	s_mov_b32 m0, s1
	v_lshl_add_u64 v[130:131], v[130:131], 1, s[70:71]
	v_readfirstlane_b32 s1, v171
	ds_read_b128 v[132:135], v169 offset:32768
	ds_read_b128 v[140:143], v169 offset:33792
	ds_read_b128 v[144:147], v169 offset:34816
	ds_read_b128 v[156:159], v169 offset:35840
	ds_read_b128 v[160:163], v165
	ds_read_b128 v[178:181], v165 offset:1024
	ds_read_b128 v[182:185], v166
	ds_read_b128 v[186:189], v166 offset:1024
	ds_read_b128 v[190:193], v167
	ds_read_b128 v[194:197], v167 offset:1024
	ds_read_b128 v[198:201], v168
	ds_read_b128 v[202:205], v168 offset:1024
	global_load_lds_dwordx4 v[136:137], off
	v_lshl_add_u64 v[130:131], v[130:131], 0, s[38:39]
	s_mov_b32 m0, s1
	s_nop 0
	global_load_lds_dwordx4 v[130:131], off
	s_barrier
	s_waitcnt lgkmcnt(0)
	s_waitcnt lgkmcnt(0)
	v_mfma_f32_16x16x32_bf16 v[126:129], v[160:163], v[132:135], v[126:129]
	v_mfma_f32_16x16x32_bf16 v[122:125], v[160:163], v[144:147], v[122:125]
	v_mfma_f32_16x16x32_bf16 v[118:121], v[182:185], v[132:135], v[118:121]
	v_mfma_f32_16x16x32_bf16 v[114:117], v[182:185], v[144:147], v[114:117]
	v_mfma_f32_16x16x32_bf16 v[110:113], v[190:193], v[132:135], v[110:113]
	v_mfma_f32_16x16x32_bf16 v[126:129], v[178:181], v[140:143], v[126:129]
	v_mfma_f32_16x16x32_bf16 v[122:125], v[178:181], v[156:159], v[122:125]
	v_mfma_f32_16x16x32_bf16 v[118:121], v[186:189], v[140:143], v[118:121]
	v_mfma_f32_16x16x32_bf16 v[114:117], v[186:189], v[156:159], v[114:117]
	v_mfma_f32_16x16x32_bf16 v[110:113], v[194:197], v[140:143], v[110:113]
	v_mfma_f32_16x16x32_bf16 v[106:109], v[190:193], v[144:147], v[106:109]
	v_mfma_f32_16x16x32_bf16 v[102:105], v[198:201], v[132:135], v[102:105]
	v_mfma_f32_16x16x32_bf16 v[98:101], v[198:201], v[144:147], v[98:101]
	v_mfma_f32_16x16x32_bf16 v[206:209], v[194:197], v[156:159], v[106:109]
	v_mfma_f32_16x16x32_bf16 v[210:213], v[202:205], v[140:143], v[102:105]
	v_mfma_f32_16x16x32_bf16 v[214:217], v[202:205], v[156:159], v[98:101]
	s_barrier
	s_nop 2
	ds_read_b128 v[98:101], v169 offset:49152
	ds_read_b128 v[102:105], v169 offset:50176
	ds_read_b128 v[106:109], v169 offset:51200
	ds_read_b128 v[218:221], v169 offset:52224
	s_barrier
	s_waitcnt lgkmcnt(0)
	s_waitcnt lgkmcnt(0)
	v_mfma_f32_16x16x32_bf16 v[94:97], v[160:163], v[98:101], v[94:97]
	v_mfma_f32_16x16x32_bf16 v[90:93], v[160:163], v[106:109], v[90:93]
	v_mfma_f32_16x16x32_bf16 v[82:85], v[182:185], v[98:101], v[82:85]
	v_mfma_f32_16x16x32_bf16 v[62:65], v[190:193], v[98:101], v[62:65]
	v_mfma_f32_16x16x32_bf16 v[58:61], v[190:193], v[106:109], v[58:61]
	v_mfma_f32_16x16x32_bf16 v[54:57], v[198:201], v[98:101], v[54:57]
	v_mfma_f32_16x16x32_bf16 v[50:53], v[198:201], v[106:109], v[50:53]
	v_mfma_f32_16x16x32_bf16 v[94:97], v[178:181], v[102:105], v[94:97]
	v_mfma_f32_16x16x32_bf16 v[90:93], v[178:181], v[218:221], v[90:93]
	v_mfma_f32_16x16x32_bf16 v[82:85], v[186:189], v[102:105], v[82:85]
	v_mfma_f32_16x16x32_bf16 v[66:69], v[182:185], v[106:109], v[66:69]
	v_mfma_f32_16x16x32_bf16 v[62:65], v[194:197], v[102:105], v[62:65]
	v_mfma_f32_16x16x32_bf16 v[58:61], v[194:197], v[218:221], v[58:61]
	v_mfma_f32_16x16x32_bf16 v[54:57], v[202:205], v[102:105], v[54:57]
	v_mfma_f32_16x16x32_bf16 v[50:53], v[202:205], v[218:221], v[50:53]
	v_mfma_f32_16x16x32_bf16 v[160:163], v[186:189], v[218:221], v[66:69]
	s_barrier
	s_nop 0
	ds_read_b128 v[66:69], v165 offset:16384
	ds_read_b128 v[178:181], v165 offset:17408
	ds_read_b128 v[182:185], v166 offset:16384
	ds_read_b128 v[186:189], v166 offset:17408
	ds_read_b128 v[190:193], v167 offset:16384
	ds_read_b128 v[164:167], v167 offset:17408
	ds_read_b128 v[194:197], v168 offset:16384
	ds_read_b128 v[168:171], v168 offset:17408
	s_waitcnt vmcnt(4)
	s_barrier
	s_waitcnt lgkmcnt(0)
	s_waitcnt lgkmcnt(0)
	v_mfma_f32_16x16x32_bf16 v[46:49], v[66:69], v[132:135], v[46:49]
	v_mfma_f32_16x16x32_bf16 v[42:45], v[66:69], v[144:147], v[42:45]
	v_mfma_f32_16x16x32_bf16 v[30:33], v[190:193], v[132:135], v[30:33]
	v_mfma_f32_16x16x32_bf16 v[26:29], v[190:193], v[144:147], v[26:29]
	v_mfma_f32_16x16x32_bf16 v[22:25], v[194:197], v[132:135], v[22:25]
	v_mfma_f32_16x16x32_bf16 v[18:21], v[194:197], v[144:147], v[18:21]
	v_mfma_f32_16x16x32_bf16 v[46:49], v[178:181], v[140:143], v[46:49]
	v_mfma_f32_16x16x32_bf16 v[42:45], v[178:181], v[156:159], v[42:45]
	v_mfma_f32_16x16x32_bf16 v[38:41], v[182:185], v[132:135], v[38:41]
	v_mfma_f32_16x16x32_bf16 v[34:37], v[182:185], v[144:147], v[34:37]
	v_mfma_f32_16x16x32_bf16 v[30:33], v[164:167], v[140:143], v[30:33]
	v_mfma_f32_16x16x32_bf16 v[26:29], v[164:167], v[156:159], v[26:29]
	v_mfma_f32_16x16x32_bf16 v[22:25], v[168:171], v[140:143], v[22:25]
	v_mfma_f32_16x16x32_bf16 v[18:21], v[168:171], v[156:159], v[18:21]
	v_mfma_f32_16x16x32_bf16 v[198:201], v[186:189], v[140:143], v[38:41]
	v_mfma_f32_16x16x32_bf16 v[202:205], v[186:189], v[156:159], v[34:37]
	v_mfma_f32_16x16x32_bf16 v[2:5], v[182:185], v[106:109], v[2:5]
	v_mfma_f32_16x16x32_bf16 v[134:137], v[186:189], v[218:221], v[2:5]
	v_mfma_f32_16x16x32_bf16 v[2:5], v[190:193], v[98:101], v[70:73]
	v_mfma_f32_16x16x32_bf16 v[140:143], v[164:167], v[102:105], v[2:5]
	v_mfma_f32_16x16x32_bf16 v[2:5], v[190:193], v[106:109], v[74:77]
	v_mfma_f32_16x16x32_bf16 v[14:17], v[66:69], v[98:101], v[14:17]
	v_mfma_f32_16x16x32_bf16 v[10:13], v[66:69], v[106:109], v[10:13]
	v_mfma_f32_16x16x32_bf16 v[144:147], v[164:167], v[218:221], v[2:5]
	v_mfma_f32_16x16x32_bf16 v[2:5], v[194:197], v[98:101], v[78:81]
	v_mfma_f32_16x16x32_bf16 v[14:17], v[178:181], v[102:105], v[14:17]
	v_mfma_f32_16x16x32_bf16 v[10:13], v[178:181], v[218:221], v[10:13]
	v_mfma_f32_16x16x32_bf16 v[6:9], v[182:185], v[98:101], v[6:9]
	v_mfma_f32_16x16x32_bf16 v[156:159], v[168:171], v[102:105], v[2:5]
	v_mfma_f32_16x16x32_bf16 v[2:5], v[194:197], v[106:109], v[86:89]
	v_mfma_f32_16x16x32_bf16 v[130:133], v[186:189], v[102:105], v[6:9]
	v_mfma_f32_16x16x32_bf16 v[164:167], v[168:171], v[218:221], v[2:5]
	s_barrier
	s_nop 3
	ds_read_b128 v[2:5], v154
	ds_read_b128 v[6:9], v154 offset:1024
	ds_read_b128 v[168:171], v154 offset:2048
	ds_read_b128 v[178:181], v154 offset:3072
	ds_read_b128 v[34:37], v153
	ds_read_b128 v[38:41], v153 offset:1024
	ds_read_b128 v[78:81], v172
	ds_read_b128 v[86:89], v172 offset:1024
	ds_read_b128 v[182:185], v173
	ds_read_b128 v[186:189], v173 offset:1024
	ds_read_b128 v[190:193], v174
	ds_read_b128 v[194:197], v174 offset:1024
	s_waitcnt vmcnt(2)
	s_barrier
	s_waitcnt lgkmcnt(0)
	s_waitcnt lgkmcnt(0)
	v_mfma_f32_16x16x32_bf16 v[66:69], v[34:37], v[2:5], v[126:129]
	v_mfma_f32_16x16x32_bf16 v[126:129], v[38:41], v[6:9], v[66:69]
	v_mfma_f32_16x16x32_bf16 v[66:69], v[34:37], v[168:171], v[122:125]
	v_mfma_f32_16x16x32_bf16 v[98:101], v[38:41], v[178:181], v[66:69]
	v_mfma_f32_16x16x32_bf16 v[66:69], v[78:81], v[2:5], v[118:121]
	v_mfma_f32_16x16x32_bf16 v[102:105], v[86:89], v[6:9], v[66:69]
	v_mfma_f32_16x16x32_bf16 v[66:69], v[78:81], v[168:171], v[114:117]
	v_mfma_f32_16x16x32_bf16 v[106:109], v[86:89], v[178:181], v[66:69]
	v_mfma_f32_16x16x32_bf16 v[66:69], v[182:185], v[2:5], v[110:113]
	v_mfma_f32_16x16x32_bf16 v[110:113], v[186:189], v[6:9], v[66:69]
	v_mfma_f32_16x16x32_bf16 v[66:69], v[182:185], v[168:171], v[206:209]
	v_mfma_f32_16x16x32_bf16 v[114:117], v[186:189], v[178:181], v[66:69]
	v_mfma_f32_16x16x32_bf16 v[66:69], v[190:193], v[2:5], v[210:213]
	v_mfma_f32_16x16x32_bf16 v[118:121], v[194:197], v[6:9], v[66:69]
	v_mfma_f32_16x16x32_bf16 v[66:69], v[190:193], v[168:171], v[214:217]
	v_mfma_f32_16x16x32_bf16 v[122:125], v[194:197], v[178:181], v[66:69]
	s_barrier
	ds_read_b128 v[206:209], v152
	ds_read_b128 v[210:213], v152 offset:1024
	ds_read_b128 v[214:217], v152 offset:2048
	ds_read_b128 v[152:155], v152 offset:3072
	s_waitcnt vmcnt(0)
	s_barrier
	s_waitcnt lgkmcnt(0)
	s_waitcnt lgkmcnt(0)
	v_mfma_f32_16x16x32_bf16 v[66:69], v[34:37], v[206:209], v[94:97]
	v_mfma_f32_16x16x32_bf16 v[34:37], v[34:37], v[214:217], v[90:93]
	v_mfma_f32_16x16x32_bf16 v[70:73], v[38:41], v[152:155], v[34:37]
	v_mfma_f32_16x16x32_bf16 v[34:37], v[78:81], v[206:209], v[82:85]
	v_mfma_f32_16x16x32_bf16 v[74:77], v[86:89], v[210:213], v[34:37]
	v_mfma_f32_16x16x32_bf16 v[34:37], v[78:81], v[214:217], v[160:163]
	v_mfma_f32_16x16x32_bf16 v[78:81], v[86:89], v[152:155], v[34:37]
	v_mfma_f32_16x16x32_bf16 v[34:37], v[182:185], v[206:209], v[62:65]
	v_mfma_f32_16x16x32_bf16 v[82:85], v[186:189], v[210:213], v[34:37]
	v_mfma_f32_16x16x32_bf16 v[34:37], v[182:185], v[214:217], v[58:61]
	v_mfma_f32_16x16x32_bf16 v[86:89], v[186:189], v[152:155], v[34:37]
	v_mfma_f32_16x16x32_bf16 v[34:37], v[190:193], v[206:209], v[54:57]
	v_mfma_f32_16x16x32_bf16 v[90:93], v[194:197], v[210:213], v[34:37]
	v_mfma_f32_16x16x32_bf16 v[34:37], v[190:193], v[214:217], v[50:53]
	v_mfma_f32_16x16x32_bf16 v[66:69], v[38:41], v[210:213], v[66:69]
	v_mfma_f32_16x16x32_bf16 v[94:97], v[194:197], v[152:155], v[34:37]
	s_barrier
	ds_read_b128 v[160:163], v151
	ds_read_b128 v[148:151], v151 offset:1024
	ds_read_b128 v[182:185], v175
	ds_read_b128 v[172:175], v175 offset:1024
	ds_read_b128 v[186:189], v176
	ds_read_b128 v[190:193], v176 offset:1024
	ds_read_b128 v[194:197], v177
	ds_read_b128 v[218:221], v177 offset:1024
	s_barrier
	s_waitcnt lgkmcnt(0)
	s_waitcnt lgkmcnt(0)
	v_mfma_f32_16x16x32_bf16 v[34:37], v[160:163], v[2:5], v[46:49]
	v_mfma_f32_16x16x32_bf16 v[38:41], v[160:163], v[168:171], v[42:45]
	v_mfma_f32_16x16x32_bf16 v[42:45], v[182:185], v[2:5], v[198:201]
	v_mfma_f32_16x16x32_bf16 v[30:33], v[186:189], v[2:5], v[30:33]
	v_mfma_f32_16x16x32_bf16 v[2:5], v[194:197], v[2:5], v[22:25]
	v_mfma_f32_16x16x32_bf16 v[46:49], v[182:185], v[168:171], v[202:205]
	v_mfma_f32_16x16x32_bf16 v[26:29], v[186:189], v[168:171], v[26:29]
	v_mfma_f32_16x16x32_bf16 v[58:61], v[218:221], v[6:9], v[2:5]
	v_mfma_f32_16x16x32_bf16 v[2:5], v[194:197], v[168:171], v[18:21]
	v_mfma_f32_16x16x32_bf16 v[34:37], v[148:151], v[6:9], v[34:37]
	v_mfma_f32_16x16x32_bf16 v[38:41], v[148:151], v[178:181], v[38:41]
	v_mfma_f32_16x16x32_bf16 v[42:45], v[172:175], v[6:9], v[42:45]
	v_mfma_f32_16x16x32_bf16 v[46:49], v[172:175], v[178:181], v[46:49]
	v_mfma_f32_16x16x32_bf16 v[50:53], v[190:193], v[6:9], v[30:33]
	v_mfma_f32_16x16x32_bf16 v[54:57], v[190:193], v[178:181], v[26:29]
	v_mfma_f32_16x16x32_bf16 v[62:65], v[218:221], v[178:181], v[2:5]
	v_mfma_f32_16x16x32_bf16 v[2:5], v[160:163], v[206:209], v[14:17]
	v_mfma_f32_16x16x32_bf16 v[6:9], v[160:163], v[214:217], v[10:13]
	v_mfma_f32_16x16x32_bf16 v[10:13], v[182:185], v[206:209], v[130:133]
	v_mfma_f32_16x16x32_bf16 v[14:17], v[182:185], v[214:217], v[134:137]
	v_mfma_f32_16x16x32_bf16 v[18:21], v[186:189], v[206:209], v[140:143]
	v_mfma_f32_16x16x32_bf16 v[22:25], v[186:189], v[214:217], v[144:147]
	v_mfma_f32_16x16x32_bf16 v[26:29], v[194:197], v[206:209], v[156:159]
	v_mfma_f32_16x16x32_bf16 v[30:33], v[194:197], v[214:217], v[164:167]
	v_mfma_f32_16x16x32_bf16 v[2:5], v[148:151], v[210:213], v[2:5]
	v_mfma_f32_16x16x32_bf16 v[6:9], v[148:151], v[152:155], v[6:9]
	v_mfma_f32_16x16x32_bf16 v[10:13], v[172:175], v[210:213], v[10:13]
	v_mfma_f32_16x16x32_bf16 v[14:17], v[172:175], v[152:155], v[14:17]
	v_mfma_f32_16x16x32_bf16 v[18:21], v[190:193], v[210:213], v[18:21]
	v_mfma_f32_16x16x32_bf16 v[22:25], v[190:193], v[152:155], v[22:25]
	v_mfma_f32_16x16x32_bf16 v[26:29], v[218:221], v[210:213], v[26:29]
	v_mfma_f32_16x16x32_bf16 v[30:33], v[218:221], v[152:155], v[30:33]
	s_setprio 0
	s_cmpk_gt_u32 s51, 0xff
	s_barrier
	s_cbranch_scc1 .LBB0_1783
	s_barrier

.LBB0_1912:
	s_ashr_i32 s37, s36, 31
	s_lshl_b64 s[0:1], s[36:37], 11
	s_add_u32 s44, s20, s0
	s_addc_u32 s45, s21, s1
	v_add_u32_e32 v155, s33, v142
	v_lshlrev_b64 v[12:13], 1, v[130:131]
	v_lshl_add_u64 v[14:15], s[44:45], 0, v[12:13]
	v_readfirstlane_b32 s35, v155
	v_add_u32_e32 v156, 0x2000, v155
	v_lshl_add_u64 v[14:15], v[14:15], 0, s[2:3]
	s_mov_b32 m0, s35
	v_mov_b32_e32 v133, v131
	v_readfirstlane_b32 s35, v156
	s_barrier
	global_load_lds_dwordx4 v[14:15], off
	v_lshlrev_b64 v[14:15], 1, v[132:133]
	s_mov_b32 m0, s35
	s_ashr_i32 s35, s34, 31
	v_lshl_add_u64 v[16:17], s[44:45], 0, v[14:15]
	s_lshl_b64 s[44:45], s[34:35], 11
	s_add_u32 s44, s60, s44
	v_lshl_add_u64 v[16:17], v[16:17], 0, s[2:3]
	s_addc_u32 s45, s61, s45
	v_add_u32_e32 v157, s46, v142
	global_load_lds_dwordx4 v[16:17], off
	v_lshl_add_u64 v[16:17], s[44:45], 0, v[12:13]
	v_readfirstlane_b32 s35, v157
	s_bitset1_b32 s36, 7
	v_lshl_add_u64 v[16:17], v[16:17], 0, s[2:3]
	s_mov_b32 m0, s35
	s_ashr_i32 s37, s36, 31
	global_load_lds_dwordx4 v[16:17], off
	v_lshl_add_u64 v[16:17], s[44:45], 0, v[14:15]
	s_lshl_b64 s[44:45], s[36:37], 11
	v_add_u32_e32 v158, 0x2000, v157
	s_add_u32 s44, s20, s44
	v_readfirstlane_b32 s35, v158
	s_addc_u32 s45, s21, s45
	v_add_u32_e32 v159, s47, v142
	v_lshl_add_u64 v[16:17], v[16:17], 0, s[2:3]
	s_mov_b32 m0, s35
	v_lshl_add_u64 v[12:13], s[44:45], 0, v[12:13]
	v_readfirstlane_b32 s35, v159
	global_load_lds_dwordx4 v[16:17], off
	v_lshl_add_u64 v[12:13], v[12:13], 0, s[2:3]
	s_mov_b32 m0, s35
	v_add_u32_e32 v160, 0x2000, v159
	global_load_lds_dwordx4 v[12:13], off
	v_lshl_add_u64 v[12:13], s[44:45], 0, v[14:15]
	v_readfirstlane_b32 s35, v160
	v_lshl_add_u64 v[12:13], v[12:13], 0, s[2:3]
	s_mov_b32 m0, s35
	v_lshlrev_b32_e32 v2, 13, v2
	global_load_lds_dwordx4 v[12:13], off
	v_and_b32_e32 v2, 0xffffc000, v2
	v_lshl_add_u32 v2, v4, 10, v2
	v_lshlrev_b32_e32 v4, 13, v6
	v_and_b32_e32 v11, 15, v3
	v_and_b32_e32 v18, 48, v3
	v_lshlrev_b32_e32 v12, 2, v3
	v_lshlrev_b32_e32 v3, 6, v3
	v_and_b32_e32 v4, 0xffffc000, v4
	v_and_b32_e32 v12, 32, v12
	s_lshl_b32 s35, s39, 6
	s_lshl_b32 s37, s41, 13
	v_and_b32_e32 v3, 0x3c0, v3
	v_lshl_add_u32 v4, v8, 10, v4
	s_and_b32 s35, s35, 0x3000
	v_bitop3_b32 v3, v3, v12, v18 bitop3:0x36
	s_or_b32 s41, s37, 0x800
	s_or_b32 s44, s37, 0x1000
	s_or_b32 s45, s37, 0x1800
	v_or_b32_e32 v2, v2, v5
	v_or_b32_e32 v4, v4, v9
	v_add_u32_e32 v162, 0, v3
	v_add_u32_e32 v163, s46, v3
	v_add_u32_e32 v164, s48, v3
	v_add_u32_sdwa v2, v2, sext(v7) dst_sel:DWORD dst_unused:UNUSED_PAD src0_sel:DWORD src1_sel:WORD_0
	v_mov_b32_e32 v3, v131
	s_add_u32 s0, s62, s0
	v_add_u32_sdwa v4, v4, sext(v10) dst_sel:DWORD dst_unused:UNUSED_PAD src0_sel:DWORD src1_sel:WORD_0
	v_mov_b32_e32 v5, v131
	v_lshlrev_b64 v[2:3], 1, v[2:3]
	s_addc_u32 s1, s63, s1
	v_lshlrev_b64 v[4:5], 1, v[4:5]
	v_lshl_add_u64 v[134:135], s[0:1], 0, v[2:3]
	v_lshl_add_u64 v[136:137], s[0:1], 0, v[4:5]
	s_sub_i32 s1, s52, s55
	s_sub_i32 s1, s1, s54
	s_sext_i32_i16 s1, s1
	s_lshl_b32 s0, s53, 11
	s_lshl_b32 s1, s1, 8
	s_add_i32 s0, s0, s1
	s_ashr_i32 s1, s0, 31
	s_lshl_b64 s[0:1], s[0:1], 11
	v_lshlrev_b32_e32 v11, 6, v11
	s_add_u32 s0, s60, s0
	s_waitcnt vmcnt(6)
	v_bitop3_b32 v11, v11, v12, v18 bitop3:0x36
	s_addc_u32 s1, s61, s1
	v_add_u32_e32 v161, 0, v11
	v_add_u32_e32 v13, s33, v11
	v_add_u32_e32 v14, s47, v11
	v_add_u32_e32 v12, s46, v11
	v_add_u32_e32 v11, s48, v11
	v_lshl_add_u64 v[138:139], s[0:1], 0, v[2:3]
	v_mov_b32_e32 v2, 0
	v_lshl_add_u64 v[140:141], s[0:1], 0, v[4:5]
	s_mov_b32 s52, -2
	s_mov_b64 s[0:1], 0
	v_add_u32_e32 v154, s35, v13
	v_add_u32_e32 v153, s37, v12
	v_add_u32_e32 v152, s35, v14
	v_add_u32_e32 v151, s37, v11
	v_mov_b32_e32 v3, v2
	v_mov_b32_e32 v4, v2
	v_mov_b32_e32 v5, v2
	v_mov_b32_e32 v6, v2
	v_mov_b32_e32 v7, v2
	v_mov_b32_e32 v8, v2
	v_mov_b32_e32 v9, v2
	v_mov_b32_e32 v10, v2
	v_mov_b32_e32 v11, v2
	v_mov_b32_e32 v12, v2
	v_mov_b32_e32 v13, v2
	v_mov_b32_e32 v14, v2
	v_mov_b32_e32 v15, v2
	v_mov_b32_e32 v16, v2
	v_mov_b32_e32 v17, v2
	v_mov_b32_e32 v18, v2
	v_mov_b32_e32 v19, v2
	v_mov_b32_e32 v20, v2
	v_mov_b32_e32 v21, v2
	v_mov_b32_e32 v22, v2
	v_mov_b32_e32 v23, v2
	v_mov_b32_e32 v24, v2
	v_mov_b32_e32 v25, v2
	v_mov_b32_e32 v26, v2
	v_mov_b32_e32 v27, v2
	v_mov_b32_e32 v28, v2
	v_mov_b32_e32 v29, v2
	v_mov_b32_e32 v30, v2
	v_mov_b32_e32 v31, v2
	v_mov_b32_e32 v32, v2
	v_mov_b32_e32 v33, v2
	v_mov_b32_e32 v34, v2
	v_mov_b32_e32 v35, v2
	v_mov_b32_e32 v36, v2
	v_mov_b32_e32 v37, v2
	v_mov_b32_e32 v38, v2
	v_mov_b32_e32 v39, v2
	v_mov_b32_e32 v40, v2
	v_mov_b32_e32 v41, v2
	v_mov_b32_e32 v42, v2
	v_mov_b32_e32 v43, v2
	v_mov_b32_e32 v44, v2
	v_mov_b32_e32 v45, v2
	v_mov_b32_e32 v46, v2
	v_mov_b32_e32 v47, v2
	v_mov_b32_e32 v48, v2
	v_mov_b32_e32 v49, v2
	v_mov_b32_e32 v50, v2
	v_mov_b32_e32 v51, v2
	v_mov_b32_e32 v52, v2
	v_mov_b32_e32 v53, v2
	v_mov_b32_e32 v54, v2
	v_mov_b32_e32 v55, v2
	v_mov_b32_e32 v56, v2
	v_mov_b32_e32 v57, v2
	v_mov_b32_e32 v58, v2
	v_mov_b32_e32 v59, v2
	v_mov_b32_e32 v60, v2
	v_mov_b32_e32 v61, v2
	v_mov_b32_e32 v62, v2
	v_mov_b32_e32 v63, v2
	v_mov_b32_e32 v64, v2
	v_mov_b32_e32 v65, v2
	v_mov_b32_e32 v66, v2
	v_mov_b32_e32 v67, v2
	v_mov_b32_e32 v68, v2
	v_mov_b32_e32 v69, v2
	v_mov_b32_e32 v82, v2
	v_mov_b32_e32 v83, v2
	v_mov_b32_e32 v84, v2
	v_mov_b32_e32 v85, v2
	v_mov_b32_e32 v90, v2
	v_mov_b32_e32 v91, v2
	v_mov_b32_e32 v92, v2
	v_mov_b32_e32 v93, v2
	v_mov_b32_e32 v94, v2
	v_mov_b32_e32 v95, v2
	v_mov_b32_e32 v96, v2
	v_mov_b32_e32 v97, v2
	v_mov_b32_e32 v98, v2
	v_mov_b32_e32 v99, v2
	v_mov_b32_e32 v100, v2
	v_mov_b32_e32 v101, v2
	v_mov_b32_e32 v102, v2
	v_mov_b32_e32 v103, v2
	v_mov_b32_e32 v104, v2
	v_mov_b32_e32 v105, v2
	v_mov_b32_e32 v106, v2
	v_mov_b32_e32 v107, v2
	v_mov_b32_e32 v108, v2
	v_mov_b32_e32 v109, v2
	v_mov_b32_e32 v110, v2
	v_mov_b32_e32 v111, v2
	v_mov_b32_e32 v112, v2
	v_mov_b32_e32 v113, v2
	v_mov_b32_e32 v114, v2
	v_mov_b32_e32 v115, v2
	v_mov_b32_e32 v116, v2
	v_mov_b32_e32 v117, v2
	v_mov_b32_e32 v118, v2
	v_mov_b32_e32 v119, v2
	v_mov_b32_e32 v120, v2
	v_mov_b32_e32 v121, v2
	v_mov_b32_e32 v122, v2
	v_mov_b32_e32 v123, v2
	v_mov_b32_e32 v124, v2
	v_mov_b32_e32 v125, v2
	v_mov_b32_e32 v126, v2
	v_mov_b32_e32 v127, v2
	v_mov_b32_e32 v128, v2
	v_mov_b32_e32 v129, v2
	v_mov_b32_e32 v70, v2
	v_mov_b32_e32 v71, v2
	v_mov_b32_e32 v72, v2
	v_mov_b32_e32 v73, v2
	v_mov_b32_e32 v74, v2
	v_mov_b32_e32 v75, v2
	v_mov_b32_e32 v76, v2
	v_mov_b32_e32 v77, v2
	v_mov_b32_e32 v78, v2
	v_mov_b32_e32 v79, v2
	v_mov_b32_e32 v80, v2
	v_mov_b32_e32 v81, v2
	v_mov_b32_e32 v86, v2
	v_mov_b32_e32 v87, v2
	v_mov_b32_e32 v88, v2
	v_mov_b32_e32 v89, v2
	s_barrier
	v_readfirstlane_b32 s99, v0
	s_nop 3
	s_lshr_b32 s99, s99, 6
	s_cmp_lt_u32 s99, 4
	s_cbranch_scc0 .Lprio_k6
	s_setprio 1
.Lprio_k6:
.LBB0_1913:
	v_add_u32_e32 v169, s35, v161
	ds_read_b128 v[172:175], v169 offset:32768
	ds_read_b128 v[176:179], v169 offset:33792
	ds_read_b128 v[180:183], v169 offset:34816
	ds_read_b128 v[184:187], v169 offset:35840
	v_add_u32_e32 v170, s48, v142
	v_lshl_add_u64 v[224:225], v[138:139], 0, s[0:1]
	v_readfirstlane_b32 s53, v170
	v_add_u32_e32 v171, 0x2000, v170
	v_add_u32_e32 v165, s37, v161
	v_add_u32_e32 v166, s41, v162
	v_add_u32_e32 v167, s44, v162
	v_add_u32_e32 v168, s45, v162
	v_lshl_add_u64 v[220:221], v[224:225], 0, s[6:7]
	s_mov_b32 m0, s53
	v_lshl_add_u64 v[246:247], v[140:141], 0, s[0:1]
	v_readfirstlane_b32 s53, v171
	ds_read_b128 v[188:191], v165
	ds_read_b128 v[192:195], v165 offset:1024
	ds_read_b128 v[196:199], v166
	ds_read_b128 v[200:203], v166 offset:1024
	ds_read_b128 v[204:207], v167
	ds_read_b128 v[208:211], v167 offset:1024
	ds_read_b128 v[212:215], v168
	ds_read_b128 v[216:219], v168 offset:1024
	global_load_lds_dwordx4 v[220:221], off
	v_lshl_add_u64 v[220:221], v[246:247], 0, s[6:7]
	s_mov_b32 m0, s53
	s_nop 0
	global_load_lds_dwordx4 v[220:221], off
	s_waitcnt lgkmcnt(8)
	s_barrier
	s_waitcnt lgkmcnt(0)
	s_waitcnt lgkmcnt(0)
	v_mfma_f32_16x16x32_bf16 v[126:129], v[172:175], v[188:191], v[126:129]
	v_mfma_f32_16x16x32_bf16 v[122:125], v[180:183], v[188:191], v[122:125]
	v_mfma_f32_16x16x32_bf16 v[118:121], v[172:175], v[196:199], v[118:121]
	v_mfma_f32_16x16x32_bf16 v[114:117], v[180:183], v[196:199], v[114:117]
	v_mfma_f32_16x16x32_bf16 v[110:113], v[172:175], v[204:207], v[110:113]
	v_mfma_f32_16x16x32_bf16 v[106:109], v[180:183], v[204:207], v[106:109]
	v_mfma_f32_16x16x32_bf16 v[102:105], v[172:175], v[212:215], v[102:105]
	v_mfma_f32_16x16x32_bf16 v[98:101], v[180:183], v[212:215], v[98:101]
	v_mfma_f32_16x16x32_bf16 v[126:129], v[176:179], v[192:195], v[126:129]
	v_mfma_f32_16x16x32_bf16 v[122:125], v[184:187], v[192:195], v[122:125]
	v_mfma_f32_16x16x32_bf16 v[118:121], v[176:179], v[200:203], v[118:121]
	v_mfma_f32_16x16x32_bf16 v[114:117], v[184:187], v[200:203], v[114:117]
	v_mfma_f32_16x16x32_bf16 v[110:113], v[176:179], v[208:211], v[110:113]
	v_mfma_f32_16x16x32_bf16 v[106:109], v[184:187], v[208:211], v[106:109]
	v_mfma_f32_16x16x32_bf16 v[102:105], v[176:179], v[216:219], v[102:105]
	v_mfma_f32_16x16x32_bf16 v[98:101], v[184:187], v[216:219], v[98:101]
	s_barrier
	v_lshl_add_u64 v[248:249], v[134:135], 0, s[0:1]
	v_readfirstlane_b32 s53, v144
	v_lshl_add_u64 v[238:239], v[248:249], 0, s[8:9]
	s_mov_b32 m0, s53
	v_lshl_add_u64 v[250:251], v[136:137], 0, s[0:1]
	v_readfirstlane_b32 s53, v145
	ds_read_b128 v[220:223], v169 offset:49152
	ds_read_b128 v[226:229], v169 offset:50176
	ds_read_b128 v[230:233], v169 offset:51200
	ds_read_b128 v[234:237], v169 offset:52224
	global_load_lds_dwordx4 v[238:239], off
	v_lshl_add_u64 v[238:239], v[250:251], 0, s[8:9]
	s_mov_b32 m0, s53
	s_nop 0
	global_load_lds_dwordx4 v[238:239], off
	s_barrier
	s_waitcnt lgkmcnt(0)
	s_waitcnt lgkmcnt(0)
	v_mfma_f32_16x16x32_bf16 v[94:97], v[220:223], v[188:191], v[94:97]
	v_mfma_f32_16x16x32_bf16 v[90:93], v[230:233], v[188:191], v[90:93]
	v_mfma_f32_16x16x32_bf16 v[82:85], v[220:223], v[196:199], v[82:85]
	v_mfma_f32_16x16x32_bf16 v[66:69], v[230:233], v[196:199], v[66:69]
	v_mfma_f32_16x16x32_bf16 v[62:65], v[220:223], v[204:207], v[62:65]
	v_mfma_f32_16x16x32_bf16 v[58:61], v[230:233], v[204:207], v[58:61]
	v_mfma_f32_16x16x32_bf16 v[54:57], v[220:223], v[212:215], v[54:57]
	v_mfma_f32_16x16x32_bf16 v[50:53], v[230:233], v[212:215], v[50:53]
	v_mfma_f32_16x16x32_bf16 v[94:97], v[226:229], v[192:195], v[94:97]
	v_mfma_f32_16x16x32_bf16 v[90:93], v[234:237], v[192:195], v[90:93]
	v_mfma_f32_16x16x32_bf16 v[82:85], v[226:229], v[200:203], v[82:85]
	v_mfma_f32_16x16x32_bf16 v[66:69], v[234:237], v[200:203], v[66:69]
	v_mfma_f32_16x16x32_bf16 v[62:65], v[226:229], v[208:211], v[62:65]
	v_mfma_f32_16x16x32_bf16 v[58:61], v[234:237], v[208:211], v[58:61]
	v_mfma_f32_16x16x32_bf16 v[54:57], v[226:229], v[216:219], v[54:57]
	v_mfma_f32_16x16x32_bf16 v[50:53], v[234:237], v[216:219], v[50:53]
	v_readfirstlane_b32 s53, v143
	v_lshl_add_u64 v[238:239], v[224:225], 0, s[10:11]
	s_mov_b32 m0, s53
	v_readfirstlane_b32 s53, v146
	s_barrier
	ds_read_b128 v[188:191], v165 offset:16384
	ds_read_b128 v[192:195], v165 offset:17408
	ds_read_b128 v[196:199], v166 offset:16384
	ds_read_b128 v[200:203], v166 offset:17408
	ds_read_b128 v[204:207], v167 offset:16384
	ds_read_b128 v[208:211], v167 offset:17408
	ds_read_b128 v[212:215], v168 offset:16384
	ds_read_b128 v[216:219], v168 offset:17408
	global_load_lds_dwordx4 v[238:239], off
	v_lshl_add_u64 v[238:239], v[246:247], 0, s[10:11]
	s_mov_b32 m0, s53
	s_nop 0
	global_load_lds_dwordx4 v[238:239], off
	s_barrier
	s_waitcnt lgkmcnt(0)
	s_waitcnt lgkmcnt(0)
	v_mfma_f32_16x16x32_bf16 v[46:49], v[172:175], v[188:191], v[46:49]
	v_mfma_f32_16x16x32_bf16 v[42:45], v[180:183], v[188:191], v[42:45]
	v_mfma_f32_16x16x32_bf16 v[38:41], v[172:175], v[196:199], v[38:41]
	v_mfma_f32_16x16x32_bf16 v[34:37], v[180:183], v[196:199], v[34:37]
	v_mfma_f32_16x16x32_bf16 v[30:33], v[172:175], v[204:207], v[30:33]
	v_mfma_f32_16x16x32_bf16 v[26:29], v[180:183], v[204:207], v[26:29]
	v_mfma_f32_16x16x32_bf16 v[22:25], v[172:175], v[212:215], v[22:25]
	v_mfma_f32_16x16x32_bf16 v[18:21], v[180:183], v[212:215], v[18:21]
	v_mfma_f32_16x16x32_bf16 v[46:49], v[176:179], v[192:195], v[46:49]
	v_mfma_f32_16x16x32_bf16 v[42:45], v[184:187], v[192:195], v[42:45]
	v_mfma_f32_16x16x32_bf16 v[38:41], v[176:179], v[200:203], v[38:41]
	v_mfma_f32_16x16x32_bf16 v[34:37], v[184:187], v[200:203], v[34:37]
	v_mfma_f32_16x16x32_bf16 v[30:33], v[176:179], v[208:211], v[30:33]
	v_mfma_f32_16x16x32_bf16 v[26:29], v[184:187], v[208:211], v[26:29]
	v_mfma_f32_16x16x32_bf16 v[22:25], v[176:179], v[216:219], v[22:25]
	v_mfma_f32_16x16x32_bf16 v[18:21], v[184:187], v[216:219], v[18:21]
	s_barrier
	v_readfirstlane_b32 s53, v147
	v_lshl_add_u64 v[172:173], v[248:249], 0, s[12:13]
	s_mov_b32 m0, s53
	v_readfirstlane_b32 s53, v148
	global_load_lds_dwordx4 v[172:173], off
	v_lshl_add_u64 v[172:173], v[250:251], 0, s[12:13]
	s_mov_b32 m0, s53
	s_nop 0
	global_load_lds_dwordx4 v[172:173], off
	s_waitcnt vmcnt(6)
	s_barrier
	v_mfma_f32_16x16x32_bf16 v[14:17], v[220:223], v[188:191], v[14:17]
	v_mfma_f32_16x16x32_bf16 v[10:13], v[230:233], v[188:191], v[10:13]
	v_mfma_f32_16x16x32_bf16 v[6:9], v[220:223], v[196:199], v[6:9]
	v_mfma_f32_16x16x32_bf16 v[2:5], v[230:233], v[196:199], v[2:5]
	v_mfma_f32_16x16x32_bf16 v[70:73], v[220:223], v[204:207], v[70:73]
	v_mfma_f32_16x16x32_bf16 v[74:77], v[230:233], v[204:207], v[74:77]
	v_mfma_f32_16x16x32_bf16 v[78:81], v[220:223], v[212:215], v[78:81]
	v_mfma_f32_16x16x32_bf16 v[86:89], v[230:233], v[212:215], v[86:89]
	v_mfma_f32_16x16x32_bf16 v[14:17], v[226:229], v[192:195], v[14:17]
	v_mfma_f32_16x16x32_bf16 v[10:13], v[234:237], v[192:195], v[10:13]
	v_mfma_f32_16x16x32_bf16 v[6:9], v[226:229], v[200:203], v[6:9]
	v_mfma_f32_16x16x32_bf16 v[2:5], v[234:237], v[200:203], v[2:5]
	v_mfma_f32_16x16x32_bf16 v[70:73], v[226:229], v[208:211], v[70:73]
	v_mfma_f32_16x16x32_bf16 v[74:77], v[234:237], v[208:211], v[74:77]
	v_mfma_f32_16x16x32_bf16 v[78:81], v[226:229], v[216:219], v[78:81]
	v_mfma_f32_16x16x32_bf16 v[86:89], v[234:237], v[216:219], v[86:89]
	s_barrier
	ds_read_b128 v[178:181], v154
	ds_read_b128 v[182:185], v154 offset:1024
	ds_read_b128 v[186:189], v154 offset:2048
	ds_read_b128 v[190:193], v154 offset:3072
	v_readfirstlane_b32 s53, v149
	v_add_u32_e32 v172, s41, v163
	v_add_u32_e32 v173, s44, v163
	v_add_u32_e32 v174, s45, v163
	v_lshl_add_u64 v[176:177], v[224:225], 0, s[18:19]
	s_mov_b32 m0, s53
	v_readfirstlane_b32 s53, v150
	ds_read_b128 v[194:197], v153
	ds_read_b128 v[198:201], v153 offset:1024
	ds_read_b128 v[202:205], v172
	ds_read_b128 v[206:209], v172 offset:1024
	ds_read_b128 v[210:213], v173
	ds_read_b128 v[214:217], v173 offset:1024
	ds_read_b128 v[218:221], v174
	ds_read_b128 v[226:229], v174 offset:1024
	global_load_lds_dwordx4 v[176:177], off
	v_lshl_add_u64 v[176:177], v[246:247], 0, s[18:19]
	s_mov_b32 m0, s53
	s_nop 0
	global_load_lds_dwordx4 v[176:177], off
	s_waitcnt lgkmcnt(8)
	s_barrier
	s_waitcnt lgkmcnt(0)
	s_waitcnt lgkmcnt(0)
	v_mfma_f32_16x16x32_bf16 v[126:129], v[178:181], v[194:197], v[126:129]
	v_mfma_f32_16x16x32_bf16 v[122:125], v[186:189], v[194:197], v[122:125]
	v_mfma_f32_16x16x32_bf16 v[118:121], v[178:181], v[202:205], v[118:121]
	v_mfma_f32_16x16x32_bf16 v[114:117], v[186:189], v[202:205], v[114:117]
	v_mfma_f32_16x16x32_bf16 v[110:113], v[178:181], v[210:213], v[110:113]
	v_mfma_f32_16x16x32_bf16 v[106:109], v[186:189], v[210:213], v[106:109]
	v_mfma_f32_16x16x32_bf16 v[102:105], v[178:181], v[218:221], v[102:105]
	v_mfma_f32_16x16x32_bf16 v[98:101], v[186:189], v[218:221], v[98:101]
	v_mfma_f32_16x16x32_bf16 v[126:129], v[182:185], v[198:201], v[126:129]
	v_mfma_f32_16x16x32_bf16 v[122:125], v[190:193], v[198:201], v[122:125]
	v_mfma_f32_16x16x32_bf16 v[118:121], v[182:185], v[206:209], v[118:121]
	v_mfma_f32_16x16x32_bf16 v[114:117], v[190:193], v[206:209], v[114:117]
	v_mfma_f32_16x16x32_bf16 v[110:113], v[182:185], v[214:217], v[110:113]
	v_mfma_f32_16x16x32_bf16 v[106:109], v[190:193], v[214:217], v[106:109]
	v_mfma_f32_16x16x32_bf16 v[102:105], v[182:185], v[226:229], v[102:105]
	v_mfma_f32_16x16x32_bf16 v[98:101], v[190:193], v[226:229], v[98:101]
	s_barrier
	v_readfirstlane_b32 s53, v155
	v_lshl_add_u64 v[176:177], v[248:249], 0, s[22:23]
	s_mov_b32 m0, s53
	v_readfirstlane_b32 s53, v156
	ds_read_b128 v[230:233], v152
	ds_read_b128 v[234:237], v152 offset:1024
	ds_read_b128 v[238:241], v152 offset:2048
	ds_read_b128 v[242:245], v152 offset:3072
	global_load_lds_dwordx4 v[176:177], off
	v_lshl_add_u64 v[176:177], v[250:251], 0, s[22:23]
	s_mov_b32 m0, s53
	s_nop 0
	global_load_lds_dwordx4 v[176:177], off
	s_barrier
	s_waitcnt lgkmcnt(0)
	s_waitcnt lgkmcnt(0)
	v_mfma_f32_16x16x32_bf16 v[94:97], v[230:233], v[194:197], v[94:97]
	v_mfma_f32_16x16x32_bf16 v[90:93], v[238:241], v[194:197], v[90:93]
	v_mfma_f32_16x16x32_bf16 v[82:85], v[230:233], v[202:205], v[82:85]
	v_mfma_f32_16x16x32_bf16 v[66:69], v[238:241], v[202:205], v[66:69]
	v_mfma_f32_16x16x32_bf16 v[62:65], v[230:233], v[210:213], v[62:65]
	v_mfma_f32_16x16x32_bf16 v[58:61], v[238:241], v[210:213], v[58:61]
	v_mfma_f32_16x16x32_bf16 v[54:57], v[230:233], v[218:221], v[54:57]
	v_mfma_f32_16x16x32_bf16 v[50:53], v[238:241], v[218:221], v[50:53]
	v_mfma_f32_16x16x32_bf16 v[94:97], v[234:237], v[198:201], v[94:97]
	v_mfma_f32_16x16x32_bf16 v[90:93], v[242:245], v[198:201], v[90:93]
	v_mfma_f32_16x16x32_bf16 v[82:85], v[234:237], v[206:209], v[82:85]
	v_mfma_f32_16x16x32_bf16 v[66:69], v[242:245], v[206:209], v[66:69]
	v_mfma_f32_16x16x32_bf16 v[62:65], v[234:237], v[214:217], v[62:65]
	v_mfma_f32_16x16x32_bf16 v[58:61], v[242:245], v[214:217], v[58:61]
	v_mfma_f32_16x16x32_bf16 v[54:57], v[234:237], v[226:229], v[54:57]
	v_mfma_f32_16x16x32_bf16 v[50:53], v[242:245], v[226:229], v[50:53]
	v_readfirstlane_b32 s53, v157
	v_add_u32_e32 v175, s41, v164
	v_add_u32_e32 v176, s44, v164
	v_add_u32_e32 v177, s45, v164
	v_lshl_add_u64 v[222:223], v[224:225], 0, s[24:25]
	s_mov_b32 m0, s53
	v_readfirstlane_b32 s53, v158
	s_barrier
	ds_read_b128 v[194:197], v151
	ds_read_b128 v[198:201], v151 offset:1024
	ds_read_b128 v[202:205], v175
	ds_read_b128 v[206:209], v175 offset:1024
	ds_read_b128 v[210:213], v176
	ds_read_b128 v[214:217], v176 offset:1024
	ds_read_b128 v[218:221], v177
	ds_read_b128 v[226:229], v177 offset:1024
	global_load_lds_dwordx4 v[222:223], off
	v_lshl_add_u64 v[222:223], v[246:247], 0, s[24:25]
	s_mov_b32 m0, s53
	s_nop 0
	global_load_lds_dwordx4 v[222:223], off
	s_barrier
	s_waitcnt lgkmcnt(0)
	s_waitcnt lgkmcnt(0)
	v_mfma_f32_16x16x32_bf16 v[46:49], v[178:181], v[194:197], v[46:49]
	v_mfma_f32_16x16x32_bf16 v[42:45], v[186:189], v[194:197], v[42:45]
	v_mfma_f32_16x16x32_bf16 v[38:41], v[178:181], v[202:205], v[38:41]
	v_mfma_f32_16x16x32_bf16 v[34:37], v[186:189], v[202:205], v[34:37]
	v_mfma_f32_16x16x32_bf16 v[30:33], v[178:181], v[210:213], v[30:33]
	v_mfma_f32_16x16x32_bf16 v[26:29], v[186:189], v[210:213], v[26:29]
	v_mfma_f32_16x16x32_bf16 v[22:25], v[178:181], v[218:221], v[22:25]
	v_mfma_f32_16x16x32_bf16 v[18:21], v[186:189], v[218:221], v[18:21]
	v_mfma_f32_16x16x32_bf16 v[46:49], v[182:185], v[198:201], v[46:49]
	v_mfma_f32_16x16x32_bf16 v[42:45], v[190:193], v[198:201], v[42:45]
	v_mfma_f32_16x16x32_bf16 v[38:41], v[182:185], v[206:209], v[38:41]
	v_mfma_f32_16x16x32_bf16 v[34:37], v[190:193], v[206:209], v[34:37]
	v_mfma_f32_16x16x32_bf16 v[30:33], v[182:185], v[214:217], v[30:33]
	v_mfma_f32_16x16x32_bf16 v[26:29], v[190:193], v[214:217], v[26:29]
	v_mfma_f32_16x16x32_bf16 v[22:25], v[182:185], v[226:229], v[22:25]
	v_mfma_f32_16x16x32_bf16 v[18:21], v[190:193], v[226:229], v[18:21]
	s_barrier
	v_readfirstlane_b32 s53, v159
	v_lshl_add_u64 v[178:179], v[248:249], 0, s[26:27]
	s_mov_b32 m0, s53
	v_readfirstlane_b32 s53, v160
	global_load_lds_dwordx4 v[178:179], off
	v_lshl_add_u64 v[178:179], v[250:251], 0, s[26:27]
	s_mov_b32 m0, s53
	s_nop 0
	global_load_lds_dwordx4 v[178:179], off
	s_waitcnt vmcnt(6)
	s_barrier
	v_mfma_f32_16x16x32_bf16 v[14:17], v[230:233], v[194:197], v[14:17]
	v_mfma_f32_16x16x32_bf16 v[10:13], v[238:241], v[194:197], v[10:13]
	v_mfma_f32_16x16x32_bf16 v[6:9], v[230:233], v[202:205], v[6:9]
	v_mfma_f32_16x16x32_bf16 v[2:5], v[238:241], v[202:205], v[2:5]
	v_mfma_f32_16x16x32_bf16 v[70:73], v[230:233], v[210:213], v[70:73]
	v_mfma_f32_16x16x32_bf16 v[74:77], v[238:241], v[210:213], v[74:77]
	v_mfma_f32_16x16x32_bf16 v[78:81], v[230:233], v[218:221], v[78:81]
	v_mfma_f32_16x16x32_bf16 v[86:89], v[238:241], v[218:221], v[86:89]
	v_mfma_f32_16x16x32_bf16 v[14:17], v[234:237], v[198:201], v[14:17]
	v_mfma_f32_16x16x32_bf16 v[10:13], v[242:245], v[198:201], v[10:13]
	v_mfma_f32_16x16x32_bf16 v[6:9], v[234:237], v[206:209], v[6:9]
	v_mfma_f32_16x16x32_bf16 v[2:5], v[242:245], v[206:209], v[2:5]
	v_mfma_f32_16x16x32_bf16 v[70:73], v[234:237], v[214:217], v[70:73]
	v_mfma_f32_16x16x32_bf16 v[74:77], v[242:245], v[214:217], v[74:77]
	v_mfma_f32_16x16x32_bf16 v[78:81], v[234:237], v[226:229], v[78:81]
	v_mfma_f32_16x16x32_bf16 v[86:89], v[242:245], v[226:229], v[86:89]
	s_add_i32 s52, s52, 2
	s_add_u32 s0, s0, 0x100
	s_addc_u32 s1, s1, 0
	s_cmp_lt_u32 s52, 12
	s_barrier
	s_cbranch_scc1 .LBB0_1913
	s_or_b32 s0, s34, 0x80
	s_ashr_i32 s1, s0, 31
	s_lshl_b64 s[44:45], s[0:1], 11
	s_add_u32 s44, s60, s44
	s_addc_u32 s45, s61, s45
	v_lshl_add_u64 v[202:203], v[130:131], 1, s[44:45]
	v_readfirstlane_b32 s1, v170
	v_lshl_add_u64 v[202:203], v[202:203], 0, s[28:29]
	s_mov_b32 m0, s1
	v_lshl_add_u64 v[132:133], v[132:133], 1, s[44:45]
	v_readfirstlane_b32 s1, v171
	ds_read_b128 v[134:137], v169 offset:32768
	ds_read_b128 v[138:141], v169 offset:33792
	ds_read_b128 v[142:145], v169 offset:34816
	ds_read_b128 v[146:149], v169 offset:35840
	ds_read_b128 v[156:159], v165
	ds_read_b128 v[160:163], v165 offset:1024
	ds_read_b128 v[178:181], v166
	ds_read_b128 v[182:185], v166 offset:1024
	ds_read_b128 v[186:189], v167
	ds_read_b128 v[190:193], v167 offset:1024
	ds_read_b128 v[194:197], v168
	ds_read_b128 v[198:201], v168 offset:1024
	global_load_lds_dwordx4 v[202:203], off
	v_lshl_add_u64 v[132:133], v[132:133], 0, s[28:29]
	s_mov_b32 m0, s1
	s_nop 0
	global_load_lds_dwordx4 v[132:133], off
	s_barrier
	s_waitcnt lgkmcnt(0)
	s_waitcnt lgkmcnt(0)
	v_mfma_f32_16x16x32_bf16 v[126:129], v[134:137], v[156:159], v[126:129]
	v_mfma_f32_16x16x32_bf16 v[122:125], v[142:145], v[156:159], v[122:125]
	v_mfma_f32_16x16x32_bf16 v[118:121], v[134:137], v[178:181], v[118:121]
	v_mfma_f32_16x16x32_bf16 v[114:117], v[142:145], v[178:181], v[114:117]
	v_mfma_f32_16x16x32_bf16 v[110:113], v[134:137], v[186:189], v[110:113]
	v_mfma_f32_16x16x32_bf16 v[126:129], v[138:141], v[160:163], v[126:129]
	v_mfma_f32_16x16x32_bf16 v[122:125], v[146:149], v[160:163], v[122:125]
	v_mfma_f32_16x16x32_bf16 v[118:121], v[138:141], v[182:185], v[118:121]
	v_mfma_f32_16x16x32_bf16 v[114:117], v[146:149], v[182:185], v[114:117]
	v_mfma_f32_16x16x32_bf16 v[110:113], v[138:141], v[190:193], v[110:113]
	v_mfma_f32_16x16x32_bf16 v[106:109], v[142:145], v[186:189], v[106:109]
	v_mfma_f32_16x16x32_bf16 v[102:105], v[134:137], v[194:197], v[102:105]
	v_mfma_f32_16x16x32_bf16 v[98:101], v[142:145], v[194:197], v[98:101]
	v_mfma_f32_16x16x32_bf16 v[202:205], v[146:149], v[190:193], v[106:109]
	v_mfma_f32_16x16x32_bf16 v[206:209], v[138:141], v[198:201], v[102:105]
	v_mfma_f32_16x16x32_bf16 v[210:213], v[146:149], v[198:201], v[98:101]
	s_barrier
	s_nop 2
	ds_read_b128 v[98:101], v169 offset:49152
	ds_read_b128 v[102:105], v169 offset:50176
	ds_read_b128 v[106:109], v169 offset:51200
	ds_read_b128 v[214:217], v169 offset:52224
	s_barrier
	s_waitcnt lgkmcnt(0)
	s_waitcnt lgkmcnt(0)
	v_mfma_f32_16x16x32_bf16 v[94:97], v[98:101], v[156:159], v[94:97]
	v_mfma_f32_16x16x32_bf16 v[90:93], v[106:109], v[156:159], v[90:93]
	v_mfma_f32_16x16x32_bf16 v[82:85], v[98:101], v[178:181], v[82:85]
	v_mfma_f32_16x16x32_bf16 v[62:65], v[98:101], v[186:189], v[62:65]
	v_mfma_f32_16x16x32_bf16 v[58:61], v[106:109], v[186:189], v[58:61]
	v_mfma_f32_16x16x32_bf16 v[54:57], v[98:101], v[194:197], v[54:57]
	v_mfma_f32_16x16x32_bf16 v[50:53], v[106:109], v[194:197], v[50:53]
	v_mfma_f32_16x16x32_bf16 v[94:97], v[102:105], v[160:163], v[94:97]
	v_mfma_f32_16x16x32_bf16 v[90:93], v[214:217], v[160:163], v[90:93]
	v_mfma_f32_16x16x32_bf16 v[82:85], v[102:105], v[182:185], v[82:85]
	v_mfma_f32_16x16x32_bf16 v[66:69], v[106:109], v[178:181], v[66:69]
	v_mfma_f32_16x16x32_bf16 v[62:65], v[102:105], v[190:193], v[62:65]
	v_mfma_f32_16x16x32_bf16 v[58:61], v[214:217], v[190:193], v[58:61]
	v_mfma_f32_16x16x32_bf16 v[54:57], v[102:105], v[198:201], v[54:57]
	v_mfma_f32_16x16x32_bf16 v[50:53], v[214:217], v[198:201], v[50:53]
	v_mfma_f32_16x16x32_bf16 v[156:159], v[214:217], v[182:185], v[66:69]
	s_barrier
	s_nop 0
	ds_read_b128 v[66:69], v165 offset:16384
	ds_read_b128 v[160:163], v165 offset:17408
	ds_read_b128 v[178:181], v166 offset:16384
	ds_read_b128 v[182:185], v166 offset:17408
	ds_read_b128 v[186:189], v167 offset:16384
	ds_read_b128 v[164:167], v167 offset:17408
	ds_read_b128 v[190:193], v168 offset:16384
	ds_read_b128 v[168:171], v168 offset:17408
	s_waitcnt vmcnt(4)
	s_barrier
	s_waitcnt lgkmcnt(0)
	s_waitcnt lgkmcnt(0)
	v_mfma_f32_16x16x32_bf16 v[46:49], v[134:137], v[66:69], v[46:49]
	v_mfma_f32_16x16x32_bf16 v[42:45], v[142:145], v[66:69], v[42:45]
	v_mfma_f32_16x16x32_bf16 v[30:33], v[134:137], v[186:189], v[30:33]
	v_mfma_f32_16x16x32_bf16 v[26:29], v[142:145], v[186:189], v[26:29]
	v_mfma_f32_16x16x32_bf16 v[22:25], v[134:137], v[190:193], v[22:25]
	v_mfma_f32_16x16x32_bf16 v[18:21], v[142:145], v[190:193], v[18:21]
	v_mfma_f32_16x16x32_bf16 v[46:49], v[138:141], v[160:163], v[46:49]
	v_mfma_f32_16x16x32_bf16 v[42:45], v[146:149], v[160:163], v[42:45]
	v_mfma_f32_16x16x32_bf16 v[38:41], v[134:137], v[178:181], v[38:41]
	v_mfma_f32_16x16x32_bf16 v[34:37], v[142:145], v[178:181], v[34:37]
	v_mfma_f32_16x16x32_bf16 v[30:33], v[138:141], v[164:167], v[30:33]
	v_mfma_f32_16x16x32_bf16 v[26:29], v[146:149], v[164:167], v[26:29]
	v_mfma_f32_16x16x32_bf16 v[22:25], v[138:141], v[168:171], v[22:25]
	v_mfma_f32_16x16x32_bf16 v[18:21], v[146:149], v[168:171], v[18:21]
	v_mfma_f32_16x16x32_bf16 v[194:197], v[138:141], v[182:185], v[38:41]
	v_mfma_f32_16x16x32_bf16 v[198:201], v[146:149], v[182:185], v[34:37]
	v_mfma_f32_16x16x32_bf16 v[2:5], v[106:109], v[178:181], v[2:5]
	v_mfma_f32_16x16x32_bf16 v[136:139], v[214:217], v[182:185], v[2:5]
	v_mfma_f32_16x16x32_bf16 v[2:5], v[98:101], v[186:189], v[70:73]
	v_mfma_f32_16x16x32_bf16 v[140:143], v[102:105], v[164:167], v[2:5]
	v_mfma_f32_16x16x32_bf16 v[2:5], v[106:109], v[186:189], v[74:77]
	v_mfma_f32_16x16x32_bf16 v[14:17], v[98:101], v[66:69], v[14:17]
	v_mfma_f32_16x16x32_bf16 v[10:13], v[106:109], v[66:69], v[10:13]
	v_mfma_f32_16x16x32_bf16 v[144:147], v[214:217], v[164:167], v[2:5]
	v_mfma_f32_16x16x32_bf16 v[2:5], v[98:101], v[190:193], v[78:81]
	v_mfma_f32_16x16x32_bf16 v[14:17], v[102:105], v[160:163], v[14:17]
	v_mfma_f32_16x16x32_bf16 v[10:13], v[214:217], v[160:163], v[10:13]
	v_mfma_f32_16x16x32_bf16 v[6:9], v[98:101], v[178:181], v[6:9]
	v_mfma_f32_16x16x32_bf16 v[160:163], v[102:105], v[168:171], v[2:5]
	v_mfma_f32_16x16x32_bf16 v[2:5], v[106:109], v[190:193], v[86:89]
	v_mfma_f32_16x16x32_bf16 v[132:135], v[102:105], v[182:185], v[6:9]
	v_mfma_f32_16x16x32_bf16 v[164:167], v[214:217], v[168:171], v[2:5]
	s_barrier
	s_nop 3
	ds_read_b128 v[2:5], v154
	ds_read_b128 v[6:9], v154 offset:1024
	ds_read_b128 v[168:171], v154 offset:2048
	ds_read_b128 v[178:181], v154 offset:3072
	ds_read_b128 v[34:37], v153
	ds_read_b128 v[38:41], v153 offset:1024
	ds_read_b128 v[78:81], v172
	ds_read_b128 v[86:89], v172 offset:1024
	ds_read_b128 v[182:185], v173
	ds_read_b128 v[186:189], v173 offset:1024
	ds_read_b128 v[190:193], v174
	ds_read_b128 v[214:217], v174 offset:1024
	s_waitcnt vmcnt(2)
	s_barrier
	s_waitcnt lgkmcnt(0)
	s_waitcnt lgkmcnt(0)
	v_mfma_f32_16x16x32_bf16 v[66:69], v[2:5], v[34:37], v[126:129]
	v_mfma_f32_16x16x32_bf16 v[126:129], v[6:9], v[38:41], v[66:69]
	v_mfma_f32_16x16x32_bf16 v[66:69], v[168:171], v[34:37], v[122:125]
	v_mfma_f32_16x16x32_bf16 v[98:101], v[178:181], v[38:41], v[66:69]
	v_mfma_f32_16x16x32_bf16 v[66:69], v[2:5], v[78:81], v[118:121]
	v_mfma_f32_16x16x32_bf16 v[102:105], v[6:9], v[86:89], v[66:69]
	v_mfma_f32_16x16x32_bf16 v[66:69], v[168:171], v[78:81], v[114:117]
	v_mfma_f32_16x16x32_bf16 v[106:109], v[178:181], v[86:89], v[66:69]
	v_mfma_f32_16x16x32_bf16 v[66:69], v[2:5], v[182:185], v[110:113]
	v_mfma_f32_16x16x32_bf16 v[110:113], v[6:9], v[186:189], v[66:69]
	v_mfma_f32_16x16x32_bf16 v[66:69], v[168:171], v[182:185], v[202:205]
	v_mfma_f32_16x16x32_bf16 v[114:117], v[178:181], v[186:189], v[66:69]
	v_mfma_f32_16x16x32_bf16 v[66:69], v[2:5], v[190:193], v[206:209]
	v_mfma_f32_16x16x32_bf16 v[118:121], v[6:9], v[214:217], v[66:69]
	v_mfma_f32_16x16x32_bf16 v[66:69], v[168:171], v[190:193], v[210:213]
	v_mfma_f32_16x16x32_bf16 v[122:125], v[178:181], v[214:217], v[66:69]
	s_barrier
	ds_read_b128 v[202:205], v152
	ds_read_b128 v[206:209], v152 offset:1024
	ds_read_b128 v[210:213], v152 offset:2048
	ds_read_b128 v[152:155], v152 offset:3072
	s_waitcnt vmcnt(0)
	s_barrier
	s_waitcnt lgkmcnt(0)
	s_waitcnt lgkmcnt(0)
	v_mfma_f32_16x16x32_bf16 v[66:69], v[202:205], v[34:37], v[94:97]
	v_mfma_f32_16x16x32_bf16 v[34:37], v[210:213], v[34:37], v[90:93]
	v_mfma_f32_16x16x32_bf16 v[70:73], v[152:155], v[38:41], v[34:37]
	v_mfma_f32_16x16x32_bf16 v[34:37], v[202:205], v[78:81], v[82:85]
	v_mfma_f32_16x16x32_bf16 v[74:77], v[206:209], v[86:89], v[34:37]
	v_mfma_f32_16x16x32_bf16 v[34:37], v[210:213], v[78:81], v[156:159]
	v_mfma_f32_16x16x32_bf16 v[78:81], v[152:155], v[86:89], v[34:37]
	v_mfma_f32_16x16x32_bf16 v[34:37], v[202:205], v[182:185], v[62:65]
	v_mfma_f32_16x16x32_bf16 v[82:85], v[206:209], v[186:189], v[34:37]
	v_mfma_f32_16x16x32_bf16 v[34:37], v[210:213], v[182:185], v[58:61]
	v_mfma_f32_16x16x32_bf16 v[86:89], v[152:155], v[186:189], v[34:37]
	v_mfma_f32_16x16x32_bf16 v[34:37], v[202:205], v[190:193], v[54:57]
	v_mfma_f32_16x16x32_bf16 v[90:93], v[206:209], v[214:217], v[34:37]
	v_mfma_f32_16x16x32_bf16 v[34:37], v[210:213], v[190:193], v[50:53]
	v_mfma_f32_16x16x32_bf16 v[66:69], v[206:209], v[38:41], v[66:69]
	v_mfma_f32_16x16x32_bf16 v[94:97], v[152:155], v[214:217], v[34:37]
	s_barrier
	ds_read_b128 v[156:159], v151
	ds_read_b128 v[148:151], v151 offset:1024
	ds_read_b128 v[182:185], v175
	ds_read_b128 v[172:175], v175 offset:1024
	ds_read_b128 v[186:189], v176
	ds_read_b128 v[190:193], v176 offset:1024
	ds_read_b128 v[214:217], v177
	ds_read_b128 v[218:221], v177 offset:1024
	s_barrier
	s_waitcnt lgkmcnt(0)
	s_waitcnt lgkmcnt(0)
	v_mfma_f32_16x16x32_bf16 v[34:37], v[2:5], v[156:159], v[46:49]
	v_mfma_f32_16x16x32_bf16 v[38:41], v[168:171], v[156:159], v[42:45]
	v_mfma_f32_16x16x32_bf16 v[42:45], v[2:5], v[182:185], v[194:197]
	v_mfma_f32_16x16x32_bf16 v[30:33], v[2:5], v[186:189], v[30:33]
	v_mfma_f32_16x16x32_bf16 v[2:5], v[2:5], v[214:217], v[22:25]
	v_mfma_f32_16x16x32_bf16 v[46:49], v[168:171], v[182:185], v[198:201]
	v_mfma_f32_16x16x32_bf16 v[26:29], v[168:171], v[186:189], v[26:29]
	v_mfma_f32_16x16x32_bf16 v[58:61], v[6:9], v[218:221], v[2:5]
	v_mfma_f32_16x16x32_bf16 v[2:5], v[168:171], v[214:217], v[18:21]
	v_mfma_f32_16x16x32_bf16 v[34:37], v[6:9], v[148:151], v[34:37]
	v_mfma_f32_16x16x32_bf16 v[38:41], v[178:181], v[148:151], v[38:41]
	v_mfma_f32_16x16x32_bf16 v[42:45], v[6:9], v[172:175], v[42:45]
	v_mfma_f32_16x16x32_bf16 v[46:49], v[178:181], v[172:175], v[46:49]
	v_mfma_f32_16x16x32_bf16 v[50:53], v[6:9], v[190:193], v[30:33]
	v_mfma_f32_16x16x32_bf16 v[54:57], v[178:181], v[190:193], v[26:29]
	v_mfma_f32_16x16x32_bf16 v[62:65], v[178:181], v[218:221], v[2:5]
	v_mfma_f32_16x16x32_bf16 v[2:5], v[202:205], v[156:159], v[14:17]
	v_mfma_f32_16x16x32_bf16 v[6:9], v[210:213], v[156:159], v[10:13]
	v_mfma_f32_16x16x32_bf16 v[10:13], v[202:205], v[182:185], v[132:135]
	v_mfma_f32_16x16x32_bf16 v[14:17], v[210:213], v[182:185], v[136:139]
	v_mfma_f32_16x16x32_bf16 v[18:21], v[202:205], v[186:189], v[140:143]
	v_mfma_f32_16x16x32_bf16 v[22:25], v[210:213], v[186:189], v[144:147]
	v_mfma_f32_16x16x32_bf16 v[26:29], v[202:205], v[214:217], v[160:163]
	v_mfma_f32_16x16x32_bf16 v[30:33], v[210:213], v[214:217], v[164:167]
	v_mfma_f32_16x16x32_bf16 v[2:5], v[206:209], v[148:151], v[2:5]
	v_mfma_f32_16x16x32_bf16 v[6:9], v[152:155], v[148:151], v[6:9]
	v_mfma_f32_16x16x32_bf16 v[10:13], v[206:209], v[172:175], v[10:13]
	v_mfma_f32_16x16x32_bf16 v[14:17], v[152:155], v[172:175], v[14:17]
	v_mfma_f32_16x16x32_bf16 v[18:21], v[206:209], v[190:193], v[18:21]
	v_mfma_f32_16x16x32_bf16 v[22:25], v[152:155], v[190:193], v[22:25]
	v_mfma_f32_16x16x32_bf16 v[26:29], v[206:209], v[218:221], v[26:29]
	v_mfma_f32_16x16x32_bf16 v[30:33], v[152:155], v[218:221], v[30:33]
	s_setprio 0
	s_cmpk_gt_u32 s39, 0xff
	s_barrier
	s_cbranch_scc1 .LBB0_1916
	s_barrier

.LBB0_1991:
	s_lshl_b32 s36, s52, 8
	s_ashr_i32 s37, s36, 31
	s_mul_i32 s52, s52, 0x160000
	s_mul_hi_i32 s1, s36, 0x1600
	s_add_u32 s0, s16, s52
	s_addc_u32 s1, s17, s1
	v_add_u32_e32 v156, s33, v143
	v_lshlrev_b64 v[12:13], 1, v[130:131]
	v_lshl_add_u64 v[14:15], s[0:1], 0, v[12:13]
	v_readfirstlane_b32 s52, v156
	v_lshl_add_u64 v[14:15], v[14:15], 0, s[2:3]
	s_mov_b32 m0, s52
	v_mov_b32_e32 v133, v131
	s_barrier
	global_load_lds_dwordx4 v[14:15], off
	v_lshlrev_b64 v[14:15], 1, v[132:133]
	v_add_u32_e32 v157, 0x2000, v156
	v_lshl_add_u64 v[16:17], s[0:1], 0, v[14:15]
	v_readfirstlane_b32 s0, v157
	s_mov_b32 m0, s0
	s_add_u32 s0, s94, s54
	v_lshl_add_u64 v[16:17], v[16:17], 0, s[2:3]
	s_addc_u32 s1, s95, s53
	v_add_u32_e32 v158, s44, v143
	global_load_lds_dwordx4 v[16:17], off
	v_lshl_add_u64 v[16:17], s[0:1], 0, v[12:13]
	v_readfirstlane_b32 s52, v158
	v_lshl_add_u64 v[16:17], v[16:17], 0, s[2:3]
	s_mov_b32 m0, s52
	v_add_u32_e32 v159, 0x2000, v158
	global_load_lds_dwordx4 v[16:17], off
	v_lshl_add_u64 v[16:17], s[0:1], 0, v[14:15]
	v_readfirstlane_b32 s0, v159
	s_mov_b32 m0, s0
	s_or_b32 s0, s36, 0x80
	s_ashr_i32 s1, s0, 31
	s_mul_i32 s52, s0, 0x1600
	s_mul_hi_i32 s53, s0, 0x1600
	s_add_u32 s52, s16, s52
	s_addc_u32 s53, s17, s53
	v_add_u32_e32 v160, s45, v143
	v_lshl_add_u64 v[16:17], v[16:17], 0, s[2:3]
	v_lshl_add_u64 v[12:13], s[52:53], 0, v[12:13]
	v_readfirstlane_b32 s54, v160
	global_load_lds_dwordx4 v[16:17], off
	v_lshl_add_u64 v[12:13], v[12:13], 0, s[2:3]
	s_mov_b32 m0, s54
	v_add_u32_e32 v161, 0x2000, v160
	global_load_lds_dwordx4 v[12:13], off
	v_lshl_add_u64 v[12:13], s[52:53], 0, v[14:15]
	v_readfirstlane_b32 s52, v161
	v_lshl_add_u64 v[12:13], v[12:13], 0, s[2:3]
	s_mov_b32 m0, s52
	v_and_b32_e32 v11, 15, v3
	global_load_lds_dwordx4 v[12:13], off
	v_and_b32_e32 v18, 48, v3
	v_lshlrev_b32_e32 v12, 2, v3
	v_lshlrev_b32_e32 v3, 6, v3
	v_and_b32_e32 v12, 32, v12
	v_and_b32_e32 v3, 0x3c0, v3
	v_bitop3_b32 v3, v3, v12, v18 bitop3:0x36
	v_add_u32_e32 v163, 0, v3
	v_add_u32_e32 v164, s44, v3
	v_add_u32_e32 v165, s46, v3
	v_lshrrev_b32_e32 v3, 1, v2
	v_mul_lo_u32 v2, v4, s31
	v_mad_u64_u32 v[2:3], s[68:69], v3, s47, v[2:3]
	v_or_b32_e32 v2, v2, v5
	v_lshrrev_b32_e32 v5, 1, v7
	v_mul_lo_u32 v4, v8, s31
	v_mad_u64_u32 v[4:5], s[68:69], v5, s47, v[4:5]
	v_or_b32_e32 v4, v4, v9
	v_add_u32_sdwa v2, v2, sext(v6) dst_sel:DWORD dst_unused:UNUSED_PAD src0_sel:DWORD src1_sel:WORD_0
	v_mov_b32_e32 v3, v131
	v_add_u32_sdwa v4, v4, sext(v10) dst_sel:DWORD dst_unused:UNUSED_PAD src0_sel:DWORD src1_sel:WORD_0
	v_mov_b32_e32 v5, v131
	v_lshlrev_b64 v[2:3], 1, v[2:3]
	v_lshlrev_b64 v[4:5], 1, v[4:5]
	v_mad_i64_i32 v[134:135], s[68:69], s36, v1, v[2:3]
	v_mad_i64_i32 v[136:137], s[68:69], s36, v1, v[4:5]
	s_lshl_b32 s68, s43, 11
	s_sub_i32 s42, s42, s65
	s_lshl_b32 s43, s43, 5
	s_sub_i32 s42, s42, s43
	s_sext_i32_i8 s42, s42
	v_lshlrev_b32_e32 v11, 6, v11
	s_lshl_b32 s42, s42, 8
	s_waitcnt vmcnt(6)
	v_bitop3_b32 v11, v11, v12, v18 bitop3:0x36
	s_lshl_b32 s52, s51, 6
	s_add_i32 s68, s68, s42
	v_add_u32_e32 v162, 0, v11
	v_add_u32_e32 v13, s33, v11
	v_add_u32_e32 v14, s45, v11
	s_and_b32 s52, s52, 0x3000
	s_lshl_b32 s53, s55, 13
	v_add_u32_e32 v12, s44, v11
	v_add_u32_e32 v11, s46, v11
	v_mad_i64_i32 v[138:139], s[42:43], s68, v1, v[2:3]
	v_mad_i64_i32 v[140:141], s[42:43], s68, v1, v[4:5]
	v_mov_b32_e32 v2, 0
	s_or_b32 s54, s53, 0x800
	s_or_b32 s55, s53, 0x1000
	s_or_b32 s64, s53, 0x1800
	s_mov_b32 s65, -2
	v_add_u32_e32 v155, s52, v13
	v_add_u32_e32 v154, s53, v12
	v_add_u32_e32 v153, s52, v14
	v_add_u32_e32 v152, s53, v11
	s_mov_b64 s[42:43], s[62:63]
	v_mov_b32_e32 v3, v2
	v_mov_b32_e32 v4, v2
	v_mov_b32_e32 v5, v2
	v_mov_b32_e32 v6, v2
	v_mov_b32_e32 v7, v2
	v_mov_b32_e32 v8, v2
	v_mov_b32_e32 v9, v2
	v_mov_b32_e32 v10, v2
	v_mov_b32_e32 v11, v2
	v_mov_b32_e32 v12, v2
	v_mov_b32_e32 v13, v2
	v_mov_b32_e32 v14, v2
	v_mov_b32_e32 v15, v2
	v_mov_b32_e32 v16, v2
	v_mov_b32_e32 v17, v2
	v_mov_b32_e32 v18, v2
	v_mov_b32_e32 v19, v2
	v_mov_b32_e32 v20, v2
	v_mov_b32_e32 v21, v2
	v_mov_b32_e32 v22, v2
	v_mov_b32_e32 v23, v2
	v_mov_b32_e32 v24, v2
	v_mov_b32_e32 v25, v2
	v_mov_b32_e32 v26, v2
	v_mov_b32_e32 v27, v2
	v_mov_b32_e32 v28, v2
	v_mov_b32_e32 v29, v2
	v_mov_b32_e32 v30, v2
	v_mov_b32_e32 v31, v2
	v_mov_b32_e32 v32, v2
	v_mov_b32_e32 v33, v2
	v_mov_b32_e32 v34, v2
	v_mov_b32_e32 v35, v2
	v_mov_b32_e32 v36, v2
	v_mov_b32_e32 v37, v2
	v_mov_b32_e32 v38, v2
	v_mov_b32_e32 v39, v2
	v_mov_b32_e32 v40, v2
	v_mov_b32_e32 v41, v2
	v_mov_b32_e32 v42, v2
	v_mov_b32_e32 v43, v2
	v_mov_b32_e32 v44, v2
	v_mov_b32_e32 v45, v2
	v_mov_b32_e32 v46, v2
	v_mov_b32_e32 v47, v2
	v_mov_b32_e32 v48, v2
	v_mov_b32_e32 v49, v2
	v_mov_b32_e32 v50, v2
	v_mov_b32_e32 v51, v2
	v_mov_b32_e32 v52, v2
	v_mov_b32_e32 v53, v2
	v_mov_b32_e32 v54, v2
	v_mov_b32_e32 v55, v2
	v_mov_b32_e32 v56, v2
	v_mov_b32_e32 v57, v2
	v_mov_b32_e32 v58, v2
	v_mov_b32_e32 v59, v2
	v_mov_b32_e32 v60, v2
	v_mov_b32_e32 v61, v2
	v_mov_b32_e32 v62, v2
	v_mov_b32_e32 v63, v2
	v_mov_b32_e32 v64, v2
	v_mov_b32_e32 v65, v2
	v_mov_b32_e32 v66, v2
	v_mov_b32_e32 v67, v2
	v_mov_b32_e32 v68, v2
	v_mov_b32_e32 v69, v2
	v_mov_b32_e32 v82, v2
	v_mov_b32_e32 v83, v2
	v_mov_b32_e32 v84, v2
	v_mov_b32_e32 v85, v2
	v_mov_b32_e32 v90, v2
	v_mov_b32_e32 v91, v2
	v_mov_b32_e32 v92, v2
	v_mov_b32_e32 v93, v2
	v_mov_b32_e32 v94, v2
	v_mov_b32_e32 v95, v2
	v_mov_b32_e32 v96, v2
	v_mov_b32_e32 v97, v2
	v_mov_b32_e32 v98, v2
	v_mov_b32_e32 v99, v2
	v_mov_b32_e32 v100, v2
	v_mov_b32_e32 v101, v2
	v_mov_b32_e32 v102, v2
	v_mov_b32_e32 v103, v2
	v_mov_b32_e32 v104, v2
	v_mov_b32_e32 v105, v2
	v_mov_b32_e32 v106, v2
	v_mov_b32_e32 v107, v2
	v_mov_b32_e32 v108, v2
	v_mov_b32_e32 v109, v2
	v_mov_b32_e32 v110, v2
	v_mov_b32_e32 v111, v2
	v_mov_b32_e32 v112, v2
	v_mov_b32_e32 v113, v2
	v_mov_b32_e32 v114, v2
	v_mov_b32_e32 v115, v2
	v_mov_b32_e32 v116, v2
	v_mov_b32_e32 v117, v2
	v_mov_b32_e32 v118, v2
	v_mov_b32_e32 v119, v2
	v_mov_b32_e32 v120, v2
	v_mov_b32_e32 v121, v2
	v_mov_b32_e32 v122, v2
	v_mov_b32_e32 v123, v2
	v_mov_b32_e32 v124, v2
	v_mov_b32_e32 v125, v2
	v_mov_b32_e32 v126, v2
	v_mov_b32_e32 v127, v2
	v_mov_b32_e32 v128, v2
	v_mov_b32_e32 v129, v2
	v_mov_b32_e32 v70, v2
	v_mov_b32_e32 v71, v2
	v_mov_b32_e32 v72, v2
	v_mov_b32_e32 v73, v2
	v_mov_b32_e32 v74, v2
	v_mov_b32_e32 v75, v2
	v_mov_b32_e32 v76, v2
	v_mov_b32_e32 v77, v2
	v_mov_b32_e32 v78, v2
	v_mov_b32_e32 v79, v2
	v_mov_b32_e32 v80, v2
	v_mov_b32_e32 v81, v2
	v_mov_b32_e32 v86, v2
	v_mov_b32_e32 v87, v2
	v_mov_b32_e32 v88, v2
	v_mov_b32_e32 v89, v2
	s_barrier
	v_readfirstlane_b32 s99, v0
	s_nop 3
	s_lshr_b32 s99, s99, 6
	s_cmp_lt_u32 s99, 4
	s_cbranch_scc0 .Lprio_k7
	s_setprio 1
.Lprio_k7:
.LBB0_1992:
	v_add_u32_e32 v170, s52, v162
	ds_read_b128 v[174:177], v170 offset:32768
	ds_read_b128 v[178:181], v170 offset:33792
	ds_read_b128 v[182:185], v170 offset:34816
	ds_read_b128 v[186:189], v170 offset:35840
	v_add_u32_e32 v171, s46, v143
	v_lshl_add_u64 v[224:225], s[42:43], 0, v[138:139]
	v_readfirstlane_b32 s68, v171
	v_add_u32_e32 v166, s53, v162
	v_add_u32_e32 v167, s54, v163
	v_add_u32_e32 v168, s55, v163
	v_add_u32_e32 v169, s64, v163
	v_lshl_add_u64 v[172:173], v[224:225], 0, s[4:5]
	s_mov_b32 m0, s68
	ds_read_b128 v[190:193], v166
	ds_read_b128 v[194:197], v166 offset:1024
	ds_read_b128 v[198:201], v167
	ds_read_b128 v[202:205], v167 offset:1024
	ds_read_b128 v[206:209], v168
	ds_read_b128 v[210:213], v168 offset:1024
	ds_read_b128 v[214:217], v169
	ds_read_b128 v[218:221], v169 offset:1024
	global_load_lds_dwordx4 v[172:173], off
	v_add_u32_e32 v172, 0x2000, v171
	v_lshl_add_u64 v[246:247], s[42:43], 0, v[140:141]
	v_readfirstlane_b32 s68, v172
	v_lshl_add_u64 v[222:223], v[246:247], 0, s[4:5]
	s_mov_b32 m0, s68
	s_nop 0
	global_load_lds_dwordx4 v[222:223], off
	s_waitcnt lgkmcnt(8)
	s_barrier
	s_waitcnt lgkmcnt(0)
	s_waitcnt lgkmcnt(0)
	v_mfma_f32_16x16x32_bf16 v[126:129], v[190:193], v[174:177], v[126:129]
	v_mfma_f32_16x16x32_bf16 v[122:125], v[190:193], v[182:185], v[122:125]
	v_mfma_f32_16x16x32_bf16 v[118:121], v[198:201], v[174:177], v[118:121]
	v_mfma_f32_16x16x32_bf16 v[114:117], v[198:201], v[182:185], v[114:117]
	v_mfma_f32_16x16x32_bf16 v[110:113], v[206:209], v[174:177], v[110:113]
	v_mfma_f32_16x16x32_bf16 v[106:109], v[206:209], v[182:185], v[106:109]
	v_mfma_f32_16x16x32_bf16 v[102:105], v[214:217], v[174:177], v[102:105]
	v_mfma_f32_16x16x32_bf16 v[98:101], v[214:217], v[182:185], v[98:101]
	v_mfma_f32_16x16x32_bf16 v[126:129], v[194:197], v[178:181], v[126:129]
	v_mfma_f32_16x16x32_bf16 v[122:125], v[194:197], v[186:189], v[122:125]
	v_mfma_f32_16x16x32_bf16 v[118:121], v[202:205], v[178:181], v[118:121]
	v_mfma_f32_16x16x32_bf16 v[114:117], v[202:205], v[186:189], v[114:117]
	v_mfma_f32_16x16x32_bf16 v[110:113], v[210:213], v[178:181], v[110:113]
	v_mfma_f32_16x16x32_bf16 v[106:109], v[210:213], v[186:189], v[106:109]
	v_mfma_f32_16x16x32_bf16 v[102:105], v[218:221], v[178:181], v[102:105]
	v_mfma_f32_16x16x32_bf16 v[98:101], v[218:221], v[186:189], v[98:101]
	s_barrier
	v_lshl_add_u64 v[248:249], s[42:43], 0, v[134:135]
	v_readfirstlane_b32 s68, v145
	v_lshl_add_u64 v[222:223], v[248:249], 0, s[6:7]
	s_mov_b32 m0, s68
	v_lshl_add_u64 v[250:251], s[42:43], 0, v[136:137]
	v_readfirstlane_b32 s68, v146
	ds_read_b128 v[226:229], v170 offset:49152
	ds_read_b128 v[230:233], v170 offset:50176
	ds_read_b128 v[234:237], v170 offset:51200
	ds_read_b128 v[238:241], v170 offset:52224
	global_load_lds_dwordx4 v[222:223], off
	v_lshl_add_u64 v[222:223], v[250:251], 0, s[6:7]
	s_mov_b32 m0, s68
	s_nop 0
	global_load_lds_dwordx4 v[222:223], off
	s_barrier
	s_waitcnt lgkmcnt(0)
	s_waitcnt lgkmcnt(0)
	v_mfma_f32_16x16x32_bf16 v[94:97], v[190:193], v[226:229], v[94:97]
	v_mfma_f32_16x16x32_bf16 v[90:93], v[190:193], v[234:237], v[90:93]
	v_mfma_f32_16x16x32_bf16 v[82:85], v[198:201], v[226:229], v[82:85]
	v_mfma_f32_16x16x32_bf16 v[66:69], v[198:201], v[234:237], v[66:69]
	v_mfma_f32_16x16x32_bf16 v[62:65], v[206:209], v[226:229], v[62:65]
	v_mfma_f32_16x16x32_bf16 v[58:61], v[206:209], v[234:237], v[58:61]
	v_mfma_f32_16x16x32_bf16 v[54:57], v[214:217], v[226:229], v[54:57]
	v_mfma_f32_16x16x32_bf16 v[50:53], v[214:217], v[234:237], v[50:53]
	v_mfma_f32_16x16x32_bf16 v[94:97], v[194:197], v[230:233], v[94:97]
	v_mfma_f32_16x16x32_bf16 v[90:93], v[194:197], v[238:241], v[90:93]
	v_mfma_f32_16x16x32_bf16 v[82:85], v[202:205], v[230:233], v[82:85]
	v_mfma_f32_16x16x32_bf16 v[66:69], v[202:205], v[238:241], v[66:69]
	v_mfma_f32_16x16x32_bf16 v[62:65], v[210:213], v[230:233], v[62:65]
	v_mfma_f32_16x16x32_bf16 v[58:61], v[210:213], v[238:241], v[58:61]
	v_mfma_f32_16x16x32_bf16 v[54:57], v[218:221], v[230:233], v[54:57]
	v_mfma_f32_16x16x32_bf16 v[50:53], v[218:221], v[238:241], v[50:53]
	v_readfirstlane_b32 s68, v144
	v_lshl_add_u64 v[222:223], v[224:225], 0, s[8:9]
	s_mov_b32 m0, s68
	v_readfirstlane_b32 s68, v147
	s_barrier
	ds_read_b128 v[190:193], v166 offset:16384
	ds_read_b128 v[194:197], v166 offset:17408
	ds_read_b128 v[198:201], v167 offset:16384
	ds_read_b128 v[202:205], v167 offset:17408
	ds_read_b128 v[206:209], v168 offset:16384
	ds_read_b128 v[210:213], v168 offset:17408
	ds_read_b128 v[214:217], v169 offset:16384
	ds_read_b128 v[218:221], v169 offset:17408
	global_load_lds_dwordx4 v[222:223], off
	v_lshl_add_u64 v[222:223], v[246:247], 0, s[8:9]
	s_mov_b32 m0, s68
	s_nop 0
	global_load_lds_dwordx4 v[222:223], off
	s_barrier
	s_waitcnt lgkmcnt(0)
	s_waitcnt lgkmcnt(0)
	v_mfma_f32_16x16x32_bf16 v[46:49], v[190:193], v[174:177], v[46:49]
	v_mfma_f32_16x16x32_bf16 v[42:45], v[190:193], v[182:185], v[42:45]
	v_mfma_f32_16x16x32_bf16 v[38:41], v[198:201], v[174:177], v[38:41]
	v_mfma_f32_16x16x32_bf16 v[34:37], v[198:201], v[182:185], v[34:37]
	v_mfma_f32_16x16x32_bf16 v[30:33], v[206:209], v[174:177], v[30:33]
	v_mfma_f32_16x16x32_bf16 v[26:29], v[206:209], v[182:185], v[26:29]
	v_mfma_f32_16x16x32_bf16 v[22:25], v[214:217], v[174:177], v[22:25]
	v_mfma_f32_16x16x32_bf16 v[18:21], v[214:217], v[182:185], v[18:21]
	v_mfma_f32_16x16x32_bf16 v[46:49], v[194:197], v[178:181], v[46:49]
	v_mfma_f32_16x16x32_bf16 v[42:45], v[194:197], v[186:189], v[42:45]
	v_mfma_f32_16x16x32_bf16 v[38:41], v[202:205], v[178:181], v[38:41]
	v_mfma_f32_16x16x32_bf16 v[34:37], v[202:205], v[186:189], v[34:37]
	v_mfma_f32_16x16x32_bf16 v[30:33], v[210:213], v[178:181], v[30:33]
	v_mfma_f32_16x16x32_bf16 v[26:29], v[210:213], v[186:189], v[26:29]
	v_mfma_f32_16x16x32_bf16 v[22:25], v[218:221], v[178:181], v[22:25]
	v_mfma_f32_16x16x32_bf16 v[18:21], v[218:221], v[186:189], v[18:21]
	s_barrier
	v_readfirstlane_b32 s68, v148
	v_lshl_add_u64 v[174:175], v[248:249], 0, s[10:11]
	s_mov_b32 m0, s68
	v_readfirstlane_b32 s68, v149
	global_load_lds_dwordx4 v[174:175], off
	v_lshl_add_u64 v[174:175], v[250:251], 0, s[10:11]
	s_mov_b32 m0, s68
	s_nop 0
	global_load_lds_dwordx4 v[174:175], off
	s_waitcnt vmcnt(6)
	s_barrier
	v_mfma_f32_16x16x32_bf16 v[14:17], v[190:193], v[226:229], v[14:17]
	v_mfma_f32_16x16x32_bf16 v[10:13], v[190:193], v[234:237], v[10:13]
	v_mfma_f32_16x16x32_bf16 v[6:9], v[198:201], v[226:229], v[6:9]
	v_mfma_f32_16x16x32_bf16 v[2:5], v[198:201], v[234:237], v[2:5]
	v_mfma_f32_16x16x32_bf16 v[70:73], v[206:209], v[226:229], v[70:73]
	v_mfma_f32_16x16x32_bf16 v[74:77], v[206:209], v[234:237], v[74:77]
	v_mfma_f32_16x16x32_bf16 v[78:81], v[214:217], v[226:229], v[78:81]
	v_mfma_f32_16x16x32_bf16 v[86:89], v[214:217], v[234:237], v[86:89]
	v_mfma_f32_16x16x32_bf16 v[14:17], v[194:197], v[230:233], v[14:17]
	v_mfma_f32_16x16x32_bf16 v[10:13], v[194:197], v[238:241], v[10:13]
	v_mfma_f32_16x16x32_bf16 v[6:9], v[202:205], v[230:233], v[6:9]
	v_mfma_f32_16x16x32_bf16 v[2:5], v[202:205], v[238:241], v[2:5]
	v_mfma_f32_16x16x32_bf16 v[70:73], v[210:213], v[230:233], v[70:73]
	v_mfma_f32_16x16x32_bf16 v[74:77], v[210:213], v[238:241], v[74:77]
	v_mfma_f32_16x16x32_bf16 v[78:81], v[218:221], v[230:233], v[78:81]
	v_mfma_f32_16x16x32_bf16 v[86:89], v[218:221], v[238:241], v[86:89]
	s_barrier
	ds_read_b128 v[180:183], v155
	ds_read_b128 v[184:187], v155 offset:1024
	ds_read_b128 v[188:191], v155 offset:2048
	ds_read_b128 v[192:195], v155 offset:3072
	v_readfirstlane_b32 s68, v150
	v_add_u32_e32 v173, s54, v164
	v_add_u32_e32 v174, s55, v164
	v_add_u32_e32 v175, s64, v164
	v_lshl_add_u64 v[226:227], v[224:225], 0, s[12:13]
	s_mov_b32 m0, s68
	v_readfirstlane_b32 s68, v151
	ds_read_b128 v[176:179], v154
	ds_read_b128 v[196:199], v154 offset:1024
	ds_read_b128 v[200:203], v173
	ds_read_b128 v[204:207], v173 offset:1024
	ds_read_b128 v[208:211], v174
	ds_read_b128 v[212:215], v174 offset:1024
	ds_read_b128 v[216:219], v175
	ds_read_b128 v[220:223], v175 offset:1024
	global_load_lds_dwordx4 v[226:227], off
	v_lshl_add_u64 v[226:227], v[246:247], 0, s[12:13]
	s_mov_b32 m0, s68
	s_nop 0
	global_load_lds_dwordx4 v[226:227], off
	s_waitcnt lgkmcnt(8)
	s_barrier
	s_waitcnt lgkmcnt(0)
	s_waitcnt lgkmcnt(0)
	v_mfma_f32_16x16x32_bf16 v[126:129], v[176:179], v[180:183], v[126:129]
	v_mfma_f32_16x16x32_bf16 v[122:125], v[176:179], v[188:191], v[122:125]
	v_mfma_f32_16x16x32_bf16 v[118:121], v[200:203], v[180:183], v[118:121]
	v_mfma_f32_16x16x32_bf16 v[114:117], v[200:203], v[188:191], v[114:117]
	v_mfma_f32_16x16x32_bf16 v[110:113], v[208:211], v[180:183], v[110:113]
	v_mfma_f32_16x16x32_bf16 v[106:109], v[208:211], v[188:191], v[106:109]
	v_mfma_f32_16x16x32_bf16 v[102:105], v[216:219], v[180:183], v[102:105]
	v_mfma_f32_16x16x32_bf16 v[98:101], v[216:219], v[188:191], v[98:101]
	v_mfma_f32_16x16x32_bf16 v[126:129], v[196:199], v[184:187], v[126:129]
	v_mfma_f32_16x16x32_bf16 v[122:125], v[196:199], v[192:195], v[122:125]
	v_mfma_f32_16x16x32_bf16 v[118:121], v[204:207], v[184:187], v[118:121]
	v_mfma_f32_16x16x32_bf16 v[114:117], v[204:207], v[192:195], v[114:117]
	v_mfma_f32_16x16x32_bf16 v[110:113], v[212:215], v[184:187], v[110:113]
	v_mfma_f32_16x16x32_bf16 v[106:109], v[212:215], v[192:195], v[106:109]
	v_mfma_f32_16x16x32_bf16 v[102:105], v[220:223], v[184:187], v[102:105]
	v_mfma_f32_16x16x32_bf16 v[98:101], v[220:223], v[192:195], v[98:101]
	s_barrier
	v_readfirstlane_b32 s68, v156
	v_lshl_add_u64 v[242:243], v[248:249], 0, s[18:19]
	s_mov_b32 m0, s68
	v_readfirstlane_b32 s68, v157
	ds_read_b128 v[226:229], v153
	ds_read_b128 v[230:233], v153 offset:1024
	ds_read_b128 v[234:237], v153 offset:2048
	ds_read_b128 v[238:241], v153 offset:3072
	global_load_lds_dwordx4 v[242:243], off
	v_lshl_add_u64 v[242:243], v[250:251], 0, s[18:19]
	s_mov_b32 m0, s68
	s_nop 0
	global_load_lds_dwordx4 v[242:243], off
	s_barrier
	s_waitcnt lgkmcnt(0)
	s_waitcnt lgkmcnt(0)
	v_mfma_f32_16x16x32_bf16 v[94:97], v[176:179], v[226:229], v[94:97]
	v_mfma_f32_16x16x32_bf16 v[90:93], v[176:179], v[234:237], v[90:93]
	v_mfma_f32_16x16x32_bf16 v[82:85], v[200:203], v[226:229], v[82:85]
	v_mfma_f32_16x16x32_bf16 v[66:69], v[200:203], v[234:237], v[66:69]
	v_mfma_f32_16x16x32_bf16 v[62:65], v[208:211], v[226:229], v[62:65]
	v_mfma_f32_16x16x32_bf16 v[58:61], v[208:211], v[234:237], v[58:61]
	v_mfma_f32_16x16x32_bf16 v[54:57], v[216:219], v[226:229], v[54:57]
	v_mfma_f32_16x16x32_bf16 v[50:53], v[216:219], v[234:237], v[50:53]
	v_mfma_f32_16x16x32_bf16 v[94:97], v[196:199], v[230:233], v[94:97]
	v_mfma_f32_16x16x32_bf16 v[90:93], v[196:199], v[238:241], v[90:93]
	v_mfma_f32_16x16x32_bf16 v[82:85], v[204:207], v[230:233], v[82:85]
	v_mfma_f32_16x16x32_bf16 v[66:69], v[204:207], v[238:241], v[66:69]
	v_mfma_f32_16x16x32_bf16 v[62:65], v[212:215], v[230:233], v[62:65]
	v_mfma_f32_16x16x32_bf16 v[58:61], v[212:215], v[238:241], v[58:61]
	v_mfma_f32_16x16x32_bf16 v[54:57], v[220:223], v[230:233], v[54:57]
	v_mfma_f32_16x16x32_bf16 v[50:53], v[220:223], v[238:241], v[50:53]
	v_readfirstlane_b32 s68, v158
	v_add_u32_e32 v176, s54, v165
	v_add_u32_e32 v177, s55, v165
	v_add_u32_e32 v178, s64, v165
	v_lshl_add_u64 v[224:225], v[224:225], 0, s[20:21]
	s_mov_b32 m0, s68
	v_readfirstlane_b32 s68, v159
	s_barrier
	ds_read_b128 v[196:199], v152
	ds_read_b128 v[200:203], v152 offset:1024
	ds_read_b128 v[204:207], v176
	ds_read_b128 v[208:211], v176 offset:1024
	ds_read_b128 v[212:215], v177
	ds_read_b128 v[216:219], v177 offset:1024
	ds_read_b128 v[220:223], v178
	ds_read_b128 v[242:245], v178 offset:1024
	global_load_lds_dwordx4 v[224:225], off
	v_lshl_add_u64 v[224:225], v[246:247], 0, s[20:21]
	s_mov_b32 m0, s68
	s_nop 0
	global_load_lds_dwordx4 v[224:225], off
	s_barrier
	s_waitcnt lgkmcnt(0)
	s_waitcnt lgkmcnt(0)
	v_mfma_f32_16x16x32_bf16 v[46:49], v[196:199], v[180:183], v[46:49]
	v_mfma_f32_16x16x32_bf16 v[42:45], v[196:199], v[188:191], v[42:45]
	v_mfma_f32_16x16x32_bf16 v[38:41], v[204:207], v[180:183], v[38:41]
	v_mfma_f32_16x16x32_bf16 v[34:37], v[204:207], v[188:191], v[34:37]
	v_mfma_f32_16x16x32_bf16 v[30:33], v[212:215], v[180:183], v[30:33]
	v_mfma_f32_16x16x32_bf16 v[26:29], v[212:215], v[188:191], v[26:29]
	v_mfma_f32_16x16x32_bf16 v[22:25], v[220:223], v[180:183], v[22:25]
	v_mfma_f32_16x16x32_bf16 v[18:21], v[220:223], v[188:191], v[18:21]
	v_mfma_f32_16x16x32_bf16 v[46:49], v[200:203], v[184:187], v[46:49]
	v_mfma_f32_16x16x32_bf16 v[42:45], v[200:203], v[192:195], v[42:45]
	v_mfma_f32_16x16x32_bf16 v[38:41], v[208:211], v[184:187], v[38:41]
	v_mfma_f32_16x16x32_bf16 v[34:37], v[208:211], v[192:195], v[34:37]
	v_mfma_f32_16x16x32_bf16 v[30:33], v[216:219], v[184:187], v[30:33]
	v_mfma_f32_16x16x32_bf16 v[26:29], v[216:219], v[192:195], v[26:29]
	v_mfma_f32_16x16x32_bf16 v[22:25], v[242:245], v[184:187], v[22:25]
	v_mfma_f32_16x16x32_bf16 v[18:21], v[242:245], v[192:195], v[18:21]
	s_barrier
	v_readfirstlane_b32 s68, v160
	v_lshl_add_u64 v[180:181], v[248:249], 0, s[22:23]
	s_mov_b32 m0, s68
	v_readfirstlane_b32 s68, v161
	global_load_lds_dwordx4 v[180:181], off
	v_lshl_add_u64 v[180:181], v[250:251], 0, s[22:23]
	s_mov_b32 m0, s68
	s_nop 0
	global_load_lds_dwordx4 v[180:181], off
	s_waitcnt vmcnt(6)
	s_barrier
	v_mfma_f32_16x16x32_bf16 v[14:17], v[196:199], v[226:229], v[14:17]
	v_mfma_f32_16x16x32_bf16 v[10:13], v[196:199], v[234:237], v[10:13]
	v_mfma_f32_16x16x32_bf16 v[6:9], v[204:207], v[226:229], v[6:9]
	v_mfma_f32_16x16x32_bf16 v[2:5], v[204:207], v[234:237], v[2:5]
	v_mfma_f32_16x16x32_bf16 v[70:73], v[212:215], v[226:229], v[70:73]
	v_mfma_f32_16x16x32_bf16 v[74:77], v[212:215], v[234:237], v[74:77]
	v_mfma_f32_16x16x32_bf16 v[78:81], v[220:223], v[226:229], v[78:81]
	v_mfma_f32_16x16x32_bf16 v[86:89], v[220:223], v[234:237], v[86:89]
	v_mfma_f32_16x16x32_bf16 v[14:17], v[200:203], v[230:233], v[14:17]
	v_mfma_f32_16x16x32_bf16 v[10:13], v[200:203], v[238:241], v[10:13]
	v_mfma_f32_16x16x32_bf16 v[6:9], v[208:211], v[230:233], v[6:9]
	v_mfma_f32_16x16x32_bf16 v[2:5], v[208:211], v[238:241], v[2:5]
	v_mfma_f32_16x16x32_bf16 v[70:73], v[216:219], v[230:233], v[70:73]
	v_mfma_f32_16x16x32_bf16 v[74:77], v[216:219], v[238:241], v[74:77]
	v_mfma_f32_16x16x32_bf16 v[78:81], v[242:245], v[230:233], v[78:81]
	v_mfma_f32_16x16x32_bf16 v[86:89], v[242:245], v[238:241], v[86:89]
	s_add_i32 s65, s65, 2
	s_add_u32 s42, s42, 0x100
	s_addc_u32 s43, s43, 0
	s_cmp_lt_u32 s65, 40
	s_barrier
	s_cbranch_scc1 .LBB0_1992
	s_or_b32 s42, s49, 0x80
	s_mul_i32 s52, s42, 0x1600
	s_mul_hi_i32 s43, s42, 0x1600
	s_add_u32 s52, s94, s52
	s_addc_u32 s43, s95, s43
	s_add_u32 s52, s52, 0x1580
	s_addc_u32 s53, s43, 0
	v_readfirstlane_b32 s43, v171
	v_lshl_add_u64 v[164:165], v[130:131], 1, s[52:53]
	s_mov_b32 m0, s43
	v_readfirstlane_b32 s43, v172
	ds_read_b128 v[134:137], v170 offset:32768
	ds_read_b128 v[138:141], v170 offset:33792
	ds_read_b128 v[144:147], v170 offset:34816
	ds_read_b128 v[148:151], v170 offset:35840
	ds_read_b128 v[156:159], v166
	ds_read_b128 v[160:163], v166 offset:1024
	ds_read_b128 v[180:183], v167
	ds_read_b128 v[184:187], v167 offset:1024
	ds_read_b128 v[188:191], v168
	ds_read_b128 v[192:195], v168 offset:1024
	ds_read_b128 v[196:199], v169
	ds_read_b128 v[200:203], v169 offset:1024
	global_load_lds_dwordx4 v[164:165], off
	v_lshl_add_u64 v[132:133], v[132:133], 1, s[52:53]
	s_mov_b32 m0, s43
	s_nop 0
	global_load_lds_dwordx4 v[132:133], off
	s_barrier
	s_waitcnt lgkmcnt(0)
	s_waitcnt lgkmcnt(0)
	v_mfma_f32_16x16x32_bf16 v[126:129], v[156:159], v[134:137], v[126:129]
	v_mfma_f32_16x16x32_bf16 v[122:125], v[156:159], v[144:147], v[122:125]
	v_mfma_f32_16x16x32_bf16 v[118:121], v[180:183], v[134:137], v[118:121]
	v_mfma_f32_16x16x32_bf16 v[114:117], v[180:183], v[144:147], v[114:117]
	v_mfma_f32_16x16x32_bf16 v[110:113], v[188:191], v[134:137], v[110:113]
	v_mfma_f32_16x16x32_bf16 v[126:129], v[160:163], v[138:141], v[126:129]
	v_mfma_f32_16x16x32_bf16 v[122:125], v[160:163], v[148:151], v[122:125]
	v_mfma_f32_16x16x32_bf16 v[118:121], v[184:187], v[138:141], v[118:121]
	v_mfma_f32_16x16x32_bf16 v[114:117], v[184:187], v[148:151], v[114:117]
	v_mfma_f32_16x16x32_bf16 v[110:113], v[192:195], v[138:141], v[110:113]
	v_mfma_f32_16x16x32_bf16 v[106:109], v[188:191], v[144:147], v[106:109]
	v_mfma_f32_16x16x32_bf16 v[102:105], v[196:199], v[134:137], v[102:105]
	v_mfma_f32_16x16x32_bf16 v[98:101], v[196:199], v[144:147], v[98:101]
	v_mfma_f32_16x16x32_bf16 v[204:207], v[192:195], v[148:151], v[106:109]
	v_mfma_f32_16x16x32_bf16 v[208:211], v[200:203], v[138:141], v[102:105]
	v_mfma_f32_16x16x32_bf16 v[212:215], v[200:203], v[148:151], v[98:101]
	s_barrier
	s_nop 2
	ds_read_b128 v[98:101], v170 offset:49152
	ds_read_b128 v[102:105], v170 offset:50176
	ds_read_b128 v[106:109], v170 offset:51200
	ds_read_b128 v[216:219], v170 offset:52224
	s_barrier
	s_waitcnt lgkmcnt(0)
	s_waitcnt lgkmcnt(0)
	v_mfma_f32_16x16x32_bf16 v[94:97], v[156:159], v[98:101], v[94:97]
	v_mfma_f32_16x16x32_bf16 v[90:93], v[156:159], v[106:109], v[90:93]
	v_mfma_f32_16x16x32_bf16 v[82:85], v[180:183], v[98:101], v[82:85]
	v_mfma_f32_16x16x32_bf16 v[62:65], v[188:191], v[98:101], v[62:65]
	v_mfma_f32_16x16x32_bf16 v[58:61], v[188:191], v[106:109], v[58:61]
	v_mfma_f32_16x16x32_bf16 v[54:57], v[196:199], v[98:101], v[54:57]
	v_mfma_f32_16x16x32_bf16 v[50:53], v[196:199], v[106:109], v[50:53]
	v_mfma_f32_16x16x32_bf16 v[94:97], v[160:163], v[102:105], v[94:97]
	v_mfma_f32_16x16x32_bf16 v[90:93], v[160:163], v[216:219], v[90:93]
	v_mfma_f32_16x16x32_bf16 v[82:85], v[184:187], v[102:105], v[82:85]
	v_mfma_f32_16x16x32_bf16 v[66:69], v[180:183], v[106:109], v[66:69]
	v_mfma_f32_16x16x32_bf16 v[62:65], v[192:195], v[102:105], v[62:65]
	v_mfma_f32_16x16x32_bf16 v[58:61], v[192:195], v[216:219], v[58:61]
	v_mfma_f32_16x16x32_bf16 v[54:57], v[200:203], v[102:105], v[54:57]
	v_mfma_f32_16x16x32_bf16 v[50:53], v[200:203], v[216:219], v[50:53]
	v_mfma_f32_16x16x32_bf16 v[156:159], v[184:187], v[216:219], v[66:69]
	s_barrier
	s_nop 0
	ds_read_b128 v[66:69], v166 offset:16384
	ds_read_b128 v[160:163], v166 offset:17408
	ds_read_b128 v[180:183], v167 offset:16384
	ds_read_b128 v[164:167], v167 offset:17408
	ds_read_b128 v[184:187], v168 offset:16384
	ds_read_b128 v[188:191], v168 offset:17408
	ds_read_b128 v[192:195], v169 offset:16384
	ds_read_b128 v[168:171], v169 offset:17408
	s_waitcnt vmcnt(4)
	s_barrier
	s_waitcnt lgkmcnt(0)
	s_waitcnt lgkmcnt(0)
	v_mfma_f32_16x16x32_bf16 v[46:49], v[66:69], v[134:137], v[46:49]
	v_mfma_f32_16x16x32_bf16 v[42:45], v[66:69], v[144:147], v[42:45]
	v_mfma_f32_16x16x32_bf16 v[30:33], v[184:187], v[134:137], v[30:33]
	v_mfma_f32_16x16x32_bf16 v[26:29], v[184:187], v[144:147], v[26:29]
	v_mfma_f32_16x16x32_bf16 v[22:25], v[192:195], v[134:137], v[22:25]
	v_mfma_f32_16x16x32_bf16 v[18:21], v[192:195], v[144:147], v[18:21]
	v_mfma_f32_16x16x32_bf16 v[46:49], v[160:163], v[138:141], v[46:49]
	v_mfma_f32_16x16x32_bf16 v[42:45], v[160:163], v[148:151], v[42:45]
	v_mfma_f32_16x16x32_bf16 v[38:41], v[180:183], v[134:137], v[38:41]
	v_mfma_f32_16x16x32_bf16 v[34:37], v[180:183], v[144:147], v[34:37]
	v_mfma_f32_16x16x32_bf16 v[30:33], v[188:191], v[138:141], v[30:33]
	v_mfma_f32_16x16x32_bf16 v[26:29], v[188:191], v[148:151], v[26:29]
	v_mfma_f32_16x16x32_bf16 v[22:25], v[168:171], v[138:141], v[22:25]
	v_mfma_f32_16x16x32_bf16 v[18:21], v[168:171], v[148:151], v[18:21]
	v_mfma_f32_16x16x32_bf16 v[196:199], v[164:167], v[138:141], v[38:41]
	v_mfma_f32_16x16x32_bf16 v[200:203], v[164:167], v[148:151], v[34:37]
	v_mfma_f32_16x16x32_bf16 v[2:5], v[180:183], v[106:109], v[2:5]
	v_mfma_f32_16x16x32_bf16 v[136:139], v[164:167], v[216:219], v[2:5]
	v_mfma_f32_16x16x32_bf16 v[2:5], v[184:187], v[98:101], v[70:73]
	v_mfma_f32_16x16x32_bf16 v[144:147], v[188:191], v[102:105], v[2:5]
	v_mfma_f32_16x16x32_bf16 v[2:5], v[184:187], v[106:109], v[74:77]
	v_mfma_f32_16x16x32_bf16 v[14:17], v[66:69], v[98:101], v[14:17]
	v_mfma_f32_16x16x32_bf16 v[10:13], v[66:69], v[106:109], v[10:13]
	v_mfma_f32_16x16x32_bf16 v[148:151], v[188:191], v[216:219], v[2:5]
	v_mfma_f32_16x16x32_bf16 v[2:5], v[192:195], v[98:101], v[78:81]
	v_mfma_f32_16x16x32_bf16 v[14:17], v[160:163], v[102:105], v[14:17]
	v_mfma_f32_16x16x32_bf16 v[10:13], v[160:163], v[216:219], v[10:13]
	v_mfma_f32_16x16x32_bf16 v[6:9], v[180:183], v[98:101], v[6:9]
	v_mfma_f32_16x16x32_bf16 v[160:163], v[168:171], v[102:105], v[2:5]
	v_mfma_f32_16x16x32_bf16 v[2:5], v[192:195], v[106:109], v[86:89]
	v_mfma_f32_16x16x32_bf16 v[132:135], v[164:167], v[102:105], v[6:9]
	v_mfma_f32_16x16x32_bf16 v[164:167], v[168:171], v[216:219], v[2:5]
	s_barrier
	s_nop 3
	ds_read_b128 v[2:5], v155
	ds_read_b128 v[6:9], v155 offset:1024
	ds_read_b128 v[168:171], v155 offset:2048
	ds_read_b128 v[180:183], v155 offset:3072
	ds_read_b128 v[34:37], v154
	ds_read_b128 v[38:41], v154 offset:1024
	ds_read_b128 v[78:81], v173
	ds_read_b128 v[86:89], v173 offset:1024
	ds_read_b128 v[184:187], v174
	ds_read_b128 v[188:191], v174 offset:1024
	ds_read_b128 v[192:195], v175
	ds_read_b128 v[172:175], v175 offset:1024
	s_waitcnt vmcnt(2)
	s_barrier
	s_waitcnt lgkmcnt(0)
	s_waitcnt lgkmcnt(0)
	v_mfma_f32_16x16x32_bf16 v[66:69], v[34:37], v[2:5], v[126:129]
	v_mfma_f32_16x16x32_bf16 v[126:129], v[38:41], v[6:9], v[66:69]
	v_mfma_f32_16x16x32_bf16 v[66:69], v[34:37], v[168:171], v[122:125]
	v_mfma_f32_16x16x32_bf16 v[98:101], v[38:41], v[180:183], v[66:69]
	v_mfma_f32_16x16x32_bf16 v[66:69], v[78:81], v[2:5], v[118:121]
	v_mfma_f32_16x16x32_bf16 v[102:105], v[86:89], v[6:9], v[66:69]
	v_mfma_f32_16x16x32_bf16 v[66:69], v[78:81], v[168:171], v[114:117]
	v_mfma_f32_16x16x32_bf16 v[106:109], v[86:89], v[180:183], v[66:69]
	v_mfma_f32_16x16x32_bf16 v[66:69], v[184:187], v[2:5], v[110:113]
	v_mfma_f32_16x16x32_bf16 v[110:113], v[188:191], v[6:9], v[66:69]
	v_mfma_f32_16x16x32_bf16 v[66:69], v[184:187], v[168:171], v[204:207]
	v_mfma_f32_16x16x32_bf16 v[114:117], v[188:191], v[180:183], v[66:69]
	v_mfma_f32_16x16x32_bf16 v[66:69], v[192:195], v[2:5], v[208:211]
	v_mfma_f32_16x16x32_bf16 v[118:121], v[172:175], v[6:9], v[66:69]
	v_mfma_f32_16x16x32_bf16 v[66:69], v[192:195], v[168:171], v[212:215]
	v_mfma_f32_16x16x32_bf16 v[122:125], v[172:175], v[180:183], v[66:69]
	s_barrier
	ds_read_b128 v[204:207], v153
	ds_read_b128 v[208:211], v153 offset:1024
	ds_read_b128 v[212:215], v153 offset:2048
	ds_read_b128 v[216:219], v153 offset:3072
	s_waitcnt vmcnt(0)
	s_barrier
	s_waitcnt lgkmcnt(0)
	s_waitcnt lgkmcnt(0)
	v_mfma_f32_16x16x32_bf16 v[66:69], v[34:37], v[204:207], v[94:97]
	v_mfma_f32_16x16x32_bf16 v[34:37], v[34:37], v[212:215], v[90:93]
	v_mfma_f32_16x16x32_bf16 v[70:73], v[38:41], v[216:219], v[34:37]
	v_mfma_f32_16x16x32_bf16 v[34:37], v[78:81], v[204:207], v[82:85]
	v_mfma_f32_16x16x32_bf16 v[74:77], v[86:89], v[208:211], v[34:37]
	v_mfma_f32_16x16x32_bf16 v[34:37], v[78:81], v[212:215], v[156:159]
	v_mfma_f32_16x16x32_bf16 v[78:81], v[86:89], v[216:219], v[34:37]
	v_mfma_f32_16x16x32_bf16 v[34:37], v[184:187], v[204:207], v[62:65]
	v_mfma_f32_16x16x32_bf16 v[82:85], v[188:191], v[208:211], v[34:37]
	v_mfma_f32_16x16x32_bf16 v[34:37], v[184:187], v[212:215], v[58:61]
	v_mfma_f32_16x16x32_bf16 v[86:89], v[188:191], v[216:219], v[34:37]
	v_mfma_f32_16x16x32_bf16 v[34:37], v[192:195], v[204:207], v[54:57]
	v_mfma_f32_16x16x32_bf16 v[90:93], v[172:175], v[208:211], v[34:37]
	v_mfma_f32_16x16x32_bf16 v[34:37], v[192:195], v[212:215], v[50:53]
	v_mfma_f32_16x16x32_bf16 v[66:69], v[38:41], v[208:211], v[66:69]
	v_mfma_f32_16x16x32_bf16 v[94:97], v[172:175], v[216:219], v[34:37]
	s_barrier
	ds_read_b128 v[154:157], v152
	ds_read_b128 v[172:175], v152 offset:1024
	ds_read_b128 v[184:187], v176
	ds_read_b128 v[188:191], v176 offset:1024
	ds_read_b128 v[192:195], v177
	ds_read_b128 v[220:223], v177 offset:1024
	ds_read_b128 v[226:229], v178
	ds_read_b128 v[176:179], v178 offset:1024
	s_barrier
	s_waitcnt lgkmcnt(0)
	s_waitcnt lgkmcnt(0)
	v_mfma_f32_16x16x32_bf16 v[34:37], v[154:157], v[2:5], v[46:49]
	v_mfma_f32_16x16x32_bf16 v[38:41], v[154:157], v[168:171], v[42:45]
	v_mfma_f32_16x16x32_bf16 v[42:45], v[184:187], v[2:5], v[196:199]
	v_mfma_f32_16x16x32_bf16 v[30:33], v[192:195], v[2:5], v[30:33]
	v_mfma_f32_16x16x32_bf16 v[2:5], v[226:229], v[2:5], v[22:25]
	v_mfma_f32_16x16x32_bf16 v[46:49], v[184:187], v[168:171], v[200:203]
	v_mfma_f32_16x16x32_bf16 v[26:29], v[192:195], v[168:171], v[26:29]
	v_mfma_f32_16x16x32_bf16 v[58:61], v[176:179], v[6:9], v[2:5]
	v_mfma_f32_16x16x32_bf16 v[2:5], v[226:229], v[168:171], v[18:21]
	v_mfma_f32_16x16x32_bf16 v[34:37], v[172:175], v[6:9], v[34:37]
	v_mfma_f32_16x16x32_bf16 v[38:41], v[172:175], v[180:183], v[38:41]
	v_mfma_f32_16x16x32_bf16 v[42:45], v[188:191], v[6:9], v[42:45]
	v_mfma_f32_16x16x32_bf16 v[46:49], v[188:191], v[180:183], v[46:49]
	v_mfma_f32_16x16x32_bf16 v[50:53], v[220:223], v[6:9], v[30:33]
	v_mfma_f32_16x16x32_bf16 v[54:57], v[220:223], v[180:183], v[26:29]
	v_mfma_f32_16x16x32_bf16 v[62:65], v[176:179], v[180:183], v[2:5]
	v_mfma_f32_16x16x32_bf16 v[2:5], v[154:157], v[204:207], v[14:17]
	v_mfma_f32_16x16x32_bf16 v[6:9], v[154:157], v[212:215], v[10:13]
	v_mfma_f32_16x16x32_bf16 v[10:13], v[184:187], v[204:207], v[132:135]
	v_mfma_f32_16x16x32_bf16 v[14:17], v[184:187], v[212:215], v[136:139]
	v_mfma_f32_16x16x32_bf16 v[18:21], v[192:195], v[204:207], v[144:147]
	v_mfma_f32_16x16x32_bf16 v[22:25], v[192:195], v[212:215], v[148:151]
	v_mfma_f32_16x16x32_bf16 v[26:29], v[226:229], v[204:207], v[160:163]
	v_mfma_f32_16x16x32_bf16 v[30:33], v[226:229], v[212:215], v[164:167]
	v_mfma_f32_16x16x32_bf16 v[2:5], v[172:175], v[208:211], v[2:5]
	v_mfma_f32_16x16x32_bf16 v[6:9], v[172:175], v[216:219], v[6:9]
	v_mfma_f32_16x16x32_bf16 v[10:13], v[188:191], v[208:211], v[10:13]
	v_mfma_f32_16x16x32_bf16 v[14:17], v[188:191], v[216:219], v[14:17]
	v_mfma_f32_16x16x32_bf16 v[18:21], v[220:223], v[208:211], v[18:21]
	v_mfma_f32_16x16x32_bf16 v[22:25], v[220:223], v[216:219], v[22:25]
	v_mfma_f32_16x16x32_bf16 v[26:29], v[176:179], v[208:211], v[26:29]
	v_mfma_f32_16x16x32_bf16 v[30:33], v[176:179], v[216:219], v[30:33]
	s_setprio 0
	s_cmpk_gt_u32 s51, 0xff
	s_barrier
	s_cbranch_scc1 .LBB0_1995
	s_barrier
